# also drop the 96 now back-to-back duplicate s_waitcnt lgkmcnt(0) in the GEMM K loops / peeled iterations
# speedup vs baseline: 1.0108x; 1.0108x over previous
; #define PG8_STAGE(bufoff, gbase, voff) do { _Pragma("unroll") for (int _i = 0; _i < 2; ++_i) \
;         __builtin_amdgcn_global_load_lds((const unsigned*)((const char*)(gbase) + (voff)[_i]), (LAS unsigned*)(lds + (bufoff) + ldsw + _i * 8192), 16, 0, 0); } while (0)
; #define PG8_LDA(dst, b, h) do { _Pragma("unroll") for (int m = 0; m < 4; ++m) _Pragma("unroll") for (int k = 0; k < 2; ++k) dst[m][k] = *(const LAS bf16x8*)(lds + PG8_SA(b, h) + aoff + m * 2048 + k * 1024); } while (0)
; #define PG8_LDB(dst, b, h) do { _Pragma("unroll") for (int n = 0; n < 2; ++n) _Pragma("unroll") for (int k = 0; k < 2; ++k) dst[n][k] = *(const LAS bf16x8*)(lds + PG8_SB(b, h) + boff + n * 2048 + k * 1024); } while (0)
; #define PG8_MMA(ai, bj, At, Bt) do { __builtin_amdgcn_s_setprio(1); _Pragma("unroll") for (int m = 0; m < 4; ++m) _Pragma("unroll") for (int n = 0; n < 2; ++n) _Pragma("unroll") for (int k = 0; k < 2; ++k) \
;         acc[ai][bj][m][n] = __builtin_amdgcn_mfma_f32_16x16x32_bf16(Bt[n][k], At[m][k], acc[ai][bj][m][n], 0, 0, 0); __builtin_amdgcn_s_setprio(0); } while (0)
; #define PG8_BAR __builtin_amdgcn_s_barrier()
; template <class Epi>
; __device__ __forceinline__ void gemm_phase(LAS unsigned char* lds, const Gemm g, const StaticOrder& S, const Epi& E) {
;     ...
;         const bool has_next = S.next(ui + 1, nxt);
;         const char* nA = has_next ? (const char*)g.A + (size_t)nxt.pm * tstepA : cA; const char* nB = has_next ? (const char*)g.Bt + (size_t)nxt.pn * tstepB : cB;
;         for (int t = 0; t < nt; t += 2) {
;             const bool last = (t == nt - 2);
;             const char* a1 = cA + (size_t)(t + 1) * kstep;
;             const char* a2 = last ? nA : cA + (size_t)(t + 2) * kstep; const char* b2 = last ? nB : cB + (size_t)(t + 2) * kstep;
;             const char* a3 = a2 + kstep; const char* b3 = b2 + kstep;
;             if (last) E.pre(cur, wr, fr, epre);
;             PG8_LDB(B0, 0, 0); PG8_SCHED; PG8_LDA(At, 0, 0); PG8_STAGE(PG8_SA(1, 1), a1 + hstepA, voffA);
;             PG8_WAIT_L(8); PG8_BAR; PG8_WAIT_L(0); PG8_MMA(0, 0, At, B0); PG8_BAR; PG8_SCHED;
;             PG8_LDB(B1, 0, 1); PG8_STAGE(PG8_SB(0, 0), b2, voffB);
;             PG8_BAR; PG8_WAIT_L(0); PG8_MMA(0, 1, At, B1); PG8_BAR;
;             PG8_LDA(At, 0, 1); PG8_STAGE(PG8_SA(0, 0), a2, voffA);
;             PG8_BAR; PG8_WAIT_L(0); PG8_MMA(1, 0, At, B0); PG8_BAR; PG8_SCHED;
.LBB0_204:
	s_ashr_i32 s13, s12, 31
	v_cmp_lt_i64_e32 vcc, s[14:15], v[142:143]
	s_lshl_b64 s[14:15], s[12:13], 19
	s_add_u32 s14, s76, s14
	s_addc_u32 s15, s77, s15
	s_and_b64 s[16:17], vcc, exec
	s_cselect_b32 s13, s15, s21
	s_cselect_b32 s19, s14, s20
	s_ashr_i32 s11, s10, 31
	s_lshl_b64 s[16:17], s[10:11], 19
	s_add_u32 s16, s74, s16
	s_addc_u32 s17, s75, s17
	s_and_b64 s[24:25], vcc, exec
	s_cselect_b32 s11, s17, s23
	s_cselect_b32 s44, s16, s22
	s_add_u32 s20, s20, 0x40080
	s_addc_u32 s21, s21, 0
	s_add_u32 s45, s22, 0x100
	s_addc_u32 s46, s23, 0
	s_mov_b32 s47, -2
	s_waitcnt lgkmcnt(0)
	ds_read_b128 v[146:149], v170
	ds_read_b128 v[154:157], v170 offset:1024
	ds_read_b128 v[158:161], v170 offset:2048
	ds_read_b128 v[162:165], v170 offset:3072
	s_add_u32 s22, s20, 0xfffc0080
	s_addc_u32 s23, s21, -1
	s_cmp_eq_u32 s47, 12
	s_cselect_b32 s25, s13, s23
	s_cselect_b32 s24, s19, s22
	s_cselect_b32 s23, s11, s46
	s_cselect_b32 s22, s44, s45
	v_lshl_add_u64 v[150:151], s[20:21], 0, v[138:139]
	s_add_i32 m0, s30, 0xc000
	ds_read_b128 v[174:177], v171
	ds_read_b128 v[178:181], v171 offset:1024
	ds_read_b128 v[182:185], v171 offset:2048
	ds_read_b128 v[186:189], v171 offset:3072
	ds_read_b128 v[190:193], v171 offset:4096
	ds_read_b128 v[194:197], v171 offset:5120
	ds_read_b128 v[198:201], v171 offset:6144
	ds_read_b128 v[202:205], v171 offset:7168
	global_load_lds_dwordx4 v[150:151], off
	v_lshl_add_u64 v[150:151], s[20:21], 0, v[140:141]
	s_add_i32 m0, s30, 0xe000
	s_nop 0
	global_load_lds_dwordx4 v[150:151], off
	s_waitcnt lgkmcnt(8)
	s_barrier
	s_waitcnt lgkmcnt(0)
	v_mfma_f32_16x16x32_bf16 v[76:79], v[146:149], v[174:177], 0
	v_mfma_f32_16x16x32_bf16 v[64:67], v[158:161], v[174:177], 0
	v_mfma_f32_16x16x32_bf16 v[60:63], v[146:149], v[182:185], 0
	v_mfma_f32_16x16x32_bf16 v[56:59], v[158:161], v[182:185], 0
	v_mfma_f32_16x16x32_bf16 v[48:51], v[146:149], v[190:193], 0
	v_mfma_f32_16x16x32_bf16 v[40:43], v[158:161], v[190:193], 0
	v_mfma_f32_16x16x32_bf16 v[36:39], v[146:149], v[198:201], 0
	v_mfma_f32_16x16x32_bf16 v[32:35], v[158:161], v[198:201], 0
	v_mfma_f32_16x16x32_bf16 v[76:79], v[154:157], v[178:181], v[76:79]
	v_mfma_f32_16x16x32_bf16 v[64:67], v[162:165], v[178:181], v[64:67]
	v_mfma_f32_16x16x32_bf16 v[60:63], v[154:157], v[186:189], v[60:63]
	v_mfma_f32_16x16x32_bf16 v[56:59], v[162:165], v[186:189], v[56:59]
	v_mfma_f32_16x16x32_bf16 v[48:51], v[154:157], v[194:197], v[48:51]
	v_mfma_f32_16x16x32_bf16 v[40:43], v[162:165], v[194:197], v[40:43]
	v_mfma_f32_16x16x32_bf16 v[36:39], v[154:157], v[202:205], v[36:39]
	v_mfma_f32_16x16x32_bf16 v[32:35], v[162:165], v[202:205], v[32:35]
	s_barrier
	s_add_i32 s48, s39, s27
	v_lshl_add_u64 v[150:151], s[22:23], 0, v[132:133]
	s_mov_b32 m0, s48
	ds_read_b128 v[206:209], v172
	ds_read_b128 v[210:213], v172 offset:1024
	ds_read_b128 v[214:217], v172 offset:2048
	ds_read_b128 v[218:221], v172 offset:3072
	global_load_lds_dwordx4 v[150:151], off
	v_lshl_add_u64 v[166:167], s[22:23], 0, v[128:129]
	s_add_i32 m0, s48, 0x2000
	s_nop 0
	global_load_lds_dwordx4 v[166:167], off
	s_barrier
	s_waitcnt lgkmcnt(0)
	v_mfma_f32_16x16x32_bf16 v[124:127], v[206:209], v[174:177], 0
	v_mfma_f32_16x16x32_bf16 v[120:123], v[214:217], v[174:177], 0
	v_mfma_f32_16x16x32_bf16 v[116:119], v[206:209], v[182:185], 0
	v_mfma_f32_16x16x32_bf16 v[112:115], v[214:217], v[182:185], 0
	v_mfma_f32_16x16x32_bf16 v[108:111], v[206:209], v[190:193], 0
	v_mfma_f32_16x16x32_bf16 v[104:107], v[214:217], v[190:193], 0
	v_mfma_f32_16x16x32_bf16 v[100:103], v[206:209], v[198:201], 0
	v_mfma_f32_16x16x32_bf16 v[96:99], v[214:217], v[198:201], 0
	v_mfma_f32_16x16x32_bf16 v[124:127], v[210:213], v[178:181], v[124:127]
	v_mfma_f32_16x16x32_bf16 v[120:123], v[218:221], v[178:181], v[120:123]
	v_mfma_f32_16x16x32_bf16 v[116:119], v[210:213], v[186:189], v[116:119]
	v_mfma_f32_16x16x32_bf16 v[112:115], v[218:221], v[186:189], v[112:115]
	v_mfma_f32_16x16x32_bf16 v[108:111], v[210:213], v[194:197], v[108:111]
	v_mfma_f32_16x16x32_bf16 v[104:107], v[218:221], v[194:197], v[104:107]
	v_mfma_f32_16x16x32_bf16 v[100:103], v[210:213], v[202:205], v[100:103]
	v_mfma_f32_16x16x32_bf16 v[96:99], v[218:221], v[202:205], v[96:99]
	s_mov_b32 m0, s30
	v_lshl_add_u64 v[222:223], s[24:25], 0, v[134:135]
	s_barrier
	ds_read_b128 v[174:177], v171 offset:16384
	ds_read_b128 v[178:181], v171 offset:17408
	ds_read_b128 v[182:185], v171 offset:18432
	ds_read_b128 v[186:189], v171 offset:19456
	ds_read_b128 v[190:193], v171 offset:20480
	ds_read_b128 v[194:197], v171 offset:21504
	ds_read_b128 v[198:201], v171 offset:22528
	ds_read_b128 v[202:205], v171 offset:23552
	global_load_lds_dwordx4 v[222:223], off
	v_lshl_add_u64 v[224:225], s[24:25], 0, v[130:131]
	s_mov_b32 m0, s31
	s_nop 0
	global_load_lds_dwordx4 v[224:225], off
	s_barrier
	s_waitcnt lgkmcnt(0)
	v_mfma_f32_16x16x32_bf16 v[28:31], v[146:149], v[174:177], 0
	v_mfma_f32_16x16x32_bf16 v[24:27], v[158:161], v[174:177], 0
	v_mfma_f32_16x16x32_bf16 v[20:23], v[146:149], v[182:185], 0
	v_mfma_f32_16x16x32_bf16 v[16:19], v[158:161], v[182:185], 0
	v_mfma_f32_16x16x32_bf16 v[12:15], v[146:149], v[190:193], 0
	v_mfma_f32_16x16x32_bf16 v[8:11], v[158:161], v[190:193], 0
	v_mfma_f32_16x16x32_bf16 v[4:7], v[146:149], v[198:201], 0
	v_mfma_f32_16x16x32_bf16 v[0:3], v[158:161], v[198:201], 0
	v_mfma_f32_16x16x32_bf16 v[28:31], v[154:157], v[178:181], v[28:31]
	v_mfma_f32_16x16x32_bf16 v[24:27], v[162:165], v[178:181], v[24:27]
	v_mfma_f32_16x16x32_bf16 v[20:23], v[154:157], v[186:189], v[20:23]
	v_mfma_f32_16x16x32_bf16 v[16:19], v[162:165], v[186:189], v[16:19]
	v_mfma_f32_16x16x32_bf16 v[12:15], v[154:157], v[194:197], v[12:15]
	v_mfma_f32_16x16x32_bf16 v[8:11], v[162:165], v[194:197], v[8:11]
	v_mfma_f32_16x16x32_bf16 v[4:7], v[154:157], v[202:205], v[4:7]
	v_mfma_f32_16x16x32_bf16 v[0:3], v[162:165], v[202:205], v[0:3]
	s_barrier
; #define PG8_STAGE(bufoff, gbase, voff) do { _Pragma("unroll") for (int _i = 0; _i < 2; ++_i) \
;         __builtin_amdgcn_global_load_lds((const unsigned*)((const char*)(gbase) + (voff)[_i]), (LAS unsigned*)(lds + (bufoff) + ldsw + _i * 8192), 16, 0, 0); } while (0)
; #define PG8_LDA(dst, b, h) do { _Pragma("unroll") for (int m = 0; m < 4; ++m) _Pragma("unroll") for (int k = 0; k < 2; ++k) dst[m][k] = *(const LAS bf16x8*)(lds + PG8_SA(b, h) + aoff + m * 2048 + k * 1024); } while (0)
; #define PG8_LDB(dst, b, h) do { _Pragma("unroll") for (int n = 0; n < 2; ++n) _Pragma("unroll") for (int k = 0; k < 2; ++k) dst[n][k] = *(const LAS bf16x8*)(lds + PG8_SB(b, h) + boff + n * 2048 + k * 1024); } while (0)
; #define PG8_MMA(ai, bj, At, Bt) do { __builtin_amdgcn_s_setprio(1); _Pragma("unroll") for (int m = 0; m < 4; ++m) _Pragma("unroll") for (int n = 0; n < 2; ++n) _Pragma("unroll") for (int k = 0; k < 2; ++k) \
;         acc[ai][bj][m][n] = __builtin_amdgcn_mfma_f32_16x16x32_bf16(Bt[n][k], At[m][k], acc[ai][bj][m][n], 0, 0, 0); __builtin_amdgcn_s_setprio(0); } while (0)
; #define PG8_WAIT_V(n) asm volatile("s_waitcnt vmcnt(" #n ")" ::: "memory")
; #define PG8_WAIT_L(n) asm volatile("s_waitcnt lgkmcnt(" #n ")" ::: "memory")
; #define PG8_BAR __builtin_amdgcn_s_barrier()
; #define PG8_SCHED __builtin_amdgcn_sched_barrier(0)
; template <class Epi>
; __device__ __forceinline__ void gemm_phase(LAS unsigned char* lds, const Gemm g, const StaticOrder& S, const Epi& E) {
;     ...
;             PG8_BAR; PG8_WAIT_L(0); PG8_MMA(1, 0, At, B0); PG8_BAR; PG8_SCHED;
;             PG8_STAGE(PG8_SB(0, 1), b2 + hstepB, voffB);
;             PG8_WAIT_V(6); PG8_BAR; PG8_MMA(1, 1, At, B1); PG8_BAR;
;             PG8_LDB(B0, 1, 0); PG8_SCHED; PG8_LDA(At, 1, 0); PG8_STAGE(PG8_SA(0, 1), a2 + hstepA, voffA);
;             PG8_WAIT_L(8); PG8_BAR; PG8_WAIT_L(0); PG8_MMA(0, 0, At, B0); PG8_BAR; PG8_SCHED;
;             PG8_LDB(B1, 1, 1); PG8_STAGE(PG8_SB(1, 0), b3, voffB);
;             PG8_BAR; PG8_WAIT_L(0); PG8_MMA(0, 1, At, B1); PG8_BAR;
;             PG8_LDA(At, 1, 1); PG8_STAGE(PG8_SA(1, 0), a3, voffA);
;             PG8_BAR; PG8_WAIT_L(0); PG8_MMA(1, 0, At, B0); PG8_BAR; PG8_SCHED;
;             PG8_STAGE(PG8_SB(1, 1), b3 + hstepB, voffB);
;             PG8_WAIT_V(6); PG8_BAR; PG8_MMA(1, 1, At, B1); PG8_BAR;
	s_add_u32 s48, s22, 0x40000
	s_addc_u32 s49, s23, 0
	s_add_i32 s50, s40, s27
	v_lshl_add_u64 v[146:147], s[48:49], 0, v[132:133]
	s_mov_b32 m0, s50
	s_nop 0
	global_load_lds_dwordx4 v[146:147], off
	v_lshl_add_u64 v[146:147], s[48:49], 0, v[128:129]
	s_add_i32 m0, s50, 0x2000
	s_nop 0
	global_load_lds_dwordx4 v[146:147], off
	s_waitcnt vmcnt(6)
	s_barrier
	v_mfma_f32_16x16x32_bf16 v[92:95], v[206:209], v[174:177], 0
	v_mfma_f32_16x16x32_bf16 v[88:91], v[214:217], v[174:177], 0
	v_mfma_f32_16x16x32_bf16 v[84:87], v[206:209], v[182:185], 0
	v_mfma_f32_16x16x32_bf16 v[80:83], v[214:217], v[182:185], 0
	v_mfma_f32_16x16x32_bf16 v[72:75], v[206:209], v[190:193], 0
	v_mfma_f32_16x16x32_bf16 v[68:71], v[214:217], v[190:193], 0
	v_mfma_f32_16x16x32_bf16 v[52:55], v[206:209], v[198:201], 0
	v_mfma_f32_16x16x32_bf16 v[44:47], v[214:217], v[198:201], 0
	v_mfma_f32_16x16x32_bf16 v[92:95], v[210:213], v[178:181], v[92:95]
	v_mfma_f32_16x16x32_bf16 v[88:91], v[218:221], v[178:181], v[88:91]
	v_mfma_f32_16x16x32_bf16 v[84:87], v[210:213], v[186:189], v[84:87]
	v_mfma_f32_16x16x32_bf16 v[80:83], v[218:221], v[186:189], v[80:83]
	v_mfma_f32_16x16x32_bf16 v[72:75], v[210:213], v[194:197], v[72:75]
	v_mfma_f32_16x16x32_bf16 v[68:71], v[218:221], v[194:197], v[68:71]
	v_mfma_f32_16x16x32_bf16 v[52:55], v[210:213], v[202:205], v[52:55]
	v_mfma_f32_16x16x32_bf16 v[44:47], v[218:221], v[202:205], v[44:47]
	s_add_i32 s48, 0, 0x18000
	v_add_u32_e32 v162, s48, v168
	s_barrier
	ds_read_b128 v[146:149], v162
	ds_read_b128 v[154:157], v162 offset:1024
	ds_read_b128 v[158:161], v162 offset:2048
	ds_read_b128 v[162:165], v162 offset:3072
	s_add_u32 s24, s24, 0x40000
	s_addc_u32 s25, s25, 0
	s_mov_b32 m0, s33
	v_lshl_add_u64 v[206:207], s[24:25], 0, v[134:135]
	ds_read_b128 v[174:177], v171 offset:32768
	ds_read_b128 v[178:181], v171 offset:33792
	ds_read_b128 v[182:185], v171 offset:34816
	ds_read_b128 v[186:189], v171 offset:35840
	ds_read_b128 v[190:193], v171 offset:36864
	ds_read_b128 v[194:197], v171 offset:37888
	ds_read_b128 v[198:201], v171 offset:38912
	ds_read_b128 v[202:205], v171 offset:39936
	global_load_lds_dwordx4 v[206:207], off
	v_lshl_add_u64 v[206:207], s[24:25], 0, v[130:131]
	s_mov_b32 m0, s34
	s_nop 0
	global_load_lds_dwordx4 v[206:207], off
	s_waitcnt lgkmcnt(8)
	s_barrier
	s_waitcnt lgkmcnt(0)
	v_mfma_f32_16x16x32_bf16 v[76:79], v[146:149], v[174:177], v[76:79]
	v_mfma_f32_16x16x32_bf16 v[64:67], v[158:161], v[174:177], v[64:67]
	v_mfma_f32_16x16x32_bf16 v[60:63], v[146:149], v[182:185], v[60:63]
	v_mfma_f32_16x16x32_bf16 v[56:59], v[158:161], v[182:185], v[56:59]
	v_mfma_f32_16x16x32_bf16 v[48:51], v[146:149], v[190:193], v[48:51]
	v_mfma_f32_16x16x32_bf16 v[40:43], v[158:161], v[190:193], v[40:43]
	v_mfma_f32_16x16x32_bf16 v[36:39], v[146:149], v[198:201], v[36:39]
	v_mfma_f32_16x16x32_bf16 v[32:35], v[158:161], v[198:201], v[32:35]
	v_mfma_f32_16x16x32_bf16 v[76:79], v[154:157], v[178:181], v[76:79]
	v_mfma_f32_16x16x32_bf16 v[64:67], v[162:165], v[178:181], v[64:67]
	v_mfma_f32_16x16x32_bf16 v[60:63], v[154:157], v[186:189], v[60:63]
	v_mfma_f32_16x16x32_bf16 v[56:59], v[162:165], v[186:189], v[56:59]
	v_mfma_f32_16x16x32_bf16 v[48:51], v[154:157], v[194:197], v[48:51]
	v_mfma_f32_16x16x32_bf16 v[40:43], v[162:165], v[194:197], v[40:43]
	v_mfma_f32_16x16x32_bf16 v[36:39], v[154:157], v[202:205], v[36:39]
	v_mfma_f32_16x16x32_bf16 v[32:35], v[162:165], v[202:205], v[32:35]
	s_barrier
	s_add_i32 s24, 0, 0x1c000
	s_add_i32 s25, s48, s27
	v_add_u32_e32 v218, s24, v168
	v_lshl_add_u64 v[150:151], v[150:151], 0, s[6:7]
	s_mov_b32 m0, s25
	ds_read_b128 v[206:209], v218
	ds_read_b128 v[210:213], v218 offset:1024
	ds_read_b128 v[214:217], v218 offset:2048
	ds_read_b128 v[218:221], v218 offset:3072
	global_load_lds_dwordx4 v[150:151], off
	v_lshl_add_u64 v[150:151], v[166:167], 0, s[6:7]
	s_add_i32 m0, s25, 0x2000
	s_nop 0
	global_load_lds_dwordx4 v[150:151], off
	s_barrier
	s_waitcnt lgkmcnt(0)
	v_mfma_f32_16x16x32_bf16 v[124:127], v[206:209], v[174:177], v[124:127]
	v_mfma_f32_16x16x32_bf16 v[120:123], v[214:217], v[174:177], v[120:123]
	v_mfma_f32_16x16x32_bf16 v[116:119], v[206:209], v[182:185], v[116:119]
	v_mfma_f32_16x16x32_bf16 v[112:115], v[214:217], v[182:185], v[112:115]
	v_mfma_f32_16x16x32_bf16 v[108:111], v[206:209], v[190:193], v[108:111]
	v_mfma_f32_16x16x32_bf16 v[104:107], v[214:217], v[190:193], v[104:107]
	v_mfma_f32_16x16x32_bf16 v[100:103], v[206:209], v[198:201], v[100:103]
	v_mfma_f32_16x16x32_bf16 v[96:99], v[214:217], v[198:201], v[96:99]
	v_mfma_f32_16x16x32_bf16 v[124:127], v[210:213], v[178:181], v[124:127]
	v_mfma_f32_16x16x32_bf16 v[120:123], v[218:221], v[178:181], v[120:123]
	v_mfma_f32_16x16x32_bf16 v[116:119], v[210:213], v[186:189], v[116:119]
	v_mfma_f32_16x16x32_bf16 v[112:115], v[218:221], v[186:189], v[112:115]
	v_mfma_f32_16x16x32_bf16 v[108:111], v[210:213], v[194:197], v[108:111]
	v_mfma_f32_16x16x32_bf16 v[104:107], v[218:221], v[194:197], v[104:107]
	v_mfma_f32_16x16x32_bf16 v[100:103], v[210:213], v[202:205], v[100:103]
	v_mfma_f32_16x16x32_bf16 v[96:99], v[218:221], v[202:205], v[96:99]
	s_mov_b32 m0, s36
	v_lshl_add_u64 v[150:151], v[222:223], 0, s[6:7]
	s_barrier
	ds_read_b128 v[174:177], v171 offset:49152
	ds_read_b128 v[178:181], v171 offset:50176
	ds_read_b128 v[182:185], v171 offset:51200
	ds_read_b128 v[186:189], v171 offset:52224
	ds_read_b128 v[190:193], v171 offset:53248
	ds_read_b128 v[194:197], v171 offset:54272
	ds_read_b128 v[198:201], v171 offset:55296
	ds_read_b128 v[202:205], v171 offset:56320
	global_load_lds_dwordx4 v[150:151], off
	v_lshl_add_u64 v[150:151], v[224:225], 0, s[6:7]
	s_mov_b32 m0, s37
	s_nop 0
	global_load_lds_dwordx4 v[150:151], off
	s_barrier
; #define PG8_STAGE(bufoff, gbase, voff) do { _Pragma("unroll") for (int _i = 0; _i < 2; ++_i) \
;         __builtin_amdgcn_global_load_lds((const unsigned*)((const char*)(gbase) + (voff)[_i]), (LAS unsigned*)(lds + (bufoff) + ldsw + _i * 8192), 16, 0, 0); } while (0)
; #define PG8_LDA(dst, b, h) do { _Pragma("unroll") for (int m = 0; m < 4; ++m) _Pragma("unroll") for (int k = 0; k < 2; ++k) dst[m][k] = *(const LAS bf16x8*)(lds + PG8_SA(b, h) + aoff + m * 2048 + k * 1024); } while (0)
; #define PG8_LDB(dst, b, h) do { _Pragma("unroll") for (int n = 0; n < 2; ++n) _Pragma("unroll") for (int k = 0; k < 2; ++k) dst[n][k] = *(const LAS bf16x8*)(lds + PG8_SB(b, h) + boff + n * 2048 + k * 1024); } while (0)
; #define PG8_WAIT_V(n) asm volatile("s_waitcnt vmcnt(" #n ")" ::: "memory")
; #define PG8_WAIT_L(n) asm volatile("s_waitcnt lgkmcnt(" #n ")" ::: "memory")
; #define PG8_BAR __builtin_amdgcn_s_barrier()
; #define PG8_SCHED __builtin_amdgcn_sched_barrier(0)
; template <class Epi>
; __device__ __forceinline__ void gemm_phase(LAS unsigned char* lds, const Gemm g, const StaticOrder& S, const Epi& E) {
;     ...
;             PG8_LDB(B0, 0, 0); PG8_SCHED; PG8_LDA(At, 0, 0); PG8_STAGE(PG8_SA(1, 1), a1 + hstepA, voffA);
;             PG8_WAIT_L(8); PG8_BAR; PG8_WAIT_L(0); PG8_MMA(0, 0, At, B0); PG8_BAR; PG8_SCHED;
;             PG8_LDB(B1, 0, 1); PG8_STAGE(PG8_SB(0, 0), b2, voffB);
;             PG8_BAR; PG8_WAIT_L(0); PG8_MMA(0, 1, At, B1); PG8_BAR;
;             PG8_LDA(At, 0, 1); PG8_STAGE(PG8_SA(0, 0), a2, voffA);
;             PG8_BAR; PG8_WAIT_L(0); PG8_MMA(1, 0, At, B0); PG8_BAR; PG8_SCHED;
;             PG8_STAGE(PG8_SB(0, 1), b2 + hstepB, voffB);
;             PG8_WAIT_V(6); PG8_BAR; PG8_MMA(1, 1, At, B1); PG8_BAR;
;             PG8_LDB(B0, 1, 0); PG8_SCHED; PG8_LDA(At, 1, 0); PG8_STAGE(PG8_SA(0, 1), a2 + hstepA, voffA);
;             PG8_WAIT_L(8); PG8_BAR; PG8_WAIT_L(0); PG8_MMA(0, 0, At, B0); PG8_BAR; PG8_SCHED;
;             PG8_LDB(B1, 1, 1); PG8_STAGE(PG8_SB(1, 0), b3, voffB);
;             PG8_BAR; PG8_WAIT_L(0); PG8_MMA(0, 1, At, B1); PG8_BAR;
;             PG8_LDA(At, 1, 1); PG8_STAGE(PG8_SA(1, 0), a3, voffA);
;             PG8_BAR; PG8_WAIT_L(0); PG8_MMA(1, 0, At, B0); PG8_BAR; PG8_SCHED;
;             PG8_STAGE(PG8_SB(1, 1), b3 + hstepB, voffB);
;             PG8_WAIT_V(6); PG8_BAR; PG8_MMA(1, 1, At, B1); PG8_BAR;
	s_waitcnt lgkmcnt(0)
	v_mfma_f32_16x16x32_bf16 v[28:31], v[146:149], v[174:177], v[28:31]
	v_mfma_f32_16x16x32_bf16 v[24:27], v[158:161], v[174:177], v[24:27]
	v_mfma_f32_16x16x32_bf16 v[20:23], v[146:149], v[182:185], v[20:23]
	v_mfma_f32_16x16x32_bf16 v[16:19], v[158:161], v[182:185], v[16:19]
	v_mfma_f32_16x16x32_bf16 v[12:15], v[146:149], v[190:193], v[12:15]
	v_mfma_f32_16x16x32_bf16 v[8:11], v[158:161], v[190:193], v[8:11]
	v_mfma_f32_16x16x32_bf16 v[4:7], v[146:149], v[198:201], v[4:7]
	v_mfma_f32_16x16x32_bf16 v[0:3], v[158:161], v[198:201], v[0:3]
	v_mfma_f32_16x16x32_bf16 v[28:31], v[154:157], v[178:181], v[28:31]
	v_mfma_f32_16x16x32_bf16 v[24:27], v[162:165], v[178:181], v[24:27]
	v_mfma_f32_16x16x32_bf16 v[20:23], v[154:157], v[186:189], v[20:23]
	v_mfma_f32_16x16x32_bf16 v[16:19], v[162:165], v[186:189], v[16:19]
	v_mfma_f32_16x16x32_bf16 v[12:15], v[154:157], v[194:197], v[12:15]
	v_mfma_f32_16x16x32_bf16 v[8:11], v[162:165], v[194:197], v[8:11]
	v_mfma_f32_16x16x32_bf16 v[4:7], v[154:157], v[202:205], v[4:7]
	v_mfma_f32_16x16x32_bf16 v[0:3], v[162:165], v[202:205], v[0:3]
	s_barrier
	s_add_u32 s22, s22, 0x40080
	s_addc_u32 s23, s23, 0
	s_add_i32 s24, s24, s27
	v_lshl_add_u64 v[146:147], s[22:23], 0, v[132:133]
	s_mov_b32 m0, s24
	s_nop 0
	global_load_lds_dwordx4 v[146:147], off
	v_lshl_add_u64 v[146:147], s[22:23], 0, v[128:129]
	s_add_i32 m0, s24, 0x2000
	s_nop 0
	global_load_lds_dwordx4 v[146:147], off
	s_waitcnt vmcnt(6)
	s_barrier
	v_mfma_f32_16x16x32_bf16 v[92:95], v[206:209], v[174:177], v[92:95]
	v_mfma_f32_16x16x32_bf16 v[88:91], v[214:217], v[174:177], v[88:91]
	v_mfma_f32_16x16x32_bf16 v[84:87], v[206:209], v[182:185], v[84:87]
	v_mfma_f32_16x16x32_bf16 v[80:83], v[214:217], v[182:185], v[80:83]
	v_mfma_f32_16x16x32_bf16 v[72:75], v[206:209], v[190:193], v[72:75]
	v_mfma_f32_16x16x32_bf16 v[68:71], v[214:217], v[190:193], v[68:71]
	v_mfma_f32_16x16x32_bf16 v[52:55], v[206:209], v[198:201], v[52:55]
	v_mfma_f32_16x16x32_bf16 v[44:47], v[214:217], v[198:201], v[44:47]
	v_mfma_f32_16x16x32_bf16 v[92:95], v[210:213], v[178:181], v[92:95]
	v_mfma_f32_16x16x32_bf16 v[88:91], v[218:221], v[178:181], v[88:91]
	v_mfma_f32_16x16x32_bf16 v[84:87], v[210:213], v[186:189], v[84:87]
	v_mfma_f32_16x16x32_bf16 v[80:83], v[218:221], v[186:189], v[80:83]
	v_mfma_f32_16x16x32_bf16 v[72:75], v[210:213], v[194:197], v[72:75]
	v_mfma_f32_16x16x32_bf16 v[68:71], v[218:221], v[194:197], v[68:71]
	v_mfma_f32_16x16x32_bf16 v[52:55], v[210:213], v[202:205], v[52:55]
	v_mfma_f32_16x16x32_bf16 v[44:47], v[218:221], v[202:205], v[44:47]
	s_add_i32 s47, s47, 2
	s_add_u32 s20, s20, 0x100
	s_addc_u32 s21, s21, 0
	s_add_u32 s45, s45, 0x100
	s_addc_u32 s46, s46, 0
	s_cmp_gt_u32 s47, 13
	s_barrier
.LBB0_205:
	ds_read_b128 v[146:149], v170
	ds_read_b128 v[154:157], v170 offset:1024
	ds_read_b128 v[158:161], v170 offset:2048
	ds_read_b128 v[162:165], v170 offset:3072
	s_add_u32 s22, s20, 0xfffc0080
	s_addc_u32 s23, s21, -1
	s_cmp_eq_u32 s47, 12
	s_cselect_b32 s25, s13, s23
	s_cselect_b32 s24, s19, s22
	s_cselect_b32 s23, s11, s46
	s_cselect_b32 s22, s44, s45
	v_lshl_add_u64 v[150:151], s[20:21], 0, v[138:139]
	s_add_i32 m0, s30, 0xc000
	ds_read_b128 v[174:177], v171
	ds_read_b128 v[178:181], v171 offset:1024
	ds_read_b128 v[182:185], v171 offset:2048
	ds_read_b128 v[186:189], v171 offset:3072
	ds_read_b128 v[190:193], v171 offset:4096
	ds_read_b128 v[194:197], v171 offset:5120
	ds_read_b128 v[198:201], v171 offset:6144
	ds_read_b128 v[202:205], v171 offset:7168
	global_load_lds_dwordx4 v[150:151], off
	v_lshl_add_u64 v[150:151], s[20:21], 0, v[140:141]
	s_add_i32 m0, s30, 0xe000
	s_nop 0
	global_load_lds_dwordx4 v[150:151], off
	s_waitcnt lgkmcnt(8)
	s_barrier
	s_waitcnt lgkmcnt(0)
	v_mfma_f32_16x16x32_bf16 v[76:79], v[146:149], v[174:177], v[76:79]
	v_mfma_f32_16x16x32_bf16 v[64:67], v[158:161], v[174:177], v[64:67]
	v_mfma_f32_16x16x32_bf16 v[60:63], v[146:149], v[182:185], v[60:63]
	v_mfma_f32_16x16x32_bf16 v[56:59], v[158:161], v[182:185], v[56:59]
	v_mfma_f32_16x16x32_bf16 v[48:51], v[146:149], v[190:193], v[48:51]
	v_mfma_f32_16x16x32_bf16 v[40:43], v[158:161], v[190:193], v[40:43]
	v_mfma_f32_16x16x32_bf16 v[36:39], v[146:149], v[198:201], v[36:39]
	v_mfma_f32_16x16x32_bf16 v[32:35], v[158:161], v[198:201], v[32:35]
	v_mfma_f32_16x16x32_bf16 v[76:79], v[154:157], v[178:181], v[76:79]
	v_mfma_f32_16x16x32_bf16 v[64:67], v[162:165], v[178:181], v[64:67]
	v_mfma_f32_16x16x32_bf16 v[60:63], v[154:157], v[186:189], v[60:63]
	v_mfma_f32_16x16x32_bf16 v[56:59], v[162:165], v[186:189], v[56:59]
	v_mfma_f32_16x16x32_bf16 v[48:51], v[154:157], v[194:197], v[48:51]
	v_mfma_f32_16x16x32_bf16 v[40:43], v[162:165], v[194:197], v[40:43]
	v_mfma_f32_16x16x32_bf16 v[36:39], v[154:157], v[202:205], v[36:39]
	v_mfma_f32_16x16x32_bf16 v[32:35], v[162:165], v[202:205], v[32:35]
	s_barrier
	s_add_i32 s48, s39, s27
	v_lshl_add_u64 v[150:151], s[22:23], 0, v[132:133]
	s_mov_b32 m0, s48
	ds_read_b128 v[206:209], v172
	ds_read_b128 v[210:213], v172 offset:1024
	ds_read_b128 v[214:217], v172 offset:2048
	ds_read_b128 v[218:221], v172 offset:3072
	global_load_lds_dwordx4 v[150:151], off
	v_lshl_add_u64 v[166:167], s[22:23], 0, v[128:129]
	s_add_i32 m0, s48, 0x2000
	s_nop 0
	global_load_lds_dwordx4 v[166:167], off
	s_barrier
; #define PG8_STAGE(bufoff, gbase, voff) do { _Pragma("unroll") for (int _i = 0; _i < 2; ++_i) \
;         __builtin_amdgcn_global_load_lds((const unsigned*)((const char*)(gbase) + (voff)[_i]), (LAS unsigned*)(lds + (bufoff) + ldsw + _i * 8192), 16, 0, 0); } while (0)
; #define PG8_LDA(dst, b, h) do { _Pragma("unroll") for (int m = 0; m < 4; ++m) _Pragma("unroll") for (int k = 0; k < 2; ++k) dst[m][k] = *(const LAS bf16x8*)(lds + PG8_SA(b, h) + aoff + m * 2048 + k * 1024); } while (0)
; #define PG8_LDB(dst, b, h) do { _Pragma("unroll") for (int n = 0; n < 2; ++n) _Pragma("unroll") for (int k = 0; k < 2; ++k) dst[n][k] = *(const LAS bf16x8*)(lds + PG8_SB(b, h) + boff + n * 2048 + k * 1024); } while (0)
; #define PG8_MMA(ai, bj, At, Bt) do { __builtin_amdgcn_s_setprio(1); _Pragma("unroll") for (int m = 0; m < 4; ++m) _Pragma("unroll") for (int n = 0; n < 2; ++n) _Pragma("unroll") for (int k = 0; k < 2; ++k) \
;         acc[ai][bj][m][n] = __builtin_amdgcn_mfma_f32_16x16x32_bf16(Bt[n][k], At[m][k], acc[ai][bj][m][n], 0, 0, 0); __builtin_amdgcn_s_setprio(0); } while (0)
; #define PG8_WAIT_V(n) asm volatile("s_waitcnt vmcnt(" #n ")" ::: "memory")
; #define PG8_WAIT_L(n) asm volatile("s_waitcnt lgkmcnt(" #n ")" ::: "memory")
; #define PG8_BAR __builtin_amdgcn_s_barrier()
; #define PG8_SCHED __builtin_amdgcn_sched_barrier(0)
; template <class Epi>
; __device__ __forceinline__ void gemm_phase(LAS unsigned char* lds, const Gemm g, const StaticOrder& S, const Epi& E) {
;     ...
;             PG8_BAR; PG8_WAIT_L(0); PG8_MMA(0, 1, At, B1); PG8_BAR;
;             PG8_LDA(At, 0, 1); PG8_STAGE(PG8_SA(0, 0), a2, voffA);
;             PG8_BAR; PG8_WAIT_L(0); PG8_MMA(1, 0, At, B0); PG8_BAR; PG8_SCHED;
;             PG8_STAGE(PG8_SB(0, 1), b2 + hstepB, voffB);
;             PG8_WAIT_V(6); PG8_BAR; PG8_MMA(1, 1, At, B1); PG8_BAR;
;             PG8_LDB(B0, 1, 0); PG8_SCHED; PG8_LDA(At, 1, 0); PG8_STAGE(PG8_SA(0, 1), a2 + hstepA, voffA);
;             PG8_WAIT_L(8); PG8_BAR; PG8_WAIT_L(0); PG8_MMA(0, 0, At, B0); PG8_BAR; PG8_SCHED;
;             PG8_LDB(B1, 1, 1); PG8_STAGE(PG8_SB(1, 0), b3, voffB);
;             PG8_BAR; PG8_WAIT_L(0); PG8_MMA(0, 1, At, B1); PG8_BAR;
;             PG8_LDA(At, 1, 1); PG8_STAGE(PG8_SA(1, 0), a3, voffA);
	s_waitcnt lgkmcnt(0)
	v_mfma_f32_16x16x32_bf16 v[124:127], v[206:209], v[174:177], v[124:127]
	v_mfma_f32_16x16x32_bf16 v[120:123], v[214:217], v[174:177], v[120:123]
	v_mfma_f32_16x16x32_bf16 v[116:119], v[206:209], v[182:185], v[116:119]
	v_mfma_f32_16x16x32_bf16 v[112:115], v[214:217], v[182:185], v[112:115]
	v_mfma_f32_16x16x32_bf16 v[108:111], v[206:209], v[190:193], v[108:111]
	v_mfma_f32_16x16x32_bf16 v[104:107], v[214:217], v[190:193], v[104:107]
	v_mfma_f32_16x16x32_bf16 v[100:103], v[206:209], v[198:201], v[100:103]
	v_mfma_f32_16x16x32_bf16 v[96:99], v[214:217], v[198:201], v[96:99]
	v_mfma_f32_16x16x32_bf16 v[124:127], v[210:213], v[178:181], v[124:127]
	v_mfma_f32_16x16x32_bf16 v[120:123], v[218:221], v[178:181], v[120:123]
	v_mfma_f32_16x16x32_bf16 v[116:119], v[210:213], v[186:189], v[116:119]
	v_mfma_f32_16x16x32_bf16 v[112:115], v[218:221], v[186:189], v[112:115]
	v_mfma_f32_16x16x32_bf16 v[108:111], v[210:213], v[194:197], v[108:111]
	v_mfma_f32_16x16x32_bf16 v[104:107], v[218:221], v[194:197], v[104:107]
	v_mfma_f32_16x16x32_bf16 v[100:103], v[210:213], v[202:205], v[100:103]
	v_mfma_f32_16x16x32_bf16 v[96:99], v[218:221], v[202:205], v[96:99]
	s_mov_b32 m0, s30
	v_lshl_add_u64 v[222:223], s[24:25], 0, v[134:135]
	s_barrier
	ds_read_b128 v[174:177], v171 offset:16384
	ds_read_b128 v[178:181], v171 offset:17408
	ds_read_b128 v[182:185], v171 offset:18432
	ds_read_b128 v[186:189], v171 offset:19456
	ds_read_b128 v[190:193], v171 offset:20480
	ds_read_b128 v[194:197], v171 offset:21504
	ds_read_b128 v[198:201], v171 offset:22528
	ds_read_b128 v[202:205], v171 offset:23552
	global_load_lds_dwordx4 v[222:223], off
	v_lshl_add_u64 v[224:225], s[24:25], 0, v[130:131]
	s_mov_b32 m0, s31
	s_nop 0
	global_load_lds_dwordx4 v[224:225], off
	s_barrier
	s_waitcnt lgkmcnt(0)
	v_mfma_f32_16x16x32_bf16 v[28:31], v[146:149], v[174:177], v[28:31]
	v_mfma_f32_16x16x32_bf16 v[24:27], v[158:161], v[174:177], v[24:27]
	v_mfma_f32_16x16x32_bf16 v[20:23], v[146:149], v[182:185], v[20:23]
	v_mfma_f32_16x16x32_bf16 v[16:19], v[158:161], v[182:185], v[16:19]
	v_mfma_f32_16x16x32_bf16 v[12:15], v[146:149], v[190:193], v[12:15]
	v_mfma_f32_16x16x32_bf16 v[8:11], v[158:161], v[190:193], v[8:11]
	v_mfma_f32_16x16x32_bf16 v[4:7], v[146:149], v[198:201], v[4:7]
	v_mfma_f32_16x16x32_bf16 v[0:3], v[158:161], v[198:201], v[0:3]
	v_mfma_f32_16x16x32_bf16 v[28:31], v[154:157], v[178:181], v[28:31]
	v_mfma_f32_16x16x32_bf16 v[24:27], v[162:165], v[178:181], v[24:27]
	v_mfma_f32_16x16x32_bf16 v[20:23], v[154:157], v[186:189], v[20:23]
	v_mfma_f32_16x16x32_bf16 v[16:19], v[162:165], v[186:189], v[16:19]
	v_mfma_f32_16x16x32_bf16 v[12:15], v[154:157], v[194:197], v[12:15]
	v_mfma_f32_16x16x32_bf16 v[8:11], v[162:165], v[194:197], v[8:11]
	v_mfma_f32_16x16x32_bf16 v[4:7], v[154:157], v[202:205], v[4:7]
	v_mfma_f32_16x16x32_bf16 v[0:3], v[162:165], v[202:205], v[0:3]
	s_barrier
	s_add_u32 s48, s22, 0x40000
	s_addc_u32 s49, s23, 0
	s_add_i32 s50, s40, s27
	v_lshl_add_u64 v[146:147], s[48:49], 0, v[132:133]
	s_mov_b32 m0, s50
	s_nop 0
	global_load_lds_dwordx4 v[146:147], off
	v_lshl_add_u64 v[146:147], s[48:49], 0, v[128:129]
	s_add_i32 m0, s50, 0x2000
	s_nop 0
	global_load_lds_dwordx4 v[146:147], off
	s_waitcnt vmcnt(6)
	s_barrier
	v_mfma_f32_16x16x32_bf16 v[92:95], v[206:209], v[174:177], v[92:95]
	v_mfma_f32_16x16x32_bf16 v[88:91], v[214:217], v[174:177], v[88:91]
	v_mfma_f32_16x16x32_bf16 v[84:87], v[206:209], v[182:185], v[84:87]
	v_mfma_f32_16x16x32_bf16 v[80:83], v[214:217], v[182:185], v[80:83]
	v_mfma_f32_16x16x32_bf16 v[72:75], v[206:209], v[190:193], v[72:75]
	v_mfma_f32_16x16x32_bf16 v[68:71], v[214:217], v[190:193], v[68:71]
	v_mfma_f32_16x16x32_bf16 v[52:55], v[206:209], v[198:201], v[52:55]
	v_mfma_f32_16x16x32_bf16 v[44:47], v[214:217], v[198:201], v[44:47]
	v_mfma_f32_16x16x32_bf16 v[92:95], v[210:213], v[178:181], v[92:95]
	v_mfma_f32_16x16x32_bf16 v[88:91], v[218:221], v[178:181], v[88:91]
	v_mfma_f32_16x16x32_bf16 v[84:87], v[210:213], v[186:189], v[84:87]
	v_mfma_f32_16x16x32_bf16 v[80:83], v[218:221], v[186:189], v[80:83]
	v_mfma_f32_16x16x32_bf16 v[72:75], v[210:213], v[194:197], v[72:75]
	v_mfma_f32_16x16x32_bf16 v[68:71], v[218:221], v[194:197], v[68:71]
	v_mfma_f32_16x16x32_bf16 v[52:55], v[210:213], v[202:205], v[52:55]
	v_mfma_f32_16x16x32_bf16 v[44:47], v[218:221], v[202:205], v[44:47]
	s_add_i32 s48, 0, 0x18000
	v_add_u32_e32 v162, s48, v168
	s_barrier
	ds_read_b128 v[146:149], v162
	ds_read_b128 v[154:157], v162 offset:1024
	ds_read_b128 v[158:161], v162 offset:2048
	ds_read_b128 v[162:165], v162 offset:3072
	s_add_u32 s24, s24, 0x40000
	s_addc_u32 s25, s25, 0
	s_mov_b32 m0, s33
	v_lshl_add_u64 v[206:207], s[24:25], 0, v[134:135]
	ds_read_b128 v[174:177], v171 offset:32768
	ds_read_b128 v[178:181], v171 offset:33792
	ds_read_b128 v[182:185], v171 offset:34816
	ds_read_b128 v[186:189], v171 offset:35840
	ds_read_b128 v[190:193], v171 offset:36864
	ds_read_b128 v[194:197], v171 offset:37888
	ds_read_b128 v[198:201], v171 offset:38912
	ds_read_b128 v[202:205], v171 offset:39936
	global_load_lds_dwordx4 v[206:207], off
	v_lshl_add_u64 v[206:207], s[24:25], 0, v[130:131]
	s_mov_b32 m0, s34
	s_nop 0
	global_load_lds_dwordx4 v[206:207], off
	s_waitcnt lgkmcnt(8)
	s_barrier
; #define PG8_STAGE(bufoff, gbase, voff) do { _Pragma("unroll") for (int _i = 0; _i < 2; ++_i) \
;         __builtin_amdgcn_global_load_lds((const unsigned*)((const char*)(gbase) + (voff)[_i]), (LAS unsigned*)(lds + (bufoff) + ldsw + _i * 8192), 16, 0, 0); } while (0)
; #define PG8_LDA(dst, b, h) do { _Pragma("unroll") for (int m = 0; m < 4; ++m) _Pragma("unroll") for (int k = 0; k < 2; ++k) dst[m][k] = *(const LAS bf16x8*)(lds + PG8_SA(b, h) + aoff + m * 2048 + k * 1024); } while (0)
; #define PG8_LDB(dst, b, h) do { _Pragma("unroll") for (int n = 0; n < 2; ++n) _Pragma("unroll") for (int k = 0; k < 2; ++k) dst[n][k] = *(const LAS bf16x8*)(lds + PG8_SB(b, h) + boff + n * 2048 + k * 1024); } while (0)
; #define PG8_MMA(ai, bj, At, Bt) do { __builtin_amdgcn_s_setprio(1); _Pragma("unroll") for (int m = 0; m < 4; ++m) _Pragma("unroll") for (int n = 0; n < 2; ++n) _Pragma("unroll") for (int k = 0; k < 2; ++k) \
;         acc[ai][bj][m][n] = __builtin_amdgcn_mfma_f32_16x16x32_bf16(Bt[n][k], At[m][k], acc[ai][bj][m][n], 0, 0, 0); __builtin_amdgcn_s_setprio(0); } while (0)
; #define PG8_WAIT_V(n) asm volatile("s_waitcnt vmcnt(" #n ")" ::: "memory")
; #define PG8_WAIT_L(n) asm volatile("s_waitcnt lgkmcnt(" #n ")" ::: "memory")
; #define PG8_BAR __builtin_amdgcn_s_barrier()
; #define PG8_SCHED __builtin_amdgcn_sched_barrier(0)
; template <class Epi>
; __device__ __forceinline__ void gemm_phase(LAS unsigned char* lds, const Gemm g, const StaticOrder& S, const Epi& E) {
;     ...
;             PG8_BAR; PG8_WAIT_L(0); PG8_MMA(1, 0, At, B0); PG8_BAR; PG8_SCHED;
;             PG8_STAGE(PG8_SB(0, 1), b2 + hstepB, voffB);
;             PG8_WAIT_V(6); PG8_BAR; PG8_MMA(1, 1, At, B1); PG8_BAR;
;             PG8_LDB(B0, 1, 0); PG8_SCHED; PG8_LDA(At, 1, 0); PG8_STAGE(PG8_SA(0, 1), a2 + hstepA, voffA);
;             PG8_WAIT_L(8); PG8_BAR; PG8_WAIT_L(0); PG8_MMA(0, 0, At, B0); PG8_BAR; PG8_SCHED;
;             PG8_LDB(B1, 1, 1); PG8_STAGE(PG8_SB(1, 0), b3, voffB);
;             PG8_BAR; PG8_WAIT_L(0); PG8_MMA(0, 1, At, B1); PG8_BAR;
;             PG8_LDA(At, 1, 1); PG8_STAGE(PG8_SA(1, 0), a3, voffA);
;             PG8_BAR; PG8_WAIT_L(0); PG8_MMA(1, 0, At, B0); PG8_BAR; PG8_SCHED;
;             PG8_STAGE(PG8_SB(1, 1), b3 + hstepB, voffB);
;             PG8_WAIT_V(6); PG8_BAR; PG8_MMA(1, 1, At, B1); PG8_BAR;
	s_waitcnt lgkmcnt(0)
	v_mfma_f32_16x16x32_bf16 v[76:79], v[146:149], v[174:177], v[76:79]
	v_mfma_f32_16x16x32_bf16 v[64:67], v[158:161], v[174:177], v[64:67]
	v_mfma_f32_16x16x32_bf16 v[60:63], v[146:149], v[182:185], v[60:63]
	v_mfma_f32_16x16x32_bf16 v[56:59], v[158:161], v[182:185], v[56:59]
	v_mfma_f32_16x16x32_bf16 v[48:51], v[146:149], v[190:193], v[48:51]
	v_mfma_f32_16x16x32_bf16 v[40:43], v[158:161], v[190:193], v[40:43]
	v_mfma_f32_16x16x32_bf16 v[36:39], v[146:149], v[198:201], v[36:39]
	v_mfma_f32_16x16x32_bf16 v[32:35], v[158:161], v[198:201], v[32:35]
	v_mfma_f32_16x16x32_bf16 v[76:79], v[154:157], v[178:181], v[76:79]
	v_mfma_f32_16x16x32_bf16 v[64:67], v[162:165], v[178:181], v[64:67]
	v_mfma_f32_16x16x32_bf16 v[60:63], v[154:157], v[186:189], v[60:63]
	v_mfma_f32_16x16x32_bf16 v[56:59], v[162:165], v[186:189], v[56:59]
	v_mfma_f32_16x16x32_bf16 v[48:51], v[154:157], v[194:197], v[48:51]
	v_mfma_f32_16x16x32_bf16 v[40:43], v[162:165], v[194:197], v[40:43]
	v_mfma_f32_16x16x32_bf16 v[36:39], v[154:157], v[202:205], v[36:39]
	v_mfma_f32_16x16x32_bf16 v[32:35], v[162:165], v[202:205], v[32:35]
	s_barrier
	s_add_i32 s24, 0, 0x1c000
	s_add_i32 s25, s48, s27
	v_add_u32_e32 v218, s24, v168
	v_lshl_add_u64 v[150:151], v[150:151], 0, s[6:7]
	s_mov_b32 m0, s25
	ds_read_b128 v[206:209], v218
	ds_read_b128 v[210:213], v218 offset:1024
	ds_read_b128 v[214:217], v218 offset:2048
	ds_read_b128 v[218:221], v218 offset:3072
	global_load_lds_dwordx4 v[150:151], off
	v_lshl_add_u64 v[150:151], v[166:167], 0, s[6:7]
	s_add_i32 m0, s25, 0x2000
	s_nop 0
	global_load_lds_dwordx4 v[150:151], off
	s_barrier
	s_waitcnt lgkmcnt(0)
	v_mfma_f32_16x16x32_bf16 v[124:127], v[206:209], v[174:177], v[124:127]
	v_mfma_f32_16x16x32_bf16 v[120:123], v[214:217], v[174:177], v[120:123]
	v_mfma_f32_16x16x32_bf16 v[116:119], v[206:209], v[182:185], v[116:119]
	v_mfma_f32_16x16x32_bf16 v[112:115], v[214:217], v[182:185], v[112:115]
	v_mfma_f32_16x16x32_bf16 v[108:111], v[206:209], v[190:193], v[108:111]
	v_mfma_f32_16x16x32_bf16 v[104:107], v[214:217], v[190:193], v[104:107]
	v_mfma_f32_16x16x32_bf16 v[100:103], v[206:209], v[198:201], v[100:103]
	v_mfma_f32_16x16x32_bf16 v[96:99], v[214:217], v[198:201], v[96:99]
	v_mfma_f32_16x16x32_bf16 v[124:127], v[210:213], v[178:181], v[124:127]
	v_mfma_f32_16x16x32_bf16 v[120:123], v[218:221], v[178:181], v[120:123]
	v_mfma_f32_16x16x32_bf16 v[116:119], v[210:213], v[186:189], v[116:119]
	v_mfma_f32_16x16x32_bf16 v[112:115], v[218:221], v[186:189], v[112:115]
	v_mfma_f32_16x16x32_bf16 v[108:111], v[210:213], v[194:197], v[108:111]
	v_mfma_f32_16x16x32_bf16 v[104:107], v[218:221], v[194:197], v[104:107]
	v_mfma_f32_16x16x32_bf16 v[100:103], v[210:213], v[202:205], v[100:103]
	v_mfma_f32_16x16x32_bf16 v[96:99], v[218:221], v[202:205], v[96:99]
	s_mov_b32 m0, s36
	v_lshl_add_u64 v[150:151], v[222:223], 0, s[6:7]
	s_barrier
	ds_read_b128 v[174:177], v171 offset:49152
	ds_read_b128 v[178:181], v171 offset:50176
	ds_read_b128 v[182:185], v171 offset:51200
	ds_read_b128 v[186:189], v171 offset:52224
	ds_read_b128 v[190:193], v171 offset:53248
	ds_read_b128 v[194:197], v171 offset:54272
	ds_read_b128 v[198:201], v171 offset:55296
	ds_read_b128 v[202:205], v171 offset:56320
	global_load_lds_dwordx4 v[150:151], off
	v_lshl_add_u64 v[150:151], v[224:225], 0, s[6:7]
	s_mov_b32 m0, s37
	s_nop 0
	global_load_lds_dwordx4 v[150:151], off
	s_barrier
	s_waitcnt lgkmcnt(0)
	v_mfma_f32_16x16x32_bf16 v[28:31], v[146:149], v[174:177], v[28:31]
	v_mfma_f32_16x16x32_bf16 v[24:27], v[158:161], v[174:177], v[24:27]
	v_mfma_f32_16x16x32_bf16 v[20:23], v[146:149], v[182:185], v[20:23]
	v_mfma_f32_16x16x32_bf16 v[16:19], v[158:161], v[182:185], v[16:19]
	v_mfma_f32_16x16x32_bf16 v[12:15], v[146:149], v[190:193], v[12:15]
	v_mfma_f32_16x16x32_bf16 v[8:11], v[158:161], v[190:193], v[8:11]
	v_mfma_f32_16x16x32_bf16 v[4:7], v[146:149], v[198:201], v[4:7]
	v_mfma_f32_16x16x32_bf16 v[0:3], v[158:161], v[198:201], v[0:3]
	v_mfma_f32_16x16x32_bf16 v[28:31], v[154:157], v[178:181], v[28:31]
	v_mfma_f32_16x16x32_bf16 v[24:27], v[162:165], v[178:181], v[24:27]
	v_mfma_f32_16x16x32_bf16 v[20:23], v[154:157], v[186:189], v[20:23]
	v_mfma_f32_16x16x32_bf16 v[16:19], v[162:165], v[186:189], v[16:19]
	v_mfma_f32_16x16x32_bf16 v[12:15], v[154:157], v[194:197], v[12:15]
	v_mfma_f32_16x16x32_bf16 v[8:11], v[162:165], v[194:197], v[8:11]
	v_mfma_f32_16x16x32_bf16 v[4:7], v[154:157], v[202:205], v[4:7]
	v_mfma_f32_16x16x32_bf16 v[0:3], v[162:165], v[202:205], v[0:3]
	s_barrier
	s_add_u32 s22, s22, 0x40080
	s_addc_u32 s23, s23, 0
	s_add_i32 s24, s24, s27
	v_lshl_add_u64 v[146:147], s[22:23], 0, v[132:133]
	s_mov_b32 m0, s24
	s_nop 0
	global_load_lds_dwordx4 v[146:147], off
	v_lshl_add_u64 v[146:147], s[22:23], 0, v[128:129]
	s_add_i32 m0, s24, 0x2000
	s_nop 0
	global_load_lds_dwordx4 v[146:147], off
	s_waitcnt vmcnt(6)
	s_barrier
	v_mfma_f32_16x16x32_bf16 v[92:95], v[206:209], v[174:177], v[92:95]
	v_mfma_f32_16x16x32_bf16 v[88:91], v[214:217], v[174:177], v[88:91]
	v_mfma_f32_16x16x32_bf16 v[84:87], v[206:209], v[182:185], v[84:87]
	v_mfma_f32_16x16x32_bf16 v[80:83], v[214:217], v[182:185], v[80:83]
	v_mfma_f32_16x16x32_bf16 v[72:75], v[206:209], v[190:193], v[72:75]
	v_mfma_f32_16x16x32_bf16 v[68:71], v[214:217], v[190:193], v[68:71]
	v_mfma_f32_16x16x32_bf16 v[52:55], v[206:209], v[198:201], v[52:55]
	v_mfma_f32_16x16x32_bf16 v[44:47], v[214:217], v[198:201], v[44:47]
	v_mfma_f32_16x16x32_bf16 v[92:95], v[210:213], v[178:181], v[92:95]
	v_mfma_f32_16x16x32_bf16 v[88:91], v[218:221], v[178:181], v[88:91]
	v_mfma_f32_16x16x32_bf16 v[84:87], v[210:213], v[186:189], v[84:87]
	v_mfma_f32_16x16x32_bf16 v[80:83], v[218:221], v[186:189], v[80:83]
	v_mfma_f32_16x16x32_bf16 v[72:75], v[210:213], v[194:197], v[72:75]
	v_mfma_f32_16x16x32_bf16 v[68:71], v[218:221], v[194:197], v[68:71]
	v_mfma_f32_16x16x32_bf16 v[52:55], v[210:213], v[202:205], v[52:55]
	v_mfma_f32_16x16x32_bf16 v[44:47], v[218:221], v[202:205], v[44:47]
	s_add_i32 s47, s47, 2
	s_add_u32 s20, s20, 0x100
	s_addc_u32 s21, s21, 0
	s_add_u32 s45, s45, 0x100
	s_addc_u32 s46, s46, 0
	s_cmp_gt_u32 s47, 13
	s_barrier
; __device__ __forceinline__ unsigned pk2(float lo, float hi) { const f32x2 v = (f32x2){lo, hi}; const bf16x2_t b = __builtin_convertvector(v, bf16x2_t); return __builtin_bit_cast(unsigned, b); }
;     __device__ __forceinline__ void operator()(const f32x4 (&acc)[2][2][4][2], const Unit& u, int wr, int wc, int fr, int fq, const float (&)[8]) const {
;     ...
;         if (DT && u.pn == 20) {
;             if (wc == 0) {
; #pragma unroll
;                 for (int ai = 0; ai < 2; ++ai)
; #pragma unroll
;                     for (int m = 0; m < 4; ++m) { const int row = row0 + ai * HALF + m * 16; const float rs = rsqrtf(ep[ai * 4 + m] * (1.0f / 1024.0f) + EPS);
;                         *(f32x4*)(dt + (size_t)row * 32 + 8 * fq) = acc[ai][0][m][0] * rs; *(f32x4*)(dt + (size_t)row * 32 + 8 * fq + 4) = acc[ai][0][m][1] * rs; }
;             }
;             return;
;         }
;         const int col0 = u.pn * BM + wc * 32 + 8 * fq;
; #pragma unroll
;         for (int ai = 0; ai < 2; ++ai)
; #pragma unroll
;             for (int m = 0; m < 4; ++m) { const int row = row0 + ai * HALF + m * 16; const float rs = rsqrtf(ep[ai * 4 + m] * (1.0f / 1024.0f) + EPS);
;                 u16* rowp = O + (size_t)row * ldc + col0;
; #pragma unroll
;                 for (int bj = 0; bj < 2; ++bj) { f32x4 v0 = acc[ai][bj][m][0] * rs, v1 = acc[ai][bj][m][1] * rs;
;                     if (ACT == 1) {
; #pragma unroll
;                         for (int j = 0; j < 4; ++j) { const float a0 = fmaxf(v0[j], 0.f), a1 = fmaxf(v1[j], 0.f); v0[j] = a0 * a0; v1[j] = a1 * a1; } }
;                     u32x4 w; w.x = pk2(v0[0], v0[1]); w.y = pk2(v0[2], v0[3]); w.z = pk2(v1[0], v1[1]); w.w = pk2(v1[2], v1[3]);
;                     *(u32x4*)(rowp + bj * HALF) = w; } }
	s_cbranch_scc0 .LBB0_205
	s_bfe_u32 vcc_lo, s18, 0x20003
	s_lshl_b32 vcc_lo, vcc_lo, 10
	s_add_i32 vcc_lo, vcc_lo, 0x20010
	v_lshl_add_u32 v236, v153, 2, vcc_lo
	ds_read_b32 v228, v236
	ds_read_b32 v229, v236 offset:64
	ds_read_b32 v230, v236 offset:128
	ds_read_b32 v231, v236 offset:192
	ds_read_b32 v232, v236 offset:512
	ds_read_b32 v233, v236 offset:576
	ds_read_b32 v234, v236 offset:640
	ds_read_b32 v235, v236 offset:704
	s_waitcnt lgkmcnt(0)
	v_lshl_add_u32 v162, s18, 8, v153
	v_ashrrev_i32_e32 v163, 31, v162
	v_or_b32_e32 v160, 16, v162
	v_or_b32_e32 v158, 32, v162
	v_or_b32_e32 v156, 48, v162
	v_ashrrev_i32_e32 v161, 31, v160
	v_ashrrev_i32_e32 v159, 31, v158
	v_ashrrev_i32_e32 v157, 31, v156
	v_add_u32_e32 v154, 0x80, v162
	v_add_u32_e32 v150, 0x90, v162
	v_add_u32_e32 v148, 0xa0, v162
	v_add_u32_e32 v146, 0xb0, v162
	v_ashrrev_i32_e32 v155, 31, v154
	v_ashrrev_i32_e32 v151, 31, v150
	v_ashrrev_i32_e32 v149, 31, v148
	v_ashrrev_i32_e32 v147, 31, v146
	s_cmp_lg_u32 s43, 20
	s_mov_b64 s[18:19], -1
	s_cbranch_scc0 .LBB0_208
	s_waitcnt vmcnt(8)
	v_lshl_or_b32 v166, s43, 8, v169
	v_ashrrev_i32_e32 v167, 31, v166
	v_lshlrev_b64 v[166:167], 1, v[166:167]
	v_mov_b32_e32 v186, v228
	v_mov_b64_e32 v[164:165], s[96:97]
	v_mad_i64_i32 v[182:183], s[18:19], v162, s42, v[164:165]
	v_lshl_add_u64 v[188:189], v[182:183], 0, v[166:167]
	v_pk_mul_f32 v[184:185], v[78:79], v[186:187] op_sel_hi:[1,0]
	v_pk_mul_f32 v[182:183], v[76:77], v[186:187] op_sel_hi:[1,0]
	v_pk_mul_f32 v[190:191], v[66:67], v[186:187] op_sel_hi:[1,0]
	v_pk_mul_f32 v[192:193], v[64:65], v[186:187] op_sel_hi:[1,0]
	v_cvt_pk_bf16_f32 v182, v182, v183
	v_cvt_pk_bf16_f32 v183, v184, v185
	v_cvt_pk_bf16_f32 v184, v192, v193
	v_cvt_pk_bf16_f32 v185, v190, v191
	v_pk_mul_f32 v[124:125], v[124:125], v[186:187] op_sel_hi:[1,0]
	global_store_dwordx4 v[188:189], v[182:185], off
	v_pk_mul_f32 v[126:127], v[126:127], v[186:187] op_sel_hi:[1,0]
	s_nop 0
	v_pk_mul_f32 v[182:183], v[122:123], v[186:187] op_sel_hi:[1,0]
	v_pk_mul_f32 v[122:123], v[120:121], v[186:187] op_sel_hi:[1,0]
	v_cvt_pk_bf16_f32 v120, v124, v125
	v_cvt_pk_bf16_f32 v121, v126, v127
	v_cvt_pk_bf16_f32 v122, v122, v123
	v_cvt_pk_bf16_f32 v123, v182, v183
	global_store_dwordx4 v[188:189], v[120:123], off offset:256
	s_nop 1
	v_mov_b32_e32 v124, v229
	v_mad_i64_i32 v[120:121], s[18:19], v160, s42, v[164:165]
	v_lshl_add_u64 v[126:127], v[120:121], 0, v[166:167]
	v_pk_mul_f32 v[122:123], v[62:63], v[124:125] op_sel_hi:[1,0]
	v_pk_mul_f32 v[120:121], v[60:61], v[124:125] op_sel_hi:[1,0]
	v_pk_mul_f32 v[182:183], v[58:59], v[124:125] op_sel_hi:[1,0]
	v_pk_mul_f32 v[184:185], v[56:57], v[124:125] op_sel_hi:[1,0]
	v_cvt_pk_bf16_f32 v120, v120, v121
	v_cvt_pk_bf16_f32 v121, v122, v123
	v_cvt_pk_bf16_f32 v122, v184, v185
	v_cvt_pk_bf16_f32 v123, v182, v183
	v_pk_mul_f32 v[116:117], v[116:117], v[124:125] op_sel_hi:[1,0]
	global_store_dwordx4 v[126:127], v[120:123], off
	v_pk_mul_f32 v[118:119], v[118:119], v[124:125] op_sel_hi:[1,0]
	s_nop 0
	v_pk_mul_f32 v[120:121], v[114:115], v[124:125] op_sel_hi:[1,0]
	v_pk_mul_f32 v[114:115], v[112:113], v[124:125] op_sel_hi:[1,0]
	v_cvt_pk_bf16_f32 v112, v116, v117
	v_cvt_pk_bf16_f32 v113, v118, v119
	v_cvt_pk_bf16_f32 v114, v114, v115
	v_cvt_pk_bf16_f32 v115, v120, v121
	global_store_dwordx4 v[126:127], v[112:115], off offset:256
	s_nop 1
	v_mov_b32_e32 v116, v230
	v_mad_i64_i32 v[112:113], s[18:19], v158, s42, v[164:165]
	v_lshl_add_u64 v[118:119], v[112:113], 0, v[166:167]
	v_pk_mul_f32 v[114:115], v[50:51], v[116:117] op_sel_hi:[1,0]
	v_pk_mul_f32 v[112:113], v[48:49], v[116:117] op_sel_hi:[1,0]
	v_pk_mul_f32 v[120:121], v[42:43], v[116:117] op_sel_hi:[1,0]
	v_pk_mul_f32 v[122:123], v[40:41], v[116:117] op_sel_hi:[1,0]
	v_cvt_pk_bf16_f32 v112, v112, v113
	v_cvt_pk_bf16_f32 v113, v114, v115
	v_cvt_pk_bf16_f32 v114, v122, v123
	v_cvt_pk_bf16_f32 v115, v120, v121
	v_pk_mul_f32 v[108:109], v[108:109], v[116:117] op_sel_hi:[1,0]
	global_store_dwordx4 v[118:119], v[112:115], off
	v_pk_mul_f32 v[110:111], v[110:111], v[116:117] op_sel_hi:[1,0]
	s_nop 0
	v_pk_mul_f32 v[112:113], v[106:107], v[116:117] op_sel_hi:[1,0]
	v_pk_mul_f32 v[106:107], v[104:105], v[116:117] op_sel_hi:[1,0]
	v_cvt_pk_bf16_f32 v104, v108, v109
	v_cvt_pk_bf16_f32 v105, v110, v111
	v_cvt_pk_bf16_f32 v106, v106, v107
	v_cvt_pk_bf16_f32 v107, v112, v113
	global_store_dwordx4 v[118:119], v[104:107], off offset:256
	s_nop 1
	v_mov_b32_e32 v108, v231
	v_mad_i64_i32 v[104:105], s[18:19], v156, s42, v[164:165]
	v_lshl_add_u64 v[110:111], v[104:105], 0, v[166:167]
	v_pk_mul_f32 v[106:107], v[38:39], v[108:109] op_sel_hi:[1,0]
	v_pk_mul_f32 v[104:105], v[36:37], v[108:109] op_sel_hi:[1,0]
	v_pk_mul_f32 v[112:113], v[34:35], v[108:109] op_sel_hi:[1,0]
; __device__ __forceinline__ unsigned pk2(float lo, float hi) { const f32x2 v = (f32x2){lo, hi}; const bf16x2_t b = __builtin_convertvector(v, bf16x2_t); return __builtin_bit_cast(unsigned, b); }
;     __device__ __forceinline__ void operator()(const f32x4 (&acc)[2][2][4][2], const Unit& u, int wr, int wc, int fr, int fq, const float (&)[8]) const {
;     ...
;         for (int ai = 0; ai < 2; ++ai)
; #pragma unroll
;             for (int m = 0; m < 4; ++m) { const int row = row0 + ai * HALF + m * 16; const float rs = rsqrtf(ep[ai * 4 + m] * (1.0f / 1024.0f) + EPS);
;                 u16* rowp = O + (size_t)row * ldc + col0;
; #pragma unroll
;                 for (int bj = 0; bj < 2; ++bj) { f32x4 v0 = acc[ai][bj][m][0] * rs, v1 = acc[ai][bj][m][1] * rs;
;                     if (ACT == 1) {
; #pragma unroll
;                         for (int j = 0; j < 4; ++j) { const float a0 = fmaxf(v0[j], 0.f), a1 = fmaxf(v1[j], 0.f); v0[j] = a0 * a0; v1[j] = a1 * a1; } }
;                     u32x4 w; w.x = pk2(v0[0], v0[1]); w.y = pk2(v0[2], v0[3]); w.z = pk2(v1[0], v1[1]); w.w = pk2(v1[2], v1[3]);
;                     *(u32x4*)(rowp + bj * HALF) = w; } }
	v_pk_mul_f32 v[114:115], v[32:33], v[108:109] op_sel_hi:[1,0]
	v_cvt_pk_bf16_f32 v104, v104, v105
	v_cvt_pk_bf16_f32 v105, v106, v107
	v_cvt_pk_bf16_f32 v106, v114, v115
	v_cvt_pk_bf16_f32 v107, v112, v113
	v_pk_mul_f32 v[100:101], v[100:101], v[108:109] op_sel_hi:[1,0]
	global_store_dwordx4 v[110:111], v[104:107], off
	v_pk_mul_f32 v[102:103], v[102:103], v[108:109] op_sel_hi:[1,0]
	s_nop 0
	v_pk_mul_f32 v[104:105], v[98:99], v[108:109] op_sel_hi:[1,0]
	v_pk_mul_f32 v[98:99], v[96:97], v[108:109] op_sel_hi:[1,0]
	v_cvt_pk_bf16_f32 v96, v100, v101
	v_cvt_pk_bf16_f32 v97, v102, v103
	v_cvt_pk_bf16_f32 v98, v98, v99
	v_cvt_pk_bf16_f32 v99, v104, v105
	global_store_dwordx4 v[110:111], v[96:99], off offset:256
	s_nop 1
	v_mov_b32_e32 v100, v232
	v_mad_i64_i32 v[96:97], s[18:19], v154, s42, v[164:165]
	v_lshl_add_u64 v[102:103], v[96:97], 0, v[166:167]
	v_pk_mul_f32 v[98:99], v[30:31], v[100:101] op_sel_hi:[1,0]
	v_pk_mul_f32 v[96:97], v[28:29], v[100:101] op_sel_hi:[1,0]
	v_pk_mul_f32 v[104:105], v[26:27], v[100:101] op_sel_hi:[1,0]
	v_pk_mul_f32 v[106:107], v[24:25], v[100:101] op_sel_hi:[1,0]
	v_cvt_pk_bf16_f32 v96, v96, v97
	v_cvt_pk_bf16_f32 v97, v98, v99
	v_cvt_pk_bf16_f32 v98, v106, v107
	v_cvt_pk_bf16_f32 v99, v104, v105
	v_pk_mul_f32 v[92:93], v[92:93], v[100:101] op_sel_hi:[1,0]
	global_store_dwordx4 v[102:103], v[96:99], off
	v_pk_mul_f32 v[94:95], v[94:95], v[100:101] op_sel_hi:[1,0]
	s_nop 0
	v_pk_mul_f32 v[96:97], v[90:91], v[100:101] op_sel_hi:[1,0]
	v_pk_mul_f32 v[90:91], v[88:89], v[100:101] op_sel_hi:[1,0]
	v_cvt_pk_bf16_f32 v88, v92, v93
	v_cvt_pk_bf16_f32 v89, v94, v95
	v_cvt_pk_bf16_f32 v90, v90, v91
	v_cvt_pk_bf16_f32 v91, v96, v97
	global_store_dwordx4 v[102:103], v[88:91], off offset:256
	s_nop 1
	v_mov_b32_e32 v92, v233
	v_mad_i64_i32 v[88:89], s[18:19], v150, s42, v[164:165]
	v_lshl_add_u64 v[94:95], v[88:89], 0, v[166:167]
	v_pk_mul_f32 v[90:91], v[22:23], v[92:93] op_sel_hi:[1,0]
	v_pk_mul_f32 v[88:89], v[20:21], v[92:93] op_sel_hi:[1,0]
	v_pk_mul_f32 v[96:97], v[18:19], v[92:93] op_sel_hi:[1,0]
	v_pk_mul_f32 v[98:99], v[16:17], v[92:93] op_sel_hi:[1,0]
	v_cvt_pk_bf16_f32 v88, v88, v89
	v_cvt_pk_bf16_f32 v89, v90, v91
	v_cvt_pk_bf16_f32 v90, v98, v99
	v_cvt_pk_bf16_f32 v91, v96, v97
	v_pk_mul_f32 v[84:85], v[84:85], v[92:93] op_sel_hi:[1,0]
	global_store_dwordx4 v[94:95], v[88:91], off
	v_pk_mul_f32 v[86:87], v[86:87], v[92:93] op_sel_hi:[1,0]
	s_nop 0
	v_pk_mul_f32 v[88:89], v[82:83], v[92:93] op_sel_hi:[1,0]
	v_pk_mul_f32 v[82:83], v[80:81], v[92:93] op_sel_hi:[1,0]
	v_cvt_pk_bf16_f32 v80, v84, v85
	v_cvt_pk_bf16_f32 v81, v86, v87
	v_cvt_pk_bf16_f32 v82, v82, v83
	v_cvt_pk_bf16_f32 v83, v88, v89
	global_store_dwordx4 v[94:95], v[80:83], off offset:256
	s_nop 1
	v_mov_b32_e32 v84, v234
	v_mad_i64_i32 v[80:81], s[18:19], v148, s42, v[164:165]
	v_lshl_add_u64 v[86:87], v[80:81], 0, v[166:167]
	v_pk_mul_f32 v[82:83], v[14:15], v[84:85] op_sel_hi:[1,0]
	v_pk_mul_f32 v[80:81], v[12:13], v[84:85] op_sel_hi:[1,0]
	v_pk_mul_f32 v[88:89], v[10:11], v[84:85] op_sel_hi:[1,0]
	v_pk_mul_f32 v[90:91], v[8:9], v[84:85] op_sel_hi:[1,0]
	v_cvt_pk_bf16_f32 v80, v80, v81
	v_cvt_pk_bf16_f32 v81, v82, v83
	v_cvt_pk_bf16_f32 v82, v90, v91
	v_cvt_pk_bf16_f32 v83, v88, v89
	v_pk_mul_f32 v[72:73], v[72:73], v[84:85] op_sel_hi:[1,0]
	global_store_dwordx4 v[86:87], v[80:83], off
	v_pk_mul_f32 v[74:75], v[74:75], v[84:85] op_sel_hi:[1,0]
	s_nop 0
	v_pk_mul_f32 v[80:81], v[70:71], v[84:85] op_sel_hi:[1,0]
	v_pk_mul_f32 v[70:71], v[68:69], v[84:85] op_sel_hi:[1,0]
	v_cvt_pk_bf16_f32 v68, v72, v73
	v_cvt_pk_bf16_f32 v69, v74, v75
	v_cvt_pk_bf16_f32 v70, v70, v71
	v_cvt_pk_bf16_f32 v71, v80, v81
	global_store_dwordx4 v[86:87], v[68:71], off offset:256
	s_nop 1
	v_mov_b32_e32 v72, v235
	v_mad_i64_i32 v[68:69], s[18:19], v146, s42, v[164:165]
	v_lshl_add_u64 v[74:75], v[68:69], 0, v[166:167]
	v_pk_mul_f32 v[70:71], v[6:7], v[72:73] op_sel_hi:[1,0]
	v_pk_mul_f32 v[68:69], v[4:5], v[72:73] op_sel_hi:[1,0]
	v_pk_mul_f32 v[80:81], v[2:3], v[72:73] op_sel_hi:[1,0]
	v_pk_mul_f32 v[82:83], v[0:1], v[72:73] op_sel_hi:[1,0]
	v_cvt_pk_bf16_f32 v68, v68, v69
	v_cvt_pk_bf16_f32 v69, v70, v71
	v_cvt_pk_bf16_f32 v70, v82, v83
	v_cvt_pk_bf16_f32 v71, v80, v81
	global_store_dwordx4 v[74:75], v[68:71], off
	v_pk_mul_f32 v[54:55], v[54:55], v[72:73] op_sel_hi:[1,0]
	v_pk_mul_f32 v[52:53], v[52:53], v[72:73] op_sel_hi:[1,0]
	v_pk_mul_f32 v[68:69], v[46:47], v[72:73] op_sel_hi:[1,0]
	v_pk_mul_f32 v[46:47], v[44:45], v[72:73] op_sel_hi:[1,0]
	v_cvt_pk_bf16_f32 v44, v52, v53
	v_cvt_pk_bf16_f32 v45, v54, v55
	v_cvt_pk_bf16_f32 v46, v46, v47
	v_cvt_pk_bf16_f32 v47, v68, v69
	global_store_dwordx4 v[74:75], v[44:47], off offset:256
	s_mov_b64 s[18:19], 0

; #define PG8_STAGE(bufoff, gbase, voff) do { _Pragma("unroll") for (int _i = 0; _i < 2; ++_i) \
;         __builtin_amdgcn_global_load_lds((const unsigned*)((const char*)(gbase) + (voff)[_i]), (LAS unsigned*)(lds + (bufoff) + ldsw + _i * 8192), 16, 0, 0); } while (0)
; #define PG8_LDA(dst, b, h) do { _Pragma("unroll") for (int m = 0; m < 4; ++m) _Pragma("unroll") for (int k = 0; k < 2; ++k) dst[m][k] = *(const LAS bf16x8*)(lds + PG8_SA(b, h) + aoff + m * 2048 + k * 1024); } while (0)
; #define PG8_LDB(dst, b, h) do { _Pragma("unroll") for (int n = 0; n < 2; ++n) _Pragma("unroll") for (int k = 0; k < 2; ++k) dst[n][k] = *(const LAS bf16x8*)(lds + PG8_SB(b, h) + boff + n * 2048 + k * 1024); } while (0)
; #define PG8_MMA(ai, bj, At, Bt) do { __builtin_amdgcn_s_setprio(1); _Pragma("unroll") for (int m = 0; m < 4; ++m) _Pragma("unroll") for (int n = 0; n < 2; ++n) _Pragma("unroll") for (int k = 0; k < 2; ++k) \
;         acc[ai][bj][m][n] = __builtin_amdgcn_mfma_f32_16x16x32_bf16(Bt[n][k], At[m][k], acc[ai][bj][m][n], 0, 0, 0); __builtin_amdgcn_s_setprio(0); } while (0)
; #define PG8_BAR __builtin_amdgcn_s_barrier()
; template <class Epi>
; __device__ __forceinline__ void gemm_phase(LAS unsigned char* lds, const Gemm g, const StaticOrder& S, const Epi& E) {
;     ...
;         const bool has_next = S.next(ui + 1, nxt);
;         const char* nA = has_next ? (const char*)g.A + (size_t)nxt.pm * tstepA : cA; const char* nB = has_next ? (const char*)g.Bt + (size_t)nxt.pn * tstepB : cB;
;         for (int t = 0; t < nt; t += 2) {
;             const bool last = (t == nt - 2);
;             const char* a1 = cA + (size_t)(t + 1) * kstep;
;             const char* a2 = last ? nA : cA + (size_t)(t + 2) * kstep; const char* b2 = last ? nB : cB + (size_t)(t + 2) * kstep;
;             const char* a3 = a2 + kstep; const char* b3 = b2 + kstep;
;             if (last) E.pre(cur, wr, fr, epre);
;             PG8_LDB(B0, 0, 0); PG8_SCHED; PG8_LDA(At, 0, 0); PG8_STAGE(PG8_SA(1, 1), a1 + hstepA, voffA);
;             PG8_WAIT_L(8); PG8_BAR; PG8_WAIT_L(0); PG8_MMA(0, 0, At, B0); PG8_BAR; PG8_SCHED;
;             PG8_LDB(B1, 0, 1); PG8_STAGE(PG8_SB(0, 0), b2, voffB);
;             PG8_BAR; PG8_WAIT_L(0); PG8_MMA(0, 1, At, B1); PG8_BAR;
;             PG8_LDA(At, 0, 1); PG8_STAGE(PG8_SA(0, 0), a2, voffA);
;             PG8_BAR; PG8_WAIT_L(0); PG8_MMA(1, 0, At, B0); PG8_BAR; PG8_SCHED;
.LBB0_683:
	s_ashr_i32 s17, s16, 31
	s_lshl_b64 s[20:21], s[16:17], 20
	s_add_u32 s20, s29, s20
	s_addc_u32 s21, s30, s21
	s_and_b64 s[4:5], s[4:5], exec
	s_cselect_b32 s17, s21, s23
	s_cselect_b32 s45, s20, s22
	s_add_u32 s4, s24, 0x140080
	s_addc_u32 s5, s25, 0
	s_add_u32 s46, s22, 0x100
	s_addc_u32 s47, s23, 0
	s_mov_b32 s48, -2
	s_waitcnt lgkmcnt(0)
	ds_read_b128 v[128:131], v191
	ds_read_b128 v[132:135], v191 offset:1024
	ds_read_b128 v[136:139], v191 offset:2048
	ds_read_b128 v[140:143], v191 offset:3072
	s_add_u32 s22, s4, 0xffec0080
	s_addc_u32 s23, s5, -1
	s_cmp_eq_u32 s48, 28
	s_cselect_b32 s25, s19, s23
	s_cselect_b32 s24, s18, s22
	s_cselect_b32 s23, s17, s47
	s_cselect_b32 s22, s45, s46
	v_lshl_add_u64 v[186:187], s[4:5], 0, v[162:163]
	s_add_i32 m0, s11, 0xc000
	ds_read_b128 v[144:147], v192
	ds_read_b128 v[148:151], v192 offset:1024
	ds_read_b128 v[170:173], v192 offset:2048
	ds_read_b128 v[174:177], v192 offset:3072
	ds_read_b128 v[178:181], v192 offset:4096
	ds_read_b128 v[182:185], v192 offset:5120
	ds_read_b128 v[196:199], v192 offset:6144
	ds_read_b128 v[200:203], v192 offset:7168
	global_load_lds_dwordx4 v[186:187], off
	v_lshl_add_u64 v[186:187], s[4:5], 0, v[164:165]
	s_add_i32 m0, s11, 0xe000
	s_nop 0
	global_load_lds_dwordx4 v[186:187], off
	s_waitcnt lgkmcnt(8)
	s_barrier
	s_waitcnt lgkmcnt(0)
	v_mfma_f32_16x16x32_bf16 v[124:127], v[128:131], v[144:147], 0
	v_mfma_f32_16x16x32_bf16 v[120:123], v[136:139], v[144:147], 0
	v_mfma_f32_16x16x32_bf16 v[108:111], v[128:131], v[170:173], 0
	v_mfma_f32_16x16x32_bf16 v[104:107], v[136:139], v[170:173], 0
	v_mfma_f32_16x16x32_bf16 v[92:95], v[128:131], v[178:181], 0
	v_mfma_f32_16x16x32_bf16 v[88:91], v[136:139], v[178:181], 0
	v_mfma_f32_16x16x32_bf16 v[76:79], v[128:131], v[196:199], 0
	v_mfma_f32_16x16x32_bf16 v[72:75], v[136:139], v[196:199], 0
	v_mfma_f32_16x16x32_bf16 v[124:127], v[132:135], v[148:151], v[124:127]
	v_mfma_f32_16x16x32_bf16 v[120:123], v[140:143], v[148:151], v[120:123]
	v_mfma_f32_16x16x32_bf16 v[108:111], v[132:135], v[174:177], v[108:111]
	v_mfma_f32_16x16x32_bf16 v[104:107], v[140:143], v[174:177], v[104:107]
	v_mfma_f32_16x16x32_bf16 v[92:95], v[132:135], v[182:185], v[92:95]
	v_mfma_f32_16x16x32_bf16 v[88:91], v[140:143], v[182:185], v[88:91]
	v_mfma_f32_16x16x32_bf16 v[76:79], v[132:135], v[200:203], v[76:79]
	v_mfma_f32_16x16x32_bf16 v[72:75], v[140:143], v[200:203], v[72:75]
	s_barrier
	s_add_i32 s49, s42, s31
	v_lshl_add_u64 v[186:187], s[22:23], 0, v[156:157]
	s_mov_b32 m0, s49
	ds_read_b128 v[204:207], v193
	ds_read_b128 v[208:211], v193 offset:1024
	ds_read_b128 v[212:215], v193 offset:2048
	ds_read_b128 v[216:219], v193 offset:3072
	global_load_lds_dwordx4 v[186:187], off
	v_lshl_add_u64 v[220:221], s[22:23], 0, v[160:161]
	s_add_i32 m0, s49, 0x2000
	s_nop 0
	global_load_lds_dwordx4 v[220:221], off
	s_barrier
	s_waitcnt lgkmcnt(0)
	v_mfma_f32_16x16x32_bf16 v[116:119], v[204:207], v[144:147], 0
	v_mfma_f32_16x16x32_bf16 v[112:115], v[212:215], v[144:147], 0
	v_mfma_f32_16x16x32_bf16 v[100:103], v[204:207], v[170:173], 0
	v_mfma_f32_16x16x32_bf16 v[96:99], v[212:215], v[170:173], 0
	v_mfma_f32_16x16x32_bf16 v[84:87], v[204:207], v[178:181], 0
	v_mfma_f32_16x16x32_bf16 v[80:83], v[212:215], v[178:181], 0
	v_mfma_f32_16x16x32_bf16 v[68:71], v[204:207], v[196:199], 0
	v_mfma_f32_16x16x32_bf16 v[64:67], v[212:215], v[196:199], 0
	v_mfma_f32_16x16x32_bf16 v[116:119], v[208:211], v[148:151], v[116:119]
	v_mfma_f32_16x16x32_bf16 v[112:115], v[216:219], v[148:151], v[112:115]
	v_mfma_f32_16x16x32_bf16 v[100:103], v[208:211], v[174:177], v[100:103]
	v_mfma_f32_16x16x32_bf16 v[96:99], v[216:219], v[174:177], v[96:99]
	v_mfma_f32_16x16x32_bf16 v[84:87], v[208:211], v[182:185], v[84:87]
	v_mfma_f32_16x16x32_bf16 v[80:83], v[216:219], v[182:185], v[80:83]
	v_mfma_f32_16x16x32_bf16 v[68:71], v[208:211], v[200:203], v[68:71]
	v_mfma_f32_16x16x32_bf16 v[64:67], v[216:219], v[200:203], v[64:67]
	s_mov_b32 m0, s11
	v_lshl_add_u64 v[222:223], s[24:25], 0, v[154:155]
	s_barrier
	ds_read_b128 v[144:147], v192 offset:16384
	ds_read_b128 v[148:151], v192 offset:17408
	ds_read_b128 v[170:173], v192 offset:18432
	ds_read_b128 v[174:177], v192 offset:19456
	ds_read_b128 v[178:181], v192 offset:20480
	ds_read_b128 v[182:185], v192 offset:21504
	ds_read_b128 v[196:199], v192 offset:22528
	ds_read_b128 v[200:203], v192 offset:23552
	global_load_lds_dwordx4 v[222:223], off
	v_lshl_add_u64 v[224:225], s[24:25], 0, v[158:159]
	s_mov_b32 m0, s34
	s_nop 0
	global_load_lds_dwordx4 v[224:225], off
	s_barrier
	s_waitcnt lgkmcnt(0)
	v_mfma_f32_16x16x32_bf16 v[60:63], v[128:131], v[144:147], 0
	v_mfma_f32_16x16x32_bf16 v[56:59], v[136:139], v[144:147], 0
	v_mfma_f32_16x16x32_bf16 v[44:47], v[128:131], v[170:173], 0
	v_mfma_f32_16x16x32_bf16 v[40:43], v[136:139], v[170:173], 0
	v_mfma_f32_16x16x32_bf16 v[28:31], v[128:131], v[178:181], 0
	v_mfma_f32_16x16x32_bf16 v[24:27], v[136:139], v[178:181], 0
	v_mfma_f32_16x16x32_bf16 v[12:15], v[128:131], v[196:199], 0
	v_mfma_f32_16x16x32_bf16 v[8:11], v[136:139], v[196:199], 0
	v_mfma_f32_16x16x32_bf16 v[60:63], v[132:135], v[148:151], v[60:63]
	v_mfma_f32_16x16x32_bf16 v[56:59], v[140:143], v[148:151], v[56:59]
	v_mfma_f32_16x16x32_bf16 v[44:47], v[132:135], v[174:177], v[44:47]
	v_mfma_f32_16x16x32_bf16 v[40:43], v[140:143], v[174:177], v[40:43]
	v_mfma_f32_16x16x32_bf16 v[28:31], v[132:135], v[182:185], v[28:31]
	v_mfma_f32_16x16x32_bf16 v[24:27], v[140:143], v[182:185], v[24:27]
	v_mfma_f32_16x16x32_bf16 v[12:15], v[132:135], v[200:203], v[12:15]
	v_mfma_f32_16x16x32_bf16 v[8:11], v[140:143], v[200:203], v[8:11]
	s_barrier
; #define PG8_STAGE(bufoff, gbase, voff) do { _Pragma("unroll") for (int _i = 0; _i < 2; ++_i) \
;         __builtin_amdgcn_global_load_lds((const unsigned*)((const char*)(gbase) + (voff)[_i]), (LAS unsigned*)(lds + (bufoff) + ldsw + _i * 8192), 16, 0, 0); } while (0)
; #define PG8_LDA(dst, b, h) do { _Pragma("unroll") for (int m = 0; m < 4; ++m) _Pragma("unroll") for (int k = 0; k < 2; ++k) dst[m][k] = *(const LAS bf16x8*)(lds + PG8_SA(b, h) + aoff + m * 2048 + k * 1024); } while (0)
; #define PG8_LDB(dst, b, h) do { _Pragma("unroll") for (int n = 0; n < 2; ++n) _Pragma("unroll") for (int k = 0; k < 2; ++k) dst[n][k] = *(const LAS bf16x8*)(lds + PG8_SB(b, h) + boff + n * 2048 + k * 1024); } while (0)
; #define PG8_MMA(ai, bj, At, Bt) do { __builtin_amdgcn_s_setprio(1); _Pragma("unroll") for (int m = 0; m < 4; ++m) _Pragma("unroll") for (int n = 0; n < 2; ++n) _Pragma("unroll") for (int k = 0; k < 2; ++k) \
;         acc[ai][bj][m][n] = __builtin_amdgcn_mfma_f32_16x16x32_bf16(Bt[n][k], At[m][k], acc[ai][bj][m][n], 0, 0, 0); __builtin_amdgcn_s_setprio(0); } while (0)
; #define PG8_WAIT_V(n) asm volatile("s_waitcnt vmcnt(" #n ")" ::: "memory")
; #define PG8_WAIT_L(n) asm volatile("s_waitcnt lgkmcnt(" #n ")" ::: "memory")
; #define PG8_BAR __builtin_amdgcn_s_barrier()
; #define PG8_SCHED __builtin_amdgcn_sched_barrier(0)
; template <class Epi>
; __device__ __forceinline__ void gemm_phase(LAS unsigned char* lds, const Gemm g, const StaticOrder& S, const Epi& E) {
;     ...
;             PG8_BAR; PG8_WAIT_L(0); PG8_MMA(1, 0, At, B0); PG8_BAR; PG8_SCHED;
;             PG8_STAGE(PG8_SB(0, 1), b2 + hstepB, voffB);
;             PG8_WAIT_V(6); PG8_BAR; PG8_MMA(1, 1, At, B1); PG8_BAR;
;             PG8_LDB(B0, 1, 0); PG8_SCHED; PG8_LDA(At, 1, 0); PG8_STAGE(PG8_SA(0, 1), a2 + hstepA, voffA);
;             PG8_WAIT_L(8); PG8_BAR; PG8_WAIT_L(0); PG8_MMA(0, 0, At, B0); PG8_BAR; PG8_SCHED;
;             PG8_LDB(B1, 1, 1); PG8_STAGE(PG8_SB(1, 0), b3, voffB);
;             PG8_BAR; PG8_WAIT_L(0); PG8_MMA(0, 1, At, B1); PG8_BAR;
;             PG8_LDA(At, 1, 1); PG8_STAGE(PG8_SA(1, 0), a3, voffA);
;             PG8_BAR; PG8_WAIT_L(0); PG8_MMA(1, 0, At, B0); PG8_BAR; PG8_SCHED;
;             PG8_STAGE(PG8_SB(1, 1), b3 + hstepB, voffB);
;             PG8_WAIT_V(6); PG8_BAR; PG8_MMA(1, 1, At, B1); PG8_BAR;
	s_add_u32 s50, s22, 0x80000
	s_addc_u32 s51, s23, 0
	s_add_i32 s49, s43, s31
	v_lshl_add_u64 v[128:129], s[50:51], 0, v[156:157]
	s_mov_b32 m0, s49
	s_nop 0
	global_load_lds_dwordx4 v[128:129], off
	v_lshl_add_u64 v[128:129], s[50:51], 0, v[160:161]
	s_add_i32 m0, s49, 0x2000
	s_nop 0
	global_load_lds_dwordx4 v[128:129], off
	s_waitcnt vmcnt(6)
	s_barrier
	v_mfma_f32_16x16x32_bf16 v[52:55], v[204:207], v[144:147], 0
	v_mfma_f32_16x16x32_bf16 v[48:51], v[212:215], v[144:147], 0
	v_mfma_f32_16x16x32_bf16 v[36:39], v[204:207], v[170:173], 0
	v_mfma_f32_16x16x32_bf16 v[32:35], v[212:215], v[170:173], 0
	v_mfma_f32_16x16x32_bf16 v[20:23], v[204:207], v[178:181], 0
	v_mfma_f32_16x16x32_bf16 v[16:19], v[212:215], v[178:181], 0
	v_mfma_f32_16x16x32_bf16 v[4:7], v[204:207], v[196:199], 0
	v_mfma_f32_16x16x32_bf16 v[0:3], v[212:215], v[196:199], 0
	v_mfma_f32_16x16x32_bf16 v[52:55], v[208:211], v[148:151], v[52:55]
	v_mfma_f32_16x16x32_bf16 v[48:51], v[216:219], v[148:151], v[48:51]
	v_mfma_f32_16x16x32_bf16 v[36:39], v[208:211], v[174:177], v[36:39]
	v_mfma_f32_16x16x32_bf16 v[32:35], v[216:219], v[174:177], v[32:35]
	v_mfma_f32_16x16x32_bf16 v[20:23], v[208:211], v[182:185], v[20:23]
	v_mfma_f32_16x16x32_bf16 v[16:19], v[216:219], v[182:185], v[16:19]
	v_mfma_f32_16x16x32_bf16 v[4:7], v[208:211], v[200:203], v[4:7]
	v_mfma_f32_16x16x32_bf16 v[0:3], v[216:219], v[200:203], v[0:3]
	s_add_i32 s49, 0, 0x18000
	v_add_u32_e32 v140, s49, v189
	s_barrier
	ds_read_b128 v[128:131], v140
	ds_read_b128 v[132:135], v140 offset:1024
	ds_read_b128 v[136:139], v140 offset:2048
	ds_read_b128 v[140:143], v140 offset:3072
	s_add_u32 s24, s24, 0x140000
	s_addc_u32 s25, s25, 0
	s_mov_b32 m0, s35
	v_lshl_add_u64 v[204:205], s[24:25], 0, v[154:155]
	ds_read_b128 v[144:147], v192 offset:32768
	ds_read_b128 v[148:151], v192 offset:33792
	ds_read_b128 v[170:173], v192 offset:34816
	ds_read_b128 v[174:177], v192 offset:35840
	ds_read_b128 v[178:181], v192 offset:36864
	ds_read_b128 v[182:185], v192 offset:37888
	ds_read_b128 v[196:199], v192 offset:38912
	ds_read_b128 v[200:203], v192 offset:39936
	global_load_lds_dwordx4 v[204:205], off
	v_lshl_add_u64 v[204:205], s[24:25], 0, v[158:159]
	s_mov_b32 m0, s36
	s_nop 0
	global_load_lds_dwordx4 v[204:205], off
	s_waitcnt lgkmcnt(8)
	s_barrier
	s_waitcnt lgkmcnt(0)
	v_mfma_f32_16x16x32_bf16 v[124:127], v[128:131], v[144:147], v[124:127]
	v_mfma_f32_16x16x32_bf16 v[120:123], v[136:139], v[144:147], v[120:123]
	v_mfma_f32_16x16x32_bf16 v[108:111], v[128:131], v[170:173], v[108:111]
	v_mfma_f32_16x16x32_bf16 v[104:107], v[136:139], v[170:173], v[104:107]
	v_mfma_f32_16x16x32_bf16 v[92:95], v[128:131], v[178:181], v[92:95]
	v_mfma_f32_16x16x32_bf16 v[88:91], v[136:139], v[178:181], v[88:91]
	v_mfma_f32_16x16x32_bf16 v[76:79], v[128:131], v[196:199], v[76:79]
	v_mfma_f32_16x16x32_bf16 v[72:75], v[136:139], v[196:199], v[72:75]
	v_mfma_f32_16x16x32_bf16 v[124:127], v[132:135], v[148:151], v[124:127]
	v_mfma_f32_16x16x32_bf16 v[120:123], v[140:143], v[148:151], v[120:123]
	v_mfma_f32_16x16x32_bf16 v[108:111], v[132:135], v[174:177], v[108:111]
	v_mfma_f32_16x16x32_bf16 v[104:107], v[140:143], v[174:177], v[104:107]
	v_mfma_f32_16x16x32_bf16 v[92:95], v[132:135], v[182:185], v[92:95]
	v_mfma_f32_16x16x32_bf16 v[88:91], v[140:143], v[182:185], v[88:91]
	v_mfma_f32_16x16x32_bf16 v[76:79], v[132:135], v[200:203], v[76:79]
	v_mfma_f32_16x16x32_bf16 v[72:75], v[140:143], v[200:203], v[72:75]
	s_barrier
	s_add_i32 s24, 0, 0x1c000
	s_add_i32 s25, s49, s31
	v_add_u32_e32 v195, s24, v189
	v_lshl_add_u64 v[186:187], v[186:187], 0, s[14:15]
	s_mov_b32 m0, s25
	ds_read_b128 v[204:207], v195
	ds_read_b128 v[208:211], v195 offset:1024
	ds_read_b128 v[212:215], v195 offset:2048
	ds_read_b128 v[216:219], v195 offset:3072
	global_load_lds_dwordx4 v[186:187], off
	v_lshl_add_u64 v[186:187], v[220:221], 0, s[14:15]
	s_add_i32 m0, s25, 0x2000
	s_nop 0
	global_load_lds_dwordx4 v[186:187], off
	s_barrier
	s_waitcnt lgkmcnt(0)
	v_mfma_f32_16x16x32_bf16 v[116:119], v[204:207], v[144:147], v[116:119]
	v_mfma_f32_16x16x32_bf16 v[112:115], v[212:215], v[144:147], v[112:115]
	v_mfma_f32_16x16x32_bf16 v[100:103], v[204:207], v[170:173], v[100:103]
	v_mfma_f32_16x16x32_bf16 v[96:99], v[212:215], v[170:173], v[96:99]
	v_mfma_f32_16x16x32_bf16 v[84:87], v[204:207], v[178:181], v[84:87]
	v_mfma_f32_16x16x32_bf16 v[80:83], v[212:215], v[178:181], v[80:83]
	v_mfma_f32_16x16x32_bf16 v[68:71], v[204:207], v[196:199], v[68:71]
	v_mfma_f32_16x16x32_bf16 v[64:67], v[212:215], v[196:199], v[64:67]
	v_mfma_f32_16x16x32_bf16 v[116:119], v[208:211], v[148:151], v[116:119]
	v_mfma_f32_16x16x32_bf16 v[112:115], v[216:219], v[148:151], v[112:115]
	v_mfma_f32_16x16x32_bf16 v[100:103], v[208:211], v[174:177], v[100:103]
	v_mfma_f32_16x16x32_bf16 v[96:99], v[216:219], v[174:177], v[96:99]
	v_mfma_f32_16x16x32_bf16 v[84:87], v[208:211], v[182:185], v[84:87]
	v_mfma_f32_16x16x32_bf16 v[80:83], v[216:219], v[182:185], v[80:83]
	v_mfma_f32_16x16x32_bf16 v[68:71], v[208:211], v[200:203], v[68:71]
	v_mfma_f32_16x16x32_bf16 v[64:67], v[216:219], v[200:203], v[64:67]
	s_mov_b32 m0, s38
	v_lshl_add_u64 v[186:187], v[222:223], 0, s[14:15]
	s_barrier
	ds_read_b128 v[144:147], v192 offset:49152
	ds_read_b128 v[148:151], v192 offset:50176
	ds_read_b128 v[170:173], v192 offset:51200
	ds_read_b128 v[174:177], v192 offset:52224
	ds_read_b128 v[178:181], v192 offset:53248
	ds_read_b128 v[182:185], v192 offset:54272
	ds_read_b128 v[196:199], v192 offset:55296
	ds_read_b128 v[200:203], v192 offset:56320
	global_load_lds_dwordx4 v[186:187], off
	v_lshl_add_u64 v[186:187], v[224:225], 0, s[14:15]
	s_mov_b32 m0, s39
	s_nop 0
	global_load_lds_dwordx4 v[186:187], off
	s_barrier
; #define PG8_STAGE(bufoff, gbase, voff) do { _Pragma("unroll") for (int _i = 0; _i < 2; ++_i) \
;         __builtin_amdgcn_global_load_lds((const unsigned*)((const char*)(gbase) + (voff)[_i]), (LAS unsigned*)(lds + (bufoff) + ldsw + _i * 8192), 16, 0, 0); } while (0)
; #define PG8_LDA(dst, b, h) do { _Pragma("unroll") for (int m = 0; m < 4; ++m) _Pragma("unroll") for (int k = 0; k < 2; ++k) dst[m][k] = *(const LAS bf16x8*)(lds + PG8_SA(b, h) + aoff + m * 2048 + k * 1024); } while (0)
; #define PG8_LDB(dst, b, h) do { _Pragma("unroll") for (int n = 0; n < 2; ++n) _Pragma("unroll") for (int k = 0; k < 2; ++k) dst[n][k] = *(const LAS bf16x8*)(lds + PG8_SB(b, h) + boff + n * 2048 + k * 1024); } while (0)
; #define PG8_WAIT_V(n) asm volatile("s_waitcnt vmcnt(" #n ")" ::: "memory")
; #define PG8_WAIT_L(n) asm volatile("s_waitcnt lgkmcnt(" #n ")" ::: "memory")
; #define PG8_BAR __builtin_amdgcn_s_barrier()
; #define PG8_SCHED __builtin_amdgcn_sched_barrier(0)
; template <class Epi>
; __device__ __forceinline__ void gemm_phase(LAS unsigned char* lds, const Gemm g, const StaticOrder& S, const Epi& E) {
;     ...
;             PG8_LDB(B0, 0, 0); PG8_SCHED; PG8_LDA(At, 0, 0); PG8_STAGE(PG8_SA(1, 1), a1 + hstepA, voffA);
;             PG8_WAIT_L(8); PG8_BAR; PG8_WAIT_L(0); PG8_MMA(0, 0, At, B0); PG8_BAR; PG8_SCHED;
;             PG8_LDB(B1, 0, 1); PG8_STAGE(PG8_SB(0, 0), b2, voffB);
;             PG8_BAR; PG8_WAIT_L(0); PG8_MMA(0, 1, At, B1); PG8_BAR;
;             PG8_LDA(At, 0, 1); PG8_STAGE(PG8_SA(0, 0), a2, voffA);
;             PG8_BAR; PG8_WAIT_L(0); PG8_MMA(1, 0, At, B0); PG8_BAR; PG8_SCHED;
;             PG8_STAGE(PG8_SB(0, 1), b2 + hstepB, voffB);
;             PG8_WAIT_V(6); PG8_BAR; PG8_MMA(1, 1, At, B1); PG8_BAR;
;             PG8_LDB(B0, 1, 0); PG8_SCHED; PG8_LDA(At, 1, 0); PG8_STAGE(PG8_SA(0, 1), a2 + hstepA, voffA);
;             PG8_WAIT_L(8); PG8_BAR; PG8_WAIT_L(0); PG8_MMA(0, 0, At, B0); PG8_BAR; PG8_SCHED;
;             PG8_LDB(B1, 1, 1); PG8_STAGE(PG8_SB(1, 0), b3, voffB);
;             PG8_BAR; PG8_WAIT_L(0); PG8_MMA(0, 1, At, B1); PG8_BAR;
;             PG8_LDA(At, 1, 1); PG8_STAGE(PG8_SA(1, 0), a3, voffA);
;             PG8_BAR; PG8_WAIT_L(0); PG8_MMA(1, 0, At, B0); PG8_BAR; PG8_SCHED;
;             PG8_STAGE(PG8_SB(1, 1), b3 + hstepB, voffB);
;             PG8_WAIT_V(6); PG8_BAR; PG8_MMA(1, 1, At, B1); PG8_BAR;
	s_waitcnt lgkmcnt(0)
	v_mfma_f32_16x16x32_bf16 v[60:63], v[128:131], v[144:147], v[60:63]
	v_mfma_f32_16x16x32_bf16 v[56:59], v[136:139], v[144:147], v[56:59]
	v_mfma_f32_16x16x32_bf16 v[44:47], v[128:131], v[170:173], v[44:47]
	v_mfma_f32_16x16x32_bf16 v[40:43], v[136:139], v[170:173], v[40:43]
	v_mfma_f32_16x16x32_bf16 v[28:31], v[128:131], v[178:181], v[28:31]
	v_mfma_f32_16x16x32_bf16 v[24:27], v[136:139], v[178:181], v[24:27]
	v_mfma_f32_16x16x32_bf16 v[12:15], v[128:131], v[196:199], v[12:15]
	v_mfma_f32_16x16x32_bf16 v[8:11], v[136:139], v[196:199], v[8:11]
	v_mfma_f32_16x16x32_bf16 v[60:63], v[132:135], v[148:151], v[60:63]
	v_mfma_f32_16x16x32_bf16 v[56:59], v[140:143], v[148:151], v[56:59]
	v_mfma_f32_16x16x32_bf16 v[44:47], v[132:135], v[174:177], v[44:47]
	v_mfma_f32_16x16x32_bf16 v[40:43], v[140:143], v[174:177], v[40:43]
	v_mfma_f32_16x16x32_bf16 v[28:31], v[132:135], v[182:185], v[28:31]
	v_mfma_f32_16x16x32_bf16 v[24:27], v[140:143], v[182:185], v[24:27]
	v_mfma_f32_16x16x32_bf16 v[12:15], v[132:135], v[200:203], v[12:15]
	v_mfma_f32_16x16x32_bf16 v[8:11], v[140:143], v[200:203], v[8:11]
	s_barrier
	s_add_u32 s22, s22, 0x80080
	s_addc_u32 s23, s23, 0
	s_add_i32 s24, s24, s31
	v_lshl_add_u64 v[128:129], s[22:23], 0, v[156:157]
	s_mov_b32 m0, s24
	s_nop 0
	global_load_lds_dwordx4 v[128:129], off
	v_lshl_add_u64 v[128:129], s[22:23], 0, v[160:161]
	s_add_i32 m0, s24, 0x2000
	s_nop 0
	global_load_lds_dwordx4 v[128:129], off
	s_waitcnt vmcnt(6)
	s_barrier
	v_mfma_f32_16x16x32_bf16 v[52:55], v[204:207], v[144:147], v[52:55]
	v_mfma_f32_16x16x32_bf16 v[48:51], v[212:215], v[144:147], v[48:51]
	v_mfma_f32_16x16x32_bf16 v[36:39], v[204:207], v[170:173], v[36:39]
	v_mfma_f32_16x16x32_bf16 v[32:35], v[212:215], v[170:173], v[32:35]
	v_mfma_f32_16x16x32_bf16 v[20:23], v[204:207], v[178:181], v[20:23]
	v_mfma_f32_16x16x32_bf16 v[16:19], v[212:215], v[178:181], v[16:19]
	v_mfma_f32_16x16x32_bf16 v[4:7], v[204:207], v[196:199], v[4:7]
	v_mfma_f32_16x16x32_bf16 v[0:3], v[212:215], v[196:199], v[0:3]
	v_mfma_f32_16x16x32_bf16 v[52:55], v[208:211], v[148:151], v[52:55]
	v_mfma_f32_16x16x32_bf16 v[48:51], v[216:219], v[148:151], v[48:51]
	v_mfma_f32_16x16x32_bf16 v[36:39], v[208:211], v[174:177], v[36:39]
	v_mfma_f32_16x16x32_bf16 v[32:35], v[216:219], v[174:177], v[32:35]
	v_mfma_f32_16x16x32_bf16 v[20:23], v[208:211], v[182:185], v[20:23]
	v_mfma_f32_16x16x32_bf16 v[16:19], v[216:219], v[182:185], v[16:19]
	v_mfma_f32_16x16x32_bf16 v[4:7], v[208:211], v[200:203], v[4:7]
	v_mfma_f32_16x16x32_bf16 v[0:3], v[216:219], v[200:203], v[0:3]
	s_add_i32 s48, s48, 2
	s_add_u32 s4, s4, 0x100
	s_addc_u32 s5, s5, 0
	s_add_u32 s46, s46, 0x100
	s_addc_u32 s47, s47, 0
	s_cmp_gt_u32 s48, 29
	s_barrier
.LBB0_684:
	ds_read_b128 v[128:131], v191
	ds_read_b128 v[132:135], v191 offset:1024
	ds_read_b128 v[136:139], v191 offset:2048
	ds_read_b128 v[140:143], v191 offset:3072
	s_add_u32 s22, s4, 0xffec0080
	s_addc_u32 s23, s5, -1
	s_cmp_eq_u32 s48, 28
	s_cselect_b32 s25, s19, s23
	s_cselect_b32 s24, s18, s22
	s_cselect_b32 s23, s17, s47
	s_cselect_b32 s22, s45, s46
	v_lshl_add_u64 v[186:187], s[4:5], 0, v[162:163]
	s_add_i32 m0, s11, 0xc000
	ds_read_b128 v[144:147], v192
	ds_read_b128 v[148:151], v192 offset:1024
	ds_read_b128 v[170:173], v192 offset:2048
	ds_read_b128 v[174:177], v192 offset:3072
	ds_read_b128 v[178:181], v192 offset:4096
	ds_read_b128 v[182:185], v192 offset:5120
	ds_read_b128 v[196:199], v192 offset:6144
	ds_read_b128 v[200:203], v192 offset:7168
	global_load_lds_dwordx4 v[186:187], off
	v_lshl_add_u64 v[186:187], s[4:5], 0, v[164:165]
	s_add_i32 m0, s11, 0xe000
	s_nop 0
	global_load_lds_dwordx4 v[186:187], off
	s_waitcnt lgkmcnt(8)
	s_barrier
	s_waitcnt lgkmcnt(0)
	v_mfma_f32_16x16x32_bf16 v[124:127], v[128:131], v[144:147], v[124:127]
	v_mfma_f32_16x16x32_bf16 v[120:123], v[136:139], v[144:147], v[120:123]
	v_mfma_f32_16x16x32_bf16 v[108:111], v[128:131], v[170:173], v[108:111]
	v_mfma_f32_16x16x32_bf16 v[104:107], v[136:139], v[170:173], v[104:107]
	v_mfma_f32_16x16x32_bf16 v[92:95], v[128:131], v[178:181], v[92:95]
	v_mfma_f32_16x16x32_bf16 v[88:91], v[136:139], v[178:181], v[88:91]
	v_mfma_f32_16x16x32_bf16 v[76:79], v[128:131], v[196:199], v[76:79]
	v_mfma_f32_16x16x32_bf16 v[72:75], v[136:139], v[196:199], v[72:75]
	v_mfma_f32_16x16x32_bf16 v[124:127], v[132:135], v[148:151], v[124:127]
	v_mfma_f32_16x16x32_bf16 v[120:123], v[140:143], v[148:151], v[120:123]
	v_mfma_f32_16x16x32_bf16 v[108:111], v[132:135], v[174:177], v[108:111]
	v_mfma_f32_16x16x32_bf16 v[104:107], v[140:143], v[174:177], v[104:107]
	v_mfma_f32_16x16x32_bf16 v[92:95], v[132:135], v[182:185], v[92:95]
	v_mfma_f32_16x16x32_bf16 v[88:91], v[140:143], v[182:185], v[88:91]
	v_mfma_f32_16x16x32_bf16 v[76:79], v[132:135], v[200:203], v[76:79]
	v_mfma_f32_16x16x32_bf16 v[72:75], v[140:143], v[200:203], v[72:75]
	s_barrier
	s_add_i32 s49, s42, s31
	v_lshl_add_u64 v[186:187], s[22:23], 0, v[156:157]
	s_mov_b32 m0, s49
	ds_read_b128 v[204:207], v193
	ds_read_b128 v[208:211], v193 offset:1024
	ds_read_b128 v[212:215], v193 offset:2048
	ds_read_b128 v[216:219], v193 offset:3072
	global_load_lds_dwordx4 v[186:187], off
	v_lshl_add_u64 v[220:221], s[22:23], 0, v[160:161]
	s_add_i32 m0, s49, 0x2000
	s_nop 0
	global_load_lds_dwordx4 v[220:221], off
	s_barrier
; #define PG8_STAGE(bufoff, gbase, voff) do { _Pragma("unroll") for (int _i = 0; _i < 2; ++_i) \
;         __builtin_amdgcn_global_load_lds((const unsigned*)((const char*)(gbase) + (voff)[_i]), (LAS unsigned*)(lds + (bufoff) + ldsw + _i * 8192), 16, 0, 0); } while (0)
; #define PG8_LDA(dst, b, h) do { _Pragma("unroll") for (int m = 0; m < 4; ++m) _Pragma("unroll") for (int k = 0; k < 2; ++k) dst[m][k] = *(const LAS bf16x8*)(lds + PG8_SA(b, h) + aoff + m * 2048 + k * 1024); } while (0)
; #define PG8_LDB(dst, b, h) do { _Pragma("unroll") for (int n = 0; n < 2; ++n) _Pragma("unroll") for (int k = 0; k < 2; ++k) dst[n][k] = *(const LAS bf16x8*)(lds + PG8_SB(b, h) + boff + n * 2048 + k * 1024); } while (0)
; #define PG8_MMA(ai, bj, At, Bt) do { __builtin_amdgcn_s_setprio(1); _Pragma("unroll") for (int m = 0; m < 4; ++m) _Pragma("unroll") for (int n = 0; n < 2; ++n) _Pragma("unroll") for (int k = 0; k < 2; ++k) \
;         acc[ai][bj][m][n] = __builtin_amdgcn_mfma_f32_16x16x32_bf16(Bt[n][k], At[m][k], acc[ai][bj][m][n], 0, 0, 0); __builtin_amdgcn_s_setprio(0); } while (0)
; #define PG8_WAIT_V(n) asm volatile("s_waitcnt vmcnt(" #n ")" ::: "memory")
; #define PG8_WAIT_L(n) asm volatile("s_waitcnt lgkmcnt(" #n ")" ::: "memory")
; #define PG8_BAR __builtin_amdgcn_s_barrier()
; #define PG8_SCHED __builtin_amdgcn_sched_barrier(0)
; template <class Epi>
; __device__ __forceinline__ void gemm_phase(LAS unsigned char* lds, const Gemm g, const StaticOrder& S, const Epi& E) {
;     ...
;             PG8_BAR; PG8_WAIT_L(0); PG8_MMA(0, 1, At, B1); PG8_BAR;
;             PG8_LDA(At, 0, 1); PG8_STAGE(PG8_SA(0, 0), a2, voffA);
;             PG8_BAR; PG8_WAIT_L(0); PG8_MMA(1, 0, At, B0); PG8_BAR; PG8_SCHED;
;             PG8_STAGE(PG8_SB(0, 1), b2 + hstepB, voffB);
;             PG8_WAIT_V(6); PG8_BAR; PG8_MMA(1, 1, At, B1); PG8_BAR;
;             PG8_LDB(B0, 1, 0); PG8_SCHED; PG8_LDA(At, 1, 0); PG8_STAGE(PG8_SA(0, 1), a2 + hstepA, voffA);
;             PG8_WAIT_L(8); PG8_BAR; PG8_WAIT_L(0); PG8_MMA(0, 0, At, B0); PG8_BAR; PG8_SCHED;
;             PG8_LDB(B1, 1, 1); PG8_STAGE(PG8_SB(1, 0), b3, voffB);
;             PG8_BAR; PG8_WAIT_L(0); PG8_MMA(0, 1, At, B1); PG8_BAR;
;             PG8_LDA(At, 1, 1); PG8_STAGE(PG8_SA(1, 0), a3, voffA);
	s_waitcnt lgkmcnt(0)
	v_mfma_f32_16x16x32_bf16 v[116:119], v[204:207], v[144:147], v[116:119]
	v_mfma_f32_16x16x32_bf16 v[112:115], v[212:215], v[144:147], v[112:115]
	v_mfma_f32_16x16x32_bf16 v[100:103], v[204:207], v[170:173], v[100:103]
	v_mfma_f32_16x16x32_bf16 v[96:99], v[212:215], v[170:173], v[96:99]
	v_mfma_f32_16x16x32_bf16 v[84:87], v[204:207], v[178:181], v[84:87]
	v_mfma_f32_16x16x32_bf16 v[80:83], v[212:215], v[178:181], v[80:83]
	v_mfma_f32_16x16x32_bf16 v[68:71], v[204:207], v[196:199], v[68:71]
	v_mfma_f32_16x16x32_bf16 v[64:67], v[212:215], v[196:199], v[64:67]
	v_mfma_f32_16x16x32_bf16 v[116:119], v[208:211], v[148:151], v[116:119]
	v_mfma_f32_16x16x32_bf16 v[112:115], v[216:219], v[148:151], v[112:115]
	v_mfma_f32_16x16x32_bf16 v[100:103], v[208:211], v[174:177], v[100:103]
	v_mfma_f32_16x16x32_bf16 v[96:99], v[216:219], v[174:177], v[96:99]
	v_mfma_f32_16x16x32_bf16 v[84:87], v[208:211], v[182:185], v[84:87]
	v_mfma_f32_16x16x32_bf16 v[80:83], v[216:219], v[182:185], v[80:83]
	v_mfma_f32_16x16x32_bf16 v[68:71], v[208:211], v[200:203], v[68:71]
	v_mfma_f32_16x16x32_bf16 v[64:67], v[216:219], v[200:203], v[64:67]
	s_mov_b32 m0, s11
	v_lshl_add_u64 v[222:223], s[24:25], 0, v[154:155]
	s_barrier
	ds_read_b128 v[144:147], v192 offset:16384
	ds_read_b128 v[148:151], v192 offset:17408
	ds_read_b128 v[170:173], v192 offset:18432
	ds_read_b128 v[174:177], v192 offset:19456
	ds_read_b128 v[178:181], v192 offset:20480
	ds_read_b128 v[182:185], v192 offset:21504
	ds_read_b128 v[196:199], v192 offset:22528
	ds_read_b128 v[200:203], v192 offset:23552
	global_load_lds_dwordx4 v[222:223], off
	v_lshl_add_u64 v[224:225], s[24:25], 0, v[158:159]
	s_mov_b32 m0, s34
	s_nop 0
	global_load_lds_dwordx4 v[224:225], off
	s_barrier
	s_waitcnt lgkmcnt(0)
	v_mfma_f32_16x16x32_bf16 v[60:63], v[128:131], v[144:147], v[60:63]
	v_mfma_f32_16x16x32_bf16 v[56:59], v[136:139], v[144:147], v[56:59]
	v_mfma_f32_16x16x32_bf16 v[44:47], v[128:131], v[170:173], v[44:47]
	v_mfma_f32_16x16x32_bf16 v[40:43], v[136:139], v[170:173], v[40:43]
	v_mfma_f32_16x16x32_bf16 v[28:31], v[128:131], v[178:181], v[28:31]
	v_mfma_f32_16x16x32_bf16 v[24:27], v[136:139], v[178:181], v[24:27]
	v_mfma_f32_16x16x32_bf16 v[12:15], v[128:131], v[196:199], v[12:15]
	v_mfma_f32_16x16x32_bf16 v[8:11], v[136:139], v[196:199], v[8:11]
	v_mfma_f32_16x16x32_bf16 v[60:63], v[132:135], v[148:151], v[60:63]
	v_mfma_f32_16x16x32_bf16 v[56:59], v[140:143], v[148:151], v[56:59]
	v_mfma_f32_16x16x32_bf16 v[44:47], v[132:135], v[174:177], v[44:47]
	v_mfma_f32_16x16x32_bf16 v[40:43], v[140:143], v[174:177], v[40:43]
	v_mfma_f32_16x16x32_bf16 v[28:31], v[132:135], v[182:185], v[28:31]
	v_mfma_f32_16x16x32_bf16 v[24:27], v[140:143], v[182:185], v[24:27]
	v_mfma_f32_16x16x32_bf16 v[12:15], v[132:135], v[200:203], v[12:15]
	v_mfma_f32_16x16x32_bf16 v[8:11], v[140:143], v[200:203], v[8:11]
	s_barrier
	s_add_u32 s50, s22, 0x80000
	s_addc_u32 s51, s23, 0
	s_add_i32 s49, s43, s31
	v_lshl_add_u64 v[128:129], s[50:51], 0, v[156:157]
	s_mov_b32 m0, s49
	s_nop 0
	global_load_lds_dwordx4 v[128:129], off
	v_lshl_add_u64 v[128:129], s[50:51], 0, v[160:161]
	s_add_i32 m0, s49, 0x2000
	s_nop 0
	global_load_lds_dwordx4 v[128:129], off
	s_waitcnt vmcnt(6)
	s_barrier
	v_mfma_f32_16x16x32_bf16 v[52:55], v[204:207], v[144:147], v[52:55]
	v_mfma_f32_16x16x32_bf16 v[48:51], v[212:215], v[144:147], v[48:51]
	v_mfma_f32_16x16x32_bf16 v[36:39], v[204:207], v[170:173], v[36:39]
	v_mfma_f32_16x16x32_bf16 v[32:35], v[212:215], v[170:173], v[32:35]
	v_mfma_f32_16x16x32_bf16 v[20:23], v[204:207], v[178:181], v[20:23]
	v_mfma_f32_16x16x32_bf16 v[16:19], v[212:215], v[178:181], v[16:19]
	v_mfma_f32_16x16x32_bf16 v[4:7], v[204:207], v[196:199], v[4:7]
	v_mfma_f32_16x16x32_bf16 v[0:3], v[212:215], v[196:199], v[0:3]
	v_mfma_f32_16x16x32_bf16 v[52:55], v[208:211], v[148:151], v[52:55]
	v_mfma_f32_16x16x32_bf16 v[48:51], v[216:219], v[148:151], v[48:51]
	v_mfma_f32_16x16x32_bf16 v[36:39], v[208:211], v[174:177], v[36:39]
	v_mfma_f32_16x16x32_bf16 v[32:35], v[216:219], v[174:177], v[32:35]
	v_mfma_f32_16x16x32_bf16 v[20:23], v[208:211], v[182:185], v[20:23]
	v_mfma_f32_16x16x32_bf16 v[16:19], v[216:219], v[182:185], v[16:19]
	v_mfma_f32_16x16x32_bf16 v[4:7], v[208:211], v[200:203], v[4:7]
	v_mfma_f32_16x16x32_bf16 v[0:3], v[216:219], v[200:203], v[0:3]
	s_add_i32 s49, 0, 0x18000
	v_add_u32_e32 v140, s49, v189
	s_barrier
	ds_read_b128 v[128:131], v140
	ds_read_b128 v[132:135], v140 offset:1024
	ds_read_b128 v[136:139], v140 offset:2048
	ds_read_b128 v[140:143], v140 offset:3072
	s_add_u32 s24, s24, 0x140000
	s_addc_u32 s25, s25, 0
	s_mov_b32 m0, s35
	v_lshl_add_u64 v[204:205], s[24:25], 0, v[154:155]
	ds_read_b128 v[144:147], v192 offset:32768
	ds_read_b128 v[148:151], v192 offset:33792
	ds_read_b128 v[170:173], v192 offset:34816
	ds_read_b128 v[174:177], v192 offset:35840
	ds_read_b128 v[178:181], v192 offset:36864
	ds_read_b128 v[182:185], v192 offset:37888
	ds_read_b128 v[196:199], v192 offset:38912
	ds_read_b128 v[200:203], v192 offset:39936
	global_load_lds_dwordx4 v[204:205], off
	v_lshl_add_u64 v[204:205], s[24:25], 0, v[158:159]
	s_mov_b32 m0, s36
	s_nop 0
	global_load_lds_dwordx4 v[204:205], off
	s_waitcnt lgkmcnt(8)
	s_barrier
; #define PG8_STAGE(bufoff, gbase, voff) do { _Pragma("unroll") for (int _i = 0; _i < 2; ++_i) \
;         __builtin_amdgcn_global_load_lds((const unsigned*)((const char*)(gbase) + (voff)[_i]), (LAS unsigned*)(lds + (bufoff) + ldsw + _i * 8192), 16, 0, 0); } while (0)
; #define PG8_LDA(dst, b, h) do { _Pragma("unroll") for (int m = 0; m < 4; ++m) _Pragma("unroll") for (int k = 0; k < 2; ++k) dst[m][k] = *(const LAS bf16x8*)(lds + PG8_SA(b, h) + aoff + m * 2048 + k * 1024); } while (0)
; #define PG8_LDB(dst, b, h) do { _Pragma("unroll") for (int n = 0; n < 2; ++n) _Pragma("unroll") for (int k = 0; k < 2; ++k) dst[n][k] = *(const LAS bf16x8*)(lds + PG8_SB(b, h) + boff + n * 2048 + k * 1024); } while (0)
; #define PG8_MMA(ai, bj, At, Bt) do { __builtin_amdgcn_s_setprio(1); _Pragma("unroll") for (int m = 0; m < 4; ++m) _Pragma("unroll") for (int n = 0; n < 2; ++n) _Pragma("unroll") for (int k = 0; k < 2; ++k) \
;         acc[ai][bj][m][n] = __builtin_amdgcn_mfma_f32_16x16x32_bf16(Bt[n][k], At[m][k], acc[ai][bj][m][n], 0, 0, 0); __builtin_amdgcn_s_setprio(0); } while (0)
; #define PG8_WAIT_V(n) asm volatile("s_waitcnt vmcnt(" #n ")" ::: "memory")
; #define PG8_WAIT_L(n) asm volatile("s_waitcnt lgkmcnt(" #n ")" ::: "memory")
; #define PG8_BAR __builtin_amdgcn_s_barrier()
; #define PG8_SCHED __builtin_amdgcn_sched_barrier(0)
; template <class Epi>
; __device__ __forceinline__ void gemm_phase(LAS unsigned char* lds, const Gemm g, const StaticOrder& S, const Epi& E) {
;     ...
;             PG8_BAR; PG8_WAIT_L(0); PG8_MMA(1, 0, At, B0); PG8_BAR; PG8_SCHED;
;             PG8_STAGE(PG8_SB(0, 1), b2 + hstepB, voffB);
;             PG8_WAIT_V(6); PG8_BAR; PG8_MMA(1, 1, At, B1); PG8_BAR;
;             PG8_LDB(B0, 1, 0); PG8_SCHED; PG8_LDA(At, 1, 0); PG8_STAGE(PG8_SA(0, 1), a2 + hstepA, voffA);
;             PG8_WAIT_L(8); PG8_BAR; PG8_WAIT_L(0); PG8_MMA(0, 0, At, B0); PG8_BAR; PG8_SCHED;
;             PG8_LDB(B1, 1, 1); PG8_STAGE(PG8_SB(1, 0), b3, voffB);
;             PG8_BAR; PG8_WAIT_L(0); PG8_MMA(0, 1, At, B1); PG8_BAR;
;             PG8_LDA(At, 1, 1); PG8_STAGE(PG8_SA(1, 0), a3, voffA);
;             PG8_BAR; PG8_WAIT_L(0); PG8_MMA(1, 0, At, B0); PG8_BAR; PG8_SCHED;
;             PG8_STAGE(PG8_SB(1, 1), b3 + hstepB, voffB);
;             PG8_WAIT_V(6); PG8_BAR; PG8_MMA(1, 1, At, B1); PG8_BAR;
	s_waitcnt lgkmcnt(0)
	v_mfma_f32_16x16x32_bf16 v[124:127], v[128:131], v[144:147], v[124:127]
	v_mfma_f32_16x16x32_bf16 v[120:123], v[136:139], v[144:147], v[120:123]
	v_mfma_f32_16x16x32_bf16 v[108:111], v[128:131], v[170:173], v[108:111]
	v_mfma_f32_16x16x32_bf16 v[104:107], v[136:139], v[170:173], v[104:107]
	v_mfma_f32_16x16x32_bf16 v[92:95], v[128:131], v[178:181], v[92:95]
	v_mfma_f32_16x16x32_bf16 v[88:91], v[136:139], v[178:181], v[88:91]
	v_mfma_f32_16x16x32_bf16 v[76:79], v[128:131], v[196:199], v[76:79]
	v_mfma_f32_16x16x32_bf16 v[72:75], v[136:139], v[196:199], v[72:75]
	v_mfma_f32_16x16x32_bf16 v[124:127], v[132:135], v[148:151], v[124:127]
	v_mfma_f32_16x16x32_bf16 v[120:123], v[140:143], v[148:151], v[120:123]
	v_mfma_f32_16x16x32_bf16 v[108:111], v[132:135], v[174:177], v[108:111]
	v_mfma_f32_16x16x32_bf16 v[104:107], v[140:143], v[174:177], v[104:107]
	v_mfma_f32_16x16x32_bf16 v[92:95], v[132:135], v[182:185], v[92:95]
	v_mfma_f32_16x16x32_bf16 v[88:91], v[140:143], v[182:185], v[88:91]
	v_mfma_f32_16x16x32_bf16 v[76:79], v[132:135], v[200:203], v[76:79]
	v_mfma_f32_16x16x32_bf16 v[72:75], v[140:143], v[200:203], v[72:75]
	s_barrier
	s_add_i32 s24, 0, 0x1c000
	s_add_i32 s25, s49, s31
	v_add_u32_e32 v195, s24, v189
	v_lshl_add_u64 v[186:187], v[186:187], 0, s[14:15]
	s_mov_b32 m0, s25
	ds_read_b128 v[204:207], v195
	ds_read_b128 v[208:211], v195 offset:1024
	ds_read_b128 v[212:215], v195 offset:2048
	ds_read_b128 v[216:219], v195 offset:3072
	global_load_lds_dwordx4 v[186:187], off
	v_lshl_add_u64 v[186:187], v[220:221], 0, s[14:15]
	s_add_i32 m0, s25, 0x2000
	s_nop 0
	global_load_lds_dwordx4 v[186:187], off
	s_barrier
	s_waitcnt lgkmcnt(0)
	v_mfma_f32_16x16x32_bf16 v[116:119], v[204:207], v[144:147], v[116:119]
	v_mfma_f32_16x16x32_bf16 v[112:115], v[212:215], v[144:147], v[112:115]
	v_mfma_f32_16x16x32_bf16 v[100:103], v[204:207], v[170:173], v[100:103]
	v_mfma_f32_16x16x32_bf16 v[96:99], v[212:215], v[170:173], v[96:99]
	v_mfma_f32_16x16x32_bf16 v[84:87], v[204:207], v[178:181], v[84:87]
	v_mfma_f32_16x16x32_bf16 v[80:83], v[212:215], v[178:181], v[80:83]
	v_mfma_f32_16x16x32_bf16 v[68:71], v[204:207], v[196:199], v[68:71]
	v_mfma_f32_16x16x32_bf16 v[64:67], v[212:215], v[196:199], v[64:67]
	v_mfma_f32_16x16x32_bf16 v[116:119], v[208:211], v[148:151], v[116:119]
	v_mfma_f32_16x16x32_bf16 v[112:115], v[216:219], v[148:151], v[112:115]
	v_mfma_f32_16x16x32_bf16 v[100:103], v[208:211], v[174:177], v[100:103]
	v_mfma_f32_16x16x32_bf16 v[96:99], v[216:219], v[174:177], v[96:99]
	v_mfma_f32_16x16x32_bf16 v[84:87], v[208:211], v[182:185], v[84:87]
	v_mfma_f32_16x16x32_bf16 v[80:83], v[216:219], v[182:185], v[80:83]
	v_mfma_f32_16x16x32_bf16 v[68:71], v[208:211], v[200:203], v[68:71]
	v_mfma_f32_16x16x32_bf16 v[64:67], v[216:219], v[200:203], v[64:67]
	s_mov_b32 m0, s38
	v_lshl_add_u64 v[186:187], v[222:223], 0, s[14:15]
	s_barrier
	ds_read_b128 v[144:147], v192 offset:49152
	ds_read_b128 v[148:151], v192 offset:50176
	ds_read_b128 v[170:173], v192 offset:51200
	ds_read_b128 v[174:177], v192 offset:52224
	ds_read_b128 v[178:181], v192 offset:53248
	ds_read_b128 v[182:185], v192 offset:54272
	ds_read_b128 v[196:199], v192 offset:55296
	ds_read_b128 v[200:203], v192 offset:56320
	global_load_lds_dwordx4 v[186:187], off
	v_lshl_add_u64 v[186:187], v[224:225], 0, s[14:15]
	s_mov_b32 m0, s39
	s_nop 0
	global_load_lds_dwordx4 v[186:187], off
	s_barrier
	s_waitcnt lgkmcnt(0)
	v_mfma_f32_16x16x32_bf16 v[60:63], v[128:131], v[144:147], v[60:63]
	v_mfma_f32_16x16x32_bf16 v[56:59], v[136:139], v[144:147], v[56:59]
	v_mfma_f32_16x16x32_bf16 v[44:47], v[128:131], v[170:173], v[44:47]
	v_mfma_f32_16x16x32_bf16 v[40:43], v[136:139], v[170:173], v[40:43]
	v_mfma_f32_16x16x32_bf16 v[28:31], v[128:131], v[178:181], v[28:31]
	v_mfma_f32_16x16x32_bf16 v[24:27], v[136:139], v[178:181], v[24:27]
	v_mfma_f32_16x16x32_bf16 v[12:15], v[128:131], v[196:199], v[12:15]
	v_mfma_f32_16x16x32_bf16 v[8:11], v[136:139], v[196:199], v[8:11]
	v_mfma_f32_16x16x32_bf16 v[60:63], v[132:135], v[148:151], v[60:63]
	v_mfma_f32_16x16x32_bf16 v[56:59], v[140:143], v[148:151], v[56:59]
	v_mfma_f32_16x16x32_bf16 v[44:47], v[132:135], v[174:177], v[44:47]
	v_mfma_f32_16x16x32_bf16 v[40:43], v[140:143], v[174:177], v[40:43]
	v_mfma_f32_16x16x32_bf16 v[28:31], v[132:135], v[182:185], v[28:31]
	v_mfma_f32_16x16x32_bf16 v[24:27], v[140:143], v[182:185], v[24:27]
	v_mfma_f32_16x16x32_bf16 v[12:15], v[132:135], v[200:203], v[12:15]
	v_mfma_f32_16x16x32_bf16 v[8:11], v[140:143], v[200:203], v[8:11]
	s_barrier
	s_add_u32 s22, s22, 0x80080
	s_addc_u32 s23, s23, 0
	s_add_i32 s24, s24, s31
	v_lshl_add_u64 v[128:129], s[22:23], 0, v[156:157]
	s_mov_b32 m0, s24
	s_nop 0
	global_load_lds_dwordx4 v[128:129], off
	v_lshl_add_u64 v[128:129], s[22:23], 0, v[160:161]
	s_add_i32 m0, s24, 0x2000
	s_nop 0
	global_load_lds_dwordx4 v[128:129], off
	s_waitcnt vmcnt(6)
	s_barrier
	v_mfma_f32_16x16x32_bf16 v[52:55], v[204:207], v[144:147], v[52:55]
	v_mfma_f32_16x16x32_bf16 v[48:51], v[212:215], v[144:147], v[48:51]
	v_mfma_f32_16x16x32_bf16 v[36:39], v[204:207], v[170:173], v[36:39]
	v_mfma_f32_16x16x32_bf16 v[32:35], v[212:215], v[170:173], v[32:35]
	v_mfma_f32_16x16x32_bf16 v[20:23], v[204:207], v[178:181], v[20:23]
	v_mfma_f32_16x16x32_bf16 v[16:19], v[212:215], v[178:181], v[16:19]
	v_mfma_f32_16x16x32_bf16 v[4:7], v[204:207], v[196:199], v[4:7]
	v_mfma_f32_16x16x32_bf16 v[0:3], v[212:215], v[196:199], v[0:3]
	v_mfma_f32_16x16x32_bf16 v[52:55], v[208:211], v[148:151], v[52:55]
	v_mfma_f32_16x16x32_bf16 v[48:51], v[216:219], v[148:151], v[48:51]
	v_mfma_f32_16x16x32_bf16 v[36:39], v[208:211], v[174:177], v[36:39]
	v_mfma_f32_16x16x32_bf16 v[32:35], v[216:219], v[174:177], v[32:35]
	v_mfma_f32_16x16x32_bf16 v[20:23], v[208:211], v[182:185], v[20:23]
	v_mfma_f32_16x16x32_bf16 v[16:19], v[216:219], v[182:185], v[16:19]
	v_mfma_f32_16x16x32_bf16 v[4:7], v[208:211], v[200:203], v[4:7]
	v_mfma_f32_16x16x32_bf16 v[0:3], v[216:219], v[200:203], v[0:3]
	s_add_i32 s48, s48, 2
	s_add_u32 s4, s4, 0x100
	s_addc_u32 s5, s5, 0
	s_add_u32 s46, s46, 0x100
	s_addc_u32 s47, s47, 0
	s_cmp_gt_u32 s48, 29
	s_barrier
	s_cbranch_scc0 .LBB0_684
	v_lshl_or_b32 v170, s10, 8, v190
	v_lshl_add_u32 v172, s12, 8, v188
	v_ashrrev_i32_e32 v171, 31, v170
	v_lshlrev_b64 v[206:207], 1, v[170:171]
	v_ashrrev_i32_e32 v173, 31, v172
	v_lshl_add_u64 v[174:175], s[76:77], 0, v[206:207]
	v_lshlrev_b64 v[208:209], 11, v[172:173]
	v_lshl_add_u64 v[128:129], v[174:175], 0, v[208:209]
	global_load_dwordx4 v[198:201], v[128:129], off
	global_load_dwordx4 v[202:205], v[128:129], off offset:256
	v_or_b32_e32 v184, 16, v172
	v_or_b32_e32 v180, 32, v172
	v_or_b32_e32 v176, 48, v172
	v_ashrrev_i32_e32 v185, 31, v184
	v_ashrrev_i32_e32 v181, 31, v180
	v_ashrrev_i32_e32 v177, 31, v176
	v_lshlrev_b64 v[186:187], 11, v[184:185]
	v_lshlrev_b64 v[182:183], 11, v[180:181]
	v_lshlrev_b64 v[178:179], 11, v[176:177]
	v_lshl_add_u64 v[128:129], v[174:175], 0, v[186:187]
	v_lshl_add_u64 v[130:131], v[174:175], 0, v[182:183]
	v_lshl_add_u64 v[196:197], v[174:175], 0, v[178:179]
	global_load_dwordx4 v[148:151], v[128:129], off
	global_load_dwordx4 v[144:147], v[128:129], off offset:256
	global_load_dwordx4 v[140:143], v[130:131], off
	global_load_dwordx4 v[136:139], v[130:131], off offset:256
	global_load_dwordx4 v[132:135], v[196:197], off
	s_nop 0
	global_load_dwordx4 v[128:131], v[196:197], off offset:256
	v_add_u32_e32 v218, 0x80, v172
	v_ashrrev_i32_e32 v219, 31, v218
	v_lshlrev_b64 v[218:219], 11, v[218:219]
	v_lshl_add_u64 v[218:219], v[174:175], 0, v[218:219]
	global_load_dwordx4 v[220:223], v[218:219], off
	global_load_dwordx4 v[224:227], v[218:219], off offset:256
	v_add_u32_e32 v218, 0x90, v172
	v_ashrrev_i32_e32 v219, 31, v218
	v_lshlrev_b64 v[218:219], 11, v[218:219]
	v_lshl_add_u64 v[218:219], v[174:175], 0, v[218:219]
	global_load_dwordx4 v[228:231], v[218:219], off
	global_load_dwordx4 v[232:235], v[218:219], off offset:256
	v_add_u32_e32 v218, 0xa0, v172
	v_ashrrev_i32_e32 v219, 31, v218
	v_lshlrev_b64 v[218:219], 11, v[218:219]
	v_lshl_add_u64 v[218:219], v[174:175], 0, v[218:219]
	global_load_dwordx4 v[236:239], v[218:219], off
	global_load_dwordx4 v[240:243], v[218:219], off offset:256
	v_add_u32_e32 v218, 0xb0, v172
	v_ashrrev_i32_e32 v219, 31, v218
	v_lshlrev_b64 v[218:219], 11, v[218:219]
	v_lshl_add_u64 v[218:219], v[174:175], 0, v[218:219]
	global_load_dwordx4 v[244:247], v[218:219], off
	global_load_dwordx4 v[252:255], v[218:219], off offset:256
	v_and_b32_e32 v196, 64, v194
	v_xor_b32_e32 v195, 16, v194
	v_add_u32_e32 v196, 64, v196
	v_xor_b32_e32 v197, 32, v194
	v_cmp_lt_i32_e32 vcc, v195, v196
	s_waitcnt vmcnt(15)
	v_lshlrev_b32_e32 v210, 16, v198
	v_cndmask_b32_e32 v195, v194, v195, vcc
	v_cmp_lt_i32_e32 vcc, v197, v196
	v_and_b32_e32 v211, 0xffff0000, v198
	s_waitcnt vmcnt(14)
	v_lshlrev_b32_e32 v214, 16, v202
	v_and_b32_e32 v215, 0xffff0000, v202
	v_cndmask_b32_e32 v197, v194, v197, vcc
	v_lshlrev_b32_e32 v212, 16, v200
	v_and_b32_e32 v213, 0xffff0000, v200
	v_lshlrev_b32_e32 v200, 16, v201
	v_and_b32_e32 v201, 0xffff0000, v201
	v_lshlrev_b32_e32 v216, 16, v204
	v_and_b32_e32 v217, 0xffff0000, v204
	v_pk_add_f32 v[124:125], v[124:125], v[210:211]
	v_pk_add_f32 v[116:117], v[116:117], v[214:215]
	v_lshlrev_b32_e32 v196, 2, v195
	v_lshlrev_b32_e32 v195, 2, v197
	v_lshlrev_b32_e32 v198, 16, v199
	v_and_b32_e32 v199, 0xffff0000, v199
	v_lshlrev_b32_e32 v202, 16, v203
	v_and_b32_e32 v203, 0xffff0000, v203
	v_pk_add_f32 v[122:123], v[122:123], v[200:201]
	v_pk_add_f32 v[200:201], v[112:113], v[216:217]
	v_mul_f32_e32 v197, v125, v125
	v_cvt_pk_bf16_f32 v112, v124, v125
	v_mul_f32_e32 v125, v117, v117
	v_pk_add_f32 v[126:127], v[126:127], v[198:199]
	v_pk_add_f32 v[118:119], v[118:119], v[202:203]
	v_fmac_f32_e32 v197, v124, v124
	v_fmac_f32_e32 v125, v116, v116
	v_fmac_f32_e32 v197, v126, v126
	v_fmac_f32_e32 v125, v118, v118
	v_pk_add_f32 v[120:121], v[120:121], v[212:213]
	v_fmac_f32_e32 v197, v127, v127
	v_fmac_f32_e32 v125, v119, v119
	v_lshlrev_b32_e32 v204, 16, v205
	v_and_b32_e32 v205, 0xffff0000, v205
	v_fmac_f32_e32 v197, v120, v120
	v_fmac_f32_e32 v125, v200, v200
	v_pk_add_f32 v[198:199], v[114:115], v[204:205]
	v_fmac_f32_e32 v197, v121, v121
	v_fmac_f32_e32 v125, v201, v201
	v_fmac_f32_e32 v197, v122, v122
	v_fmac_f32_e32 v125, v198, v198
	v_fmac_f32_e32 v197, v123, v123
	v_fmac_f32_e32 v125, v199, v199
	v_cvt_pk_bf16_f32 v115, v122, v123
	v_add_f32_e32 v122, v197, v125
	ds_bpermute_b32 v123, v196, v122
	v_cvt_pk_bf16_f32 v114, v120, v121
	v_lshl_add_u64 v[120:121], s[76:77], 0, v[208:209]
	v_cvt_pk_bf16_f32 v113, v126, v127
	v_lshl_add_u64 v[120:121], v[120:121], 0, v[206:207]
	global_store_dwordx4 v[120:121], v[112:115], off
	s_waitcnt lgkmcnt(0)
	s_nop 0
	v_add_f32_e32 v112, v122, v123
	ds_bpermute_b32 v113, v195, v112
	v_cvt_pk_bf16_f32 v114, v116, v117
	v_cvt_pk_bf16_f32 v115, v118, v119
	v_cvt_pk_bf16_f32 v116, v200, v201
	v_cvt_pk_bf16_f32 v117, v198, v199
	global_store_dwordx4 v[120:121], v[114:117], off offset:256
	s_and_saveexec_b64 s[4:5], s[0:1]
	s_cbranch_execz .LBB0_687
	s_waitcnt lgkmcnt(0)
	v_add_f32_e32 v114, v112, v113
	s_lshl_b32 s22, s10, 2
	v_lshlrev_b64 v[112:113], 6, v[172:173]
	s_ashr_i32 s23, s22, 31
	v_lshl_add_u64 v[112:113], s[6:7], 0, v[112:113]
	v_lshl_add_u64 v[112:113], s[22:23], 2, v[112:113]
	s_lshl_b32 s12, s37, 2
	v_lshl_add_u64 v[112:113], v[112:113], 0, s[12:13]
	global_store_dword v[112:113], v114, off

.LBB0_769:
	s_ashr_i32 s13, s12, 31
	v_cmp_lt_i64_e32 vcc, s[14:15], v[142:143]
	s_lshl_b64 s[14:15], s[12:13], 19
	s_add_u32 s14, s76, s14
	s_addc_u32 s15, s77, s15
	s_and_b64 s[16:17], vcc, exec
	s_cselect_b32 s13, s15, s21
	s_cselect_b32 s41, s14, s20
	s_ashr_i32 s11, s10, 31
	s_lshl_b64 s[16:17], s[10:11], 19
	s_add_u32 s16, s27, s16
	s_addc_u32 s17, s28, s17
	s_and_b64 s[24:25], vcc, exec
	s_cselect_b32 s11, s17, s23
	s_cselect_b32 s42, s16, s22
	s_add_u32 s20, s20, 0x40080
	s_addc_u32 s21, s21, 0
	s_add_u32 s43, s22, 0x100
	s_addc_u32 s44, s23, 0
	s_mov_b32 s45, -2
	ds_read_b128 v[146:149], v177
	ds_read_b128 v[154:157], v177 offset:1024
	ds_read_b128 v[158:161], v177 offset:2048
	ds_read_b128 v[162:165], v177 offset:3072
	s_add_u32 s22, s20, 0xfffc0080
	s_addc_u32 s23, s21, -1
	s_cmp_eq_u32 s45, 12
	s_cselect_b32 s25, s13, s23
	s_cselect_b32 s24, s41, s22
	s_cselect_b32 s23, s11, s44
	s_cselect_b32 s22, s42, s43
	v_lshl_add_u64 v[150:151], s[20:21], 0, v[138:139]
	s_add_i32 m0, s19, 0xc000
	ds_read_b128 v[166:169], v178
	ds_read_b128 v[170:173], v178 offset:1024
	ds_read_b128 v[182:185], v178 offset:2048
	ds_read_b128 v[186:189], v178 offset:3072
	ds_read_b128 v[190:193], v178 offset:4096
	ds_read_b128 v[194:197], v178 offset:5120
	ds_read_b128 v[198:201], v178 offset:6144
	ds_read_b128 v[202:205], v178 offset:7168
	global_load_lds_dwordx4 v[150:151], off
	v_lshl_add_u64 v[150:151], s[20:21], 0, v[140:141]
	s_add_i32 m0, s19, 0xe000
	s_nop 0
	global_load_lds_dwordx4 v[150:151], off
	s_waitcnt lgkmcnt(8)
	s_barrier
	s_waitcnt lgkmcnt(0)
	v_mfma_f32_16x16x32_bf16 v[124:127], v[146:149], v[166:169], 0
	v_mfma_f32_16x16x32_bf16 v[120:123], v[158:161], v[166:169], 0
	v_mfma_f32_16x16x32_bf16 v[108:111], v[146:149], v[182:185], 0
	v_mfma_f32_16x16x32_bf16 v[104:107], v[158:161], v[182:185], 0
	v_mfma_f32_16x16x32_bf16 v[92:95], v[146:149], v[190:193], 0
	v_mfma_f32_16x16x32_bf16 v[88:91], v[158:161], v[190:193], 0
	v_mfma_f32_16x16x32_bf16 v[76:79], v[146:149], v[198:201], 0
	v_mfma_f32_16x16x32_bf16 v[72:75], v[158:161], v[198:201], 0
	v_mfma_f32_16x16x32_bf16 v[124:127], v[154:157], v[170:173], v[124:127]
	v_mfma_f32_16x16x32_bf16 v[120:123], v[162:165], v[170:173], v[120:123]
	v_mfma_f32_16x16x32_bf16 v[108:111], v[154:157], v[186:189], v[108:111]
	v_mfma_f32_16x16x32_bf16 v[104:107], v[162:165], v[186:189], v[104:107]
	v_mfma_f32_16x16x32_bf16 v[92:95], v[154:157], v[194:197], v[92:95]
	v_mfma_f32_16x16x32_bf16 v[88:91], v[162:165], v[194:197], v[88:91]
	v_mfma_f32_16x16x32_bf16 v[76:79], v[154:157], v[202:205], v[76:79]
	v_mfma_f32_16x16x32_bf16 v[72:75], v[162:165], v[202:205], v[72:75]
	s_barrier
	s_add_i32 s46, s7, s29
	v_lshl_add_u64 v[150:151], s[22:23], 0, v[130:131]
	s_mov_b32 m0, s46
	ds_read_b128 v[206:209], v179
	ds_read_b128 v[210:213], v179 offset:1024
	ds_read_b128 v[214:217], v179 offset:2048
	ds_read_b128 v[218:221], v179 offset:3072
	global_load_lds_dwordx4 v[150:151], off
	v_lshl_add_u64 v[222:223], s[22:23], 0, v[134:135]
	s_add_i32 m0, s46, 0x2000
	s_nop 0
	global_load_lds_dwordx4 v[222:223], off
	s_barrier
	s_waitcnt lgkmcnt(0)
	v_mfma_f32_16x16x32_bf16 v[116:119], v[206:209], v[166:169], 0
	v_mfma_f32_16x16x32_bf16 v[112:115], v[214:217], v[166:169], 0
	v_mfma_f32_16x16x32_bf16 v[100:103], v[206:209], v[182:185], 0
	v_mfma_f32_16x16x32_bf16 v[96:99], v[214:217], v[182:185], 0
	v_mfma_f32_16x16x32_bf16 v[84:87], v[206:209], v[190:193], 0
	v_mfma_f32_16x16x32_bf16 v[80:83], v[214:217], v[190:193], 0
	v_mfma_f32_16x16x32_bf16 v[68:71], v[206:209], v[198:201], 0
	v_mfma_f32_16x16x32_bf16 v[64:67], v[214:217], v[198:201], 0
	v_mfma_f32_16x16x32_bf16 v[116:119], v[210:213], v[170:173], v[116:119]
	v_mfma_f32_16x16x32_bf16 v[112:115], v[218:221], v[170:173], v[112:115]
	v_mfma_f32_16x16x32_bf16 v[100:103], v[210:213], v[186:189], v[100:103]
	v_mfma_f32_16x16x32_bf16 v[96:99], v[218:221], v[186:189], v[96:99]
	v_mfma_f32_16x16x32_bf16 v[84:87], v[210:213], v[194:197], v[84:87]
	v_mfma_f32_16x16x32_bf16 v[80:83], v[218:221], v[194:197], v[80:83]
	v_mfma_f32_16x16x32_bf16 v[68:71], v[210:213], v[202:205], v[68:71]
	v_mfma_f32_16x16x32_bf16 v[64:67], v[218:221], v[202:205], v[64:67]
	s_mov_b32 m0, s19
	v_lshl_add_u64 v[224:225], s[24:25], 0, v[128:129]
	s_barrier
	ds_read_b128 v[166:169], v178 offset:16384
	ds_read_b128 v[170:173], v178 offset:17408
	ds_read_b128 v[182:185], v178 offset:18432
	ds_read_b128 v[186:189], v178 offset:19456
	ds_read_b128 v[190:193], v178 offset:20480
	ds_read_b128 v[194:197], v178 offset:21504
	ds_read_b128 v[198:201], v178 offset:22528
	ds_read_b128 v[202:205], v178 offset:23552
	global_load_lds_dwordx4 v[224:225], off
	v_lshl_add_u64 v[226:227], s[24:25], 0, v[132:133]
	s_mov_b32 m0, s30
	s_nop 0
	global_load_lds_dwordx4 v[226:227], off
	s_barrier
	s_waitcnt lgkmcnt(0)
	v_mfma_f32_16x16x32_bf16 v[60:63], v[146:149], v[166:169], 0
	v_mfma_f32_16x16x32_bf16 v[56:59], v[158:161], v[166:169], 0
	v_mfma_f32_16x16x32_bf16 v[44:47], v[146:149], v[182:185], 0
	v_mfma_f32_16x16x32_bf16 v[40:43], v[158:161], v[182:185], 0
	v_mfma_f32_16x16x32_bf16 v[28:31], v[146:149], v[190:193], 0
	v_mfma_f32_16x16x32_bf16 v[24:27], v[158:161], v[190:193], 0
	v_mfma_f32_16x16x32_bf16 v[12:15], v[146:149], v[198:201], 0
	v_mfma_f32_16x16x32_bf16 v[8:11], v[158:161], v[198:201], 0
	v_mfma_f32_16x16x32_bf16 v[60:63], v[154:157], v[170:173], v[60:63]
	v_mfma_f32_16x16x32_bf16 v[56:59], v[162:165], v[170:173], v[56:59]
	v_mfma_f32_16x16x32_bf16 v[44:47], v[154:157], v[186:189], v[44:47]
	v_mfma_f32_16x16x32_bf16 v[40:43], v[162:165], v[186:189], v[40:43]
	v_mfma_f32_16x16x32_bf16 v[28:31], v[154:157], v[194:197], v[28:31]
	v_mfma_f32_16x16x32_bf16 v[24:27], v[162:165], v[194:197], v[24:27]
	v_mfma_f32_16x16x32_bf16 v[12:15], v[154:157], v[202:205], v[12:15]
	v_mfma_f32_16x16x32_bf16 v[8:11], v[162:165], v[202:205], v[8:11]
	s_barrier
	s_add_u32 s46, s22, 0x40000
	s_addc_u32 s47, s23, 0
	s_add_i32 s48, s38, s29
	v_lshl_add_u64 v[146:147], s[46:47], 0, v[130:131]
	s_mov_b32 m0, s48
	s_nop 0
	global_load_lds_dwordx4 v[146:147], off
	v_lshl_add_u64 v[146:147], s[46:47], 0, v[134:135]
	s_add_i32 m0, s48, 0x2000
	s_nop 0
	global_load_lds_dwordx4 v[146:147], off
	s_waitcnt vmcnt(6)
	s_barrier
	v_mfma_f32_16x16x32_bf16 v[52:55], v[206:209], v[166:169], 0
	v_mfma_f32_16x16x32_bf16 v[48:51], v[214:217], v[166:169], 0
	v_mfma_f32_16x16x32_bf16 v[36:39], v[206:209], v[182:185], 0
	v_mfma_f32_16x16x32_bf16 v[32:35], v[214:217], v[182:185], 0
	v_mfma_f32_16x16x32_bf16 v[20:23], v[206:209], v[190:193], 0
	v_mfma_f32_16x16x32_bf16 v[16:19], v[214:217], v[190:193], 0
	v_mfma_f32_16x16x32_bf16 v[4:7], v[206:209], v[198:201], 0
	v_mfma_f32_16x16x32_bf16 v[0:3], v[214:217], v[198:201], 0
	v_mfma_f32_16x16x32_bf16 v[52:55], v[210:213], v[170:173], v[52:55]
	v_mfma_f32_16x16x32_bf16 v[48:51], v[218:221], v[170:173], v[48:51]
	v_mfma_f32_16x16x32_bf16 v[36:39], v[210:213], v[186:189], v[36:39]
	v_mfma_f32_16x16x32_bf16 v[32:35], v[218:221], v[186:189], v[32:35]
	v_mfma_f32_16x16x32_bf16 v[20:23], v[210:213], v[194:197], v[20:23]
	v_mfma_f32_16x16x32_bf16 v[16:19], v[218:221], v[194:197], v[16:19]
	v_mfma_f32_16x16x32_bf16 v[4:7], v[210:213], v[202:205], v[4:7]
	v_mfma_f32_16x16x32_bf16 v[0:3], v[218:221], v[202:205], v[0:3]
	s_add_i32 s46, 0, 0x18000
	v_add_u32_e32 v162, s46, v175
	s_barrier
	ds_read_b128 v[146:149], v162
	ds_read_b128 v[154:157], v162 offset:1024
	ds_read_b128 v[158:161], v162 offset:2048
	ds_read_b128 v[162:165], v162 offset:3072
	s_add_u32 s24, s24, 0x40000
	s_addc_u32 s25, s25, 0
	s_mov_b32 m0, s31
	v_lshl_add_u64 v[206:207], s[24:25], 0, v[128:129]
	ds_read_b128 v[166:169], v178 offset:32768
	ds_read_b128 v[170:173], v178 offset:33792
	ds_read_b128 v[182:185], v178 offset:34816
	ds_read_b128 v[186:189], v178 offset:35840
	ds_read_b128 v[190:193], v178 offset:36864
	ds_read_b128 v[194:197], v178 offset:37888
	ds_read_b128 v[198:201], v178 offset:38912
	ds_read_b128 v[202:205], v178 offset:39936
	global_load_lds_dwordx4 v[206:207], off
	v_lshl_add_u64 v[206:207], s[24:25], 0, v[132:133]
	s_mov_b32 m0, s33
	s_nop 0
	global_load_lds_dwordx4 v[206:207], off
	s_waitcnt lgkmcnt(8)
	s_barrier
	s_waitcnt lgkmcnt(0)
	v_mfma_f32_16x16x32_bf16 v[124:127], v[146:149], v[166:169], v[124:127]
	v_mfma_f32_16x16x32_bf16 v[120:123], v[158:161], v[166:169], v[120:123]
	v_mfma_f32_16x16x32_bf16 v[108:111], v[146:149], v[182:185], v[108:111]
	v_mfma_f32_16x16x32_bf16 v[104:107], v[158:161], v[182:185], v[104:107]
	v_mfma_f32_16x16x32_bf16 v[92:95], v[146:149], v[190:193], v[92:95]
	v_mfma_f32_16x16x32_bf16 v[88:91], v[158:161], v[190:193], v[88:91]
	v_mfma_f32_16x16x32_bf16 v[76:79], v[146:149], v[198:201], v[76:79]
	v_mfma_f32_16x16x32_bf16 v[72:75], v[158:161], v[198:201], v[72:75]
	v_mfma_f32_16x16x32_bf16 v[124:127], v[154:157], v[170:173], v[124:127]
	v_mfma_f32_16x16x32_bf16 v[120:123], v[162:165], v[170:173], v[120:123]
	v_mfma_f32_16x16x32_bf16 v[108:111], v[154:157], v[186:189], v[108:111]
	v_mfma_f32_16x16x32_bf16 v[104:107], v[162:165], v[186:189], v[104:107]
	v_mfma_f32_16x16x32_bf16 v[92:95], v[154:157], v[194:197], v[92:95]
	v_mfma_f32_16x16x32_bf16 v[88:91], v[162:165], v[194:197], v[88:91]
	v_mfma_f32_16x16x32_bf16 v[76:79], v[154:157], v[202:205], v[76:79]
	v_mfma_f32_16x16x32_bf16 v[72:75], v[162:165], v[202:205], v[72:75]
	s_barrier
	s_add_i32 s24, 0, 0x1c000
	s_add_i32 s25, s46, s29
	v_add_u32_e32 v181, s24, v175
	v_lshl_add_u64 v[150:151], v[150:151], 0, s[4:5]
	s_mov_b32 m0, s25
	ds_read_b128 v[206:209], v181
	ds_read_b128 v[210:213], v181 offset:1024
	ds_read_b128 v[214:217], v181 offset:2048
	ds_read_b128 v[218:221], v181 offset:3072
	global_load_lds_dwordx4 v[150:151], off
	v_lshl_add_u64 v[150:151], v[222:223], 0, s[4:5]
	s_add_i32 m0, s25, 0x2000
	s_nop 0
	global_load_lds_dwordx4 v[150:151], off
	s_barrier
	s_waitcnt lgkmcnt(0)
	v_mfma_f32_16x16x32_bf16 v[116:119], v[206:209], v[166:169], v[116:119]
	v_mfma_f32_16x16x32_bf16 v[112:115], v[214:217], v[166:169], v[112:115]
	v_mfma_f32_16x16x32_bf16 v[100:103], v[206:209], v[182:185], v[100:103]
	v_mfma_f32_16x16x32_bf16 v[96:99], v[214:217], v[182:185], v[96:99]
	v_mfma_f32_16x16x32_bf16 v[84:87], v[206:209], v[190:193], v[84:87]
	v_mfma_f32_16x16x32_bf16 v[80:83], v[214:217], v[190:193], v[80:83]
	v_mfma_f32_16x16x32_bf16 v[68:71], v[206:209], v[198:201], v[68:71]
	v_mfma_f32_16x16x32_bf16 v[64:67], v[214:217], v[198:201], v[64:67]
	v_mfma_f32_16x16x32_bf16 v[116:119], v[210:213], v[170:173], v[116:119]
	v_mfma_f32_16x16x32_bf16 v[112:115], v[218:221], v[170:173], v[112:115]
	v_mfma_f32_16x16x32_bf16 v[100:103], v[210:213], v[186:189], v[100:103]
	v_mfma_f32_16x16x32_bf16 v[96:99], v[218:221], v[186:189], v[96:99]
	v_mfma_f32_16x16x32_bf16 v[84:87], v[210:213], v[194:197], v[84:87]
	v_mfma_f32_16x16x32_bf16 v[80:83], v[218:221], v[194:197], v[80:83]
	v_mfma_f32_16x16x32_bf16 v[68:71], v[210:213], v[202:205], v[68:71]
	v_mfma_f32_16x16x32_bf16 v[64:67], v[218:221], v[202:205], v[64:67]
	s_mov_b32 m0, s35
	v_lshl_add_u64 v[150:151], v[224:225], 0, s[4:5]
	s_barrier
	ds_read_b128 v[166:169], v178 offset:49152
	ds_read_b128 v[170:173], v178 offset:50176
	ds_read_b128 v[182:185], v178 offset:51200
	ds_read_b128 v[186:189], v178 offset:52224
	ds_read_b128 v[190:193], v178 offset:53248
	ds_read_b128 v[194:197], v178 offset:54272
	ds_read_b128 v[198:201], v178 offset:55296
	ds_read_b128 v[202:205], v178 offset:56320
	global_load_lds_dwordx4 v[150:151], off
	v_lshl_add_u64 v[150:151], v[226:227], 0, s[4:5]
	s_mov_b32 m0, s36
	s_nop 0
	global_load_lds_dwordx4 v[150:151], off
	s_barrier
	s_waitcnt lgkmcnt(0)
	v_mfma_f32_16x16x32_bf16 v[60:63], v[146:149], v[166:169], v[60:63]
	v_mfma_f32_16x16x32_bf16 v[56:59], v[158:161], v[166:169], v[56:59]
	v_mfma_f32_16x16x32_bf16 v[44:47], v[146:149], v[182:185], v[44:47]
	v_mfma_f32_16x16x32_bf16 v[40:43], v[158:161], v[182:185], v[40:43]
	v_mfma_f32_16x16x32_bf16 v[28:31], v[146:149], v[190:193], v[28:31]
	v_mfma_f32_16x16x32_bf16 v[24:27], v[158:161], v[190:193], v[24:27]
	v_mfma_f32_16x16x32_bf16 v[12:15], v[146:149], v[198:201], v[12:15]
	v_mfma_f32_16x16x32_bf16 v[8:11], v[158:161], v[198:201], v[8:11]
	v_mfma_f32_16x16x32_bf16 v[60:63], v[154:157], v[170:173], v[60:63]
	v_mfma_f32_16x16x32_bf16 v[56:59], v[162:165], v[170:173], v[56:59]
	v_mfma_f32_16x16x32_bf16 v[44:47], v[154:157], v[186:189], v[44:47]
	v_mfma_f32_16x16x32_bf16 v[40:43], v[162:165], v[186:189], v[40:43]
	v_mfma_f32_16x16x32_bf16 v[28:31], v[154:157], v[194:197], v[28:31]
	v_mfma_f32_16x16x32_bf16 v[24:27], v[162:165], v[194:197], v[24:27]
	v_mfma_f32_16x16x32_bf16 v[12:15], v[154:157], v[202:205], v[12:15]
	v_mfma_f32_16x16x32_bf16 v[8:11], v[162:165], v[202:205], v[8:11]
	s_barrier
	s_add_u32 s22, s22, 0x40080
	s_addc_u32 s23, s23, 0
	s_add_i32 s24, s24, s29
	v_lshl_add_u64 v[146:147], s[22:23], 0, v[130:131]
	s_mov_b32 m0, s24
	s_nop 0
	global_load_lds_dwordx4 v[146:147], off
	v_lshl_add_u64 v[146:147], s[22:23], 0, v[134:135]
	s_add_i32 m0, s24, 0x2000
	s_nop 0
	global_load_lds_dwordx4 v[146:147], off
	s_waitcnt vmcnt(6)
	s_barrier
	v_mfma_f32_16x16x32_bf16 v[52:55], v[206:209], v[166:169], v[52:55]
	v_mfma_f32_16x16x32_bf16 v[48:51], v[214:217], v[166:169], v[48:51]
	v_mfma_f32_16x16x32_bf16 v[36:39], v[206:209], v[182:185], v[36:39]
	v_mfma_f32_16x16x32_bf16 v[32:35], v[214:217], v[182:185], v[32:35]
	v_mfma_f32_16x16x32_bf16 v[20:23], v[206:209], v[190:193], v[20:23]
	v_mfma_f32_16x16x32_bf16 v[16:19], v[214:217], v[190:193], v[16:19]
	v_mfma_f32_16x16x32_bf16 v[4:7], v[206:209], v[198:201], v[4:7]
	v_mfma_f32_16x16x32_bf16 v[0:3], v[214:217], v[198:201], v[0:3]
	v_mfma_f32_16x16x32_bf16 v[52:55], v[210:213], v[170:173], v[52:55]
	v_mfma_f32_16x16x32_bf16 v[48:51], v[218:221], v[170:173], v[48:51]
	v_mfma_f32_16x16x32_bf16 v[36:39], v[210:213], v[186:189], v[36:39]
	v_mfma_f32_16x16x32_bf16 v[32:35], v[218:221], v[186:189], v[32:35]
	v_mfma_f32_16x16x32_bf16 v[20:23], v[210:213], v[194:197], v[20:23]
	v_mfma_f32_16x16x32_bf16 v[16:19], v[218:221], v[194:197], v[16:19]
	v_mfma_f32_16x16x32_bf16 v[4:7], v[210:213], v[202:205], v[4:7]
	v_mfma_f32_16x16x32_bf16 v[0:3], v[218:221], v[202:205], v[0:3]
	s_add_i32 s45, s45, 2
	s_add_u32 s20, s20, 0x100
	s_addc_u32 s21, s21, 0
	s_add_u32 s43, s43, 0x100
	s_addc_u32 s44, s44, 0
	s_cmp_gt_u32 s45, 13
	s_barrier
.LBB0_770:
	ds_read_b128 v[146:149], v177
	ds_read_b128 v[154:157], v177 offset:1024
	ds_read_b128 v[158:161], v177 offset:2048
	ds_read_b128 v[162:165], v177 offset:3072
	s_add_u32 s22, s20, 0xfffc0080
	s_addc_u32 s23, s21, -1
	s_cmp_eq_u32 s45, 12
	s_cselect_b32 s25, s13, s23
	s_cselect_b32 s24, s41, s22
	s_cselect_b32 s23, s11, s44
	s_cselect_b32 s22, s42, s43
	v_lshl_add_u64 v[150:151], s[20:21], 0, v[138:139]
	s_add_i32 m0, s19, 0xc000
	ds_read_b128 v[166:169], v178
	ds_read_b128 v[170:173], v178 offset:1024
	ds_read_b128 v[182:185], v178 offset:2048
	ds_read_b128 v[186:189], v178 offset:3072
	ds_read_b128 v[190:193], v178 offset:4096
	ds_read_b128 v[194:197], v178 offset:5120
	ds_read_b128 v[198:201], v178 offset:6144
	ds_read_b128 v[202:205], v178 offset:7168
	global_load_lds_dwordx4 v[150:151], off
	v_lshl_add_u64 v[150:151], s[20:21], 0, v[140:141]
	s_add_i32 m0, s19, 0xe000
	s_nop 0
	global_load_lds_dwordx4 v[150:151], off
	s_waitcnt lgkmcnt(8)
	s_barrier
	s_waitcnt lgkmcnt(0)
	v_mfma_f32_16x16x32_bf16 v[124:127], v[146:149], v[166:169], v[124:127]
	v_mfma_f32_16x16x32_bf16 v[120:123], v[158:161], v[166:169], v[120:123]
	v_mfma_f32_16x16x32_bf16 v[108:111], v[146:149], v[182:185], v[108:111]
	v_mfma_f32_16x16x32_bf16 v[104:107], v[158:161], v[182:185], v[104:107]
	v_mfma_f32_16x16x32_bf16 v[92:95], v[146:149], v[190:193], v[92:95]
	v_mfma_f32_16x16x32_bf16 v[88:91], v[158:161], v[190:193], v[88:91]
	v_mfma_f32_16x16x32_bf16 v[76:79], v[146:149], v[198:201], v[76:79]
	v_mfma_f32_16x16x32_bf16 v[72:75], v[158:161], v[198:201], v[72:75]
	v_mfma_f32_16x16x32_bf16 v[124:127], v[154:157], v[170:173], v[124:127]
	v_mfma_f32_16x16x32_bf16 v[120:123], v[162:165], v[170:173], v[120:123]
	v_mfma_f32_16x16x32_bf16 v[108:111], v[154:157], v[186:189], v[108:111]
	v_mfma_f32_16x16x32_bf16 v[104:107], v[162:165], v[186:189], v[104:107]
	v_mfma_f32_16x16x32_bf16 v[92:95], v[154:157], v[194:197], v[92:95]
	v_mfma_f32_16x16x32_bf16 v[88:91], v[162:165], v[194:197], v[88:91]
	v_mfma_f32_16x16x32_bf16 v[76:79], v[154:157], v[202:205], v[76:79]
	v_mfma_f32_16x16x32_bf16 v[72:75], v[162:165], v[202:205], v[72:75]
	s_barrier
	s_add_i32 s46, s7, s29
	v_lshl_add_u64 v[150:151], s[22:23], 0, v[130:131]
	s_mov_b32 m0, s46
	ds_read_b128 v[206:209], v179
	ds_read_b128 v[210:213], v179 offset:1024
	ds_read_b128 v[214:217], v179 offset:2048
	ds_read_b128 v[218:221], v179 offset:3072
	global_load_lds_dwordx4 v[150:151], off
	v_lshl_add_u64 v[222:223], s[22:23], 0, v[134:135]
	s_add_i32 m0, s46, 0x2000
	s_nop 0
	global_load_lds_dwordx4 v[222:223], off
	s_barrier
	s_waitcnt lgkmcnt(0)
	v_mfma_f32_16x16x32_bf16 v[116:119], v[206:209], v[166:169], v[116:119]
	v_mfma_f32_16x16x32_bf16 v[112:115], v[214:217], v[166:169], v[112:115]
	v_mfma_f32_16x16x32_bf16 v[100:103], v[206:209], v[182:185], v[100:103]
	v_mfma_f32_16x16x32_bf16 v[96:99], v[214:217], v[182:185], v[96:99]
	v_mfma_f32_16x16x32_bf16 v[84:87], v[206:209], v[190:193], v[84:87]
	v_mfma_f32_16x16x32_bf16 v[80:83], v[214:217], v[190:193], v[80:83]
	v_mfma_f32_16x16x32_bf16 v[68:71], v[206:209], v[198:201], v[68:71]
	v_mfma_f32_16x16x32_bf16 v[64:67], v[214:217], v[198:201], v[64:67]
	v_mfma_f32_16x16x32_bf16 v[116:119], v[210:213], v[170:173], v[116:119]
	v_mfma_f32_16x16x32_bf16 v[112:115], v[218:221], v[170:173], v[112:115]
	v_mfma_f32_16x16x32_bf16 v[100:103], v[210:213], v[186:189], v[100:103]
	v_mfma_f32_16x16x32_bf16 v[96:99], v[218:221], v[186:189], v[96:99]
	v_mfma_f32_16x16x32_bf16 v[84:87], v[210:213], v[194:197], v[84:87]
	v_mfma_f32_16x16x32_bf16 v[80:83], v[218:221], v[194:197], v[80:83]
	v_mfma_f32_16x16x32_bf16 v[68:71], v[210:213], v[202:205], v[68:71]
	v_mfma_f32_16x16x32_bf16 v[64:67], v[218:221], v[202:205], v[64:67]
	s_mov_b32 m0, s19
	v_lshl_add_u64 v[224:225], s[24:25], 0, v[128:129]
	s_barrier
	ds_read_b128 v[166:169], v178 offset:16384
	ds_read_b128 v[170:173], v178 offset:17408
	ds_read_b128 v[182:185], v178 offset:18432
	ds_read_b128 v[186:189], v178 offset:19456
	ds_read_b128 v[190:193], v178 offset:20480
	ds_read_b128 v[194:197], v178 offset:21504
	ds_read_b128 v[198:201], v178 offset:22528
	ds_read_b128 v[202:205], v178 offset:23552
	global_load_lds_dwordx4 v[224:225], off
	v_lshl_add_u64 v[226:227], s[24:25], 0, v[132:133]
	s_mov_b32 m0, s30
	s_nop 0
	global_load_lds_dwordx4 v[226:227], off
	s_barrier
	s_waitcnt lgkmcnt(0)
	v_mfma_f32_16x16x32_bf16 v[60:63], v[146:149], v[166:169], v[60:63]
	v_mfma_f32_16x16x32_bf16 v[56:59], v[158:161], v[166:169], v[56:59]
	v_mfma_f32_16x16x32_bf16 v[44:47], v[146:149], v[182:185], v[44:47]
	v_mfma_f32_16x16x32_bf16 v[40:43], v[158:161], v[182:185], v[40:43]
	v_mfma_f32_16x16x32_bf16 v[28:31], v[146:149], v[190:193], v[28:31]
	v_mfma_f32_16x16x32_bf16 v[24:27], v[158:161], v[190:193], v[24:27]
	v_mfma_f32_16x16x32_bf16 v[12:15], v[146:149], v[198:201], v[12:15]
	v_mfma_f32_16x16x32_bf16 v[8:11], v[158:161], v[198:201], v[8:11]
	v_mfma_f32_16x16x32_bf16 v[60:63], v[154:157], v[170:173], v[60:63]
	v_mfma_f32_16x16x32_bf16 v[56:59], v[162:165], v[170:173], v[56:59]
	v_mfma_f32_16x16x32_bf16 v[44:47], v[154:157], v[186:189], v[44:47]
	v_mfma_f32_16x16x32_bf16 v[40:43], v[162:165], v[186:189], v[40:43]
	v_mfma_f32_16x16x32_bf16 v[28:31], v[154:157], v[194:197], v[28:31]
	v_mfma_f32_16x16x32_bf16 v[24:27], v[162:165], v[194:197], v[24:27]
	v_mfma_f32_16x16x32_bf16 v[12:15], v[154:157], v[202:205], v[12:15]
	v_mfma_f32_16x16x32_bf16 v[8:11], v[162:165], v[202:205], v[8:11]
	s_barrier
	s_add_u32 s46, s22, 0x40000
	s_addc_u32 s47, s23, 0
	s_add_i32 s48, s38, s29
	v_lshl_add_u64 v[146:147], s[46:47], 0, v[130:131]
	s_mov_b32 m0, s48
	s_nop 0
	global_load_lds_dwordx4 v[146:147], off
	v_lshl_add_u64 v[146:147], s[46:47], 0, v[134:135]
	s_add_i32 m0, s48, 0x2000
	s_nop 0
	global_load_lds_dwordx4 v[146:147], off
	s_waitcnt vmcnt(6)
	s_barrier
	v_mfma_f32_16x16x32_bf16 v[52:55], v[206:209], v[166:169], v[52:55]
	v_mfma_f32_16x16x32_bf16 v[48:51], v[214:217], v[166:169], v[48:51]
	v_mfma_f32_16x16x32_bf16 v[36:39], v[206:209], v[182:185], v[36:39]
	v_mfma_f32_16x16x32_bf16 v[32:35], v[214:217], v[182:185], v[32:35]
	v_mfma_f32_16x16x32_bf16 v[20:23], v[206:209], v[190:193], v[20:23]
	v_mfma_f32_16x16x32_bf16 v[16:19], v[214:217], v[190:193], v[16:19]
	v_mfma_f32_16x16x32_bf16 v[4:7], v[206:209], v[198:201], v[4:7]
	v_mfma_f32_16x16x32_bf16 v[0:3], v[214:217], v[198:201], v[0:3]
	v_mfma_f32_16x16x32_bf16 v[52:55], v[210:213], v[170:173], v[52:55]
	v_mfma_f32_16x16x32_bf16 v[48:51], v[218:221], v[170:173], v[48:51]
	v_mfma_f32_16x16x32_bf16 v[36:39], v[210:213], v[186:189], v[36:39]
	v_mfma_f32_16x16x32_bf16 v[32:35], v[218:221], v[186:189], v[32:35]
	v_mfma_f32_16x16x32_bf16 v[20:23], v[210:213], v[194:197], v[20:23]
	v_mfma_f32_16x16x32_bf16 v[16:19], v[218:221], v[194:197], v[16:19]
	v_mfma_f32_16x16x32_bf16 v[4:7], v[210:213], v[202:205], v[4:7]
	v_mfma_f32_16x16x32_bf16 v[0:3], v[218:221], v[202:205], v[0:3]
	s_add_i32 s46, 0, 0x18000
	v_add_u32_e32 v162, s46, v175
	s_barrier
	ds_read_b128 v[146:149], v162
	ds_read_b128 v[154:157], v162 offset:1024
	ds_read_b128 v[158:161], v162 offset:2048
	ds_read_b128 v[162:165], v162 offset:3072
	s_add_u32 s24, s24, 0x40000
	s_addc_u32 s25, s25, 0
	s_mov_b32 m0, s31
	v_lshl_add_u64 v[206:207], s[24:25], 0, v[128:129]
	ds_read_b128 v[166:169], v178 offset:32768
	ds_read_b128 v[170:173], v178 offset:33792
	ds_read_b128 v[182:185], v178 offset:34816
	ds_read_b128 v[186:189], v178 offset:35840
	ds_read_b128 v[190:193], v178 offset:36864
	ds_read_b128 v[194:197], v178 offset:37888
	ds_read_b128 v[198:201], v178 offset:38912
	ds_read_b128 v[202:205], v178 offset:39936
	global_load_lds_dwordx4 v[206:207], off
	v_lshl_add_u64 v[206:207], s[24:25], 0, v[132:133]
	s_mov_b32 m0, s33
	s_nop 0
	global_load_lds_dwordx4 v[206:207], off
	s_waitcnt lgkmcnt(8)
	s_barrier
	s_waitcnt lgkmcnt(0)
	v_mfma_f32_16x16x32_bf16 v[124:127], v[146:149], v[166:169], v[124:127]
	v_mfma_f32_16x16x32_bf16 v[120:123], v[158:161], v[166:169], v[120:123]
	v_mfma_f32_16x16x32_bf16 v[108:111], v[146:149], v[182:185], v[108:111]
	v_mfma_f32_16x16x32_bf16 v[104:107], v[158:161], v[182:185], v[104:107]
	v_mfma_f32_16x16x32_bf16 v[92:95], v[146:149], v[190:193], v[92:95]
	v_mfma_f32_16x16x32_bf16 v[88:91], v[158:161], v[190:193], v[88:91]
	v_mfma_f32_16x16x32_bf16 v[76:79], v[146:149], v[198:201], v[76:79]
	v_mfma_f32_16x16x32_bf16 v[72:75], v[158:161], v[198:201], v[72:75]
	v_mfma_f32_16x16x32_bf16 v[124:127], v[154:157], v[170:173], v[124:127]
	v_mfma_f32_16x16x32_bf16 v[120:123], v[162:165], v[170:173], v[120:123]
	v_mfma_f32_16x16x32_bf16 v[108:111], v[154:157], v[186:189], v[108:111]
	v_mfma_f32_16x16x32_bf16 v[104:107], v[162:165], v[186:189], v[104:107]
	v_mfma_f32_16x16x32_bf16 v[92:95], v[154:157], v[194:197], v[92:95]
	v_mfma_f32_16x16x32_bf16 v[88:91], v[162:165], v[194:197], v[88:91]
	v_mfma_f32_16x16x32_bf16 v[76:79], v[154:157], v[202:205], v[76:79]
	v_mfma_f32_16x16x32_bf16 v[72:75], v[162:165], v[202:205], v[72:75]
	s_barrier
	s_add_i32 s24, 0, 0x1c000
	s_add_i32 s25, s46, s29
	v_add_u32_e32 v181, s24, v175
	v_lshl_add_u64 v[150:151], v[150:151], 0, s[4:5]
	s_mov_b32 m0, s25
	ds_read_b128 v[206:209], v181
	ds_read_b128 v[210:213], v181 offset:1024
	ds_read_b128 v[214:217], v181 offset:2048
	ds_read_b128 v[218:221], v181 offset:3072
	global_load_lds_dwordx4 v[150:151], off
	v_lshl_add_u64 v[150:151], v[222:223], 0, s[4:5]
	s_add_i32 m0, s25, 0x2000
	s_nop 0
	global_load_lds_dwordx4 v[150:151], off
	s_barrier
	s_waitcnt lgkmcnt(0)
	v_mfma_f32_16x16x32_bf16 v[116:119], v[206:209], v[166:169], v[116:119]
	v_mfma_f32_16x16x32_bf16 v[112:115], v[214:217], v[166:169], v[112:115]
	v_mfma_f32_16x16x32_bf16 v[100:103], v[206:209], v[182:185], v[100:103]
	v_mfma_f32_16x16x32_bf16 v[96:99], v[214:217], v[182:185], v[96:99]
	v_mfma_f32_16x16x32_bf16 v[84:87], v[206:209], v[190:193], v[84:87]
	v_mfma_f32_16x16x32_bf16 v[80:83], v[214:217], v[190:193], v[80:83]
	v_mfma_f32_16x16x32_bf16 v[68:71], v[206:209], v[198:201], v[68:71]
	v_mfma_f32_16x16x32_bf16 v[64:67], v[214:217], v[198:201], v[64:67]
	v_mfma_f32_16x16x32_bf16 v[116:119], v[210:213], v[170:173], v[116:119]
	v_mfma_f32_16x16x32_bf16 v[112:115], v[218:221], v[170:173], v[112:115]
	v_mfma_f32_16x16x32_bf16 v[100:103], v[210:213], v[186:189], v[100:103]
	v_mfma_f32_16x16x32_bf16 v[96:99], v[218:221], v[186:189], v[96:99]
	v_mfma_f32_16x16x32_bf16 v[84:87], v[210:213], v[194:197], v[84:87]
	v_mfma_f32_16x16x32_bf16 v[80:83], v[218:221], v[194:197], v[80:83]
	v_mfma_f32_16x16x32_bf16 v[68:71], v[210:213], v[202:205], v[68:71]
	v_mfma_f32_16x16x32_bf16 v[64:67], v[218:221], v[202:205], v[64:67]
	s_mov_b32 m0, s35
	v_lshl_add_u64 v[150:151], v[224:225], 0, s[4:5]
	s_barrier
	ds_read_b128 v[166:169], v178 offset:49152
	ds_read_b128 v[170:173], v178 offset:50176
	ds_read_b128 v[182:185], v178 offset:51200
	ds_read_b128 v[186:189], v178 offset:52224
	ds_read_b128 v[190:193], v178 offset:53248
	ds_read_b128 v[194:197], v178 offset:54272
	ds_read_b128 v[198:201], v178 offset:55296
	ds_read_b128 v[202:205], v178 offset:56320
	global_load_lds_dwordx4 v[150:151], off
	v_lshl_add_u64 v[150:151], v[226:227], 0, s[4:5]
	s_mov_b32 m0, s36
	s_nop 0
	global_load_lds_dwordx4 v[150:151], off
	s_barrier
	s_waitcnt lgkmcnt(0)
	v_mfma_f32_16x16x32_bf16 v[60:63], v[146:149], v[166:169], v[60:63]
	v_mfma_f32_16x16x32_bf16 v[56:59], v[158:161], v[166:169], v[56:59]
	v_mfma_f32_16x16x32_bf16 v[44:47], v[146:149], v[182:185], v[44:47]
	v_mfma_f32_16x16x32_bf16 v[40:43], v[158:161], v[182:185], v[40:43]
	v_mfma_f32_16x16x32_bf16 v[28:31], v[146:149], v[190:193], v[28:31]
	v_mfma_f32_16x16x32_bf16 v[24:27], v[158:161], v[190:193], v[24:27]
	v_mfma_f32_16x16x32_bf16 v[12:15], v[146:149], v[198:201], v[12:15]
	v_mfma_f32_16x16x32_bf16 v[8:11], v[158:161], v[198:201], v[8:11]
	v_mfma_f32_16x16x32_bf16 v[60:63], v[154:157], v[170:173], v[60:63]
	v_mfma_f32_16x16x32_bf16 v[56:59], v[162:165], v[170:173], v[56:59]
	v_mfma_f32_16x16x32_bf16 v[44:47], v[154:157], v[186:189], v[44:47]
	v_mfma_f32_16x16x32_bf16 v[40:43], v[162:165], v[186:189], v[40:43]
	v_mfma_f32_16x16x32_bf16 v[28:31], v[154:157], v[194:197], v[28:31]
	v_mfma_f32_16x16x32_bf16 v[24:27], v[162:165], v[194:197], v[24:27]
	v_mfma_f32_16x16x32_bf16 v[12:15], v[154:157], v[202:205], v[12:15]
	v_mfma_f32_16x16x32_bf16 v[8:11], v[162:165], v[202:205], v[8:11]
	s_barrier
	s_add_u32 s22, s22, 0x40080
	s_addc_u32 s23, s23, 0
	s_add_i32 s24, s24, s29
	v_lshl_add_u64 v[146:147], s[22:23], 0, v[130:131]
	s_mov_b32 m0, s24
	s_nop 0
	global_load_lds_dwordx4 v[146:147], off
	v_lshl_add_u64 v[146:147], s[22:23], 0, v[134:135]
	s_add_i32 m0, s24, 0x2000
	s_nop 0
	global_load_lds_dwordx4 v[146:147], off
	s_waitcnt vmcnt(6)
	s_barrier
	v_mfma_f32_16x16x32_bf16 v[52:55], v[206:209], v[166:169], v[52:55]
	v_mfma_f32_16x16x32_bf16 v[48:51], v[214:217], v[166:169], v[48:51]
	v_mfma_f32_16x16x32_bf16 v[36:39], v[206:209], v[182:185], v[36:39]
	v_mfma_f32_16x16x32_bf16 v[32:35], v[214:217], v[182:185], v[32:35]
	v_mfma_f32_16x16x32_bf16 v[20:23], v[206:209], v[190:193], v[20:23]
	v_mfma_f32_16x16x32_bf16 v[16:19], v[214:217], v[190:193], v[16:19]
	v_mfma_f32_16x16x32_bf16 v[4:7], v[206:209], v[198:201], v[4:7]
	v_mfma_f32_16x16x32_bf16 v[0:3], v[214:217], v[198:201], v[0:3]
	v_mfma_f32_16x16x32_bf16 v[52:55], v[210:213], v[170:173], v[52:55]
	v_mfma_f32_16x16x32_bf16 v[48:51], v[218:221], v[170:173], v[48:51]
	v_mfma_f32_16x16x32_bf16 v[36:39], v[210:213], v[186:189], v[36:39]
	v_mfma_f32_16x16x32_bf16 v[32:35], v[218:221], v[186:189], v[32:35]
	v_mfma_f32_16x16x32_bf16 v[20:23], v[210:213], v[194:197], v[20:23]
	v_mfma_f32_16x16x32_bf16 v[16:19], v[218:221], v[194:197], v[16:19]
	v_mfma_f32_16x16x32_bf16 v[4:7], v[210:213], v[202:205], v[4:7]
	v_mfma_f32_16x16x32_bf16 v[0:3], v[218:221], v[202:205], v[0:3]
	s_add_i32 s45, s45, 2
	s_add_u32 s20, s20, 0x100
	s_addc_u32 s21, s21, 0
	s_add_u32 s43, s43, 0x100
	s_addc_u32 s44, s44, 0
	s_cmp_gt_u32 s45, 13
	s_barrier
	s_cbranch_scc0 .LBB0_770
	s_bfe_u32 vcc_lo, s18, 0x20003
	s_lshl_b32 vcc_lo, vcc_lo, 10
	s_add_i32 vcc_lo, vcc_lo, 0x20010
	v_lshl_add_u32 v236, v174, 2, vcc_lo
	ds_read_b32 v228, v236
	ds_read_b32 v229, v236 offset:64
	ds_read_b32 v230, v236 offset:128
	ds_read_b32 v231, v236 offset:192
	ds_read_b32 v232, v236 offset:512
	ds_read_b32 v233, v236 offset:576
	ds_read_b32 v234, v236 offset:640
	ds_read_b32 v235, v236 offset:704
	s_waitcnt lgkmcnt(0)
	v_lshl_add_u32 v148, s18, 8, v174
	v_ashrrev_i32_e32 v149, 31, v148
	v_or_b32_e32 v172, 16, v148
	v_ashrrev_i32_e32 v173, 31, v172
	v_or_b32_e32 v168, 32, v148
	v_or_b32_e32 v164, 48, v148
	v_ashrrev_i32_e32 v169, 31, v168
	v_ashrrev_i32_e32 v165, 31, v164
	v_add_u32_e32 v162, 0x80, v148
	v_add_u32_e32 v156, 0x90, v148
	v_ashrrev_i32_e32 v163, 31, v162
	v_ashrrev_i32_e32 v157, 31, v156
	v_add_u32_e32 v150, 0xa0, v148
	v_ashrrev_i32_e32 v151, 31, v150
	v_add_u32_e32 v146, 0xb0, v148
	v_ashrrev_i32_e32 v147, 31, v146
	v_lshl_or_b32 v166, s40, 8, v176
	v_ashrrev_i32_e32 v167, 31, v166
	v_lshlrev_b64 v[170:171], 13, v[148:149]
	v_lshlrev_b64 v[148:149], 1, v[166:167]
	v_lshl_add_u64 v[166:167], s[96:97], 0, v[170:171]
	v_lshl_add_u64 v[212:213], v[166:167], 0, v[148:149]
	s_mov_b32 s40, s10
	s_mov_b32 s18, s12
	s_mov_b64 s[22:23], s[16:17]
	s_mov_b64 s[20:21], s[14:15]
	s_waitcnt vmcnt(8)
	s_waitcnt lgkmcnt(0)
	s_waitcnt lgkmcnt(0)
	v_mov_b32_e32 v184, v228
	v_pk_mul_f32 v[120:121], v[120:121], v[184:185] op_sel_hi:[1,0]
	v_pk_mul_f32 v[126:127], v[126:127], v[184:185] op_sel_hi:[1,0]
	v_pk_mul_f32 v[124:125], v[124:125], v[184:185] op_sel_hi:[1,0]
	v_pk_mul_f32 v[122:123], v[122:123], v[184:185] op_sel_hi:[1,0]
	v_max_f32_e32 v120, 0, v120
	v_max_f32_e32 v121, 0, v121
	v_max_f32_e32 v124, 0, v124
	v_max_f32_e32 v125, 0, v125
	v_pk_mul_f32 v[190:191], v[120:121], v[120:121]
	v_max_f32_e32 v120, 0, v126
	v_max_f32_e32 v122, 0, v122
	v_max_f32_e32 v121, 0, v127
	v_max_f32_e32 v123, 0, v123
	v_pk_mul_f32 v[124:125], v[124:125], v[124:125]
	v_pk_mul_f32 v[126:127], v[120:121], v[120:121]
	v_pk_mul_f32 v[194:195], v[122:123], v[122:123]
	v_pk_mul_f32 v[114:115], v[114:115], v[184:185] op_sel_hi:[1,0]
	v_cvt_pk_bf16_f32 v120, v124, v125
	v_cvt_pk_bf16_f32 v121, v126, v127
	v_cvt_pk_bf16_f32 v122, v190, v191
	v_cvt_pk_bf16_f32 v123, v194, v195
	v_pk_mul_f32 v[116:117], v[116:117], v[184:185] op_sel_hi:[1,0]
	v_pk_mul_f32 v[112:113], v[112:113], v[184:185] op_sel_hi:[1,0]
	v_max_f32_e32 v114, 0, v114
	v_max_f32_e32 v115, 0, v115
	global_store_dwordx4 v[212:213], v[120:123], off
	v_pk_mul_f32 v[118:119], v[118:119], v[184:185] op_sel_hi:[1,0]
	v_max_f32_e32 v116, 0, v116
	v_max_f32_e32 v112, 0, v112
	v_max_f32_e32 v117, 0, v117
	v_max_f32_e32 v113, 0, v113
	v_pk_mul_f32 v[122:123], v[114:115], v[114:115]
	v_pk_mul_f32 v[116:117], v[116:117], v[116:117]
	v_pk_mul_f32 v[120:121], v[112:113], v[112:113]
	v_max_f32_e32 v112, 0, v118
	v_max_f32_e32 v113, 0, v119
	v_pk_mul_f32 v[118:119], v[112:113], v[112:113]
	v_cvt_pk_bf16_f32 v112, v116, v117
	v_cvt_pk_bf16_f32 v113, v118, v119
	v_cvt_pk_bf16_f32 v114, v120, v121
	v_cvt_pk_bf16_f32 v115, v122, v123
	global_store_dwordx4 v[212:213], v[112:115], off offset:256
	s_nop 1
	v_mov_b32_e32 v112, v229
	v_pk_mul_f32 v[104:105], v[104:105], v[112:113] op_sel_hi:[1,0]
	v_pk_mul_f32 v[110:111], v[110:111], v[112:113] op_sel_hi:[1,0]
	v_pk_mul_f32 v[108:109], v[108:109], v[112:113] op_sel_hi:[1,0]
	v_pk_mul_f32 v[106:107], v[106:107], v[112:113] op_sel_hi:[1,0]
	v_max_f32_e32 v104, 0, v104
	v_max_f32_e32 v105, 0, v105
	v_lshlrev_b64 v[114:115], 13, v[172:173]
	v_max_f32_e32 v108, 0, v108
	v_max_f32_e32 v109, 0, v109
	v_pk_mul_f32 v[116:117], v[104:105], v[104:105]
	v_max_f32_e32 v104, 0, v110
	v_max_f32_e32 v106, 0, v106
	v_max_f32_e32 v105, 0, v111
	v_max_f32_e32 v107, 0, v107
	v_lshl_add_u64 v[114:115], s[96:97], 0, v[114:115]
	v_pk_mul_f32 v[108:109], v[108:109], v[108:109]
	v_pk_mul_f32 v[110:111], v[104:105], v[104:105]
	v_pk_mul_f32 v[118:119], v[106:107], v[106:107]
	v_pk_mul_f32 v[96:97], v[96:97], v[112:113] op_sel_hi:[1,0]
	v_lshl_add_u64 v[114:115], v[114:115], 0, v[148:149]
	v_cvt_pk_bf16_f32 v104, v108, v109
	v_cvt_pk_bf16_f32 v105, v110, v111
	v_cvt_pk_bf16_f32 v106, v116, v117
	v_cvt_pk_bf16_f32 v107, v118, v119
	v_pk_mul_f32 v[102:103], v[102:103], v[112:113] op_sel_hi:[1,0]
	v_max_f32_e32 v96, 0, v96
	v_max_f32_e32 v97, 0, v97
	global_store_dwordx4 v[114:115], v[104:107], off
	v_pk_mul_f32 v[100:101], v[100:101], v[112:113] op_sel_hi:[1,0]
	v_pk_mul_f32 v[98:99], v[98:99], v[112:113] op_sel_hi:[1,0]
	v_pk_mul_f32 v[104:105], v[96:97], v[96:97]
	v_max_f32_e32 v96, 0, v102
	v_max_f32_e32 v97, 0, v103
	v_max_f32_e32 v100, 0, v100
	v_max_f32_e32 v101, 0, v101
	v_pk_mul_f32 v[100:101], v[100:101], v[100:101]
	v_pk_mul_f32 v[108:109], v[96:97], v[96:97]
	v_cvt_pk_bf16_f32 v96, v100, v101
	s_waitcnt lgkmcnt(0)
	v_max_f32_e32 v98, 0, v98
	v_max_f32_e32 v99, 0, v99
	v_pk_mul_f32 v[110:111], v[98:99], v[98:99]
	v_cvt_pk_bf16_f32 v97, v108, v109
	v_cvt_pk_bf16_f32 v98, v104, v105
	v_cvt_pk_bf16_f32 v99, v110, v111
	global_store_dwordx4 v[114:115], v[96:99], off offset:256
	s_waitcnt lgkmcnt(0)
	s_nop 0
	s_nop 0
	s_nop 0
	s_nop 1
	v_lshlrev_b64 v[98:99], 13, v[168:169]
	v_lshl_add_u64 v[98:99], s[96:97], 0, v[98:99]
	v_lshl_add_u64 v[98:99], v[98:99], 0, v[148:149]
	v_mov_b32_e32 v100, v230
	v_pk_mul_f32 v[88:89], v[88:89], v[100:101] op_sel_hi:[1,0]
	v_pk_mul_f32 v[94:95], v[94:95], v[100:101] op_sel_hi:[1,0]
	v_pk_mul_f32 v[92:93], v[92:93], v[100:101] op_sel_hi:[1,0]
	v_pk_mul_f32 v[90:91], v[90:91], v[100:101] op_sel_hi:[1,0]
	v_max_f32_e32 v88, 0, v88
	v_max_f32_e32 v89, 0, v89
	v_max_f32_e32 v92, 0, v92
	v_max_f32_e32 v93, 0, v93
	v_pk_mul_f32 v[102:103], v[88:89], v[88:89]
	v_max_f32_e32 v88, 0, v94
	v_max_f32_e32 v90, 0, v90
	v_max_f32_e32 v89, 0, v95
	v_max_f32_e32 v91, 0, v91
	v_pk_mul_f32 v[92:93], v[92:93], v[92:93]
	v_pk_mul_f32 v[94:95], v[88:89], v[88:89]
	v_pk_mul_f32 v[104:105], v[90:91], v[90:91]
	v_pk_mul_f32 v[82:83], v[82:83], v[100:101] op_sel_hi:[1,0]
	v_cvt_pk_bf16_f32 v88, v92, v93
	v_cvt_pk_bf16_f32 v89, v94, v95
	v_cvt_pk_bf16_f32 v90, v102, v103
	v_cvt_pk_bf16_f32 v91, v104, v105
	v_pk_mul_f32 v[84:85], v[84:85], v[100:101] op_sel_hi:[1,0]
	v_pk_mul_f32 v[80:81], v[80:81], v[100:101] op_sel_hi:[1,0]
	v_max_f32_e32 v82, 0, v82
	v_max_f32_e32 v83, 0, v83
	global_store_dwordx4 v[98:99], v[88:91], off
	v_pk_mul_f32 v[86:87], v[86:87], v[100:101] op_sel_hi:[1,0]
	v_max_f32_e32 v84, 0, v84
	v_max_f32_e32 v80, 0, v80
	v_max_f32_e32 v85, 0, v85
	v_max_f32_e32 v81, 0, v81
	v_pk_mul_f32 v[90:91], v[82:83], v[82:83]
	v_pk_mul_f32 v[84:85], v[84:85], v[84:85]
	v_pk_mul_f32 v[88:89], v[80:81], v[80:81]
	v_max_f32_e32 v80, 0, v86
	v_max_f32_e32 v81, 0, v87
	v_pk_mul_f32 v[86:87], v[80:81], v[80:81]
	v_cvt_pk_bf16_f32 v80, v84, v85
	v_cvt_pk_bf16_f32 v81, v86, v87
	v_cvt_pk_bf16_f32 v82, v88, v89
	v_cvt_pk_bf16_f32 v83, v90, v91
	global_store_dwordx4 v[98:99], v[80:83], off offset:256
	s_nop 1
	v_mov_b32_e32 v80, v231
	v_pk_mul_f32 v[72:73], v[72:73], v[80:81] op_sel_hi:[1,0]
	v_pk_mul_f32 v[78:79], v[78:79], v[80:81] op_sel_hi:[1,0]
	v_pk_mul_f32 v[76:77], v[76:77], v[80:81] op_sel_hi:[1,0]
	v_pk_mul_f32 v[74:75], v[74:75], v[80:81] op_sel_hi:[1,0]
	v_max_f32_e32 v72, 0, v72
	v_max_f32_e32 v73, 0, v73
	v_lshlrev_b64 v[82:83], 13, v[164:165]
	v_max_f32_e32 v76, 0, v76
	v_max_f32_e32 v77, 0, v77
	v_pk_mul_f32 v[84:85], v[72:73], v[72:73]
	v_max_f32_e32 v72, 0, v78
	v_max_f32_e32 v74, 0, v74
	v_max_f32_e32 v73, 0, v79
	v_max_f32_e32 v75, 0, v75
	v_lshl_add_u64 v[82:83], s[96:97], 0, v[82:83]
	v_pk_mul_f32 v[76:77], v[76:77], v[76:77]
	v_pk_mul_f32 v[78:79], v[72:73], v[72:73]
	v_pk_mul_f32 v[86:87], v[74:75], v[74:75]
	v_pk_mul_f32 v[64:65], v[64:65], v[80:81] op_sel_hi:[1,0]
	v_lshl_add_u64 v[82:83], v[82:83], 0, v[148:149]
	v_cvt_pk_bf16_f32 v72, v76, v77
	v_cvt_pk_bf16_f32 v73, v78, v79
	v_cvt_pk_bf16_f32 v74, v84, v85
	v_cvt_pk_bf16_f32 v75, v86, v87
	v_pk_mul_f32 v[70:71], v[70:71], v[80:81] op_sel_hi:[1,0]
	v_max_f32_e32 v64, 0, v64
	v_max_f32_e32 v65, 0, v65
	global_store_dwordx4 v[82:83], v[72:75], off
	v_pk_mul_f32 v[68:69], v[68:69], v[80:81] op_sel_hi:[1,0]
	v_pk_mul_f32 v[66:67], v[66:67], v[80:81] op_sel_hi:[1,0]
	v_pk_mul_f32 v[72:73], v[64:65], v[64:65]
	v_max_f32_e32 v64, 0, v70
	v_max_f32_e32 v65, 0, v71
	v_max_f32_e32 v68, 0, v68
	v_max_f32_e32 v69, 0, v69
	v_pk_mul_f32 v[68:69], v[68:69], v[68:69]
	v_pk_mul_f32 v[76:77], v[64:65], v[64:65]
	v_cvt_pk_bf16_f32 v64, v68, v69
	s_waitcnt lgkmcnt(0)
	v_max_f32_e32 v66, 0, v66
	v_max_f32_e32 v67, 0, v67
	v_pk_mul_f32 v[78:79], v[66:67], v[66:67]
	v_cvt_pk_bf16_f32 v65, v76, v77
	v_cvt_pk_bf16_f32 v66, v72, v73
	v_cvt_pk_bf16_f32 v67, v78, v79
	global_store_dwordx4 v[82:83], v[64:67], off offset:256
	s_waitcnt lgkmcnt(0)
	s_nop 0
	s_nop 0
	s_nop 0
	s_nop 1
	v_lshlrev_b64 v[66:67], 13, v[162:163]
	v_lshl_add_u64 v[66:67], s[96:97], 0, v[66:67]
	v_lshl_add_u64 v[66:67], v[66:67], 0, v[148:149]
	v_mov_b32_e32 v68, v232
	v_pk_mul_f32 v[56:57], v[56:57], v[68:69] op_sel_hi:[1,0]
	v_pk_mul_f32 v[62:63], v[62:63], v[68:69] op_sel_hi:[1,0]
	v_pk_mul_f32 v[60:61], v[60:61], v[68:69] op_sel_hi:[1,0]
	v_pk_mul_f32 v[58:59], v[58:59], v[68:69] op_sel_hi:[1,0]
	v_max_f32_e32 v56, 0, v56
	v_max_f32_e32 v57, 0, v57
	v_max_f32_e32 v60, 0, v60
	v_max_f32_e32 v61, 0, v61
	v_pk_mul_f32 v[70:71], v[56:57], v[56:57]
	v_max_f32_e32 v56, 0, v62
	v_max_f32_e32 v58, 0, v58
	v_max_f32_e32 v57, 0, v63
	v_max_f32_e32 v59, 0, v59
	v_pk_mul_f32 v[60:61], v[60:61], v[60:61]
	v_pk_mul_f32 v[62:63], v[56:57], v[56:57]
	v_pk_mul_f32 v[72:73], v[58:59], v[58:59]
	v_pk_mul_f32 v[50:51], v[50:51], v[68:69] op_sel_hi:[1,0]
	v_cvt_pk_bf16_f32 v56, v60, v61
	v_cvt_pk_bf16_f32 v57, v62, v63
	v_cvt_pk_bf16_f32 v58, v70, v71
	v_cvt_pk_bf16_f32 v59, v72, v73
	v_pk_mul_f32 v[52:53], v[52:53], v[68:69] op_sel_hi:[1,0]
	v_pk_mul_f32 v[48:49], v[48:49], v[68:69] op_sel_hi:[1,0]
	v_max_f32_e32 v50, 0, v50
	v_max_f32_e32 v51, 0, v51
	global_store_dwordx4 v[66:67], v[56:59], off
	v_pk_mul_f32 v[54:55], v[54:55], v[68:69] op_sel_hi:[1,0]
	v_max_f32_e32 v52, 0, v52
	v_max_f32_e32 v48, 0, v48
	v_max_f32_e32 v53, 0, v53
	v_max_f32_e32 v49, 0, v49
	v_pk_mul_f32 v[58:59], v[50:51], v[50:51]
	v_pk_mul_f32 v[52:53], v[52:53], v[52:53]
	v_pk_mul_f32 v[56:57], v[48:49], v[48:49]
	v_max_f32_e32 v48, 0, v54
	v_max_f32_e32 v49, 0, v55
	v_pk_mul_f32 v[54:55], v[48:49], v[48:49]
	v_cvt_pk_bf16_f32 v48, v52, v53
	v_cvt_pk_bf16_f32 v49, v54, v55
	v_cvt_pk_bf16_f32 v50, v56, v57
	v_cvt_pk_bf16_f32 v51, v58, v59
	global_store_dwordx4 v[66:67], v[48:51], off offset:256
	s_nop 1
	v_mov_b32_e32 v48, v233
	v_pk_mul_f32 v[40:41], v[40:41], v[48:49] op_sel_hi:[1,0]
	v_pk_mul_f32 v[46:47], v[46:47], v[48:49] op_sel_hi:[1,0]
	v_pk_mul_f32 v[44:45], v[44:45], v[48:49] op_sel_hi:[1,0]
	v_pk_mul_f32 v[42:43], v[42:43], v[48:49] op_sel_hi:[1,0]
	v_max_f32_e32 v40, 0, v40
	v_max_f32_e32 v41, 0, v41
	v_lshlrev_b64 v[50:51], 13, v[156:157]
	v_max_f32_e32 v44, 0, v44
	v_max_f32_e32 v45, 0, v45
	v_pk_mul_f32 v[52:53], v[40:41], v[40:41]
	v_max_f32_e32 v40, 0, v46
	v_max_f32_e32 v42, 0, v42
	v_max_f32_e32 v41, 0, v47
	v_max_f32_e32 v43, 0, v43
	v_lshl_add_u64 v[50:51], s[96:97], 0, v[50:51]
	v_pk_mul_f32 v[44:45], v[44:45], v[44:45]
	v_pk_mul_f32 v[46:47], v[40:41], v[40:41]
	v_pk_mul_f32 v[54:55], v[42:43], v[42:43]
	v_pk_mul_f32 v[32:33], v[32:33], v[48:49] op_sel_hi:[1,0]
	v_lshl_add_u64 v[50:51], v[50:51], 0, v[148:149]
	v_cvt_pk_bf16_f32 v40, v44, v45
	v_cvt_pk_bf16_f32 v41, v46, v47
	v_cvt_pk_bf16_f32 v42, v52, v53
	v_cvt_pk_bf16_f32 v43, v54, v55
	v_pk_mul_f32 v[38:39], v[38:39], v[48:49] op_sel_hi:[1,0]
	v_max_f32_e32 v32, 0, v32
	v_max_f32_e32 v33, 0, v33
	global_store_dwordx4 v[50:51], v[40:43], off
	v_pk_mul_f32 v[36:37], v[36:37], v[48:49] op_sel_hi:[1,0]
	v_pk_mul_f32 v[34:35], v[34:35], v[48:49] op_sel_hi:[1,0]
	v_pk_mul_f32 v[40:41], v[32:33], v[32:33]
	v_max_f32_e32 v32, 0, v38
	v_max_f32_e32 v33, 0, v39
	v_max_f32_e32 v36, 0, v36
	v_max_f32_e32 v37, 0, v37
	v_pk_mul_f32 v[36:37], v[36:37], v[36:37]
	v_pk_mul_f32 v[44:45], v[32:33], v[32:33]
	v_cvt_pk_bf16_f32 v32, v36, v37
	s_waitcnt lgkmcnt(0)
	v_max_f32_e32 v34, 0, v34
	v_max_f32_e32 v35, 0, v35
	v_pk_mul_f32 v[46:47], v[34:35], v[34:35]
	v_cvt_pk_bf16_f32 v33, v44, v45
	v_cvt_pk_bf16_f32 v34, v40, v41
	v_cvt_pk_bf16_f32 v35, v46, v47
	global_store_dwordx4 v[50:51], v[32:35], off offset:256
	s_waitcnt lgkmcnt(0)
	s_nop 0
	s_nop 0
	s_nop 0
	s_nop 1
	v_lshlrev_b64 v[34:35], 13, v[150:151]
	v_lshl_add_u64 v[34:35], s[96:97], 0, v[34:35]
	v_lshl_add_u64 v[34:35], v[34:35], 0, v[148:149]
	v_mov_b32_e32 v36, v234
	v_pk_mul_f32 v[24:25], v[24:25], v[36:37] op_sel_hi:[1,0]
	v_pk_mul_f32 v[30:31], v[30:31], v[36:37] op_sel_hi:[1,0]
	v_pk_mul_f32 v[28:29], v[28:29], v[36:37] op_sel_hi:[1,0]
	v_pk_mul_f32 v[26:27], v[26:27], v[36:37] op_sel_hi:[1,0]
	v_max_f32_e32 v24, 0, v24
	v_max_f32_e32 v25, 0, v25
	v_max_f32_e32 v28, 0, v28
	v_max_f32_e32 v29, 0, v29
	v_pk_mul_f32 v[38:39], v[24:25], v[24:25]
	v_max_f32_e32 v24, 0, v30
	v_max_f32_e32 v26, 0, v26
	v_max_f32_e32 v25, 0, v31
	v_max_f32_e32 v27, 0, v27
	v_pk_mul_f32 v[28:29], v[28:29], v[28:29]
	v_pk_mul_f32 v[30:31], v[24:25], v[24:25]
	v_pk_mul_f32 v[40:41], v[26:27], v[26:27]
	v_pk_mul_f32 v[18:19], v[18:19], v[36:37] op_sel_hi:[1,0]
	v_cvt_pk_bf16_f32 v24, v28, v29
	v_cvt_pk_bf16_f32 v25, v30, v31
	v_cvt_pk_bf16_f32 v26, v38, v39
	v_cvt_pk_bf16_f32 v27, v40, v41
	v_pk_mul_f32 v[20:21], v[20:21], v[36:37] op_sel_hi:[1,0]
	v_pk_mul_f32 v[16:17], v[16:17], v[36:37] op_sel_hi:[1,0]
	v_max_f32_e32 v18, 0, v18
	v_max_f32_e32 v19, 0, v19
	global_store_dwordx4 v[34:35], v[24:27], off
	v_pk_mul_f32 v[22:23], v[22:23], v[36:37] op_sel_hi:[1,0]
	v_max_f32_e32 v20, 0, v20
	v_max_f32_e32 v16, 0, v16
	v_max_f32_e32 v21, 0, v21
	v_max_f32_e32 v17, 0, v17
	v_pk_mul_f32 v[26:27], v[18:19], v[18:19]
	v_pk_mul_f32 v[20:21], v[20:21], v[20:21]
	v_pk_mul_f32 v[24:25], v[16:17], v[16:17]
	v_max_f32_e32 v16, 0, v22
	v_max_f32_e32 v17, 0, v23
	v_pk_mul_f32 v[22:23], v[16:17], v[16:17]
	v_cvt_pk_bf16_f32 v16, v20, v21
	v_cvt_pk_bf16_f32 v17, v22, v23
	v_cvt_pk_bf16_f32 v18, v24, v25
	v_cvt_pk_bf16_f32 v19, v26, v27
	global_store_dwordx4 v[34:35], v[16:19], off offset:256
	s_nop 1
	v_mov_b32_e32 v16, v235
	v_pk_mul_f32 v[8:9], v[8:9], v[16:17] op_sel_hi:[1,0]
	v_pk_mul_f32 v[14:15], v[14:15], v[16:17] op_sel_hi:[1,0]
	v_pk_mul_f32 v[12:13], v[12:13], v[16:17] op_sel_hi:[1,0]
	v_pk_mul_f32 v[10:11], v[10:11], v[16:17] op_sel_hi:[1,0]
	v_max_f32_e32 v8, 0, v8
	v_max_f32_e32 v9, 0, v9
	v_lshlrev_b64 v[18:19], 13, v[146:147]
	v_max_f32_e32 v12, 0, v12
	v_max_f32_e32 v13, 0, v13
	v_pk_mul_f32 v[20:21], v[8:9], v[8:9]
	v_max_f32_e32 v8, 0, v14
	v_max_f32_e32 v10, 0, v10
	v_max_f32_e32 v9, 0, v15
	v_max_f32_e32 v11, 0, v11
	v_lshl_add_u64 v[18:19], s[96:97], 0, v[18:19]
	v_pk_mul_f32 v[12:13], v[12:13], v[12:13]
	v_pk_mul_f32 v[14:15], v[8:9], v[8:9]
	v_pk_mul_f32 v[22:23], v[10:11], v[10:11]
	v_pk_mul_f32 v[0:1], v[0:1], v[16:17] op_sel_hi:[1,0]
	v_lshl_add_u64 v[18:19], v[18:19], 0, v[148:149]
	v_cvt_pk_bf16_f32 v8, v12, v13
	v_cvt_pk_bf16_f32 v9, v14, v15
	v_cvt_pk_bf16_f32 v10, v20, v21
	v_cvt_pk_bf16_f32 v11, v22, v23
	v_pk_mul_f32 v[6:7], v[6:7], v[16:17] op_sel_hi:[1,0]
	v_pk_mul_f32 v[4:5], v[4:5], v[16:17] op_sel_hi:[1,0]
	v_pk_mul_f32 v[2:3], v[2:3], v[16:17] op_sel_hi:[1,0]
	v_max_f32_e32 v0, 0, v0
	v_max_f32_e32 v1, 0, v1
	global_store_dwordx4 v[18:19], v[8:11], off
	v_max_f32_e32 v4, 0, v4
	v_max_f32_e32 v5, 0, v5
	v_pk_mul_f32 v[8:9], v[0:1], v[0:1]
	v_max_f32_e32 v0, 0, v6
	v_max_f32_e32 v2, 0, v2
	v_max_f32_e32 v1, 0, v7
	v_max_f32_e32 v3, 0, v3
	v_pk_mul_f32 v[4:5], v[4:5], v[4:5]
	v_pk_mul_f32 v[6:7], v[0:1], v[0:1]
	v_pk_mul_f32 v[10:11], v[2:3], v[2:3]
	v_cvt_pk_bf16_f32 v0, v4, v5
	v_cvt_pk_bf16_f32 v1, v6, v7
	v_cvt_pk_bf16_f32 v2, v8, v9
	v_cvt_pk_bf16_f32 v3, v10, v11
	s_and_b64 vcc, exec, s[0:1]
	global_store_dwordx4 v[18:19], v[0:3], off offset:256
	s_cbranch_vccz .LBB0_763
	s_waitcnt vmcnt(0)
	s_cmpk_gt_u32 s9, 0xff
	s_cbranch_scc1 .LBB0_774
	s_barrier

.LBB0_843:
	s_ashr_i32 s17, s16, 31
	v_cmp_lt_i64_e32 vcc, s[18:19], v[166:167]
	s_lshl_b64 s[18:19], s[16:17], 21
	s_add_u32 s18, s96, s18
	s_addc_u32 s19, s97, s19
	s_and_b64 s[20:21], vcc, exec
	s_cselect_b32 s17, s19, s23
	s_cselect_b32 s44, s18, s22
	s_ashr_i32 s15, s14, 31
	s_lshl_b64 s[20:21], s[14:15], 21
	s_add_u32 s20, s29, s20
	s_addc_u32 s21, s30, s21
	s_and_b64 s[26:27], vcc, exec
	s_cselect_b32 s15, s21, s25
	s_cselect_b32 s45, s20, s24
	s_add_u32 s22, s22, 0x100080
	s_addc_u32 s23, s23, 0
	s_add_u32 s46, s24, 0x100
	s_addc_u32 s47, s25, 0
	s_mov_b32 s48, -2
	s_waitcnt lgkmcnt(0)
	ds_read_b128 v[128:131], v191
	ds_read_b128 v[132:135], v191 offset:1024
	ds_read_b128 v[136:139], v191 offset:2048
	ds_read_b128 v[140:143], v191 offset:3072
	s_add_u32 s24, s22, 0xfff00080
	s_addc_u32 s25, s23, -1
	s_cmp_eq_u32 s48, 60
	s_cselect_b32 s27, s17, s25
	s_cselect_b32 s26, s44, s24
	s_cselect_b32 s25, s15, s47
	s_cselect_b32 s24, s45, s46
	v_lshl_add_u64 v[186:187], s[22:23], 0, v[162:163]
	s_add_i32 m0, s7, 0xc000
	ds_read_b128 v[144:147], v192
	ds_read_b128 v[148:151], v192 offset:1024
	ds_read_b128 v[170:173], v192 offset:2048
	ds_read_b128 v[174:177], v192 offset:3072
	ds_read_b128 v[178:181], v192 offset:4096
	ds_read_b128 v[182:185], v192 offset:5120
	ds_read_b128 v[196:199], v192 offset:6144
	ds_read_b128 v[200:203], v192 offset:7168
	global_load_lds_dwordx4 v[186:187], off
	v_lshl_add_u64 v[186:187], s[22:23], 0, v[164:165]
	s_add_i32 m0, s7, 0xe000
	s_nop 0
	global_load_lds_dwordx4 v[186:187], off
	s_waitcnt lgkmcnt(8)
	s_barrier
	s_waitcnt lgkmcnt(0)
	v_mfma_f32_16x16x32_bf16 v[124:127], v[128:131], v[144:147], 0
	v_mfma_f32_16x16x32_bf16 v[120:123], v[136:139], v[144:147], 0
	v_mfma_f32_16x16x32_bf16 v[108:111], v[128:131], v[170:173], 0
	v_mfma_f32_16x16x32_bf16 v[104:107], v[136:139], v[170:173], 0
	v_mfma_f32_16x16x32_bf16 v[92:95], v[128:131], v[178:181], 0
	v_mfma_f32_16x16x32_bf16 v[88:91], v[136:139], v[178:181], 0
	v_mfma_f32_16x16x32_bf16 v[76:79], v[128:131], v[196:199], 0
	v_mfma_f32_16x16x32_bf16 v[72:75], v[136:139], v[196:199], 0
	v_mfma_f32_16x16x32_bf16 v[124:127], v[132:135], v[148:151], v[124:127]
	v_mfma_f32_16x16x32_bf16 v[120:123], v[140:143], v[148:151], v[120:123]
	v_mfma_f32_16x16x32_bf16 v[108:111], v[132:135], v[174:177], v[108:111]
	v_mfma_f32_16x16x32_bf16 v[104:107], v[140:143], v[174:177], v[104:107]
	v_mfma_f32_16x16x32_bf16 v[92:95], v[132:135], v[182:185], v[92:95]
	v_mfma_f32_16x16x32_bf16 v[88:91], v[140:143], v[182:185], v[88:91]
	v_mfma_f32_16x16x32_bf16 v[76:79], v[132:135], v[200:203], v[76:79]
	v_mfma_f32_16x16x32_bf16 v[72:75], v[140:143], v[200:203], v[72:75]
	s_barrier
	s_add_i32 s49, s42, s31
	v_lshl_add_u64 v[186:187], s[24:25], 0, v[156:157]
	s_mov_b32 m0, s49
	ds_read_b128 v[204:207], v193
	ds_read_b128 v[208:211], v193 offset:1024
	ds_read_b128 v[212:215], v193 offset:2048
	ds_read_b128 v[216:219], v193 offset:3072
	global_load_lds_dwordx4 v[186:187], off
	v_lshl_add_u64 v[220:221], s[24:25], 0, v[160:161]
	s_add_i32 m0, s49, 0x2000
	s_nop 0
	global_load_lds_dwordx4 v[220:221], off
	s_barrier
	s_waitcnt lgkmcnt(0)
	v_mfma_f32_16x16x32_bf16 v[116:119], v[204:207], v[144:147], 0
	v_mfma_f32_16x16x32_bf16 v[112:115], v[212:215], v[144:147], 0
	v_mfma_f32_16x16x32_bf16 v[100:103], v[204:207], v[170:173], 0
	v_mfma_f32_16x16x32_bf16 v[96:99], v[212:215], v[170:173], 0
	v_mfma_f32_16x16x32_bf16 v[84:87], v[204:207], v[178:181], 0
	v_mfma_f32_16x16x32_bf16 v[80:83], v[212:215], v[178:181], 0
	v_mfma_f32_16x16x32_bf16 v[68:71], v[204:207], v[196:199], 0
	v_mfma_f32_16x16x32_bf16 v[64:67], v[212:215], v[196:199], 0
	v_mfma_f32_16x16x32_bf16 v[116:119], v[208:211], v[148:151], v[116:119]
	v_mfma_f32_16x16x32_bf16 v[112:115], v[216:219], v[148:151], v[112:115]
	v_mfma_f32_16x16x32_bf16 v[100:103], v[208:211], v[174:177], v[100:103]
	v_mfma_f32_16x16x32_bf16 v[96:99], v[216:219], v[174:177], v[96:99]
	v_mfma_f32_16x16x32_bf16 v[84:87], v[208:211], v[182:185], v[84:87]
	v_mfma_f32_16x16x32_bf16 v[80:83], v[216:219], v[182:185], v[80:83]
	v_mfma_f32_16x16x32_bf16 v[68:71], v[208:211], v[200:203], v[68:71]
	v_mfma_f32_16x16x32_bf16 v[64:67], v[216:219], v[200:203], v[64:67]
	s_mov_b32 m0, s7
	v_lshl_add_u64 v[222:223], s[26:27], 0, v[154:155]
	s_barrier
	ds_read_b128 v[144:147], v192 offset:16384
	ds_read_b128 v[148:151], v192 offset:17408
	ds_read_b128 v[170:173], v192 offset:18432
	ds_read_b128 v[174:177], v192 offset:19456
	ds_read_b128 v[178:181], v192 offset:20480
	ds_read_b128 v[182:185], v192 offset:21504
	ds_read_b128 v[196:199], v192 offset:22528
	ds_read_b128 v[200:203], v192 offset:23552
	global_load_lds_dwordx4 v[222:223], off
	v_lshl_add_u64 v[224:225], s[26:27], 0, v[158:159]
	s_mov_b32 m0, s34
	s_nop 0
	global_load_lds_dwordx4 v[224:225], off
	s_barrier
	s_waitcnt lgkmcnt(0)
	v_mfma_f32_16x16x32_bf16 v[60:63], v[128:131], v[144:147], 0
	v_mfma_f32_16x16x32_bf16 v[56:59], v[136:139], v[144:147], 0
	v_mfma_f32_16x16x32_bf16 v[44:47], v[128:131], v[170:173], 0
	v_mfma_f32_16x16x32_bf16 v[40:43], v[136:139], v[170:173], 0
	v_mfma_f32_16x16x32_bf16 v[28:31], v[128:131], v[178:181], 0
	v_mfma_f32_16x16x32_bf16 v[24:27], v[136:139], v[178:181], 0
	v_mfma_f32_16x16x32_bf16 v[12:15], v[128:131], v[196:199], 0
	v_mfma_f32_16x16x32_bf16 v[8:11], v[136:139], v[196:199], 0
	v_mfma_f32_16x16x32_bf16 v[60:63], v[132:135], v[148:151], v[60:63]
	v_mfma_f32_16x16x32_bf16 v[56:59], v[140:143], v[148:151], v[56:59]
	v_mfma_f32_16x16x32_bf16 v[44:47], v[132:135], v[174:177], v[44:47]
	v_mfma_f32_16x16x32_bf16 v[40:43], v[140:143], v[174:177], v[40:43]
	v_mfma_f32_16x16x32_bf16 v[28:31], v[132:135], v[182:185], v[28:31]
	v_mfma_f32_16x16x32_bf16 v[24:27], v[140:143], v[182:185], v[24:27]
	v_mfma_f32_16x16x32_bf16 v[12:15], v[132:135], v[200:203], v[12:15]
	v_mfma_f32_16x16x32_bf16 v[8:11], v[140:143], v[200:203], v[8:11]
	s_barrier
	s_add_u32 s50, s24, 0x100000
	s_addc_u32 s51, s25, 0
	s_add_i32 s49, s43, s31
	v_lshl_add_u64 v[128:129], s[50:51], 0, v[156:157]
	s_mov_b32 m0, s49
	s_nop 0
	global_load_lds_dwordx4 v[128:129], off
	v_lshl_add_u64 v[128:129], s[50:51], 0, v[160:161]
	s_add_i32 m0, s49, 0x2000
	s_nop 0
	global_load_lds_dwordx4 v[128:129], off
	s_waitcnt vmcnt(6)
	s_barrier
	v_mfma_f32_16x16x32_bf16 v[52:55], v[204:207], v[144:147], 0
	v_mfma_f32_16x16x32_bf16 v[48:51], v[212:215], v[144:147], 0
	v_mfma_f32_16x16x32_bf16 v[36:39], v[204:207], v[170:173], 0
	v_mfma_f32_16x16x32_bf16 v[32:35], v[212:215], v[170:173], 0
	v_mfma_f32_16x16x32_bf16 v[20:23], v[204:207], v[178:181], 0
	v_mfma_f32_16x16x32_bf16 v[16:19], v[212:215], v[178:181], 0
	v_mfma_f32_16x16x32_bf16 v[4:7], v[204:207], v[196:199], 0
	v_mfma_f32_16x16x32_bf16 v[0:3], v[212:215], v[196:199], 0
	v_mfma_f32_16x16x32_bf16 v[52:55], v[208:211], v[148:151], v[52:55]
	v_mfma_f32_16x16x32_bf16 v[48:51], v[216:219], v[148:151], v[48:51]
	v_mfma_f32_16x16x32_bf16 v[36:39], v[208:211], v[174:177], v[36:39]
	v_mfma_f32_16x16x32_bf16 v[32:35], v[216:219], v[174:177], v[32:35]
	v_mfma_f32_16x16x32_bf16 v[20:23], v[208:211], v[182:185], v[20:23]
	v_mfma_f32_16x16x32_bf16 v[16:19], v[216:219], v[182:185], v[16:19]
	v_mfma_f32_16x16x32_bf16 v[4:7], v[208:211], v[200:203], v[4:7]
	v_mfma_f32_16x16x32_bf16 v[0:3], v[216:219], v[200:203], v[0:3]
	s_add_i32 s49, 0, 0x18000
	v_add_u32_e32 v140, s49, v189
	s_barrier
	ds_read_b128 v[128:131], v140
	ds_read_b128 v[132:135], v140 offset:1024
	ds_read_b128 v[136:139], v140 offset:2048
	ds_read_b128 v[140:143], v140 offset:3072
	s_add_u32 s26, s26, 0x100000
	s_addc_u32 s27, s27, 0
	s_mov_b32 m0, s35
	v_lshl_add_u64 v[204:205], s[26:27], 0, v[154:155]
	ds_read_b128 v[144:147], v192 offset:32768
	ds_read_b128 v[148:151], v192 offset:33792
	ds_read_b128 v[170:173], v192 offset:34816
	ds_read_b128 v[174:177], v192 offset:35840
	ds_read_b128 v[178:181], v192 offset:36864
	ds_read_b128 v[182:185], v192 offset:37888
	ds_read_b128 v[196:199], v192 offset:38912
	ds_read_b128 v[200:203], v192 offset:39936
	global_load_lds_dwordx4 v[204:205], off
	v_lshl_add_u64 v[204:205], s[26:27], 0, v[158:159]
	s_mov_b32 m0, s36
	s_nop 0
	global_load_lds_dwordx4 v[204:205], off
	s_waitcnt lgkmcnt(8)
	s_barrier
	s_waitcnt lgkmcnt(0)
	v_mfma_f32_16x16x32_bf16 v[124:127], v[128:131], v[144:147], v[124:127]
	v_mfma_f32_16x16x32_bf16 v[120:123], v[136:139], v[144:147], v[120:123]
	v_mfma_f32_16x16x32_bf16 v[108:111], v[128:131], v[170:173], v[108:111]
	v_mfma_f32_16x16x32_bf16 v[104:107], v[136:139], v[170:173], v[104:107]
	v_mfma_f32_16x16x32_bf16 v[92:95], v[128:131], v[178:181], v[92:95]
	v_mfma_f32_16x16x32_bf16 v[88:91], v[136:139], v[178:181], v[88:91]
	v_mfma_f32_16x16x32_bf16 v[76:79], v[128:131], v[196:199], v[76:79]
	v_mfma_f32_16x16x32_bf16 v[72:75], v[136:139], v[196:199], v[72:75]
	v_mfma_f32_16x16x32_bf16 v[124:127], v[132:135], v[148:151], v[124:127]
	v_mfma_f32_16x16x32_bf16 v[120:123], v[140:143], v[148:151], v[120:123]
	v_mfma_f32_16x16x32_bf16 v[108:111], v[132:135], v[174:177], v[108:111]
	v_mfma_f32_16x16x32_bf16 v[104:107], v[140:143], v[174:177], v[104:107]
	v_mfma_f32_16x16x32_bf16 v[92:95], v[132:135], v[182:185], v[92:95]
	v_mfma_f32_16x16x32_bf16 v[88:91], v[140:143], v[182:185], v[88:91]
	v_mfma_f32_16x16x32_bf16 v[76:79], v[132:135], v[200:203], v[76:79]
	v_mfma_f32_16x16x32_bf16 v[72:75], v[140:143], v[200:203], v[72:75]
	s_barrier
	s_add_i32 s26, 0, 0x1c000
	s_add_i32 s27, s49, s31
	v_add_u32_e32 v195, s26, v189
	v_lshl_add_u64 v[186:187], v[186:187], 0, s[12:13]
	s_mov_b32 m0, s27
	ds_read_b128 v[204:207], v195
	ds_read_b128 v[208:211], v195 offset:1024
	ds_read_b128 v[212:215], v195 offset:2048
	ds_read_b128 v[216:219], v195 offset:3072
	global_load_lds_dwordx4 v[186:187], off
	v_lshl_add_u64 v[186:187], v[220:221], 0, s[12:13]
	s_add_i32 m0, s27, 0x2000
	s_nop 0
	global_load_lds_dwordx4 v[186:187], off
	s_barrier
	s_waitcnt lgkmcnt(0)
	v_mfma_f32_16x16x32_bf16 v[116:119], v[204:207], v[144:147], v[116:119]
	v_mfma_f32_16x16x32_bf16 v[112:115], v[212:215], v[144:147], v[112:115]
	v_mfma_f32_16x16x32_bf16 v[100:103], v[204:207], v[170:173], v[100:103]
	v_mfma_f32_16x16x32_bf16 v[96:99], v[212:215], v[170:173], v[96:99]
	v_mfma_f32_16x16x32_bf16 v[84:87], v[204:207], v[178:181], v[84:87]
	v_mfma_f32_16x16x32_bf16 v[80:83], v[212:215], v[178:181], v[80:83]
	v_mfma_f32_16x16x32_bf16 v[68:71], v[204:207], v[196:199], v[68:71]
	v_mfma_f32_16x16x32_bf16 v[64:67], v[212:215], v[196:199], v[64:67]
	v_mfma_f32_16x16x32_bf16 v[116:119], v[208:211], v[148:151], v[116:119]
	v_mfma_f32_16x16x32_bf16 v[112:115], v[216:219], v[148:151], v[112:115]
	v_mfma_f32_16x16x32_bf16 v[100:103], v[208:211], v[174:177], v[100:103]
	v_mfma_f32_16x16x32_bf16 v[96:99], v[216:219], v[174:177], v[96:99]
	v_mfma_f32_16x16x32_bf16 v[84:87], v[208:211], v[182:185], v[84:87]
	v_mfma_f32_16x16x32_bf16 v[80:83], v[216:219], v[182:185], v[80:83]
	v_mfma_f32_16x16x32_bf16 v[68:71], v[208:211], v[200:203], v[68:71]
	v_mfma_f32_16x16x32_bf16 v[64:67], v[216:219], v[200:203], v[64:67]
	s_mov_b32 m0, s38
	v_lshl_add_u64 v[186:187], v[222:223], 0, s[12:13]
	s_barrier
	ds_read_b128 v[144:147], v192 offset:49152
	ds_read_b128 v[148:151], v192 offset:50176
	ds_read_b128 v[170:173], v192 offset:51200
	ds_read_b128 v[174:177], v192 offset:52224
	ds_read_b128 v[178:181], v192 offset:53248
	ds_read_b128 v[182:185], v192 offset:54272
	ds_read_b128 v[196:199], v192 offset:55296
	ds_read_b128 v[200:203], v192 offset:56320
	global_load_lds_dwordx4 v[186:187], off
	v_lshl_add_u64 v[186:187], v[224:225], 0, s[12:13]
	s_mov_b32 m0, s39
	s_nop 0
	global_load_lds_dwordx4 v[186:187], off
	s_barrier
	s_waitcnt lgkmcnt(0)
	v_mfma_f32_16x16x32_bf16 v[60:63], v[128:131], v[144:147], v[60:63]
	v_mfma_f32_16x16x32_bf16 v[56:59], v[136:139], v[144:147], v[56:59]
	v_mfma_f32_16x16x32_bf16 v[44:47], v[128:131], v[170:173], v[44:47]
	v_mfma_f32_16x16x32_bf16 v[40:43], v[136:139], v[170:173], v[40:43]
	v_mfma_f32_16x16x32_bf16 v[28:31], v[128:131], v[178:181], v[28:31]
	v_mfma_f32_16x16x32_bf16 v[24:27], v[136:139], v[178:181], v[24:27]
	v_mfma_f32_16x16x32_bf16 v[12:15], v[128:131], v[196:199], v[12:15]
	v_mfma_f32_16x16x32_bf16 v[8:11], v[136:139], v[196:199], v[8:11]
	v_mfma_f32_16x16x32_bf16 v[60:63], v[132:135], v[148:151], v[60:63]
	v_mfma_f32_16x16x32_bf16 v[56:59], v[140:143], v[148:151], v[56:59]
	v_mfma_f32_16x16x32_bf16 v[44:47], v[132:135], v[174:177], v[44:47]
	v_mfma_f32_16x16x32_bf16 v[40:43], v[140:143], v[174:177], v[40:43]
	v_mfma_f32_16x16x32_bf16 v[28:31], v[132:135], v[182:185], v[28:31]
	v_mfma_f32_16x16x32_bf16 v[24:27], v[140:143], v[182:185], v[24:27]
	v_mfma_f32_16x16x32_bf16 v[12:15], v[132:135], v[200:203], v[12:15]
	v_mfma_f32_16x16x32_bf16 v[8:11], v[140:143], v[200:203], v[8:11]
	s_barrier
	s_add_u32 s24, s24, 0x100080
	s_addc_u32 s25, s25, 0
	s_add_i32 s26, s26, s31
	v_lshl_add_u64 v[128:129], s[24:25], 0, v[156:157]
	s_mov_b32 m0, s26
	s_nop 0
	global_load_lds_dwordx4 v[128:129], off
	v_lshl_add_u64 v[128:129], s[24:25], 0, v[160:161]
	s_add_i32 m0, s26, 0x2000
	s_nop 0
	global_load_lds_dwordx4 v[128:129], off
	s_waitcnt vmcnt(6)
	s_barrier
	v_mfma_f32_16x16x32_bf16 v[52:55], v[204:207], v[144:147], v[52:55]
	v_mfma_f32_16x16x32_bf16 v[48:51], v[212:215], v[144:147], v[48:51]
	v_mfma_f32_16x16x32_bf16 v[36:39], v[204:207], v[170:173], v[36:39]
	v_mfma_f32_16x16x32_bf16 v[32:35], v[212:215], v[170:173], v[32:35]
	v_mfma_f32_16x16x32_bf16 v[20:23], v[204:207], v[178:181], v[20:23]
	v_mfma_f32_16x16x32_bf16 v[16:19], v[212:215], v[178:181], v[16:19]
	v_mfma_f32_16x16x32_bf16 v[4:7], v[204:207], v[196:199], v[4:7]
	v_mfma_f32_16x16x32_bf16 v[0:3], v[212:215], v[196:199], v[0:3]
	v_mfma_f32_16x16x32_bf16 v[52:55], v[208:211], v[148:151], v[52:55]
	v_mfma_f32_16x16x32_bf16 v[48:51], v[216:219], v[148:151], v[48:51]
	v_mfma_f32_16x16x32_bf16 v[36:39], v[208:211], v[174:177], v[36:39]
	v_mfma_f32_16x16x32_bf16 v[32:35], v[216:219], v[174:177], v[32:35]
	v_mfma_f32_16x16x32_bf16 v[20:23], v[208:211], v[182:185], v[20:23]
	v_mfma_f32_16x16x32_bf16 v[16:19], v[216:219], v[182:185], v[16:19]
	v_mfma_f32_16x16x32_bf16 v[4:7], v[208:211], v[200:203], v[4:7]
	v_mfma_f32_16x16x32_bf16 v[0:3], v[216:219], v[200:203], v[0:3]
	s_add_i32 s48, s48, 2
	s_add_u32 s22, s22, 0x100
	s_addc_u32 s23, s23, 0
	s_add_u32 s46, s46, 0x100
	s_addc_u32 s47, s47, 0
	s_cmp_gt_u32 s48, 61
	s_barrier
.LBB0_844:
	ds_read_b128 v[128:131], v191
	ds_read_b128 v[132:135], v191 offset:1024
	ds_read_b128 v[136:139], v191 offset:2048
	ds_read_b128 v[140:143], v191 offset:3072
	s_add_u32 s24, s22, 0xfff00080
	s_addc_u32 s25, s23, -1
	s_cmp_eq_u32 s48, 60
	s_cselect_b32 s27, s17, s25
	s_cselect_b32 s26, s44, s24
	s_cselect_b32 s25, s15, s47
	s_cselect_b32 s24, s45, s46
	v_lshl_add_u64 v[186:187], s[22:23], 0, v[162:163]
	s_add_i32 m0, s7, 0xc000
	ds_read_b128 v[144:147], v192
	ds_read_b128 v[148:151], v192 offset:1024
	ds_read_b128 v[170:173], v192 offset:2048
	ds_read_b128 v[174:177], v192 offset:3072
	ds_read_b128 v[178:181], v192 offset:4096
	ds_read_b128 v[182:185], v192 offset:5120
	ds_read_b128 v[196:199], v192 offset:6144
	ds_read_b128 v[200:203], v192 offset:7168
	global_load_lds_dwordx4 v[186:187], off
	v_lshl_add_u64 v[186:187], s[22:23], 0, v[164:165]
	s_add_i32 m0, s7, 0xe000
	s_nop 0
	global_load_lds_dwordx4 v[186:187], off
	s_waitcnt lgkmcnt(8)
	s_barrier
	s_waitcnt lgkmcnt(0)
	v_mfma_f32_16x16x32_bf16 v[124:127], v[128:131], v[144:147], v[124:127]
	v_mfma_f32_16x16x32_bf16 v[120:123], v[136:139], v[144:147], v[120:123]
	v_mfma_f32_16x16x32_bf16 v[108:111], v[128:131], v[170:173], v[108:111]
	v_mfma_f32_16x16x32_bf16 v[104:107], v[136:139], v[170:173], v[104:107]
	v_mfma_f32_16x16x32_bf16 v[92:95], v[128:131], v[178:181], v[92:95]
	v_mfma_f32_16x16x32_bf16 v[88:91], v[136:139], v[178:181], v[88:91]
	v_mfma_f32_16x16x32_bf16 v[76:79], v[128:131], v[196:199], v[76:79]
	v_mfma_f32_16x16x32_bf16 v[72:75], v[136:139], v[196:199], v[72:75]
	v_mfma_f32_16x16x32_bf16 v[124:127], v[132:135], v[148:151], v[124:127]
	v_mfma_f32_16x16x32_bf16 v[120:123], v[140:143], v[148:151], v[120:123]
	v_mfma_f32_16x16x32_bf16 v[108:111], v[132:135], v[174:177], v[108:111]
	v_mfma_f32_16x16x32_bf16 v[104:107], v[140:143], v[174:177], v[104:107]
	v_mfma_f32_16x16x32_bf16 v[92:95], v[132:135], v[182:185], v[92:95]
	v_mfma_f32_16x16x32_bf16 v[88:91], v[140:143], v[182:185], v[88:91]
	v_mfma_f32_16x16x32_bf16 v[76:79], v[132:135], v[200:203], v[76:79]
	v_mfma_f32_16x16x32_bf16 v[72:75], v[140:143], v[200:203], v[72:75]
	s_barrier
	s_add_i32 s49, s42, s31
	v_lshl_add_u64 v[186:187], s[24:25], 0, v[156:157]
	s_mov_b32 m0, s49
	ds_read_b128 v[204:207], v193
	ds_read_b128 v[208:211], v193 offset:1024
	ds_read_b128 v[212:215], v193 offset:2048
	ds_read_b128 v[216:219], v193 offset:3072
	global_load_lds_dwordx4 v[186:187], off
	v_lshl_add_u64 v[220:221], s[24:25], 0, v[160:161]
	s_add_i32 m0, s49, 0x2000
	s_nop 0
	global_load_lds_dwordx4 v[220:221], off
	s_barrier
	s_waitcnt lgkmcnt(0)
	v_mfma_f32_16x16x32_bf16 v[116:119], v[204:207], v[144:147], v[116:119]
	v_mfma_f32_16x16x32_bf16 v[112:115], v[212:215], v[144:147], v[112:115]
	v_mfma_f32_16x16x32_bf16 v[100:103], v[204:207], v[170:173], v[100:103]
	v_mfma_f32_16x16x32_bf16 v[96:99], v[212:215], v[170:173], v[96:99]
	v_mfma_f32_16x16x32_bf16 v[84:87], v[204:207], v[178:181], v[84:87]
	v_mfma_f32_16x16x32_bf16 v[80:83], v[212:215], v[178:181], v[80:83]
	v_mfma_f32_16x16x32_bf16 v[68:71], v[204:207], v[196:199], v[68:71]
	v_mfma_f32_16x16x32_bf16 v[64:67], v[212:215], v[196:199], v[64:67]
	v_mfma_f32_16x16x32_bf16 v[116:119], v[208:211], v[148:151], v[116:119]
	v_mfma_f32_16x16x32_bf16 v[112:115], v[216:219], v[148:151], v[112:115]
	v_mfma_f32_16x16x32_bf16 v[100:103], v[208:211], v[174:177], v[100:103]
	v_mfma_f32_16x16x32_bf16 v[96:99], v[216:219], v[174:177], v[96:99]
	v_mfma_f32_16x16x32_bf16 v[84:87], v[208:211], v[182:185], v[84:87]
	v_mfma_f32_16x16x32_bf16 v[80:83], v[216:219], v[182:185], v[80:83]
	v_mfma_f32_16x16x32_bf16 v[68:71], v[208:211], v[200:203], v[68:71]
	v_mfma_f32_16x16x32_bf16 v[64:67], v[216:219], v[200:203], v[64:67]
	s_mov_b32 m0, s7
	v_lshl_add_u64 v[222:223], s[26:27], 0, v[154:155]
	s_barrier
	ds_read_b128 v[144:147], v192 offset:16384
	ds_read_b128 v[148:151], v192 offset:17408
	ds_read_b128 v[170:173], v192 offset:18432
	ds_read_b128 v[174:177], v192 offset:19456
	ds_read_b128 v[178:181], v192 offset:20480
	ds_read_b128 v[182:185], v192 offset:21504
	ds_read_b128 v[196:199], v192 offset:22528
	ds_read_b128 v[200:203], v192 offset:23552
	global_load_lds_dwordx4 v[222:223], off
	v_lshl_add_u64 v[224:225], s[26:27], 0, v[158:159]
	s_mov_b32 m0, s34
	s_nop 0
	global_load_lds_dwordx4 v[224:225], off
	s_barrier
	s_waitcnt lgkmcnt(0)
	v_mfma_f32_16x16x32_bf16 v[60:63], v[128:131], v[144:147], v[60:63]
	v_mfma_f32_16x16x32_bf16 v[56:59], v[136:139], v[144:147], v[56:59]
	v_mfma_f32_16x16x32_bf16 v[44:47], v[128:131], v[170:173], v[44:47]
	v_mfma_f32_16x16x32_bf16 v[40:43], v[136:139], v[170:173], v[40:43]
	v_mfma_f32_16x16x32_bf16 v[28:31], v[128:131], v[178:181], v[28:31]
	v_mfma_f32_16x16x32_bf16 v[24:27], v[136:139], v[178:181], v[24:27]
	v_mfma_f32_16x16x32_bf16 v[12:15], v[128:131], v[196:199], v[12:15]
	v_mfma_f32_16x16x32_bf16 v[8:11], v[136:139], v[196:199], v[8:11]
	v_mfma_f32_16x16x32_bf16 v[60:63], v[132:135], v[148:151], v[60:63]
	v_mfma_f32_16x16x32_bf16 v[56:59], v[140:143], v[148:151], v[56:59]
	v_mfma_f32_16x16x32_bf16 v[44:47], v[132:135], v[174:177], v[44:47]
	v_mfma_f32_16x16x32_bf16 v[40:43], v[140:143], v[174:177], v[40:43]
	v_mfma_f32_16x16x32_bf16 v[28:31], v[132:135], v[182:185], v[28:31]
	v_mfma_f32_16x16x32_bf16 v[24:27], v[140:143], v[182:185], v[24:27]
	v_mfma_f32_16x16x32_bf16 v[12:15], v[132:135], v[200:203], v[12:15]
	v_mfma_f32_16x16x32_bf16 v[8:11], v[140:143], v[200:203], v[8:11]
	s_barrier
	s_add_u32 s50, s24, 0x100000
	s_addc_u32 s51, s25, 0
	s_add_i32 s49, s43, s31
	v_lshl_add_u64 v[128:129], s[50:51], 0, v[156:157]
	s_mov_b32 m0, s49
	s_nop 0
	global_load_lds_dwordx4 v[128:129], off
	v_lshl_add_u64 v[128:129], s[50:51], 0, v[160:161]
	s_add_i32 m0, s49, 0x2000
	s_nop 0
	global_load_lds_dwordx4 v[128:129], off
	s_waitcnt vmcnt(6)
	s_barrier
	v_mfma_f32_16x16x32_bf16 v[52:55], v[204:207], v[144:147], v[52:55]
	v_mfma_f32_16x16x32_bf16 v[48:51], v[212:215], v[144:147], v[48:51]
	v_mfma_f32_16x16x32_bf16 v[36:39], v[204:207], v[170:173], v[36:39]
	v_mfma_f32_16x16x32_bf16 v[32:35], v[212:215], v[170:173], v[32:35]
	v_mfma_f32_16x16x32_bf16 v[20:23], v[204:207], v[178:181], v[20:23]
	v_mfma_f32_16x16x32_bf16 v[16:19], v[212:215], v[178:181], v[16:19]
	v_mfma_f32_16x16x32_bf16 v[4:7], v[204:207], v[196:199], v[4:7]
	v_mfma_f32_16x16x32_bf16 v[0:3], v[212:215], v[196:199], v[0:3]
	v_mfma_f32_16x16x32_bf16 v[52:55], v[208:211], v[148:151], v[52:55]
	v_mfma_f32_16x16x32_bf16 v[48:51], v[216:219], v[148:151], v[48:51]
	v_mfma_f32_16x16x32_bf16 v[36:39], v[208:211], v[174:177], v[36:39]
	v_mfma_f32_16x16x32_bf16 v[32:35], v[216:219], v[174:177], v[32:35]
	v_mfma_f32_16x16x32_bf16 v[20:23], v[208:211], v[182:185], v[20:23]
	v_mfma_f32_16x16x32_bf16 v[16:19], v[216:219], v[182:185], v[16:19]
	v_mfma_f32_16x16x32_bf16 v[4:7], v[208:211], v[200:203], v[4:7]
	v_mfma_f32_16x16x32_bf16 v[0:3], v[216:219], v[200:203], v[0:3]
	s_add_i32 s49, 0, 0x18000
	v_add_u32_e32 v140, s49, v189
	s_barrier
	ds_read_b128 v[128:131], v140
	ds_read_b128 v[132:135], v140 offset:1024
	ds_read_b128 v[136:139], v140 offset:2048
	ds_read_b128 v[140:143], v140 offset:3072
	s_add_u32 s26, s26, 0x100000
	s_addc_u32 s27, s27, 0
	s_mov_b32 m0, s35
	v_lshl_add_u64 v[204:205], s[26:27], 0, v[154:155]
	ds_read_b128 v[144:147], v192 offset:32768
	ds_read_b128 v[148:151], v192 offset:33792
	ds_read_b128 v[170:173], v192 offset:34816
	ds_read_b128 v[174:177], v192 offset:35840
	ds_read_b128 v[178:181], v192 offset:36864
	ds_read_b128 v[182:185], v192 offset:37888
	ds_read_b128 v[196:199], v192 offset:38912
	ds_read_b128 v[200:203], v192 offset:39936
	global_load_lds_dwordx4 v[204:205], off
	v_lshl_add_u64 v[204:205], s[26:27], 0, v[158:159]
	s_mov_b32 m0, s36
	s_nop 0
	global_load_lds_dwordx4 v[204:205], off
	s_waitcnt lgkmcnt(8)
	s_barrier
	s_waitcnt lgkmcnt(0)
	v_mfma_f32_16x16x32_bf16 v[124:127], v[128:131], v[144:147], v[124:127]
	v_mfma_f32_16x16x32_bf16 v[120:123], v[136:139], v[144:147], v[120:123]
	v_mfma_f32_16x16x32_bf16 v[108:111], v[128:131], v[170:173], v[108:111]
	v_mfma_f32_16x16x32_bf16 v[104:107], v[136:139], v[170:173], v[104:107]
	v_mfma_f32_16x16x32_bf16 v[92:95], v[128:131], v[178:181], v[92:95]
	v_mfma_f32_16x16x32_bf16 v[88:91], v[136:139], v[178:181], v[88:91]
	v_mfma_f32_16x16x32_bf16 v[76:79], v[128:131], v[196:199], v[76:79]
	v_mfma_f32_16x16x32_bf16 v[72:75], v[136:139], v[196:199], v[72:75]
	v_mfma_f32_16x16x32_bf16 v[124:127], v[132:135], v[148:151], v[124:127]
	v_mfma_f32_16x16x32_bf16 v[120:123], v[140:143], v[148:151], v[120:123]
	v_mfma_f32_16x16x32_bf16 v[108:111], v[132:135], v[174:177], v[108:111]
	v_mfma_f32_16x16x32_bf16 v[104:107], v[140:143], v[174:177], v[104:107]
	v_mfma_f32_16x16x32_bf16 v[92:95], v[132:135], v[182:185], v[92:95]
	v_mfma_f32_16x16x32_bf16 v[88:91], v[140:143], v[182:185], v[88:91]
	v_mfma_f32_16x16x32_bf16 v[76:79], v[132:135], v[200:203], v[76:79]
	v_mfma_f32_16x16x32_bf16 v[72:75], v[140:143], v[200:203], v[72:75]
	s_barrier
	s_add_i32 s26, 0, 0x1c000
	s_add_i32 s27, s49, s31
	v_add_u32_e32 v195, s26, v189
	v_lshl_add_u64 v[186:187], v[186:187], 0, s[12:13]
	s_mov_b32 m0, s27
	ds_read_b128 v[204:207], v195
	ds_read_b128 v[208:211], v195 offset:1024
	ds_read_b128 v[212:215], v195 offset:2048
	ds_read_b128 v[216:219], v195 offset:3072
	global_load_lds_dwordx4 v[186:187], off
	v_lshl_add_u64 v[186:187], v[220:221], 0, s[12:13]
	s_add_i32 m0, s27, 0x2000
	s_nop 0
	global_load_lds_dwordx4 v[186:187], off
	s_barrier
	s_waitcnt lgkmcnt(0)
	v_mfma_f32_16x16x32_bf16 v[116:119], v[204:207], v[144:147], v[116:119]
	v_mfma_f32_16x16x32_bf16 v[112:115], v[212:215], v[144:147], v[112:115]
	v_mfma_f32_16x16x32_bf16 v[100:103], v[204:207], v[170:173], v[100:103]
	v_mfma_f32_16x16x32_bf16 v[96:99], v[212:215], v[170:173], v[96:99]
	v_mfma_f32_16x16x32_bf16 v[84:87], v[204:207], v[178:181], v[84:87]
	v_mfma_f32_16x16x32_bf16 v[80:83], v[212:215], v[178:181], v[80:83]
	v_mfma_f32_16x16x32_bf16 v[68:71], v[204:207], v[196:199], v[68:71]
	v_mfma_f32_16x16x32_bf16 v[64:67], v[212:215], v[196:199], v[64:67]
	v_mfma_f32_16x16x32_bf16 v[116:119], v[208:211], v[148:151], v[116:119]
	v_mfma_f32_16x16x32_bf16 v[112:115], v[216:219], v[148:151], v[112:115]
	v_mfma_f32_16x16x32_bf16 v[100:103], v[208:211], v[174:177], v[100:103]
	v_mfma_f32_16x16x32_bf16 v[96:99], v[216:219], v[174:177], v[96:99]
	v_mfma_f32_16x16x32_bf16 v[84:87], v[208:211], v[182:185], v[84:87]
	v_mfma_f32_16x16x32_bf16 v[80:83], v[216:219], v[182:185], v[80:83]
	v_mfma_f32_16x16x32_bf16 v[68:71], v[208:211], v[200:203], v[68:71]
	v_mfma_f32_16x16x32_bf16 v[64:67], v[216:219], v[200:203], v[64:67]
	s_mov_b32 m0, s38
	v_lshl_add_u64 v[186:187], v[222:223], 0, s[12:13]
	s_barrier
	ds_read_b128 v[144:147], v192 offset:49152
	ds_read_b128 v[148:151], v192 offset:50176
	ds_read_b128 v[170:173], v192 offset:51200
	ds_read_b128 v[174:177], v192 offset:52224
	ds_read_b128 v[178:181], v192 offset:53248
	ds_read_b128 v[182:185], v192 offset:54272
	ds_read_b128 v[196:199], v192 offset:55296
	ds_read_b128 v[200:203], v192 offset:56320
	global_load_lds_dwordx4 v[186:187], off
	v_lshl_add_u64 v[186:187], v[224:225], 0, s[12:13]
	s_mov_b32 m0, s39
	s_nop 0
	global_load_lds_dwordx4 v[186:187], off
	s_barrier
	s_waitcnt lgkmcnt(0)
	v_mfma_f32_16x16x32_bf16 v[60:63], v[128:131], v[144:147], v[60:63]
	v_mfma_f32_16x16x32_bf16 v[56:59], v[136:139], v[144:147], v[56:59]
	v_mfma_f32_16x16x32_bf16 v[44:47], v[128:131], v[170:173], v[44:47]
	v_mfma_f32_16x16x32_bf16 v[40:43], v[136:139], v[170:173], v[40:43]
	v_mfma_f32_16x16x32_bf16 v[28:31], v[128:131], v[178:181], v[28:31]
	v_mfma_f32_16x16x32_bf16 v[24:27], v[136:139], v[178:181], v[24:27]
	v_mfma_f32_16x16x32_bf16 v[12:15], v[128:131], v[196:199], v[12:15]
	v_mfma_f32_16x16x32_bf16 v[8:11], v[136:139], v[196:199], v[8:11]
	v_mfma_f32_16x16x32_bf16 v[60:63], v[132:135], v[148:151], v[60:63]
	v_mfma_f32_16x16x32_bf16 v[56:59], v[140:143], v[148:151], v[56:59]
	v_mfma_f32_16x16x32_bf16 v[44:47], v[132:135], v[174:177], v[44:47]
	v_mfma_f32_16x16x32_bf16 v[40:43], v[140:143], v[174:177], v[40:43]
	v_mfma_f32_16x16x32_bf16 v[28:31], v[132:135], v[182:185], v[28:31]
	v_mfma_f32_16x16x32_bf16 v[24:27], v[140:143], v[182:185], v[24:27]
	v_mfma_f32_16x16x32_bf16 v[12:15], v[132:135], v[200:203], v[12:15]
	v_mfma_f32_16x16x32_bf16 v[8:11], v[140:143], v[200:203], v[8:11]
	s_barrier
	s_add_u32 s24, s24, 0x100080
	s_addc_u32 s25, s25, 0
	s_add_i32 s26, s26, s31
	v_lshl_add_u64 v[128:129], s[24:25], 0, v[156:157]
	s_mov_b32 m0, s26
	s_nop 0
	global_load_lds_dwordx4 v[128:129], off
	v_lshl_add_u64 v[128:129], s[24:25], 0, v[160:161]
	s_add_i32 m0, s26, 0x2000
	s_nop 0
	global_load_lds_dwordx4 v[128:129], off
	s_waitcnt vmcnt(6)
	s_barrier
	v_mfma_f32_16x16x32_bf16 v[52:55], v[204:207], v[144:147], v[52:55]
	v_mfma_f32_16x16x32_bf16 v[48:51], v[212:215], v[144:147], v[48:51]
	v_mfma_f32_16x16x32_bf16 v[36:39], v[204:207], v[170:173], v[36:39]
	v_mfma_f32_16x16x32_bf16 v[32:35], v[212:215], v[170:173], v[32:35]
	v_mfma_f32_16x16x32_bf16 v[20:23], v[204:207], v[178:181], v[20:23]
	v_mfma_f32_16x16x32_bf16 v[16:19], v[212:215], v[178:181], v[16:19]
	v_mfma_f32_16x16x32_bf16 v[4:7], v[204:207], v[196:199], v[4:7]
	v_mfma_f32_16x16x32_bf16 v[0:3], v[212:215], v[196:199], v[0:3]
	v_mfma_f32_16x16x32_bf16 v[52:55], v[208:211], v[148:151], v[52:55]
	v_mfma_f32_16x16x32_bf16 v[48:51], v[216:219], v[148:151], v[48:51]
	v_mfma_f32_16x16x32_bf16 v[36:39], v[208:211], v[174:177], v[36:39]
	v_mfma_f32_16x16x32_bf16 v[32:35], v[216:219], v[174:177], v[32:35]
	v_mfma_f32_16x16x32_bf16 v[20:23], v[208:211], v[182:185], v[20:23]
	v_mfma_f32_16x16x32_bf16 v[16:19], v[216:219], v[182:185], v[16:19]
	v_mfma_f32_16x16x32_bf16 v[4:7], v[208:211], v[200:203], v[4:7]
	v_mfma_f32_16x16x32_bf16 v[0:3], v[216:219], v[200:203], v[0:3]
	s_add_i32 s48, s48, 2
	s_add_u32 s22, s22, 0x100
	s_addc_u32 s23, s23, 0
	s_add_u32 s46, s46, 0x100
	s_addc_u32 s47, s47, 0
	s_cmp_gt_u32 s48, 61
	s_barrier
	s_cbranch_scc0 .LBB0_844
	v_lshl_or_b32 v170, s6, 8, v190
	v_lshl_add_u32 v172, s8, 8, v188
	v_ashrrev_i32_e32 v171, 31, v170
	v_lshlrev_b64 v[206:207], 1, v[170:171]
	v_ashrrev_i32_e32 v173, 31, v172
	v_lshl_add_u64 v[174:175], s[76:77], 0, v[206:207]
	v_lshlrev_b64 v[208:209], 11, v[172:173]
	v_lshl_add_u64 v[128:129], v[174:175], 0, v[208:209]
	global_load_dwordx4 v[198:201], v[128:129], off
	global_load_dwordx4 v[202:205], v[128:129], off offset:256
	v_or_b32_e32 v184, 16, v172
	v_or_b32_e32 v180, 32, v172
	v_or_b32_e32 v176, 48, v172
	v_ashrrev_i32_e32 v185, 31, v184
	v_ashrrev_i32_e32 v181, 31, v180
	v_ashrrev_i32_e32 v177, 31, v176
	v_lshlrev_b64 v[186:187], 11, v[184:185]
	v_lshlrev_b64 v[182:183], 11, v[180:181]
	v_lshlrev_b64 v[178:179], 11, v[176:177]
	v_lshl_add_u64 v[128:129], v[174:175], 0, v[186:187]
	v_lshl_add_u64 v[130:131], v[174:175], 0, v[182:183]
	v_lshl_add_u64 v[196:197], v[174:175], 0, v[178:179]
	global_load_dwordx4 v[148:151], v[128:129], off
	global_load_dwordx4 v[144:147], v[128:129], off offset:256
	global_load_dwordx4 v[140:143], v[130:131], off
	global_load_dwordx4 v[136:139], v[130:131], off offset:256
	global_load_dwordx4 v[132:135], v[196:197], off
	s_nop 0
	global_load_dwordx4 v[128:131], v[196:197], off offset:256
	v_add_u32_e32 v218, 0x80, v172
	v_ashrrev_i32_e32 v219, 31, v218
	v_lshlrev_b64 v[218:219], 11, v[218:219]
	v_lshl_add_u64 v[218:219], v[174:175], 0, v[218:219]
	global_load_dwordx4 v[220:223], v[218:219], off
	global_load_dwordx4 v[224:227], v[218:219], off offset:256
	v_add_u32_e32 v218, 0x90, v172
	v_ashrrev_i32_e32 v219, 31, v218
	v_lshlrev_b64 v[218:219], 11, v[218:219]
	v_lshl_add_u64 v[218:219], v[174:175], 0, v[218:219]
	global_load_dwordx4 v[228:231], v[218:219], off
	global_load_dwordx4 v[232:235], v[218:219], off offset:256
	v_add_u32_e32 v218, 0xa0, v172
	v_ashrrev_i32_e32 v219, 31, v218
	v_lshlrev_b64 v[218:219], 11, v[218:219]
	v_lshl_add_u64 v[218:219], v[174:175], 0, v[218:219]
	global_load_dwordx4 v[236:239], v[218:219], off
	global_load_dwordx4 v[240:243], v[218:219], off offset:256
	v_add_u32_e32 v218, 0xb0, v172
	v_ashrrev_i32_e32 v219, 31, v218
	v_lshlrev_b64 v[218:219], 11, v[218:219]
	v_lshl_add_u64 v[218:219], v[174:175], 0, v[218:219]
	global_load_dwordx4 v[244:247], v[218:219], off
	global_load_dwordx4 v[252:255], v[218:219], off offset:256
	v_and_b32_e32 v196, 64, v194
	v_xor_b32_e32 v195, 16, v194
	v_add_u32_e32 v196, 64, v196
	v_xor_b32_e32 v197, 32, v194
	v_cmp_lt_i32_e32 vcc, v195, v196
	s_waitcnt vmcnt(15)
	v_lshlrev_b32_e32 v210, 16, v198
	v_cndmask_b32_e32 v195, v194, v195, vcc
	v_cmp_lt_i32_e32 vcc, v197, v196
	v_and_b32_e32 v211, 0xffff0000, v198
	s_waitcnt vmcnt(14)
	v_lshlrev_b32_e32 v214, 16, v202
	v_and_b32_e32 v215, 0xffff0000, v202
	v_cndmask_b32_e32 v197, v194, v197, vcc
	v_lshlrev_b32_e32 v212, 16, v200
	v_and_b32_e32 v213, 0xffff0000, v200
	v_lshlrev_b32_e32 v200, 16, v201
	v_and_b32_e32 v201, 0xffff0000, v201
	v_lshlrev_b32_e32 v216, 16, v204
	v_and_b32_e32 v217, 0xffff0000, v204
	v_pk_add_f32 v[124:125], v[124:125], v[210:211]
	v_pk_add_f32 v[116:117], v[116:117], v[214:215]
	v_lshlrev_b32_e32 v196, 2, v195
	v_lshlrev_b32_e32 v195, 2, v197
	v_lshlrev_b32_e32 v198, 16, v199
	v_and_b32_e32 v199, 0xffff0000, v199
	v_lshlrev_b32_e32 v202, 16, v203
	v_and_b32_e32 v203, 0xffff0000, v203
	v_pk_add_f32 v[122:123], v[122:123], v[200:201]
	v_pk_add_f32 v[200:201], v[112:113], v[216:217]
	v_mul_f32_e32 v197, v125, v125
	v_cvt_pk_bf16_f32 v112, v124, v125
	v_mul_f32_e32 v125, v117, v117
	v_pk_add_f32 v[126:127], v[126:127], v[198:199]
	v_pk_add_f32 v[118:119], v[118:119], v[202:203]
	v_fmac_f32_e32 v197, v124, v124
	v_fmac_f32_e32 v125, v116, v116
	v_fmac_f32_e32 v197, v126, v126
	v_fmac_f32_e32 v125, v118, v118
	v_pk_add_f32 v[120:121], v[120:121], v[212:213]
	v_fmac_f32_e32 v197, v127, v127
	v_fmac_f32_e32 v125, v119, v119
	v_lshlrev_b32_e32 v204, 16, v205
	v_and_b32_e32 v205, 0xffff0000, v205
	v_fmac_f32_e32 v197, v120, v120
	v_fmac_f32_e32 v125, v200, v200
	v_pk_add_f32 v[198:199], v[114:115], v[204:205]
	v_fmac_f32_e32 v197, v121, v121
	v_fmac_f32_e32 v125, v201, v201
	v_fmac_f32_e32 v197, v122, v122
	v_fmac_f32_e32 v125, v198, v198
	v_fmac_f32_e32 v197, v123, v123
	v_fmac_f32_e32 v125, v199, v199
	v_cvt_pk_bf16_f32 v115, v122, v123
	v_add_f32_e32 v122, v197, v125
	ds_bpermute_b32 v123, v196, v122
	v_cvt_pk_bf16_f32 v114, v120, v121
	v_lshl_add_u64 v[120:121], s[76:77], 0, v[208:209]
	v_cvt_pk_bf16_f32 v113, v126, v127
	v_lshl_add_u64 v[120:121], v[120:121], 0, v[206:207]
	global_store_dwordx4 v[120:121], v[112:115], off
	s_waitcnt lgkmcnt(0)
	s_nop 0
	v_add_f32_e32 v112, v122, v123
	ds_bpermute_b32 v113, v195, v112
	v_cvt_pk_bf16_f32 v114, v116, v117
	v_cvt_pk_bf16_f32 v115, v118, v119
	v_cvt_pk_bf16_f32 v116, v200, v201
	v_cvt_pk_bf16_f32 v117, v198, v199
	global_store_dwordx4 v[120:121], v[114:117], off offset:256
	s_and_saveexec_b64 s[22:23], s[0:1]
	s_cbranch_execz .LBB0_847
	s_waitcnt lgkmcnt(0)
	v_add_f32_e32 v114, v112, v113
	s_lshl_b32 s24, s6, 2
	v_lshlrev_b64 v[112:113], 6, v[172:173]
	s_ashr_i32 s25, s24, 31
	v_lshl_add_u64 v[112:113], s[10:11], 0, v[112:113]
	v_lshl_add_u64 v[112:113], s[24:25], 2, v[112:113]
	s_lshl_b32 s8, s37, 2
	v_lshl_add_u64 v[112:113], v[112:113], 0, s[8:9]
	global_store_dword v[112:113], v114, off

.LBB0_921:
	s_ashr_i32 s13, s12, 31
	v_cmp_lt_i64_e32 vcc, s[14:15], v[142:143]
	s_lshl_b64 s[14:15], s[12:13], 19
	s_add_u32 s14, s76, s14
	s_addc_u32 s15, s77, s15
	s_and_b64 s[16:17], vcc, exec
	s_cselect_b32 s13, s15, s21
	s_cselect_b32 s43, s14, s20
	s_ashr_i32 s11, s10, 31
	s_lshl_b64 s[16:17], s[10:11], 19
	s_add_u32 s16, s9, s16
	s_addc_u32 s17, s26, s17
	s_and_b64 s[24:25], vcc, exec
	s_cselect_b32 s11, s17, s23
	s_cselect_b32 s44, s16, s22
	s_add_u32 s20, s20, 0x40080
	s_addc_u32 s21, s21, 0
	s_add_u32 s45, s22, 0x100
	s_addc_u32 s46, s23, 0
	s_mov_b32 s47, -2
	ds_read_b128 v[146:149], v173
	ds_read_b128 v[154:157], v173 offset:1024
	ds_read_b128 v[158:161], v173 offset:2048
	ds_read_b128 v[162:165], v173 offset:3072
	s_add_u32 s22, s20, 0xfffc0080
	s_addc_u32 s23, s21, -1
	s_cmp_eq_u32 s47, 12
	s_cselect_b32 s25, s13, s23
	s_cselect_b32 s24, s43, s22
	s_cselect_b32 s23, s11, s46
	s_cselect_b32 s22, s44, s45
	v_lshl_add_u64 v[150:151], s[20:21], 0, v[138:139]
	s_add_i32 m0, s19, 0xc000
	ds_read_b128 v[166:169], v174
	ds_read_b128 v[178:181], v174 offset:1024
	ds_read_b128 v[182:185], v174 offset:2048
	ds_read_b128 v[186:189], v174 offset:3072
	ds_read_b128 v[190:193], v174 offset:4096
	ds_read_b128 v[194:197], v174 offset:5120
	ds_read_b128 v[198:201], v174 offset:6144
	ds_read_b128 v[202:205], v174 offset:7168
	global_load_lds_dwordx4 v[150:151], off
	v_lshl_add_u64 v[150:151], s[20:21], 0, v[140:141]
	s_add_i32 m0, s19, 0xe000
	s_nop 0
	global_load_lds_dwordx4 v[150:151], off
	s_waitcnt lgkmcnt(8)
	s_barrier
	s_waitcnt lgkmcnt(0)
	v_mfma_f32_16x16x32_bf16 v[124:127], v[146:149], v[166:169], 0
	v_mfma_f32_16x16x32_bf16 v[120:123], v[158:161], v[166:169], 0
	v_mfma_f32_16x16x32_bf16 v[112:115], v[146:149], v[182:185], 0
	v_mfma_f32_16x16x32_bf16 v[104:107], v[158:161], v[182:185], 0
	v_mfma_f32_16x16x32_bf16 v[92:95], v[146:149], v[190:193], 0
	v_mfma_f32_16x16x32_bf16 v[88:91], v[158:161], v[190:193], 0
	v_mfma_f32_16x16x32_bf16 v[80:83], v[146:149], v[198:201], 0
	v_mfma_f32_16x16x32_bf16 v[72:75], v[158:161], v[198:201], 0
	v_mfma_f32_16x16x32_bf16 v[124:127], v[154:157], v[178:181], v[124:127]
	v_mfma_f32_16x16x32_bf16 v[120:123], v[162:165], v[178:181], v[120:123]
	v_mfma_f32_16x16x32_bf16 v[112:115], v[154:157], v[186:189], v[112:115]
	v_mfma_f32_16x16x32_bf16 v[104:107], v[162:165], v[186:189], v[104:107]
	v_mfma_f32_16x16x32_bf16 v[92:95], v[154:157], v[194:197], v[92:95]
	v_mfma_f32_16x16x32_bf16 v[88:91], v[162:165], v[194:197], v[88:91]
	v_mfma_f32_16x16x32_bf16 v[80:83], v[154:157], v[202:205], v[80:83]
	v_mfma_f32_16x16x32_bf16 v[72:75], v[162:165], v[202:205], v[72:75]
	s_barrier
	s_add_i32 s48, s38, s27
	v_lshl_add_u64 v[150:151], s[22:23], 0, v[132:133]
	s_mov_b32 m0, s48
	ds_read_b128 v[206:209], v175
	ds_read_b128 v[210:213], v175 offset:1024
	ds_read_b128 v[214:217], v175 offset:2048
	ds_read_b128 v[218:221], v175 offset:3072
	global_load_lds_dwordx4 v[150:151], off
	v_lshl_add_u64 v[222:223], s[22:23], 0, v[128:129]
	s_add_i32 m0, s48, 0x2000
	s_nop 0
	global_load_lds_dwordx4 v[222:223], off
	s_barrier
	s_waitcnt lgkmcnt(0)
	v_mfma_f32_16x16x32_bf16 v[116:119], v[206:209], v[166:169], 0
	v_mfma_f32_16x16x32_bf16 v[108:111], v[214:217], v[166:169], 0
	v_mfma_f32_16x16x32_bf16 v[100:103], v[206:209], v[182:185], 0
	v_mfma_f32_16x16x32_bf16 v[96:99], v[214:217], v[182:185], 0
	v_mfma_f32_16x16x32_bf16 v[84:87], v[206:209], v[190:193], 0
	v_mfma_f32_16x16x32_bf16 v[76:79], v[214:217], v[190:193], 0
	v_mfma_f32_16x16x32_bf16 v[68:71], v[206:209], v[198:201], 0
	v_mfma_f32_16x16x32_bf16 v[64:67], v[214:217], v[198:201], 0
	v_mfma_f32_16x16x32_bf16 v[116:119], v[210:213], v[178:181], v[116:119]
	v_mfma_f32_16x16x32_bf16 v[108:111], v[218:221], v[178:181], v[108:111]
	v_mfma_f32_16x16x32_bf16 v[100:103], v[210:213], v[186:189], v[100:103]
	v_mfma_f32_16x16x32_bf16 v[96:99], v[218:221], v[186:189], v[96:99]
	v_mfma_f32_16x16x32_bf16 v[84:87], v[210:213], v[194:197], v[84:87]
	v_mfma_f32_16x16x32_bf16 v[76:79], v[218:221], v[194:197], v[76:79]
	v_mfma_f32_16x16x32_bf16 v[68:71], v[210:213], v[202:205], v[68:71]
	v_mfma_f32_16x16x32_bf16 v[64:67], v[218:221], v[202:205], v[64:67]
	s_mov_b32 m0, s19
	v_lshl_add_u64 v[224:225], s[24:25], 0, v[134:135]
	s_barrier
	ds_read_b128 v[166:169], v174 offset:16384
	ds_read_b128 v[178:181], v174 offset:17408
	ds_read_b128 v[182:185], v174 offset:18432
	ds_read_b128 v[186:189], v174 offset:19456
	ds_read_b128 v[190:193], v174 offset:20480
	ds_read_b128 v[194:197], v174 offset:21504
	ds_read_b128 v[198:201], v174 offset:22528
	ds_read_b128 v[202:205], v174 offset:23552
	global_load_lds_dwordx4 v[224:225], off
	v_lshl_add_u64 v[226:227], s[24:25], 0, v[130:131]
	s_mov_b32 m0, s30
	s_nop 0
	global_load_lds_dwordx4 v[226:227], off
	s_barrier
	s_waitcnt lgkmcnt(0)
	v_mfma_f32_16x16x32_bf16 v[60:63], v[146:149], v[166:169], 0
	v_mfma_f32_16x16x32_bf16 v[56:59], v[158:161], v[166:169], 0
	v_mfma_f32_16x16x32_bf16 v[48:51], v[146:149], v[182:185], 0
	v_mfma_f32_16x16x32_bf16 v[40:43], v[158:161], v[182:185], 0
	v_mfma_f32_16x16x32_bf16 v[32:35], v[146:149], v[190:193], 0
	v_mfma_f32_16x16x32_bf16 v[24:27], v[158:161], v[190:193], 0
	v_mfma_f32_16x16x32_bf16 v[16:19], v[146:149], v[198:201], 0
	v_mfma_f32_16x16x32_bf16 v[8:11], v[158:161], v[198:201], 0
	v_mfma_f32_16x16x32_bf16 v[60:63], v[154:157], v[178:181], v[60:63]
	v_mfma_f32_16x16x32_bf16 v[56:59], v[162:165], v[178:181], v[56:59]
	v_mfma_f32_16x16x32_bf16 v[48:51], v[154:157], v[186:189], v[48:51]
	v_mfma_f32_16x16x32_bf16 v[40:43], v[162:165], v[186:189], v[40:43]
	v_mfma_f32_16x16x32_bf16 v[32:35], v[154:157], v[194:197], v[32:35]
	v_mfma_f32_16x16x32_bf16 v[24:27], v[162:165], v[194:197], v[24:27]
	v_mfma_f32_16x16x32_bf16 v[16:19], v[154:157], v[202:205], v[16:19]
	v_mfma_f32_16x16x32_bf16 v[8:11], v[162:165], v[202:205], v[8:11]
	s_barrier
	s_add_u32 s48, s22, 0x40000
	s_addc_u32 s49, s23, 0
	s_add_i32 s50, s39, s27
	v_lshl_add_u64 v[146:147], s[48:49], 0, v[132:133]
	s_mov_b32 m0, s50
	s_nop 0
	global_load_lds_dwordx4 v[146:147], off
	v_lshl_add_u64 v[146:147], s[48:49], 0, v[128:129]
	s_add_i32 m0, s50, 0x2000
	s_nop 0
	global_load_lds_dwordx4 v[146:147], off
	s_waitcnt vmcnt(6)
	s_barrier
	v_mfma_f32_16x16x32_bf16 v[52:55], v[206:209], v[166:169], 0
	v_mfma_f32_16x16x32_bf16 v[44:47], v[214:217], v[166:169], 0
	v_mfma_f32_16x16x32_bf16 v[36:39], v[206:209], v[182:185], 0
	v_mfma_f32_16x16x32_bf16 v[28:31], v[214:217], v[182:185], 0
	v_mfma_f32_16x16x32_bf16 v[20:23], v[206:209], v[190:193], 0
	v_mfma_f32_16x16x32_bf16 v[12:15], v[214:217], v[190:193], 0
	v_mfma_f32_16x16x32_bf16 v[4:7], v[206:209], v[198:201], 0
	v_mfma_f32_16x16x32_bf16 v[0:3], v[214:217], v[198:201], 0
	v_mfma_f32_16x16x32_bf16 v[52:55], v[210:213], v[178:181], v[52:55]
	v_mfma_f32_16x16x32_bf16 v[44:47], v[218:221], v[178:181], v[44:47]
	v_mfma_f32_16x16x32_bf16 v[36:39], v[210:213], v[186:189], v[36:39]
	v_mfma_f32_16x16x32_bf16 v[28:31], v[218:221], v[186:189], v[28:31]
	v_mfma_f32_16x16x32_bf16 v[20:23], v[210:213], v[194:197], v[20:23]
	v_mfma_f32_16x16x32_bf16 v[12:15], v[218:221], v[194:197], v[12:15]
	v_mfma_f32_16x16x32_bf16 v[4:7], v[210:213], v[202:205], v[4:7]
	v_mfma_f32_16x16x32_bf16 v[0:3], v[218:221], v[202:205], v[0:3]
	s_add_i32 s48, 0, 0x18000
	v_add_u32_e32 v162, s48, v171
	s_barrier
	ds_read_b128 v[146:149], v162
	ds_read_b128 v[154:157], v162 offset:1024
	ds_read_b128 v[158:161], v162 offset:2048
	ds_read_b128 v[162:165], v162 offset:3072
	s_add_u32 s24, s24, 0x40000
	s_addc_u32 s25, s25, 0
	s_mov_b32 m0, s31
	v_lshl_add_u64 v[206:207], s[24:25], 0, v[134:135]
	ds_read_b128 v[166:169], v174 offset:32768
	ds_read_b128 v[178:181], v174 offset:33792
	ds_read_b128 v[182:185], v174 offset:34816
	ds_read_b128 v[186:189], v174 offset:35840
	ds_read_b128 v[190:193], v174 offset:36864
	ds_read_b128 v[194:197], v174 offset:37888
	ds_read_b128 v[198:201], v174 offset:38912
	ds_read_b128 v[202:205], v174 offset:39936
	global_load_lds_dwordx4 v[206:207], off
	v_lshl_add_u64 v[206:207], s[24:25], 0, v[130:131]
	s_mov_b32 m0, s33
	s_nop 0
	global_load_lds_dwordx4 v[206:207], off
	s_waitcnt lgkmcnt(8)
	s_barrier
	s_waitcnt lgkmcnt(0)
	v_mfma_f32_16x16x32_bf16 v[124:127], v[146:149], v[166:169], v[124:127]
	v_mfma_f32_16x16x32_bf16 v[120:123], v[158:161], v[166:169], v[120:123]
	v_mfma_f32_16x16x32_bf16 v[112:115], v[146:149], v[182:185], v[112:115]
	v_mfma_f32_16x16x32_bf16 v[104:107], v[158:161], v[182:185], v[104:107]
	v_mfma_f32_16x16x32_bf16 v[92:95], v[146:149], v[190:193], v[92:95]
	v_mfma_f32_16x16x32_bf16 v[88:91], v[158:161], v[190:193], v[88:91]
	v_mfma_f32_16x16x32_bf16 v[80:83], v[146:149], v[198:201], v[80:83]
	v_mfma_f32_16x16x32_bf16 v[72:75], v[158:161], v[198:201], v[72:75]
	v_mfma_f32_16x16x32_bf16 v[124:127], v[154:157], v[178:181], v[124:127]
	v_mfma_f32_16x16x32_bf16 v[120:123], v[162:165], v[178:181], v[120:123]
	v_mfma_f32_16x16x32_bf16 v[112:115], v[154:157], v[186:189], v[112:115]
	v_mfma_f32_16x16x32_bf16 v[104:107], v[162:165], v[186:189], v[104:107]
	v_mfma_f32_16x16x32_bf16 v[92:95], v[154:157], v[194:197], v[92:95]
	v_mfma_f32_16x16x32_bf16 v[88:91], v[162:165], v[194:197], v[88:91]
	v_mfma_f32_16x16x32_bf16 v[80:83], v[154:157], v[202:205], v[80:83]
	v_mfma_f32_16x16x32_bf16 v[72:75], v[162:165], v[202:205], v[72:75]
	s_barrier
	s_add_i32 s24, 0, 0x1c000
	s_add_i32 s25, s48, s27
	v_add_u32_e32 v177, s24, v171
	v_lshl_add_u64 v[150:151], v[150:151], 0, s[4:5]
	s_mov_b32 m0, s25
	ds_read_b128 v[206:209], v177
	ds_read_b128 v[210:213], v177 offset:1024
	ds_read_b128 v[214:217], v177 offset:2048
	ds_read_b128 v[218:221], v177 offset:3072
	global_load_lds_dwordx4 v[150:151], off
	v_lshl_add_u64 v[150:151], v[222:223], 0, s[4:5]
	s_add_i32 m0, s25, 0x2000
	s_nop 0
	global_load_lds_dwordx4 v[150:151], off
	s_barrier
	s_waitcnt lgkmcnt(0)
	v_mfma_f32_16x16x32_bf16 v[116:119], v[206:209], v[166:169], v[116:119]
	v_mfma_f32_16x16x32_bf16 v[108:111], v[214:217], v[166:169], v[108:111]
	v_mfma_f32_16x16x32_bf16 v[100:103], v[206:209], v[182:185], v[100:103]
	v_mfma_f32_16x16x32_bf16 v[96:99], v[214:217], v[182:185], v[96:99]
	v_mfma_f32_16x16x32_bf16 v[84:87], v[206:209], v[190:193], v[84:87]
	v_mfma_f32_16x16x32_bf16 v[76:79], v[214:217], v[190:193], v[76:79]
	v_mfma_f32_16x16x32_bf16 v[68:71], v[206:209], v[198:201], v[68:71]
	v_mfma_f32_16x16x32_bf16 v[64:67], v[214:217], v[198:201], v[64:67]
	v_mfma_f32_16x16x32_bf16 v[116:119], v[210:213], v[178:181], v[116:119]
	v_mfma_f32_16x16x32_bf16 v[108:111], v[218:221], v[178:181], v[108:111]
	v_mfma_f32_16x16x32_bf16 v[100:103], v[210:213], v[186:189], v[100:103]
	v_mfma_f32_16x16x32_bf16 v[96:99], v[218:221], v[186:189], v[96:99]
	v_mfma_f32_16x16x32_bf16 v[84:87], v[210:213], v[194:197], v[84:87]
	v_mfma_f32_16x16x32_bf16 v[76:79], v[218:221], v[194:197], v[76:79]
	v_mfma_f32_16x16x32_bf16 v[68:71], v[210:213], v[202:205], v[68:71]
	v_mfma_f32_16x16x32_bf16 v[64:67], v[218:221], v[202:205], v[64:67]
	s_mov_b32 m0, s35
	v_lshl_add_u64 v[150:151], v[224:225], 0, s[4:5]
	s_barrier
	ds_read_b128 v[166:169], v174 offset:49152
	ds_read_b128 v[178:181], v174 offset:50176
	ds_read_b128 v[182:185], v174 offset:51200
	ds_read_b128 v[186:189], v174 offset:52224
	ds_read_b128 v[190:193], v174 offset:53248
	ds_read_b128 v[194:197], v174 offset:54272
	ds_read_b128 v[198:201], v174 offset:55296
	ds_read_b128 v[202:205], v174 offset:56320
	global_load_lds_dwordx4 v[150:151], off
	v_lshl_add_u64 v[150:151], v[226:227], 0, s[4:5]
	s_mov_b32 m0, s36
	s_nop 0
	global_load_lds_dwordx4 v[150:151], off
	s_barrier
	s_waitcnt lgkmcnt(0)
	v_mfma_f32_16x16x32_bf16 v[60:63], v[146:149], v[166:169], v[60:63]
	v_mfma_f32_16x16x32_bf16 v[56:59], v[158:161], v[166:169], v[56:59]
	v_mfma_f32_16x16x32_bf16 v[48:51], v[146:149], v[182:185], v[48:51]
	v_mfma_f32_16x16x32_bf16 v[40:43], v[158:161], v[182:185], v[40:43]
	v_mfma_f32_16x16x32_bf16 v[32:35], v[146:149], v[190:193], v[32:35]
	v_mfma_f32_16x16x32_bf16 v[24:27], v[158:161], v[190:193], v[24:27]
	v_mfma_f32_16x16x32_bf16 v[16:19], v[146:149], v[198:201], v[16:19]
	v_mfma_f32_16x16x32_bf16 v[8:11], v[158:161], v[198:201], v[8:11]
	v_mfma_f32_16x16x32_bf16 v[60:63], v[154:157], v[178:181], v[60:63]
	v_mfma_f32_16x16x32_bf16 v[56:59], v[162:165], v[178:181], v[56:59]
	v_mfma_f32_16x16x32_bf16 v[48:51], v[154:157], v[186:189], v[48:51]
	v_mfma_f32_16x16x32_bf16 v[40:43], v[162:165], v[186:189], v[40:43]
	v_mfma_f32_16x16x32_bf16 v[32:35], v[154:157], v[194:197], v[32:35]
	v_mfma_f32_16x16x32_bf16 v[24:27], v[162:165], v[194:197], v[24:27]
	v_mfma_f32_16x16x32_bf16 v[16:19], v[154:157], v[202:205], v[16:19]
	v_mfma_f32_16x16x32_bf16 v[8:11], v[162:165], v[202:205], v[8:11]
	s_barrier
	s_add_u32 s22, s22, 0x40080
	s_addc_u32 s23, s23, 0
	s_add_i32 s24, s24, s27
	v_lshl_add_u64 v[146:147], s[22:23], 0, v[132:133]
	s_mov_b32 m0, s24
	s_nop 0
	global_load_lds_dwordx4 v[146:147], off
	v_lshl_add_u64 v[146:147], s[22:23], 0, v[128:129]
	s_add_i32 m0, s24, 0x2000
	s_nop 0
	global_load_lds_dwordx4 v[146:147], off
	s_waitcnt vmcnt(6)
	s_barrier
	v_mfma_f32_16x16x32_bf16 v[52:55], v[206:209], v[166:169], v[52:55]
	v_mfma_f32_16x16x32_bf16 v[44:47], v[214:217], v[166:169], v[44:47]
	v_mfma_f32_16x16x32_bf16 v[36:39], v[206:209], v[182:185], v[36:39]
	v_mfma_f32_16x16x32_bf16 v[28:31], v[214:217], v[182:185], v[28:31]
	v_mfma_f32_16x16x32_bf16 v[20:23], v[206:209], v[190:193], v[20:23]
	v_mfma_f32_16x16x32_bf16 v[12:15], v[214:217], v[190:193], v[12:15]
	v_mfma_f32_16x16x32_bf16 v[4:7], v[206:209], v[198:201], v[4:7]
	v_mfma_f32_16x16x32_bf16 v[0:3], v[214:217], v[198:201], v[0:3]
	v_mfma_f32_16x16x32_bf16 v[52:55], v[210:213], v[178:181], v[52:55]
	v_mfma_f32_16x16x32_bf16 v[44:47], v[218:221], v[178:181], v[44:47]
	v_mfma_f32_16x16x32_bf16 v[36:39], v[210:213], v[186:189], v[36:39]
	v_mfma_f32_16x16x32_bf16 v[28:31], v[218:221], v[186:189], v[28:31]
	v_mfma_f32_16x16x32_bf16 v[20:23], v[210:213], v[194:197], v[20:23]
	v_mfma_f32_16x16x32_bf16 v[12:15], v[218:221], v[194:197], v[12:15]
	v_mfma_f32_16x16x32_bf16 v[4:7], v[210:213], v[202:205], v[4:7]
	v_mfma_f32_16x16x32_bf16 v[0:3], v[218:221], v[202:205], v[0:3]
	s_add_i32 s47, s47, 2
	s_add_u32 s20, s20, 0x100
	s_addc_u32 s21, s21, 0
	s_add_u32 s45, s45, 0x100
	s_addc_u32 s46, s46, 0
	s_cmp_gt_u32 s47, 13
	s_barrier
.LBB0_922:
	ds_read_b128 v[146:149], v173
	ds_read_b128 v[154:157], v173 offset:1024
	ds_read_b128 v[158:161], v173 offset:2048
	ds_read_b128 v[162:165], v173 offset:3072
	s_add_u32 s22, s20, 0xfffc0080
	s_addc_u32 s23, s21, -1
	s_cmp_eq_u32 s47, 12
	s_cselect_b32 s25, s13, s23
	s_cselect_b32 s24, s43, s22
	s_cselect_b32 s23, s11, s46
	s_cselect_b32 s22, s44, s45
	v_lshl_add_u64 v[150:151], s[20:21], 0, v[138:139]
	s_add_i32 m0, s19, 0xc000
	ds_read_b128 v[166:169], v174
	ds_read_b128 v[178:181], v174 offset:1024
	ds_read_b128 v[182:185], v174 offset:2048
	ds_read_b128 v[186:189], v174 offset:3072
	ds_read_b128 v[190:193], v174 offset:4096
	ds_read_b128 v[194:197], v174 offset:5120
	ds_read_b128 v[198:201], v174 offset:6144
	ds_read_b128 v[202:205], v174 offset:7168
	global_load_lds_dwordx4 v[150:151], off
	v_lshl_add_u64 v[150:151], s[20:21], 0, v[140:141]
	s_add_i32 m0, s19, 0xe000
	s_nop 0
	global_load_lds_dwordx4 v[150:151], off
	s_waitcnt lgkmcnt(8)
	s_barrier
	s_waitcnt lgkmcnt(0)
	v_mfma_f32_16x16x32_bf16 v[124:127], v[146:149], v[166:169], v[124:127]
	v_mfma_f32_16x16x32_bf16 v[120:123], v[158:161], v[166:169], v[120:123]
	v_mfma_f32_16x16x32_bf16 v[112:115], v[146:149], v[182:185], v[112:115]
	v_mfma_f32_16x16x32_bf16 v[104:107], v[158:161], v[182:185], v[104:107]
	v_mfma_f32_16x16x32_bf16 v[92:95], v[146:149], v[190:193], v[92:95]
	v_mfma_f32_16x16x32_bf16 v[88:91], v[158:161], v[190:193], v[88:91]
	v_mfma_f32_16x16x32_bf16 v[80:83], v[146:149], v[198:201], v[80:83]
	v_mfma_f32_16x16x32_bf16 v[72:75], v[158:161], v[198:201], v[72:75]
	v_mfma_f32_16x16x32_bf16 v[124:127], v[154:157], v[178:181], v[124:127]
	v_mfma_f32_16x16x32_bf16 v[120:123], v[162:165], v[178:181], v[120:123]
	v_mfma_f32_16x16x32_bf16 v[112:115], v[154:157], v[186:189], v[112:115]
	v_mfma_f32_16x16x32_bf16 v[104:107], v[162:165], v[186:189], v[104:107]
	v_mfma_f32_16x16x32_bf16 v[92:95], v[154:157], v[194:197], v[92:95]
	v_mfma_f32_16x16x32_bf16 v[88:91], v[162:165], v[194:197], v[88:91]
	v_mfma_f32_16x16x32_bf16 v[80:83], v[154:157], v[202:205], v[80:83]
	v_mfma_f32_16x16x32_bf16 v[72:75], v[162:165], v[202:205], v[72:75]
	s_barrier
	s_add_i32 s48, s38, s27
	v_lshl_add_u64 v[150:151], s[22:23], 0, v[132:133]
	s_mov_b32 m0, s48
	ds_read_b128 v[206:209], v175
	ds_read_b128 v[210:213], v175 offset:1024
	ds_read_b128 v[214:217], v175 offset:2048
	ds_read_b128 v[218:221], v175 offset:3072
	global_load_lds_dwordx4 v[150:151], off
	v_lshl_add_u64 v[222:223], s[22:23], 0, v[128:129]
	s_add_i32 m0, s48, 0x2000
	s_nop 0
	global_load_lds_dwordx4 v[222:223], off
	s_barrier
	s_waitcnt lgkmcnt(0)
	v_mfma_f32_16x16x32_bf16 v[116:119], v[206:209], v[166:169], v[116:119]
	v_mfma_f32_16x16x32_bf16 v[108:111], v[214:217], v[166:169], v[108:111]
	v_mfma_f32_16x16x32_bf16 v[100:103], v[206:209], v[182:185], v[100:103]
	v_mfma_f32_16x16x32_bf16 v[96:99], v[214:217], v[182:185], v[96:99]
	v_mfma_f32_16x16x32_bf16 v[84:87], v[206:209], v[190:193], v[84:87]
	v_mfma_f32_16x16x32_bf16 v[76:79], v[214:217], v[190:193], v[76:79]
	v_mfma_f32_16x16x32_bf16 v[68:71], v[206:209], v[198:201], v[68:71]
	v_mfma_f32_16x16x32_bf16 v[64:67], v[214:217], v[198:201], v[64:67]
	v_mfma_f32_16x16x32_bf16 v[116:119], v[210:213], v[178:181], v[116:119]
	v_mfma_f32_16x16x32_bf16 v[108:111], v[218:221], v[178:181], v[108:111]
	v_mfma_f32_16x16x32_bf16 v[100:103], v[210:213], v[186:189], v[100:103]
	v_mfma_f32_16x16x32_bf16 v[96:99], v[218:221], v[186:189], v[96:99]
	v_mfma_f32_16x16x32_bf16 v[84:87], v[210:213], v[194:197], v[84:87]
	v_mfma_f32_16x16x32_bf16 v[76:79], v[218:221], v[194:197], v[76:79]
	v_mfma_f32_16x16x32_bf16 v[68:71], v[210:213], v[202:205], v[68:71]
	v_mfma_f32_16x16x32_bf16 v[64:67], v[218:221], v[202:205], v[64:67]
	s_mov_b32 m0, s19
	v_lshl_add_u64 v[224:225], s[24:25], 0, v[134:135]
	s_barrier
	ds_read_b128 v[166:169], v174 offset:16384
	ds_read_b128 v[178:181], v174 offset:17408
	ds_read_b128 v[182:185], v174 offset:18432
	ds_read_b128 v[186:189], v174 offset:19456
	ds_read_b128 v[190:193], v174 offset:20480
	ds_read_b128 v[194:197], v174 offset:21504
	ds_read_b128 v[198:201], v174 offset:22528
	ds_read_b128 v[202:205], v174 offset:23552
	global_load_lds_dwordx4 v[224:225], off
	v_lshl_add_u64 v[226:227], s[24:25], 0, v[130:131]
	s_mov_b32 m0, s30
	s_nop 0
	global_load_lds_dwordx4 v[226:227], off
	s_barrier
	s_waitcnt lgkmcnt(0)
	v_mfma_f32_16x16x32_bf16 v[60:63], v[146:149], v[166:169], v[60:63]
	v_mfma_f32_16x16x32_bf16 v[56:59], v[158:161], v[166:169], v[56:59]
	v_mfma_f32_16x16x32_bf16 v[48:51], v[146:149], v[182:185], v[48:51]
	v_mfma_f32_16x16x32_bf16 v[40:43], v[158:161], v[182:185], v[40:43]
	v_mfma_f32_16x16x32_bf16 v[32:35], v[146:149], v[190:193], v[32:35]
	v_mfma_f32_16x16x32_bf16 v[24:27], v[158:161], v[190:193], v[24:27]
	v_mfma_f32_16x16x32_bf16 v[16:19], v[146:149], v[198:201], v[16:19]
	v_mfma_f32_16x16x32_bf16 v[8:11], v[158:161], v[198:201], v[8:11]
	v_mfma_f32_16x16x32_bf16 v[60:63], v[154:157], v[178:181], v[60:63]
	v_mfma_f32_16x16x32_bf16 v[56:59], v[162:165], v[178:181], v[56:59]
	v_mfma_f32_16x16x32_bf16 v[48:51], v[154:157], v[186:189], v[48:51]
	v_mfma_f32_16x16x32_bf16 v[40:43], v[162:165], v[186:189], v[40:43]
	v_mfma_f32_16x16x32_bf16 v[32:35], v[154:157], v[194:197], v[32:35]
	v_mfma_f32_16x16x32_bf16 v[24:27], v[162:165], v[194:197], v[24:27]
	v_mfma_f32_16x16x32_bf16 v[16:19], v[154:157], v[202:205], v[16:19]
	v_mfma_f32_16x16x32_bf16 v[8:11], v[162:165], v[202:205], v[8:11]
	s_barrier
	s_add_u32 s48, s22, 0x40000
	s_addc_u32 s49, s23, 0
	s_add_i32 s50, s39, s27
	v_lshl_add_u64 v[146:147], s[48:49], 0, v[132:133]
	s_mov_b32 m0, s50
	s_nop 0
	global_load_lds_dwordx4 v[146:147], off
	v_lshl_add_u64 v[146:147], s[48:49], 0, v[128:129]
	s_add_i32 m0, s50, 0x2000
	s_nop 0
	global_load_lds_dwordx4 v[146:147], off
	s_waitcnt vmcnt(6)
	s_barrier
	v_mfma_f32_16x16x32_bf16 v[52:55], v[206:209], v[166:169], v[52:55]
	v_mfma_f32_16x16x32_bf16 v[44:47], v[214:217], v[166:169], v[44:47]
	v_mfma_f32_16x16x32_bf16 v[36:39], v[206:209], v[182:185], v[36:39]
	v_mfma_f32_16x16x32_bf16 v[28:31], v[214:217], v[182:185], v[28:31]
	v_mfma_f32_16x16x32_bf16 v[20:23], v[206:209], v[190:193], v[20:23]
	v_mfma_f32_16x16x32_bf16 v[12:15], v[214:217], v[190:193], v[12:15]
	v_mfma_f32_16x16x32_bf16 v[4:7], v[206:209], v[198:201], v[4:7]
	v_mfma_f32_16x16x32_bf16 v[0:3], v[214:217], v[198:201], v[0:3]
	v_mfma_f32_16x16x32_bf16 v[52:55], v[210:213], v[178:181], v[52:55]
	v_mfma_f32_16x16x32_bf16 v[44:47], v[218:221], v[178:181], v[44:47]
	v_mfma_f32_16x16x32_bf16 v[36:39], v[210:213], v[186:189], v[36:39]
	v_mfma_f32_16x16x32_bf16 v[28:31], v[218:221], v[186:189], v[28:31]
	v_mfma_f32_16x16x32_bf16 v[20:23], v[210:213], v[194:197], v[20:23]
	v_mfma_f32_16x16x32_bf16 v[12:15], v[218:221], v[194:197], v[12:15]
	v_mfma_f32_16x16x32_bf16 v[4:7], v[210:213], v[202:205], v[4:7]
	v_mfma_f32_16x16x32_bf16 v[0:3], v[218:221], v[202:205], v[0:3]
	s_add_i32 s48, 0, 0x18000
	v_add_u32_e32 v162, s48, v171
	s_barrier
	ds_read_b128 v[146:149], v162
	ds_read_b128 v[154:157], v162 offset:1024
	ds_read_b128 v[158:161], v162 offset:2048
	ds_read_b128 v[162:165], v162 offset:3072
	s_add_u32 s24, s24, 0x40000
	s_addc_u32 s25, s25, 0
	s_mov_b32 m0, s31
	v_lshl_add_u64 v[206:207], s[24:25], 0, v[134:135]
	ds_read_b128 v[166:169], v174 offset:32768
	ds_read_b128 v[178:181], v174 offset:33792
	ds_read_b128 v[182:185], v174 offset:34816
	ds_read_b128 v[186:189], v174 offset:35840
	ds_read_b128 v[190:193], v174 offset:36864
	ds_read_b128 v[194:197], v174 offset:37888
	ds_read_b128 v[198:201], v174 offset:38912
	ds_read_b128 v[202:205], v174 offset:39936
	global_load_lds_dwordx4 v[206:207], off
	v_lshl_add_u64 v[206:207], s[24:25], 0, v[130:131]
	s_mov_b32 m0, s33
	s_nop 0
	global_load_lds_dwordx4 v[206:207], off
	s_waitcnt lgkmcnt(8)
	s_barrier
	s_waitcnt lgkmcnt(0)
	v_mfma_f32_16x16x32_bf16 v[124:127], v[146:149], v[166:169], v[124:127]
	v_mfma_f32_16x16x32_bf16 v[120:123], v[158:161], v[166:169], v[120:123]
	v_mfma_f32_16x16x32_bf16 v[112:115], v[146:149], v[182:185], v[112:115]
	v_mfma_f32_16x16x32_bf16 v[104:107], v[158:161], v[182:185], v[104:107]
	v_mfma_f32_16x16x32_bf16 v[92:95], v[146:149], v[190:193], v[92:95]
	v_mfma_f32_16x16x32_bf16 v[88:91], v[158:161], v[190:193], v[88:91]
	v_mfma_f32_16x16x32_bf16 v[80:83], v[146:149], v[198:201], v[80:83]
	v_mfma_f32_16x16x32_bf16 v[72:75], v[158:161], v[198:201], v[72:75]
	v_mfma_f32_16x16x32_bf16 v[124:127], v[154:157], v[178:181], v[124:127]
	v_mfma_f32_16x16x32_bf16 v[120:123], v[162:165], v[178:181], v[120:123]
	v_mfma_f32_16x16x32_bf16 v[112:115], v[154:157], v[186:189], v[112:115]
	v_mfma_f32_16x16x32_bf16 v[104:107], v[162:165], v[186:189], v[104:107]
	v_mfma_f32_16x16x32_bf16 v[92:95], v[154:157], v[194:197], v[92:95]
	v_mfma_f32_16x16x32_bf16 v[88:91], v[162:165], v[194:197], v[88:91]
	v_mfma_f32_16x16x32_bf16 v[80:83], v[154:157], v[202:205], v[80:83]
	v_mfma_f32_16x16x32_bf16 v[72:75], v[162:165], v[202:205], v[72:75]
	s_barrier
	s_add_i32 s24, 0, 0x1c000
	s_add_i32 s25, s48, s27
	v_add_u32_e32 v177, s24, v171
	v_lshl_add_u64 v[150:151], v[150:151], 0, s[4:5]
	s_mov_b32 m0, s25
	ds_read_b128 v[206:209], v177
	ds_read_b128 v[210:213], v177 offset:1024
	ds_read_b128 v[214:217], v177 offset:2048
	ds_read_b128 v[218:221], v177 offset:3072
	global_load_lds_dwordx4 v[150:151], off
	v_lshl_add_u64 v[150:151], v[222:223], 0, s[4:5]
	s_add_i32 m0, s25, 0x2000
	s_nop 0
	global_load_lds_dwordx4 v[150:151], off
	s_barrier
	s_waitcnt lgkmcnt(0)
	v_mfma_f32_16x16x32_bf16 v[116:119], v[206:209], v[166:169], v[116:119]
	v_mfma_f32_16x16x32_bf16 v[108:111], v[214:217], v[166:169], v[108:111]
	v_mfma_f32_16x16x32_bf16 v[100:103], v[206:209], v[182:185], v[100:103]
	v_mfma_f32_16x16x32_bf16 v[96:99], v[214:217], v[182:185], v[96:99]
	v_mfma_f32_16x16x32_bf16 v[84:87], v[206:209], v[190:193], v[84:87]
	v_mfma_f32_16x16x32_bf16 v[76:79], v[214:217], v[190:193], v[76:79]
	v_mfma_f32_16x16x32_bf16 v[68:71], v[206:209], v[198:201], v[68:71]
	v_mfma_f32_16x16x32_bf16 v[64:67], v[214:217], v[198:201], v[64:67]
	v_mfma_f32_16x16x32_bf16 v[116:119], v[210:213], v[178:181], v[116:119]
	v_mfma_f32_16x16x32_bf16 v[108:111], v[218:221], v[178:181], v[108:111]
	v_mfma_f32_16x16x32_bf16 v[100:103], v[210:213], v[186:189], v[100:103]
	v_mfma_f32_16x16x32_bf16 v[96:99], v[218:221], v[186:189], v[96:99]
	v_mfma_f32_16x16x32_bf16 v[84:87], v[210:213], v[194:197], v[84:87]
	v_mfma_f32_16x16x32_bf16 v[76:79], v[218:221], v[194:197], v[76:79]
	v_mfma_f32_16x16x32_bf16 v[68:71], v[210:213], v[202:205], v[68:71]
	v_mfma_f32_16x16x32_bf16 v[64:67], v[218:221], v[202:205], v[64:67]
	s_mov_b32 m0, s35
	v_lshl_add_u64 v[150:151], v[224:225], 0, s[4:5]
	s_barrier
	ds_read_b128 v[166:169], v174 offset:49152
	ds_read_b128 v[178:181], v174 offset:50176
	ds_read_b128 v[182:185], v174 offset:51200
	ds_read_b128 v[186:189], v174 offset:52224
	ds_read_b128 v[190:193], v174 offset:53248
	ds_read_b128 v[194:197], v174 offset:54272
	ds_read_b128 v[198:201], v174 offset:55296
	ds_read_b128 v[202:205], v174 offset:56320
	global_load_lds_dwordx4 v[150:151], off
	v_lshl_add_u64 v[150:151], v[226:227], 0, s[4:5]
	s_mov_b32 m0, s36
	s_nop 0
	global_load_lds_dwordx4 v[150:151], off
	s_barrier
	s_waitcnt lgkmcnt(0)
	v_mfma_f32_16x16x32_bf16 v[60:63], v[146:149], v[166:169], v[60:63]
	v_mfma_f32_16x16x32_bf16 v[56:59], v[158:161], v[166:169], v[56:59]
	v_mfma_f32_16x16x32_bf16 v[48:51], v[146:149], v[182:185], v[48:51]
	v_mfma_f32_16x16x32_bf16 v[40:43], v[158:161], v[182:185], v[40:43]
	v_mfma_f32_16x16x32_bf16 v[32:35], v[146:149], v[190:193], v[32:35]
	v_mfma_f32_16x16x32_bf16 v[24:27], v[158:161], v[190:193], v[24:27]
	v_mfma_f32_16x16x32_bf16 v[16:19], v[146:149], v[198:201], v[16:19]
	v_mfma_f32_16x16x32_bf16 v[8:11], v[158:161], v[198:201], v[8:11]
	v_mfma_f32_16x16x32_bf16 v[60:63], v[154:157], v[178:181], v[60:63]
	v_mfma_f32_16x16x32_bf16 v[56:59], v[162:165], v[178:181], v[56:59]
	v_mfma_f32_16x16x32_bf16 v[48:51], v[154:157], v[186:189], v[48:51]
	v_mfma_f32_16x16x32_bf16 v[40:43], v[162:165], v[186:189], v[40:43]
	v_mfma_f32_16x16x32_bf16 v[32:35], v[154:157], v[194:197], v[32:35]
	v_mfma_f32_16x16x32_bf16 v[24:27], v[162:165], v[194:197], v[24:27]
	v_mfma_f32_16x16x32_bf16 v[16:19], v[154:157], v[202:205], v[16:19]
	v_mfma_f32_16x16x32_bf16 v[8:11], v[162:165], v[202:205], v[8:11]
	s_barrier
	s_add_u32 s22, s22, 0x40080
	s_addc_u32 s23, s23, 0
	s_add_i32 s24, s24, s27
	v_lshl_add_u64 v[146:147], s[22:23], 0, v[132:133]
	s_mov_b32 m0, s24
	s_nop 0
	global_load_lds_dwordx4 v[146:147], off
	v_lshl_add_u64 v[146:147], s[22:23], 0, v[128:129]
	s_add_i32 m0, s24, 0x2000
	s_nop 0
	global_load_lds_dwordx4 v[146:147], off
	s_waitcnt vmcnt(6)
	s_barrier
	v_mfma_f32_16x16x32_bf16 v[52:55], v[206:209], v[166:169], v[52:55]
	v_mfma_f32_16x16x32_bf16 v[44:47], v[214:217], v[166:169], v[44:47]
	v_mfma_f32_16x16x32_bf16 v[36:39], v[206:209], v[182:185], v[36:39]
	v_mfma_f32_16x16x32_bf16 v[28:31], v[214:217], v[182:185], v[28:31]
	v_mfma_f32_16x16x32_bf16 v[20:23], v[206:209], v[190:193], v[20:23]
	v_mfma_f32_16x16x32_bf16 v[12:15], v[214:217], v[190:193], v[12:15]
	v_mfma_f32_16x16x32_bf16 v[4:7], v[206:209], v[198:201], v[4:7]
	v_mfma_f32_16x16x32_bf16 v[0:3], v[214:217], v[198:201], v[0:3]
	v_mfma_f32_16x16x32_bf16 v[52:55], v[210:213], v[178:181], v[52:55]
	v_mfma_f32_16x16x32_bf16 v[44:47], v[218:221], v[178:181], v[44:47]
	v_mfma_f32_16x16x32_bf16 v[36:39], v[210:213], v[186:189], v[36:39]
	v_mfma_f32_16x16x32_bf16 v[28:31], v[218:221], v[186:189], v[28:31]
	v_mfma_f32_16x16x32_bf16 v[20:23], v[210:213], v[194:197], v[20:23]
	v_mfma_f32_16x16x32_bf16 v[12:15], v[218:221], v[194:197], v[12:15]
	v_mfma_f32_16x16x32_bf16 v[4:7], v[210:213], v[202:205], v[4:7]
	v_mfma_f32_16x16x32_bf16 v[0:3], v[218:221], v[202:205], v[0:3]
	s_add_i32 s47, s47, 2
	s_add_u32 s20, s20, 0x100
	s_addc_u32 s21, s21, 0
	s_add_u32 s45, s45, 0x100
	s_addc_u32 s46, s46, 0
	s_cmp_gt_u32 s47, 13
	s_barrier
	s_cbranch_scc0 .LBB0_922
	s_bfe_u32 vcc_lo, s18, 0x20003
	s_lshl_b32 vcc_lo, vcc_lo, 10
	s_add_i32 vcc_lo, vcc_lo, 0x20010
	v_lshl_add_u32 v236, v170, 2, vcc_lo
	ds_read_b32 v228, v236
	ds_read_b32 v229, v236 offset:64
	ds_read_b32 v230, v236 offset:128
	ds_read_b32 v231, v236 offset:192
	ds_read_b32 v232, v236 offset:512
	ds_read_b32 v233, v236 offset:576
	ds_read_b32 v234, v236 offset:640
	ds_read_b32 v235, v236 offset:704
	s_waitcnt lgkmcnt(0)
	v_lshl_add_u32 v154, s18, 8, v170
	v_or_b32_e32 v206, 16, v154
	v_or_b32_e32 v168, 32, v154
	v_or_b32_e32 v162, 48, v154
	v_add_u32_e32 v160, 0x80, v154
	v_add_u32_e32 v156, 0x90, v154
	v_add_u32_e32 v150, 0xa0, v154
	v_add_u32_e32 v146, 0xb0, v154
	v_lshl_or_b32 v208, s42, 8, v172
	v_mov_b64_e32 v[148:149], s[96:97]
	v_ashrrev_i32_e32 v209, 31, v208
	v_mad_i64_i32 v[210:211], s[20:21], v154, s40, v[148:149]
	s_nop 0
	v_lshlrev_b64 v[154:155], 1, v[208:209]
	v_lshl_add_u64 v[208:209], v[210:211], 0, v[154:155]
	s_mov_b32 s42, s10
	s_mov_b32 s18, s12
	s_mov_b64 s[22:23], s[16:17]
	s_waitcnt vmcnt(8)
	s_waitcnt lgkmcnt(0)
	s_waitcnt lgkmcnt(0)
	v_mov_b32_e32 v178, v228
	v_pk_mul_f32 v[126:127], v[126:127], v[178:179] op_sel_hi:[1,0]
	v_pk_mul_f32 v[124:125], v[124:125], v[178:179] op_sel_hi:[1,0]
	v_pk_mul_f32 v[190:191], v[122:123], v[178:179] op_sel_hi:[1,0]
	v_pk_mul_f32 v[122:123], v[120:121], v[178:179] op_sel_hi:[1,0]
	v_cvt_pk_bf16_f32 v120, v124, v125
	v_cvt_pk_bf16_f32 v121, v126, v127
	v_cvt_pk_bf16_f32 v122, v122, v123
	v_cvt_pk_bf16_f32 v123, v190, v191
	v_pk_mul_f32 v[116:117], v[116:117], v[178:179] op_sel_hi:[1,0]
	global_store_dwordx4 v[208:209], v[120:123], off
	s_nop 0
	v_pk_mul_f32 v[118:119], v[118:119], v[178:179] op_sel_hi:[1,0]
	v_pk_mul_f32 v[120:121], v[110:111], v[178:179] op_sel_hi:[1,0]
	v_pk_mul_f32 v[110:111], v[108:109], v[178:179] op_sel_hi:[1,0]
	v_cvt_pk_bf16_f32 v108, v116, v117
	v_cvt_pk_bf16_f32 v109, v118, v119
	v_cvt_pk_bf16_f32 v110, v110, v111
	v_cvt_pk_bf16_f32 v111, v120, v121
	global_store_dwordx4 v[208:209], v[108:111], off offset:256
	s_nop 1
	v_mov_b32_e32 v108, v229
	v_mad_i64_i32 v[110:111], s[20:21], v206, s40, v[148:149]
	v_pk_mul_f32 v[114:115], v[114:115], v[108:109] op_sel_hi:[1,0]
	v_pk_mul_f32 v[112:113], v[112:113], v[108:109] op_sel_hi:[1,0]
	v_pk_mul_f32 v[116:117], v[106:107], v[108:109] op_sel_hi:[1,0]
	v_pk_mul_f32 v[106:107], v[104:105], v[108:109] op_sel_hi:[1,0]
	v_lshl_add_u64 v[110:111], v[110:111], 0, v[154:155]
	v_cvt_pk_bf16_f32 v104, v112, v113
	v_cvt_pk_bf16_f32 v105, v114, v115
	v_cvt_pk_bf16_f32 v106, v106, v107
	v_cvt_pk_bf16_f32 v107, v116, v117
	global_store_dwordx4 v[110:111], v[104:107], off
	v_pk_mul_f32 v[100:101], v[100:101], v[108:109] op_sel_hi:[1,0]
	v_pk_mul_f32 v[112:113], v[98:99], v[108:109] op_sel_hi:[1,0]
	v_pk_mul_f32 v[98:99], v[96:97], v[108:109] op_sel_hi:[1,0]
	v_cvt_pk_bf16_f32 v96, v100, v101
	v_pk_mul_f32 v[102:103], v[102:103], v[108:109] op_sel_hi:[1,0]
	v_cvt_pk_bf16_f32 v98, v98, v99
	s_waitcnt lgkmcnt(0)
	v_cvt_pk_bf16_f32 v97, v102, v103
	v_cvt_pk_bf16_f32 v99, v112, v113
	global_store_dwordx4 v[110:111], v[96:99], off offset:256
	s_nop 0
	s_waitcnt lgkmcnt(0)
	v_mad_i64_i32 v[98:99], s[20:21], v168, s40, v[148:149]
	v_lshl_add_u64 v[98:99], v[98:99], 0, v[154:155]
	v_mov_b32_e32 v100, v230
	v_pk_mul_f32 v[94:95], v[94:95], v[100:101] op_sel_hi:[1,0]
	v_pk_mul_f32 v[92:93], v[92:93], v[100:101] op_sel_hi:[1,0]
	v_pk_mul_f32 v[102:103], v[90:91], v[100:101] op_sel_hi:[1,0]
	v_pk_mul_f32 v[90:91], v[88:89], v[100:101] op_sel_hi:[1,0]
	v_cvt_pk_bf16_f32 v88, v92, v93
	v_cvt_pk_bf16_f32 v89, v94, v95
	v_cvt_pk_bf16_f32 v90, v90, v91
	v_cvt_pk_bf16_f32 v91, v102, v103
	v_pk_mul_f32 v[84:85], v[84:85], v[100:101] op_sel_hi:[1,0]
	global_store_dwordx4 v[98:99], v[88:91], off
	s_nop 0
	v_pk_mul_f32 v[86:87], v[86:87], v[100:101] op_sel_hi:[1,0]
	v_pk_mul_f32 v[88:89], v[78:79], v[100:101] op_sel_hi:[1,0]
	v_pk_mul_f32 v[78:79], v[76:77], v[100:101] op_sel_hi:[1,0]
	v_cvt_pk_bf16_f32 v76, v84, v85
	v_cvt_pk_bf16_f32 v77, v86, v87
	v_cvt_pk_bf16_f32 v78, v78, v79
	v_cvt_pk_bf16_f32 v79, v88, v89
	global_store_dwordx4 v[98:99], v[76:79], off offset:256
	s_nop 1
	v_mov_b32_e32 v76, v231
	v_mad_i64_i32 v[78:79], s[20:21], v162, s40, v[148:149]
	v_pk_mul_f32 v[82:83], v[82:83], v[76:77] op_sel_hi:[1,0]
	v_pk_mul_f32 v[80:81], v[80:81], v[76:77] op_sel_hi:[1,0]
	v_pk_mul_f32 v[84:85], v[74:75], v[76:77] op_sel_hi:[1,0]
	v_pk_mul_f32 v[74:75], v[72:73], v[76:77] op_sel_hi:[1,0]
	v_lshl_add_u64 v[78:79], v[78:79], 0, v[154:155]
	v_cvt_pk_bf16_f32 v72, v80, v81
	v_cvt_pk_bf16_f32 v73, v82, v83
	v_cvt_pk_bf16_f32 v74, v74, v75
	v_cvt_pk_bf16_f32 v75, v84, v85
	global_store_dwordx4 v[78:79], v[72:75], off
	v_pk_mul_f32 v[68:69], v[68:69], v[76:77] op_sel_hi:[1,0]
	v_pk_mul_f32 v[80:81], v[66:67], v[76:77] op_sel_hi:[1,0]
	v_pk_mul_f32 v[66:67], v[64:65], v[76:77] op_sel_hi:[1,0]
	v_cvt_pk_bf16_f32 v64, v68, v69
	v_pk_mul_f32 v[70:71], v[70:71], v[76:77] op_sel_hi:[1,0]
	v_cvt_pk_bf16_f32 v66, v66, v67
	s_waitcnt lgkmcnt(0)
	v_cvt_pk_bf16_f32 v65, v70, v71
	v_cvt_pk_bf16_f32 v67, v80, v81
	global_store_dwordx4 v[78:79], v[64:67], off offset:256
	s_waitcnt lgkmcnt(0)
	s_nop 0
	s_nop 0
	s_nop 0
	s_nop 1
	v_mad_i64_i32 v[66:67], s[20:21], v160, s40, v[148:149]
	v_lshl_add_u64 v[66:67], v[66:67], 0, v[154:155]
	v_mov_b32_e32 v68, v232
	v_pk_mul_f32 v[62:63], v[62:63], v[68:69] op_sel_hi:[1,0]
	v_pk_mul_f32 v[60:61], v[60:61], v[68:69] op_sel_hi:[1,0]
	v_pk_mul_f32 v[70:71], v[58:59], v[68:69] op_sel_hi:[1,0]
	v_pk_mul_f32 v[58:59], v[56:57], v[68:69] op_sel_hi:[1,0]
	v_cvt_pk_bf16_f32 v56, v60, v61
	v_cvt_pk_bf16_f32 v57, v62, v63
	v_cvt_pk_bf16_f32 v58, v58, v59
	v_cvt_pk_bf16_f32 v59, v70, v71
	v_pk_mul_f32 v[52:53], v[52:53], v[68:69] op_sel_hi:[1,0]
	global_store_dwordx4 v[66:67], v[56:59], off
	s_nop 0
	v_pk_mul_f32 v[54:55], v[54:55], v[68:69] op_sel_hi:[1,0]
	v_pk_mul_f32 v[56:57], v[46:47], v[68:69] op_sel_hi:[1,0]
	v_pk_mul_f32 v[46:47], v[44:45], v[68:69] op_sel_hi:[1,0]
	v_cvt_pk_bf16_f32 v44, v52, v53
	v_cvt_pk_bf16_f32 v45, v54, v55
	v_cvt_pk_bf16_f32 v46, v46, v47
	v_cvt_pk_bf16_f32 v47, v56, v57
	global_store_dwordx4 v[66:67], v[44:47], off offset:256
	s_nop 1
	v_mov_b32_e32 v44, v233
	v_mad_i64_i32 v[46:47], s[20:21], v156, s40, v[148:149]
	v_pk_mul_f32 v[50:51], v[50:51], v[44:45] op_sel_hi:[1,0]
	v_pk_mul_f32 v[48:49], v[48:49], v[44:45] op_sel_hi:[1,0]
	v_pk_mul_f32 v[52:53], v[42:43], v[44:45] op_sel_hi:[1,0]
	v_pk_mul_f32 v[42:43], v[40:41], v[44:45] op_sel_hi:[1,0]
	v_lshl_add_u64 v[46:47], v[46:47], 0, v[154:155]
	v_cvt_pk_bf16_f32 v40, v48, v49
	v_cvt_pk_bf16_f32 v41, v50, v51
	v_cvt_pk_bf16_f32 v42, v42, v43
	v_cvt_pk_bf16_f32 v43, v52, v53
	global_store_dwordx4 v[46:47], v[40:43], off
	v_pk_mul_f32 v[36:37], v[36:37], v[44:45] op_sel_hi:[1,0]
	v_pk_mul_f32 v[48:49], v[30:31], v[44:45] op_sel_hi:[1,0]
	v_pk_mul_f32 v[30:31], v[28:29], v[44:45] op_sel_hi:[1,0]
	v_cvt_pk_bf16_f32 v28, v36, v37
	v_pk_mul_f32 v[38:39], v[38:39], v[44:45] op_sel_hi:[1,0]
	v_cvt_pk_bf16_f32 v30, v30, v31
	s_waitcnt lgkmcnt(0)
	v_cvt_pk_bf16_f32 v29, v38, v39
	v_cvt_pk_bf16_f32 v31, v48, v49
	global_store_dwordx4 v[46:47], v[28:31], off offset:256
	s_waitcnt lgkmcnt(0)
	s_nop 0
	s_nop 0
	s_nop 0
	s_nop 1
	v_mad_i64_i32 v[30:31], s[20:21], v150, s40, v[148:149]
	v_lshl_add_u64 v[30:31], v[30:31], 0, v[154:155]
	v_mov_b32_e32 v36, v234
	v_pk_mul_f32 v[34:35], v[34:35], v[36:37] op_sel_hi:[1,0]
	v_pk_mul_f32 v[32:33], v[32:33], v[36:37] op_sel_hi:[1,0]
	v_pk_mul_f32 v[38:39], v[26:27], v[36:37] op_sel_hi:[1,0]
	v_pk_mul_f32 v[26:27], v[24:25], v[36:37] op_sel_hi:[1,0]
	v_cvt_pk_bf16_f32 v24, v32, v33
	v_cvt_pk_bf16_f32 v25, v34, v35
	v_cvt_pk_bf16_f32 v26, v26, v27
	v_cvt_pk_bf16_f32 v27, v38, v39
	v_pk_mul_f32 v[20:21], v[20:21], v[36:37] op_sel_hi:[1,0]
	global_store_dwordx4 v[30:31], v[24:27], off
	s_nop 0
	v_pk_mul_f32 v[22:23], v[22:23], v[36:37] op_sel_hi:[1,0]
	v_pk_mul_f32 v[24:25], v[14:15], v[36:37] op_sel_hi:[1,0]
	v_pk_mul_f32 v[14:15], v[12:13], v[36:37] op_sel_hi:[1,0]
	v_cvt_pk_bf16_f32 v12, v20, v21
	v_cvt_pk_bf16_f32 v13, v22, v23
	v_cvt_pk_bf16_f32 v14, v14, v15
	v_cvt_pk_bf16_f32 v15, v24, v25
	global_store_dwordx4 v[30:31], v[12:15], off offset:256
	s_nop 1
	v_mov_b32_e32 v12, v235
	v_mad_i64_i32 v[14:15], s[20:21], v146, s40, v[148:149]
	v_pk_mul_f32 v[18:19], v[18:19], v[12:13] op_sel_hi:[1,0]
	v_pk_mul_f32 v[16:17], v[16:17], v[12:13] op_sel_hi:[1,0]
	v_pk_mul_f32 v[20:21], v[10:11], v[12:13] op_sel_hi:[1,0]
	v_pk_mul_f32 v[10:11], v[8:9], v[12:13] op_sel_hi:[1,0]
	v_lshl_add_u64 v[14:15], v[14:15], 0, v[154:155]
	v_cvt_pk_bf16_f32 v8, v16, v17
	v_cvt_pk_bf16_f32 v9, v18, v19
	v_cvt_pk_bf16_f32 v10, v10, v11
	v_cvt_pk_bf16_f32 v11, v20, v21
	global_store_dwordx4 v[14:15], v[8:11], off
	v_pk_mul_f32 v[6:7], v[6:7], v[12:13] op_sel_hi:[1,0]
	v_pk_mul_f32 v[4:5], v[4:5], v[12:13] op_sel_hi:[1,0]
	v_pk_mul_f32 v[8:9], v[2:3], v[12:13] op_sel_hi:[1,0]
	v_pk_mul_f32 v[2:3], v[0:1], v[12:13] op_sel_hi:[1,0]
	v_cvt_pk_bf16_f32 v0, v4, v5
	v_cvt_pk_bf16_f32 v1, v6, v7
	v_cvt_pk_bf16_f32 v2, v2, v3
	v_cvt_pk_bf16_f32 v3, v8, v9
	s_and_b64 vcc, exec, s[0:1]
	s_mov_b64 s[20:21], s[14:15]
	global_store_dwordx4 v[14:15], v[0:3], off offset:256
	s_cbranch_vccz .LBB0_919
	s_waitcnt vmcnt(0)
	v_readlane_b32 s40, v251, 54
	s_cmpk_gt_u32 s7, 0xff
	v_readlane_b32 s41, v251, 55
	s_cbranch_scc1 .LBB0_926
	s_barrier

; #define PG8_STAGE(bufoff, gbase, voff) do { _Pragma("unroll") for (int _i = 0; _i < 2; ++_i) \
;         __builtin_amdgcn_global_load_lds((const unsigned*)((const char*)(gbase) + (voff)[_i]), (LAS unsigned*)(lds + (bufoff) + ldsw + _i * 8192), 16, 0, 0); } while (0)
; #define PG8_LDA(dst, b, h) do { _Pragma("unroll") for (int m = 0; m < 4; ++m) _Pragma("unroll") for (int k = 0; k < 2; ++k) dst[m][k] = *(const LAS bf16x8*)(lds + PG8_SA(b, h) + aoff + m * 2048 + k * 1024); } while (0)
; #define PG8_LDB(dst, b, h) do { _Pragma("unroll") for (int n = 0; n < 2; ++n) _Pragma("unroll") for (int k = 0; k < 2; ++k) dst[n][k] = *(const LAS bf16x8*)(lds + PG8_SB(b, h) + boff + n * 2048 + k * 1024); } while (0)
; #define PG8_WAIT_V(n) asm volatile("s_waitcnt vmcnt(" #n ")" ::: "memory")
; #define PG8_WAIT_L(n) asm volatile("s_waitcnt lgkmcnt(" #n ")" ::: "memory")
; #define PG8_BAR __builtin_amdgcn_s_barrier()
; #define PG8_SCHED __builtin_amdgcn_sched_barrier(0)
; template <class Epi>
; __device__ __forceinline__ void gemm_phase(LAS unsigned char* lds, const Gemm g, const StaticOrder& S, const Epi& E) {
;     ...
;     for (;;) {
;         const bool has_next = S.next(ui + 1, nxt);
;         const char* nA = has_next ? (const char*)g.A + (size_t)nxt.pm * tstepA : cA; const char* nB = has_next ? (const char*)g.Bt + (size_t)nxt.pn * tstepB : cB;
;         for (int t = 0; t < nt; t += 2) {
;             const bool last = (t == nt - 2);
;             const char* a1 = cA + (size_t)(t + 1) * kstep;
;             const char* a2 = last ? nA : cA + (size_t)(t + 2) * kstep; const char* b2 = last ? nB : cB + (size_t)(t + 2) * kstep;
;             const char* a3 = a2 + kstep; const char* b3 = b2 + kstep;
;             if (last) E.pre(cur, wr, fr, epre);
;             PG8_LDB(B0, 0, 0); PG8_SCHED; PG8_LDA(At, 0, 0); PG8_STAGE(PG8_SA(1, 1), a1 + hstepA, voffA);
;             PG8_WAIT_L(8); PG8_BAR; PG8_WAIT_L(0); PG8_MMA(0, 0, At, B0); PG8_BAR; PG8_SCHED;
;             PG8_LDB(B1, 0, 1); PG8_STAGE(PG8_SB(0, 0), b2, voffB);
;             PG8_BAR; PG8_WAIT_L(0); PG8_MMA(0, 1, At, B1); PG8_BAR;
;             PG8_LDA(At, 0, 1); PG8_STAGE(PG8_SA(0, 0), a2, voffA);
;             PG8_BAR; PG8_WAIT_L(0); PG8_MMA(1, 0, At, B0); PG8_BAR; PG8_SCHED;
;             PG8_STAGE(PG8_SB(0, 1), b2 + hstepB, voffB);
;             PG8_WAIT_V(6); PG8_BAR; PG8_MMA(1, 1, At, B1); PG8_BAR;
.LBB0_1117:
	s_ashr_i32 s17, s16, 31
	s_lshl_b64 s[20:21], s[16:17], 19
	s_add_u32 s20, s27, s20
	s_addc_u32 s21, s28, s21
	s_and_b64 s[4:5], s[4:5], exec
	s_cselect_b32 s17, s21, s23
	s_cselect_b32 s43, s20, s22
	s_add_u32 s4, s24, 0x140080
	s_addc_u32 s5, s25, 0
	s_add_u32 s44, s22, 0x100
	s_addc_u32 s45, s23, 0
	s_mov_b32 s46, -2
	s_waitcnt lgkmcnt(0)
	ds_read_b128 v[128:131], v190
	ds_read_b128 v[132:135], v190 offset:1024
	ds_read_b128 v[136:139], v190 offset:2048
	ds_read_b128 v[140:143], v190 offset:3072
	s_add_u32 s22, s4, 0xffec0080
	s_addc_u32 s23, s5, -1
	s_cmp_eq_u32 s46, 12
	s_cselect_b32 s25, s19, s23
	s_cselect_b32 s24, s18, s22
	s_cselect_b32 s23, s17, s45
	s_cselect_b32 s22, s43, s44
	v_lshl_add_u64 v[186:187], s[4:5], 0, v[162:163]
	s_add_i32 m0, s9, 0xc000
	ds_read_b128 v[144:147], v191
	ds_read_b128 v[148:151], v191 offset:1024
	ds_read_b128 v[170:173], v191 offset:2048
	ds_read_b128 v[174:177], v191 offset:3072
	ds_read_b128 v[178:181], v191 offset:4096
	ds_read_b128 v[182:185], v191 offset:5120
	ds_read_b128 v[194:197], v191 offset:6144
	ds_read_b128 v[198:201], v191 offset:7168
	global_load_lds_dwordx4 v[186:187], off
	v_lshl_add_u64 v[186:187], s[4:5], 0, v[164:165]
	s_add_i32 m0, s9, 0xe000
	s_nop 0
	global_load_lds_dwordx4 v[186:187], off
	s_waitcnt lgkmcnt(8)
	s_barrier
	s_waitcnt lgkmcnt(0)
	v_mfma_f32_16x16x32_bf16 v[124:127], v[128:131], v[144:147], 0
	v_mfma_f32_16x16x32_bf16 v[120:123], v[136:139], v[144:147], 0
	v_mfma_f32_16x16x32_bf16 v[108:111], v[128:131], v[170:173], 0
	v_mfma_f32_16x16x32_bf16 v[104:107], v[136:139], v[170:173], 0
	v_mfma_f32_16x16x32_bf16 v[92:95], v[128:131], v[178:181], 0
	v_mfma_f32_16x16x32_bf16 v[88:91], v[136:139], v[178:181], 0
	v_mfma_f32_16x16x32_bf16 v[76:79], v[128:131], v[194:197], 0
	v_mfma_f32_16x16x32_bf16 v[72:75], v[136:139], v[194:197], 0
	v_mfma_f32_16x16x32_bf16 v[124:127], v[132:135], v[148:151], v[124:127]
	v_mfma_f32_16x16x32_bf16 v[120:123], v[140:143], v[148:151], v[120:123]
	v_mfma_f32_16x16x32_bf16 v[108:111], v[132:135], v[174:177], v[108:111]
	v_mfma_f32_16x16x32_bf16 v[104:107], v[140:143], v[174:177], v[104:107]
	v_mfma_f32_16x16x32_bf16 v[92:95], v[132:135], v[182:185], v[92:95]
	v_mfma_f32_16x16x32_bf16 v[88:91], v[140:143], v[182:185], v[88:91]
	v_mfma_f32_16x16x32_bf16 v[76:79], v[132:135], v[198:201], v[76:79]
	v_mfma_f32_16x16x32_bf16 v[72:75], v[140:143], v[198:201], v[72:75]
	s_barrier
	s_add_i32 s47, s40, s29
	v_lshl_add_u64 v[186:187], s[22:23], 0, v[156:157]
	s_mov_b32 m0, s47
	ds_read_b128 v[202:205], v192
	ds_read_b128 v[206:209], v192 offset:1024
	ds_read_b128 v[210:213], v192 offset:2048
	ds_read_b128 v[214:217], v192 offset:3072
	global_load_lds_dwordx4 v[186:187], off
	v_lshl_add_u64 v[218:219], s[22:23], 0, v[160:161]
	s_add_i32 m0, s47, 0x2000
	s_nop 0
	global_load_lds_dwordx4 v[218:219], off
	s_barrier
	s_waitcnt lgkmcnt(0)
	v_mfma_f32_16x16x32_bf16 v[116:119], v[202:205], v[144:147], 0
	v_mfma_f32_16x16x32_bf16 v[112:115], v[210:213], v[144:147], 0
	v_mfma_f32_16x16x32_bf16 v[100:103], v[202:205], v[170:173], 0
	v_mfma_f32_16x16x32_bf16 v[96:99], v[210:213], v[170:173], 0
	v_mfma_f32_16x16x32_bf16 v[84:87], v[202:205], v[178:181], 0
	v_mfma_f32_16x16x32_bf16 v[80:83], v[210:213], v[178:181], 0
	v_mfma_f32_16x16x32_bf16 v[68:71], v[202:205], v[194:197], 0
	v_mfma_f32_16x16x32_bf16 v[64:67], v[210:213], v[194:197], 0
	v_mfma_f32_16x16x32_bf16 v[116:119], v[206:209], v[148:151], v[116:119]
	v_mfma_f32_16x16x32_bf16 v[112:115], v[214:217], v[148:151], v[112:115]
	v_mfma_f32_16x16x32_bf16 v[100:103], v[206:209], v[174:177], v[100:103]
	v_mfma_f32_16x16x32_bf16 v[96:99], v[214:217], v[174:177], v[96:99]
	v_mfma_f32_16x16x32_bf16 v[84:87], v[206:209], v[182:185], v[84:87]
	v_mfma_f32_16x16x32_bf16 v[80:83], v[214:217], v[182:185], v[80:83]
	v_mfma_f32_16x16x32_bf16 v[68:71], v[206:209], v[198:201], v[68:71]
	v_mfma_f32_16x16x32_bf16 v[64:67], v[214:217], v[198:201], v[64:67]
	s_mov_b32 m0, s9
	v_lshl_add_u64 v[220:221], s[24:25], 0, v[154:155]
	s_barrier
	ds_read_b128 v[144:147], v191 offset:16384
	ds_read_b128 v[148:151], v191 offset:17408
	ds_read_b128 v[170:173], v191 offset:18432
	ds_read_b128 v[174:177], v191 offset:19456
	ds_read_b128 v[178:181], v191 offset:20480
	ds_read_b128 v[182:185], v191 offset:21504
	ds_read_b128 v[194:197], v191 offset:22528
	ds_read_b128 v[198:201], v191 offset:23552
	global_load_lds_dwordx4 v[220:221], off
	v_lshl_add_u64 v[222:223], s[24:25], 0, v[158:159]
	s_mov_b32 m0, s30
	s_nop 0
	global_load_lds_dwordx4 v[222:223], off
	s_barrier
	s_waitcnt lgkmcnt(0)
	v_mfma_f32_16x16x32_bf16 v[60:63], v[128:131], v[144:147], 0
	v_mfma_f32_16x16x32_bf16 v[56:59], v[136:139], v[144:147], 0
	v_mfma_f32_16x16x32_bf16 v[44:47], v[128:131], v[170:173], 0
	v_mfma_f32_16x16x32_bf16 v[40:43], v[136:139], v[170:173], 0
	v_mfma_f32_16x16x32_bf16 v[28:31], v[128:131], v[178:181], 0
	v_mfma_f32_16x16x32_bf16 v[24:27], v[136:139], v[178:181], 0
	v_mfma_f32_16x16x32_bf16 v[12:15], v[128:131], v[194:197], 0
	v_mfma_f32_16x16x32_bf16 v[8:11], v[136:139], v[194:197], 0
	v_mfma_f32_16x16x32_bf16 v[60:63], v[132:135], v[148:151], v[60:63]
	v_mfma_f32_16x16x32_bf16 v[56:59], v[140:143], v[148:151], v[56:59]
	v_mfma_f32_16x16x32_bf16 v[44:47], v[132:135], v[174:177], v[44:47]
	v_mfma_f32_16x16x32_bf16 v[40:43], v[140:143], v[174:177], v[40:43]
	v_mfma_f32_16x16x32_bf16 v[28:31], v[132:135], v[182:185], v[28:31]
	v_mfma_f32_16x16x32_bf16 v[24:27], v[140:143], v[182:185], v[24:27]
	v_mfma_f32_16x16x32_bf16 v[12:15], v[132:135], v[198:201], v[12:15]
	v_mfma_f32_16x16x32_bf16 v[8:11], v[140:143], v[198:201], v[8:11]
	s_barrier
; #define PG8_STAGE(bufoff, gbase, voff) do { _Pragma("unroll") for (int _i = 0; _i < 2; ++_i) \
;         __builtin_amdgcn_global_load_lds((const unsigned*)((const char*)(gbase) + (voff)[_i]), (LAS unsigned*)(lds + (bufoff) + ldsw + _i * 8192), 16, 0, 0); } while (0)
; #define PG8_LDA(dst, b, h) do { _Pragma("unroll") for (int m = 0; m < 4; ++m) _Pragma("unroll") for (int k = 0; k < 2; ++k) dst[m][k] = *(const LAS bf16x8*)(lds + PG8_SA(b, h) + aoff + m * 2048 + k * 1024); } while (0)
; #define PG8_LDB(dst, b, h) do { _Pragma("unroll") for (int n = 0; n < 2; ++n) _Pragma("unroll") for (int k = 0; k < 2; ++k) dst[n][k] = *(const LAS bf16x8*)(lds + PG8_SB(b, h) + boff + n * 2048 + k * 1024); } while (0)
; #define PG8_WAIT_V(n) asm volatile("s_waitcnt vmcnt(" #n ")" ::: "memory")
; #define PG8_WAIT_L(n) asm volatile("s_waitcnt lgkmcnt(" #n ")" ::: "memory")
; #define PG8_BAR __builtin_amdgcn_s_barrier()
; #define PG8_SCHED __builtin_amdgcn_sched_barrier(0)
; template <class Epi>
; __device__ __forceinline__ void gemm_phase(LAS unsigned char* lds, const Gemm g, const StaticOrder& S, const Epi& E) {
;     ...
;             PG8_LDB(B0, 0, 0); PG8_SCHED; PG8_LDA(At, 0, 0); PG8_STAGE(PG8_SA(1, 1), a1 + hstepA, voffA);
;             PG8_WAIT_L(8); PG8_BAR; PG8_WAIT_L(0); PG8_MMA(0, 0, At, B0); PG8_BAR; PG8_SCHED;
;             PG8_LDB(B1, 0, 1); PG8_STAGE(PG8_SB(0, 0), b2, voffB);
;             PG8_BAR; PG8_WAIT_L(0); PG8_MMA(0, 1, At, B1); PG8_BAR;
;             PG8_LDA(At, 0, 1); PG8_STAGE(PG8_SA(0, 0), a2, voffA);
;             PG8_BAR; PG8_WAIT_L(0); PG8_MMA(1, 0, At, B0); PG8_BAR; PG8_SCHED;
;             PG8_STAGE(PG8_SB(0, 1), b2 + hstepB, voffB);
;             PG8_WAIT_V(6); PG8_BAR; PG8_MMA(1, 1, At, B1); PG8_BAR;
;             PG8_LDB(B0, 1, 0); PG8_SCHED; PG8_LDA(At, 1, 0); PG8_STAGE(PG8_SA(0, 1), a2 + hstepA, voffA);
;             PG8_WAIT_L(8); PG8_BAR; PG8_WAIT_L(0); PG8_MMA(0, 0, At, B0); PG8_BAR; PG8_SCHED;
;             PG8_LDB(B1, 1, 1); PG8_STAGE(PG8_SB(1, 0), b3, voffB);
;             PG8_BAR; PG8_WAIT_L(0); PG8_MMA(0, 1, At, B1); PG8_BAR;
;             PG8_LDA(At, 1, 1); PG8_STAGE(PG8_SA(1, 0), a3, voffA);
;             PG8_BAR; PG8_WAIT_L(0); PG8_MMA(1, 0, At, B0); PG8_BAR; PG8_SCHED;
;             PG8_STAGE(PG8_SB(1, 1), b3 + hstepB, voffB);
;             PG8_WAIT_V(6); PG8_BAR; PG8_MMA(1, 1, At, B1); PG8_BAR;
	s_add_u32 s48, s22, 0x40000
	s_addc_u32 s49, s23, 0
	s_add_i32 s47, s41, s29
	v_lshl_add_u64 v[128:129], s[48:49], 0, v[156:157]
	s_mov_b32 m0, s47
	s_nop 0
	global_load_lds_dwordx4 v[128:129], off
	v_lshl_add_u64 v[128:129], s[48:49], 0, v[160:161]
	s_add_i32 m0, s47, 0x2000
	s_nop 0
	global_load_lds_dwordx4 v[128:129], off
	s_waitcnt vmcnt(6)
	s_barrier
	v_mfma_f32_16x16x32_bf16 v[52:55], v[202:205], v[144:147], 0
	v_mfma_f32_16x16x32_bf16 v[48:51], v[210:213], v[144:147], 0
	v_mfma_f32_16x16x32_bf16 v[36:39], v[202:205], v[170:173], 0
	v_mfma_f32_16x16x32_bf16 v[32:35], v[210:213], v[170:173], 0
	v_mfma_f32_16x16x32_bf16 v[20:23], v[202:205], v[178:181], 0
	v_mfma_f32_16x16x32_bf16 v[16:19], v[210:213], v[178:181], 0
	v_mfma_f32_16x16x32_bf16 v[4:7], v[202:205], v[194:197], 0
	v_mfma_f32_16x16x32_bf16 v[0:3], v[210:213], v[194:197], 0
	v_mfma_f32_16x16x32_bf16 v[52:55], v[206:209], v[148:151], v[52:55]
	v_mfma_f32_16x16x32_bf16 v[48:51], v[214:217], v[148:151], v[48:51]
	v_mfma_f32_16x16x32_bf16 v[36:39], v[206:209], v[174:177], v[36:39]
	v_mfma_f32_16x16x32_bf16 v[32:35], v[214:217], v[174:177], v[32:35]
	v_mfma_f32_16x16x32_bf16 v[20:23], v[206:209], v[182:185], v[20:23]
	v_mfma_f32_16x16x32_bf16 v[16:19], v[214:217], v[182:185], v[16:19]
	v_mfma_f32_16x16x32_bf16 v[4:7], v[206:209], v[198:201], v[4:7]
	v_mfma_f32_16x16x32_bf16 v[0:3], v[214:217], v[198:201], v[0:3]
	s_add_i32 s47, 0, 0x18000
	v_add_u32_e32 v140, s47, v188
	s_barrier
	ds_read_b128 v[128:131], v140
	ds_read_b128 v[132:135], v140 offset:1024
	ds_read_b128 v[136:139], v140 offset:2048
	ds_read_b128 v[140:143], v140 offset:3072
	s_add_u32 s24, s24, 0x140000
	s_addc_u32 s25, s25, 0
	s_mov_b32 m0, s31
	v_lshl_add_u64 v[202:203], s[24:25], 0, v[154:155]
	ds_read_b128 v[144:147], v191 offset:32768
	ds_read_b128 v[148:151], v191 offset:33792
	ds_read_b128 v[170:173], v191 offset:34816
	ds_read_b128 v[174:177], v191 offset:35840
	ds_read_b128 v[178:181], v191 offset:36864
	ds_read_b128 v[182:185], v191 offset:37888
	ds_read_b128 v[194:197], v191 offset:38912
	ds_read_b128 v[198:201], v191 offset:39936
	global_load_lds_dwordx4 v[202:203], off
	v_lshl_add_u64 v[202:203], s[24:25], 0, v[158:159]
	s_mov_b32 m0, s34
	s_nop 0
	global_load_lds_dwordx4 v[202:203], off
	s_waitcnt lgkmcnt(8)
	s_barrier
	s_waitcnt lgkmcnt(0)
	v_mfma_f32_16x16x32_bf16 v[124:127], v[128:131], v[144:147], v[124:127]
	v_mfma_f32_16x16x32_bf16 v[120:123], v[136:139], v[144:147], v[120:123]
	v_mfma_f32_16x16x32_bf16 v[108:111], v[128:131], v[170:173], v[108:111]
	v_mfma_f32_16x16x32_bf16 v[104:107], v[136:139], v[170:173], v[104:107]
	v_mfma_f32_16x16x32_bf16 v[92:95], v[128:131], v[178:181], v[92:95]
	v_mfma_f32_16x16x32_bf16 v[88:91], v[136:139], v[178:181], v[88:91]
	v_mfma_f32_16x16x32_bf16 v[76:79], v[128:131], v[194:197], v[76:79]
	v_mfma_f32_16x16x32_bf16 v[72:75], v[136:139], v[194:197], v[72:75]
	v_mfma_f32_16x16x32_bf16 v[124:127], v[132:135], v[148:151], v[124:127]
	v_mfma_f32_16x16x32_bf16 v[120:123], v[140:143], v[148:151], v[120:123]
	v_mfma_f32_16x16x32_bf16 v[108:111], v[132:135], v[174:177], v[108:111]
	v_mfma_f32_16x16x32_bf16 v[104:107], v[140:143], v[174:177], v[104:107]
	v_mfma_f32_16x16x32_bf16 v[92:95], v[132:135], v[182:185], v[92:95]
	v_mfma_f32_16x16x32_bf16 v[88:91], v[140:143], v[182:185], v[88:91]
	v_mfma_f32_16x16x32_bf16 v[76:79], v[132:135], v[198:201], v[76:79]
	v_mfma_f32_16x16x32_bf16 v[72:75], v[140:143], v[198:201], v[72:75]
	s_barrier
	s_add_i32 s24, 0, 0x1c000
	s_add_i32 s25, s47, s29
	v_add_u32_e32 v214, s24, v188
	v_lshl_add_u64 v[186:187], v[186:187], 0, s[14:15]
	s_mov_b32 m0, s25
	ds_read_b128 v[202:205], v214
	ds_read_b128 v[206:209], v214 offset:1024
	ds_read_b128 v[210:213], v214 offset:2048
	ds_read_b128 v[214:217], v214 offset:3072
	global_load_lds_dwordx4 v[186:187], off
	v_lshl_add_u64 v[186:187], v[218:219], 0, s[14:15]
	s_add_i32 m0, s25, 0x2000
	s_nop 0
	global_load_lds_dwordx4 v[186:187], off
	s_barrier
	s_waitcnt lgkmcnt(0)
	v_mfma_f32_16x16x32_bf16 v[116:119], v[202:205], v[144:147], v[116:119]
	v_mfma_f32_16x16x32_bf16 v[112:115], v[210:213], v[144:147], v[112:115]
	v_mfma_f32_16x16x32_bf16 v[100:103], v[202:205], v[170:173], v[100:103]
	v_mfma_f32_16x16x32_bf16 v[96:99], v[210:213], v[170:173], v[96:99]
	v_mfma_f32_16x16x32_bf16 v[84:87], v[202:205], v[178:181], v[84:87]
	v_mfma_f32_16x16x32_bf16 v[80:83], v[210:213], v[178:181], v[80:83]
	v_mfma_f32_16x16x32_bf16 v[68:71], v[202:205], v[194:197], v[68:71]
	v_mfma_f32_16x16x32_bf16 v[64:67], v[210:213], v[194:197], v[64:67]
	v_mfma_f32_16x16x32_bf16 v[116:119], v[206:209], v[148:151], v[116:119]
	v_mfma_f32_16x16x32_bf16 v[112:115], v[214:217], v[148:151], v[112:115]
	v_mfma_f32_16x16x32_bf16 v[100:103], v[206:209], v[174:177], v[100:103]
	v_mfma_f32_16x16x32_bf16 v[96:99], v[214:217], v[174:177], v[96:99]
	v_mfma_f32_16x16x32_bf16 v[84:87], v[206:209], v[182:185], v[84:87]
	v_mfma_f32_16x16x32_bf16 v[80:83], v[214:217], v[182:185], v[80:83]
	v_mfma_f32_16x16x32_bf16 v[68:71], v[206:209], v[198:201], v[68:71]
	v_mfma_f32_16x16x32_bf16 v[64:67], v[214:217], v[198:201], v[64:67]
	s_mov_b32 m0, s36
	v_lshl_add_u64 v[186:187], v[220:221], 0, s[14:15]
	s_barrier
	ds_read_b128 v[144:147], v191 offset:49152
	ds_read_b128 v[148:151], v191 offset:50176
	ds_read_b128 v[170:173], v191 offset:51200
	ds_read_b128 v[174:177], v191 offset:52224
	ds_read_b128 v[178:181], v191 offset:53248
	ds_read_b128 v[182:185], v191 offset:54272
	ds_read_b128 v[194:197], v191 offset:55296
	ds_read_b128 v[198:201], v191 offset:56320
	global_load_lds_dwordx4 v[186:187], off
	v_lshl_add_u64 v[186:187], v[222:223], 0, s[14:15]
	s_mov_b32 m0, s37
	s_nop 0
	global_load_lds_dwordx4 v[186:187], off
	s_barrier
; #define PG8_STAGE(bufoff, gbase, voff) do { _Pragma("unroll") for (int _i = 0; _i < 2; ++_i) \
;         __builtin_amdgcn_global_load_lds((const unsigned*)((const char*)(gbase) + (voff)[_i]), (LAS unsigned*)(lds + (bufoff) + ldsw + _i * 8192), 16, 0, 0); } while (0)
; #define PG8_LDA(dst, b, h) do { _Pragma("unroll") for (int m = 0; m < 4; ++m) _Pragma("unroll") for (int k = 0; k < 2; ++k) dst[m][k] = *(const LAS bf16x8*)(lds + PG8_SA(b, h) + aoff + m * 2048 + k * 1024); } while (0)
; #define PG8_WAIT_V(n) asm volatile("s_waitcnt vmcnt(" #n ")" ::: "memory")
; template <class Epi>
; __device__ __forceinline__ void gemm_phase(LAS unsigned char* lds, const Gemm g, const StaticOrder& S, const Epi& E) {
;     ...
;         for (int t = 0; t < nt; t += 2) {
;             const bool last = (t == nt - 2);
;             const char* a1 = cA + (size_t)(t + 1) * kstep;
;             const char* a2 = last ? nA : cA + (size_t)(t + 2) * kstep; const char* b2 = last ? nB : cB + (size_t)(t + 2) * kstep;
;             const char* a3 = a2 + kstep; const char* b3 = b2 + kstep;
;             if (last) E.pre(cur, wr, fr, epre);
;             PG8_LDB(B0, 0, 0); PG8_SCHED; PG8_LDA(At, 0, 0); PG8_STAGE(PG8_SA(1, 1), a1 + hstepA, voffA);
;             PG8_WAIT_L(8); PG8_BAR; PG8_WAIT_L(0); PG8_MMA(0, 0, At, B0); PG8_BAR; PG8_SCHED;
;             PG8_LDB(B1, 0, 1); PG8_STAGE(PG8_SB(0, 0), b2, voffB);
;             PG8_BAR; PG8_WAIT_L(0); PG8_MMA(0, 1, At, B1); PG8_BAR;
;             PG8_LDA(At, 0, 1); PG8_STAGE(PG8_SA(0, 0), a2, voffA);
;             PG8_BAR; PG8_WAIT_L(0); PG8_MMA(1, 0, At, B0); PG8_BAR; PG8_SCHED;
;             PG8_STAGE(PG8_SB(0, 1), b2 + hstepB, voffB);
;             PG8_WAIT_V(6); PG8_BAR; PG8_MMA(1, 1, At, B1); PG8_BAR;
;             PG8_LDB(B0, 1, 0); PG8_SCHED; PG8_LDA(At, 1, 0); PG8_STAGE(PG8_SA(0, 1), a2 + hstepA, voffA);
;             PG8_WAIT_L(8); PG8_BAR; PG8_WAIT_L(0); PG8_MMA(0, 0, At, B0); PG8_BAR; PG8_SCHED;
;             PG8_LDB(B1, 1, 1); PG8_STAGE(PG8_SB(1, 0), b3, voffB);
;             PG8_BAR; PG8_WAIT_L(0); PG8_MMA(0, 1, At, B1); PG8_BAR;
;             PG8_LDA(At, 1, 1); PG8_STAGE(PG8_SA(1, 0), a3, voffA);
;             PG8_BAR; PG8_WAIT_L(0); PG8_MMA(1, 0, At, B0); PG8_BAR; PG8_SCHED;
;             PG8_STAGE(PG8_SB(1, 1), b3 + hstepB, voffB);
;             PG8_WAIT_V(6); PG8_BAR; PG8_MMA(1, 1, At, B1); PG8_BAR;
	s_waitcnt lgkmcnt(0)
	v_mfma_f32_16x16x32_bf16 v[60:63], v[128:131], v[144:147], v[60:63]
	v_mfma_f32_16x16x32_bf16 v[56:59], v[136:139], v[144:147], v[56:59]
	v_mfma_f32_16x16x32_bf16 v[44:47], v[128:131], v[170:173], v[44:47]
	v_mfma_f32_16x16x32_bf16 v[40:43], v[136:139], v[170:173], v[40:43]
	v_mfma_f32_16x16x32_bf16 v[28:31], v[128:131], v[178:181], v[28:31]
	v_mfma_f32_16x16x32_bf16 v[24:27], v[136:139], v[178:181], v[24:27]
	v_mfma_f32_16x16x32_bf16 v[12:15], v[128:131], v[194:197], v[12:15]
	v_mfma_f32_16x16x32_bf16 v[8:11], v[136:139], v[194:197], v[8:11]
	v_mfma_f32_16x16x32_bf16 v[60:63], v[132:135], v[148:151], v[60:63]
	v_mfma_f32_16x16x32_bf16 v[56:59], v[140:143], v[148:151], v[56:59]
	v_mfma_f32_16x16x32_bf16 v[44:47], v[132:135], v[174:177], v[44:47]
	v_mfma_f32_16x16x32_bf16 v[40:43], v[140:143], v[174:177], v[40:43]
	v_mfma_f32_16x16x32_bf16 v[28:31], v[132:135], v[182:185], v[28:31]
	v_mfma_f32_16x16x32_bf16 v[24:27], v[140:143], v[182:185], v[24:27]
	v_mfma_f32_16x16x32_bf16 v[12:15], v[132:135], v[198:201], v[12:15]
	v_mfma_f32_16x16x32_bf16 v[8:11], v[140:143], v[198:201], v[8:11]
	s_barrier
	s_add_u32 s22, s22, 0x40080
	s_addc_u32 s23, s23, 0
	s_add_i32 s24, s24, s29
	v_lshl_add_u64 v[128:129], s[22:23], 0, v[156:157]
	s_mov_b32 m0, s24
	s_nop 0
	global_load_lds_dwordx4 v[128:129], off
	v_lshl_add_u64 v[128:129], s[22:23], 0, v[160:161]
	s_add_i32 m0, s24, 0x2000
	s_nop 0
	global_load_lds_dwordx4 v[128:129], off
	s_waitcnt vmcnt(6)
	s_barrier
	v_mfma_f32_16x16x32_bf16 v[52:55], v[202:205], v[144:147], v[52:55]
	v_mfma_f32_16x16x32_bf16 v[48:51], v[210:213], v[144:147], v[48:51]
	v_mfma_f32_16x16x32_bf16 v[36:39], v[202:205], v[170:173], v[36:39]
	v_mfma_f32_16x16x32_bf16 v[32:35], v[210:213], v[170:173], v[32:35]
	v_mfma_f32_16x16x32_bf16 v[20:23], v[202:205], v[178:181], v[20:23]
	v_mfma_f32_16x16x32_bf16 v[16:19], v[210:213], v[178:181], v[16:19]
	v_mfma_f32_16x16x32_bf16 v[4:7], v[202:205], v[194:197], v[4:7]
	v_mfma_f32_16x16x32_bf16 v[0:3], v[210:213], v[194:197], v[0:3]
	v_mfma_f32_16x16x32_bf16 v[52:55], v[206:209], v[148:151], v[52:55]
	v_mfma_f32_16x16x32_bf16 v[48:51], v[214:217], v[148:151], v[48:51]
	v_mfma_f32_16x16x32_bf16 v[36:39], v[206:209], v[174:177], v[36:39]
	v_mfma_f32_16x16x32_bf16 v[32:35], v[214:217], v[174:177], v[32:35]
	v_mfma_f32_16x16x32_bf16 v[20:23], v[206:209], v[182:185], v[20:23]
	v_mfma_f32_16x16x32_bf16 v[16:19], v[214:217], v[182:185], v[16:19]
	v_mfma_f32_16x16x32_bf16 v[4:7], v[206:209], v[198:201], v[4:7]
	v_mfma_f32_16x16x32_bf16 v[0:3], v[214:217], v[198:201], v[0:3]
	s_add_i32 s46, s46, 2
	s_add_u32 s4, s4, 0x100
	s_addc_u32 s5, s5, 0
	s_add_u32 s44, s44, 0x100
	s_addc_u32 s45, s45, 0
	s_cmp_gt_u32 s46, 13
	s_barrier
.LBB0_1118:
	ds_read_b128 v[128:131], v190
	ds_read_b128 v[132:135], v190 offset:1024
	ds_read_b128 v[136:139], v190 offset:2048
	ds_read_b128 v[140:143], v190 offset:3072
	s_add_u32 s22, s4, 0xffec0080
	s_addc_u32 s23, s5, -1
	s_cmp_eq_u32 s46, 12
	s_cselect_b32 s25, s19, s23
	s_cselect_b32 s24, s18, s22
	s_cselect_b32 s23, s17, s45
	s_cselect_b32 s22, s43, s44
	v_lshl_add_u64 v[186:187], s[4:5], 0, v[162:163]
	s_add_i32 m0, s9, 0xc000
	ds_read_b128 v[144:147], v191
	ds_read_b128 v[148:151], v191 offset:1024
	ds_read_b128 v[170:173], v191 offset:2048
	ds_read_b128 v[174:177], v191 offset:3072
	ds_read_b128 v[178:181], v191 offset:4096
	ds_read_b128 v[182:185], v191 offset:5120
	ds_read_b128 v[194:197], v191 offset:6144
	ds_read_b128 v[198:201], v191 offset:7168
	global_load_lds_dwordx4 v[186:187], off
	v_lshl_add_u64 v[186:187], s[4:5], 0, v[164:165]
	s_add_i32 m0, s9, 0xe000
	s_nop 0
	global_load_lds_dwordx4 v[186:187], off
	s_waitcnt lgkmcnt(8)
	s_barrier
	s_waitcnt lgkmcnt(0)
	v_mfma_f32_16x16x32_bf16 v[124:127], v[128:131], v[144:147], v[124:127]
	v_mfma_f32_16x16x32_bf16 v[120:123], v[136:139], v[144:147], v[120:123]
	v_mfma_f32_16x16x32_bf16 v[108:111], v[128:131], v[170:173], v[108:111]
	v_mfma_f32_16x16x32_bf16 v[104:107], v[136:139], v[170:173], v[104:107]
	v_mfma_f32_16x16x32_bf16 v[92:95], v[128:131], v[178:181], v[92:95]
	v_mfma_f32_16x16x32_bf16 v[88:91], v[136:139], v[178:181], v[88:91]
	v_mfma_f32_16x16x32_bf16 v[76:79], v[128:131], v[194:197], v[76:79]
	v_mfma_f32_16x16x32_bf16 v[72:75], v[136:139], v[194:197], v[72:75]
	v_mfma_f32_16x16x32_bf16 v[124:127], v[132:135], v[148:151], v[124:127]
	v_mfma_f32_16x16x32_bf16 v[120:123], v[140:143], v[148:151], v[120:123]
	v_mfma_f32_16x16x32_bf16 v[108:111], v[132:135], v[174:177], v[108:111]
	v_mfma_f32_16x16x32_bf16 v[104:107], v[140:143], v[174:177], v[104:107]
	v_mfma_f32_16x16x32_bf16 v[92:95], v[132:135], v[182:185], v[92:95]
	v_mfma_f32_16x16x32_bf16 v[88:91], v[140:143], v[182:185], v[88:91]
	v_mfma_f32_16x16x32_bf16 v[76:79], v[132:135], v[198:201], v[76:79]
	v_mfma_f32_16x16x32_bf16 v[72:75], v[140:143], v[198:201], v[72:75]
	s_barrier
	s_add_i32 s47, s40, s29
	v_lshl_add_u64 v[186:187], s[22:23], 0, v[156:157]
	s_mov_b32 m0, s47
	ds_read_b128 v[202:205], v192
	ds_read_b128 v[206:209], v192 offset:1024
	ds_read_b128 v[210:213], v192 offset:2048
	ds_read_b128 v[214:217], v192 offset:3072
	global_load_lds_dwordx4 v[186:187], off
	v_lshl_add_u64 v[218:219], s[22:23], 0, v[160:161]
	s_add_i32 m0, s47, 0x2000
	s_nop 0
	global_load_lds_dwordx4 v[218:219], off
	s_barrier
; #define PG8_STAGE(bufoff, gbase, voff) do { _Pragma("unroll") for (int _i = 0; _i < 2; ++_i) \
;         __builtin_amdgcn_global_load_lds((const unsigned*)((const char*)(gbase) + (voff)[_i]), (LAS unsigned*)(lds + (bufoff) + ldsw + _i * 8192), 16, 0, 0); } while (0)
; #define PG8_LDA(dst, b, h) do { _Pragma("unroll") for (int m = 0; m < 4; ++m) _Pragma("unroll") for (int k = 0; k < 2; ++k) dst[m][k] = *(const LAS bf16x8*)(lds + PG8_SA(b, h) + aoff + m * 2048 + k * 1024); } while (0)
; #define PG8_LDB(dst, b, h) do { _Pragma("unroll") for (int n = 0; n < 2; ++n) _Pragma("unroll") for (int k = 0; k < 2; ++k) dst[n][k] = *(const LAS bf16x8*)(lds + PG8_SB(b, h) + boff + n * 2048 + k * 1024); } while (0)
; #define PG8_WAIT_V(n) asm volatile("s_waitcnt vmcnt(" #n ")" ::: "memory")
; #define PG8_WAIT_L(n) asm volatile("s_waitcnt lgkmcnt(" #n ")" ::: "memory")
; #define PG8_BAR __builtin_amdgcn_s_barrier()
; #define PG8_SCHED __builtin_amdgcn_sched_barrier(0)
; template <class Epi>
; __device__ __forceinline__ void gemm_phase(LAS unsigned char* lds, const Gemm g, const StaticOrder& S, const Epi& E) {
;     ...
;             PG8_LDB(B0, 0, 0); PG8_SCHED; PG8_LDA(At, 0, 0); PG8_STAGE(PG8_SA(1, 1), a1 + hstepA, voffA);
;             PG8_WAIT_L(8); PG8_BAR; PG8_WAIT_L(0); PG8_MMA(0, 0, At, B0); PG8_BAR; PG8_SCHED;
;             PG8_LDB(B1, 0, 1); PG8_STAGE(PG8_SB(0, 0), b2, voffB);
;             PG8_BAR; PG8_WAIT_L(0); PG8_MMA(0, 1, At, B1); PG8_BAR;
;             PG8_LDA(At, 0, 1); PG8_STAGE(PG8_SA(0, 0), a2, voffA);
;             PG8_BAR; PG8_WAIT_L(0); PG8_MMA(1, 0, At, B0); PG8_BAR; PG8_SCHED;
;             PG8_STAGE(PG8_SB(0, 1), b2 + hstepB, voffB);
;             PG8_WAIT_V(6); PG8_BAR; PG8_MMA(1, 1, At, B1); PG8_BAR;
;             PG8_LDB(B0, 1, 0); PG8_SCHED; PG8_LDA(At, 1, 0); PG8_STAGE(PG8_SA(0, 1), a2 + hstepA, voffA);
;             PG8_WAIT_L(8); PG8_BAR; PG8_WAIT_L(0); PG8_MMA(0, 0, At, B0); PG8_BAR; PG8_SCHED;
;             PG8_LDB(B1, 1, 1); PG8_STAGE(PG8_SB(1, 0), b3, voffB);
;             PG8_BAR; PG8_WAIT_L(0); PG8_MMA(0, 1, At, B1); PG8_BAR;
;             PG8_LDA(At, 1, 1); PG8_STAGE(PG8_SA(1, 0), a3, voffA);
;             PG8_BAR; PG8_WAIT_L(0); PG8_MMA(1, 0, At, B0); PG8_BAR; PG8_SCHED;
;             PG8_STAGE(PG8_SB(1, 1), b3 + hstepB, voffB);
;             PG8_WAIT_V(6); PG8_BAR; PG8_MMA(1, 1, At, B1); PG8_BAR;
	s_waitcnt lgkmcnt(0)
	v_mfma_f32_16x16x32_bf16 v[116:119], v[202:205], v[144:147], v[116:119]
	v_mfma_f32_16x16x32_bf16 v[112:115], v[210:213], v[144:147], v[112:115]
	v_mfma_f32_16x16x32_bf16 v[100:103], v[202:205], v[170:173], v[100:103]
	v_mfma_f32_16x16x32_bf16 v[96:99], v[210:213], v[170:173], v[96:99]
	v_mfma_f32_16x16x32_bf16 v[84:87], v[202:205], v[178:181], v[84:87]
	v_mfma_f32_16x16x32_bf16 v[80:83], v[210:213], v[178:181], v[80:83]
	v_mfma_f32_16x16x32_bf16 v[68:71], v[202:205], v[194:197], v[68:71]
	v_mfma_f32_16x16x32_bf16 v[64:67], v[210:213], v[194:197], v[64:67]
	v_mfma_f32_16x16x32_bf16 v[116:119], v[206:209], v[148:151], v[116:119]
	v_mfma_f32_16x16x32_bf16 v[112:115], v[214:217], v[148:151], v[112:115]
	v_mfma_f32_16x16x32_bf16 v[100:103], v[206:209], v[174:177], v[100:103]
	v_mfma_f32_16x16x32_bf16 v[96:99], v[214:217], v[174:177], v[96:99]
	v_mfma_f32_16x16x32_bf16 v[84:87], v[206:209], v[182:185], v[84:87]
	v_mfma_f32_16x16x32_bf16 v[80:83], v[214:217], v[182:185], v[80:83]
	v_mfma_f32_16x16x32_bf16 v[68:71], v[206:209], v[198:201], v[68:71]
	v_mfma_f32_16x16x32_bf16 v[64:67], v[214:217], v[198:201], v[64:67]
	s_mov_b32 m0, s9
	v_lshl_add_u64 v[220:221], s[24:25], 0, v[154:155]
	s_barrier
	ds_read_b128 v[144:147], v191 offset:16384
	ds_read_b128 v[148:151], v191 offset:17408
	ds_read_b128 v[170:173], v191 offset:18432
	ds_read_b128 v[174:177], v191 offset:19456
	ds_read_b128 v[178:181], v191 offset:20480
	ds_read_b128 v[182:185], v191 offset:21504
	ds_read_b128 v[194:197], v191 offset:22528
	ds_read_b128 v[198:201], v191 offset:23552
	global_load_lds_dwordx4 v[220:221], off
	v_lshl_add_u64 v[222:223], s[24:25], 0, v[158:159]
	s_mov_b32 m0, s30
	s_nop 0
	global_load_lds_dwordx4 v[222:223], off
	s_barrier
	s_waitcnt lgkmcnt(0)
	v_mfma_f32_16x16x32_bf16 v[60:63], v[128:131], v[144:147], v[60:63]
	v_mfma_f32_16x16x32_bf16 v[56:59], v[136:139], v[144:147], v[56:59]
	v_mfma_f32_16x16x32_bf16 v[44:47], v[128:131], v[170:173], v[44:47]
	v_mfma_f32_16x16x32_bf16 v[40:43], v[136:139], v[170:173], v[40:43]
	v_mfma_f32_16x16x32_bf16 v[28:31], v[128:131], v[178:181], v[28:31]
	v_mfma_f32_16x16x32_bf16 v[24:27], v[136:139], v[178:181], v[24:27]
	v_mfma_f32_16x16x32_bf16 v[12:15], v[128:131], v[194:197], v[12:15]
	v_mfma_f32_16x16x32_bf16 v[8:11], v[136:139], v[194:197], v[8:11]
	v_mfma_f32_16x16x32_bf16 v[60:63], v[132:135], v[148:151], v[60:63]
	v_mfma_f32_16x16x32_bf16 v[56:59], v[140:143], v[148:151], v[56:59]
	v_mfma_f32_16x16x32_bf16 v[44:47], v[132:135], v[174:177], v[44:47]
	v_mfma_f32_16x16x32_bf16 v[40:43], v[140:143], v[174:177], v[40:43]
	v_mfma_f32_16x16x32_bf16 v[28:31], v[132:135], v[182:185], v[28:31]
	v_mfma_f32_16x16x32_bf16 v[24:27], v[140:143], v[182:185], v[24:27]
	v_mfma_f32_16x16x32_bf16 v[12:15], v[132:135], v[198:201], v[12:15]
	v_mfma_f32_16x16x32_bf16 v[8:11], v[140:143], v[198:201], v[8:11]
	s_barrier
	s_add_u32 s48, s22, 0x40000
	s_addc_u32 s49, s23, 0
	s_add_i32 s47, s41, s29
	v_lshl_add_u64 v[128:129], s[48:49], 0, v[156:157]
	s_mov_b32 m0, s47
	s_nop 0
	global_load_lds_dwordx4 v[128:129], off
	v_lshl_add_u64 v[128:129], s[48:49], 0, v[160:161]
	s_add_i32 m0, s47, 0x2000
	s_nop 0
	global_load_lds_dwordx4 v[128:129], off
	s_waitcnt vmcnt(6)
	s_barrier
	v_mfma_f32_16x16x32_bf16 v[52:55], v[202:205], v[144:147], v[52:55]
	v_mfma_f32_16x16x32_bf16 v[48:51], v[210:213], v[144:147], v[48:51]
	v_mfma_f32_16x16x32_bf16 v[36:39], v[202:205], v[170:173], v[36:39]
	v_mfma_f32_16x16x32_bf16 v[32:35], v[210:213], v[170:173], v[32:35]
	v_mfma_f32_16x16x32_bf16 v[20:23], v[202:205], v[178:181], v[20:23]
	v_mfma_f32_16x16x32_bf16 v[16:19], v[210:213], v[178:181], v[16:19]
	v_mfma_f32_16x16x32_bf16 v[4:7], v[202:205], v[194:197], v[4:7]
	v_mfma_f32_16x16x32_bf16 v[0:3], v[210:213], v[194:197], v[0:3]
	v_mfma_f32_16x16x32_bf16 v[52:55], v[206:209], v[148:151], v[52:55]
	v_mfma_f32_16x16x32_bf16 v[48:51], v[214:217], v[148:151], v[48:51]
	v_mfma_f32_16x16x32_bf16 v[36:39], v[206:209], v[174:177], v[36:39]
	v_mfma_f32_16x16x32_bf16 v[32:35], v[214:217], v[174:177], v[32:35]
	v_mfma_f32_16x16x32_bf16 v[20:23], v[206:209], v[182:185], v[20:23]
	v_mfma_f32_16x16x32_bf16 v[16:19], v[214:217], v[182:185], v[16:19]
	v_mfma_f32_16x16x32_bf16 v[4:7], v[206:209], v[198:201], v[4:7]
	v_mfma_f32_16x16x32_bf16 v[0:3], v[214:217], v[198:201], v[0:3]
	s_add_i32 s47, 0, 0x18000
	v_add_u32_e32 v140, s47, v188
	s_barrier
	ds_read_b128 v[128:131], v140
	ds_read_b128 v[132:135], v140 offset:1024
	ds_read_b128 v[136:139], v140 offset:2048
	ds_read_b128 v[140:143], v140 offset:3072
	s_add_u32 s24, s24, 0x140000
	s_addc_u32 s25, s25, 0
	s_mov_b32 m0, s31
	v_lshl_add_u64 v[202:203], s[24:25], 0, v[154:155]
	ds_read_b128 v[144:147], v191 offset:32768
	ds_read_b128 v[148:151], v191 offset:33792
	ds_read_b128 v[170:173], v191 offset:34816
	ds_read_b128 v[174:177], v191 offset:35840
	ds_read_b128 v[178:181], v191 offset:36864
	ds_read_b128 v[182:185], v191 offset:37888
	ds_read_b128 v[194:197], v191 offset:38912
	ds_read_b128 v[198:201], v191 offset:39936
	global_load_lds_dwordx4 v[202:203], off
	v_lshl_add_u64 v[202:203], s[24:25], 0, v[158:159]
	s_mov_b32 m0, s34
	s_nop 0
	global_load_lds_dwordx4 v[202:203], off
	s_waitcnt lgkmcnt(8)
	s_barrier
; #define PG8_STAGE(bufoff, gbase, voff) do { _Pragma("unroll") for (int _i = 0; _i < 2; ++_i) \
;         __builtin_amdgcn_global_load_lds((const unsigned*)((const char*)(gbase) + (voff)[_i]), (LAS unsigned*)(lds + (bufoff) + ldsw + _i * 8192), 16, 0, 0); } while (0)
; #define PG8_LDA(dst, b, h) do { _Pragma("unroll") for (int m = 0; m < 4; ++m) _Pragma("unroll") for (int k = 0; k < 2; ++k) dst[m][k] = *(const LAS bf16x8*)(lds + PG8_SA(b, h) + aoff + m * 2048 + k * 1024); } while (0)
; #define PG8_LDB(dst, b, h) do { _Pragma("unroll") for (int n = 0; n < 2; ++n) _Pragma("unroll") for (int k = 0; k < 2; ++k) dst[n][k] = *(const LAS bf16x8*)(lds + PG8_SB(b, h) + boff + n * 2048 + k * 1024); } while (0)
; #define PG8_MMA(ai, bj, At, Bt) do { __builtin_amdgcn_s_setprio(1); _Pragma("unroll") for (int m = 0; m < 4; ++m) _Pragma("unroll") for (int n = 0; n < 2; ++n) _Pragma("unroll") for (int k = 0; k < 2; ++k) \
;         acc[ai][bj][m][n] = __builtin_amdgcn_mfma_f32_16x16x32_bf16(Bt[n][k], At[m][k], acc[ai][bj][m][n], 0, 0, 0); __builtin_amdgcn_s_setprio(0); } while (0)
; #define PG8_WAIT_V(n) asm volatile("s_waitcnt vmcnt(" #n ")" ::: "memory")
; #define PG8_WAIT_L(n) asm volatile("s_waitcnt lgkmcnt(" #n ")" ::: "memory")
; #define PG8_BAR __builtin_amdgcn_s_barrier()
; #define PG8_SCHED __builtin_amdgcn_sched_barrier(0)
; template <class Epi>
; __device__ __forceinline__ void gemm_phase(LAS unsigned char* lds, const Gemm g, const StaticOrder& S, const Epi& E) {
;     ...
;             PG8_WAIT_V(6); PG8_BAR; PG8_MMA(1, 1, At, B1); PG8_BAR;
;             PG8_LDB(B0, 1, 0); PG8_SCHED; PG8_LDA(At, 1, 0); PG8_STAGE(PG8_SA(0, 1), a2 + hstepA, voffA);
;             PG8_WAIT_L(8); PG8_BAR; PG8_WAIT_L(0); PG8_MMA(0, 0, At, B0); PG8_BAR; PG8_SCHED;
;             PG8_LDB(B1, 1, 1); PG8_STAGE(PG8_SB(1, 0), b3, voffB);
;             PG8_BAR; PG8_WAIT_L(0); PG8_MMA(0, 1, At, B1); PG8_BAR;
;             PG8_LDA(At, 1, 1); PG8_STAGE(PG8_SA(1, 0), a3, voffA);
;             PG8_BAR; PG8_WAIT_L(0); PG8_MMA(1, 0, At, B0); PG8_BAR; PG8_SCHED;
;             PG8_STAGE(PG8_SB(1, 1), b3 + hstepB, voffB);
;             PG8_WAIT_V(6); PG8_BAR; PG8_MMA(1, 1, At, B1); PG8_BAR;
	s_waitcnt lgkmcnt(0)
	v_mfma_f32_16x16x32_bf16 v[124:127], v[128:131], v[144:147], v[124:127]
	v_mfma_f32_16x16x32_bf16 v[120:123], v[136:139], v[144:147], v[120:123]
	v_mfma_f32_16x16x32_bf16 v[108:111], v[128:131], v[170:173], v[108:111]
	v_mfma_f32_16x16x32_bf16 v[104:107], v[136:139], v[170:173], v[104:107]
	v_mfma_f32_16x16x32_bf16 v[92:95], v[128:131], v[178:181], v[92:95]
	v_mfma_f32_16x16x32_bf16 v[88:91], v[136:139], v[178:181], v[88:91]
	v_mfma_f32_16x16x32_bf16 v[76:79], v[128:131], v[194:197], v[76:79]
	v_mfma_f32_16x16x32_bf16 v[72:75], v[136:139], v[194:197], v[72:75]
	v_mfma_f32_16x16x32_bf16 v[124:127], v[132:135], v[148:151], v[124:127]
	v_mfma_f32_16x16x32_bf16 v[120:123], v[140:143], v[148:151], v[120:123]
	v_mfma_f32_16x16x32_bf16 v[108:111], v[132:135], v[174:177], v[108:111]
	v_mfma_f32_16x16x32_bf16 v[104:107], v[140:143], v[174:177], v[104:107]
	v_mfma_f32_16x16x32_bf16 v[92:95], v[132:135], v[182:185], v[92:95]
	v_mfma_f32_16x16x32_bf16 v[88:91], v[140:143], v[182:185], v[88:91]
	v_mfma_f32_16x16x32_bf16 v[76:79], v[132:135], v[198:201], v[76:79]
	v_mfma_f32_16x16x32_bf16 v[72:75], v[140:143], v[198:201], v[72:75]
	s_barrier
	s_add_i32 s24, 0, 0x1c000
	s_add_i32 s25, s47, s29
	v_add_u32_e32 v214, s24, v188
	v_lshl_add_u64 v[186:187], v[186:187], 0, s[14:15]
	s_mov_b32 m0, s25
	ds_read_b128 v[202:205], v214
	ds_read_b128 v[206:209], v214 offset:1024
	ds_read_b128 v[210:213], v214 offset:2048
	ds_read_b128 v[214:217], v214 offset:3072
	global_load_lds_dwordx4 v[186:187], off
	v_lshl_add_u64 v[186:187], v[218:219], 0, s[14:15]
	s_add_i32 m0, s25, 0x2000
	s_nop 0
	global_load_lds_dwordx4 v[186:187], off
	s_barrier
	s_waitcnt lgkmcnt(0)
	v_mfma_f32_16x16x32_bf16 v[116:119], v[202:205], v[144:147], v[116:119]
	v_mfma_f32_16x16x32_bf16 v[112:115], v[210:213], v[144:147], v[112:115]
	v_mfma_f32_16x16x32_bf16 v[100:103], v[202:205], v[170:173], v[100:103]
	v_mfma_f32_16x16x32_bf16 v[96:99], v[210:213], v[170:173], v[96:99]
	v_mfma_f32_16x16x32_bf16 v[84:87], v[202:205], v[178:181], v[84:87]
	v_mfma_f32_16x16x32_bf16 v[80:83], v[210:213], v[178:181], v[80:83]
	v_mfma_f32_16x16x32_bf16 v[68:71], v[202:205], v[194:197], v[68:71]
	v_mfma_f32_16x16x32_bf16 v[64:67], v[210:213], v[194:197], v[64:67]
	v_mfma_f32_16x16x32_bf16 v[116:119], v[206:209], v[148:151], v[116:119]
	v_mfma_f32_16x16x32_bf16 v[112:115], v[214:217], v[148:151], v[112:115]
	v_mfma_f32_16x16x32_bf16 v[100:103], v[206:209], v[174:177], v[100:103]
	v_mfma_f32_16x16x32_bf16 v[96:99], v[214:217], v[174:177], v[96:99]
	v_mfma_f32_16x16x32_bf16 v[84:87], v[206:209], v[182:185], v[84:87]
	v_mfma_f32_16x16x32_bf16 v[80:83], v[214:217], v[182:185], v[80:83]
	v_mfma_f32_16x16x32_bf16 v[68:71], v[206:209], v[198:201], v[68:71]
	v_mfma_f32_16x16x32_bf16 v[64:67], v[214:217], v[198:201], v[64:67]
	s_mov_b32 m0, s36
	v_lshl_add_u64 v[186:187], v[220:221], 0, s[14:15]
	s_barrier
	ds_read_b128 v[144:147], v191 offset:49152
	ds_read_b128 v[148:151], v191 offset:50176
	ds_read_b128 v[170:173], v191 offset:51200
	ds_read_b128 v[174:177], v191 offset:52224
	ds_read_b128 v[178:181], v191 offset:53248
	ds_read_b128 v[182:185], v191 offset:54272
	ds_read_b128 v[194:197], v191 offset:55296
	ds_read_b128 v[198:201], v191 offset:56320
	global_load_lds_dwordx4 v[186:187], off
	v_lshl_add_u64 v[186:187], v[222:223], 0, s[14:15]
	s_mov_b32 m0, s37
	s_nop 0
	global_load_lds_dwordx4 v[186:187], off
	s_barrier
	s_waitcnt lgkmcnt(0)
	v_mfma_f32_16x16x32_bf16 v[60:63], v[128:131], v[144:147], v[60:63]
	v_mfma_f32_16x16x32_bf16 v[56:59], v[136:139], v[144:147], v[56:59]
	v_mfma_f32_16x16x32_bf16 v[44:47], v[128:131], v[170:173], v[44:47]
	v_mfma_f32_16x16x32_bf16 v[40:43], v[136:139], v[170:173], v[40:43]
	v_mfma_f32_16x16x32_bf16 v[28:31], v[128:131], v[178:181], v[28:31]
	v_mfma_f32_16x16x32_bf16 v[24:27], v[136:139], v[178:181], v[24:27]
	v_mfma_f32_16x16x32_bf16 v[12:15], v[128:131], v[194:197], v[12:15]
	v_mfma_f32_16x16x32_bf16 v[8:11], v[136:139], v[194:197], v[8:11]
	v_mfma_f32_16x16x32_bf16 v[60:63], v[132:135], v[148:151], v[60:63]
	v_mfma_f32_16x16x32_bf16 v[56:59], v[140:143], v[148:151], v[56:59]
	v_mfma_f32_16x16x32_bf16 v[44:47], v[132:135], v[174:177], v[44:47]
	v_mfma_f32_16x16x32_bf16 v[40:43], v[140:143], v[174:177], v[40:43]
	v_mfma_f32_16x16x32_bf16 v[28:31], v[132:135], v[182:185], v[28:31]
	v_mfma_f32_16x16x32_bf16 v[24:27], v[140:143], v[182:185], v[24:27]
	v_mfma_f32_16x16x32_bf16 v[12:15], v[132:135], v[198:201], v[12:15]
	v_mfma_f32_16x16x32_bf16 v[8:11], v[140:143], v[198:201], v[8:11]
	s_barrier
	s_add_u32 s22, s22, 0x40080
	s_addc_u32 s23, s23, 0
	s_add_i32 s24, s24, s29
	v_lshl_add_u64 v[128:129], s[22:23], 0, v[156:157]
	s_mov_b32 m0, s24
	s_nop 0
	global_load_lds_dwordx4 v[128:129], off
	v_lshl_add_u64 v[128:129], s[22:23], 0, v[160:161]
	s_add_i32 m0, s24, 0x2000
	s_nop 0
	global_load_lds_dwordx4 v[128:129], off
	s_waitcnt vmcnt(6)
	s_barrier
	v_mfma_f32_16x16x32_bf16 v[52:55], v[202:205], v[144:147], v[52:55]
	v_mfma_f32_16x16x32_bf16 v[48:51], v[210:213], v[144:147], v[48:51]
	v_mfma_f32_16x16x32_bf16 v[36:39], v[202:205], v[170:173], v[36:39]
	v_mfma_f32_16x16x32_bf16 v[32:35], v[210:213], v[170:173], v[32:35]
	v_mfma_f32_16x16x32_bf16 v[20:23], v[202:205], v[178:181], v[20:23]
	v_mfma_f32_16x16x32_bf16 v[16:19], v[210:213], v[178:181], v[16:19]
	v_mfma_f32_16x16x32_bf16 v[4:7], v[202:205], v[194:197], v[4:7]
	v_mfma_f32_16x16x32_bf16 v[0:3], v[210:213], v[194:197], v[0:3]
	v_mfma_f32_16x16x32_bf16 v[52:55], v[206:209], v[148:151], v[52:55]
	v_mfma_f32_16x16x32_bf16 v[48:51], v[214:217], v[148:151], v[48:51]
	v_mfma_f32_16x16x32_bf16 v[36:39], v[206:209], v[174:177], v[36:39]
	v_mfma_f32_16x16x32_bf16 v[32:35], v[214:217], v[174:177], v[32:35]
	v_mfma_f32_16x16x32_bf16 v[20:23], v[206:209], v[182:185], v[20:23]
	v_mfma_f32_16x16x32_bf16 v[16:19], v[214:217], v[182:185], v[16:19]
	v_mfma_f32_16x16x32_bf16 v[4:7], v[206:209], v[198:201], v[4:7]
	v_mfma_f32_16x16x32_bf16 v[0:3], v[214:217], v[198:201], v[0:3]
	s_add_i32 s46, s46, 2
	s_add_u32 s4, s4, 0x100
	s_addc_u32 s5, s5, 0
	s_add_u32 s44, s44, 0x100
	s_addc_u32 s45, s45, 0
	s_cmp_gt_u32 s46, 13
	s_barrier
; __device__ __forceinline__ unsigned pk2(float lo, float hi) { const f32x2 v = (f32x2){lo, hi}; const bf16x2_t b = __builtin_convertvector(v, bf16x2_t); return __builtin_bit_cast(unsigned, b); }
; __device__ __forceinline__ void unpack8(const u32x4 v, float* f) { f[0] = bf_lo(v.x); f[1] = bf_hi(v.x); f[2] = bf_lo(v.y); f[3] = bf_hi(v.y); f[4] = bf_lo(v.z); f[5] = bf_hi(v.z); f[6] = bf_lo(v.w); f[7] = bf_hi(v.w); }
;     __device__ __forceinline__ void operator()(const f32x4 (&acc)[2][2][4][2], const Unit& u, int wr, int wc, int fr, int fq, const float (&)[8]) const {
;         const int row0 = u.pm * BM + wr * 64 + fr, col0 = u.pn * BM + wc * 32 + 8 * fq;
; #pragma unroll
;         for (int ai = 0; ai < 2; ++ai) {
;             u32x4 bv[4][2];
; #pragma unroll
;             for (int m = 0; m < 4; ++m)
; #pragma unroll
;                 for (int bj = 0; bj < 2; ++bj) bv[m][bj] = *(const u32x4*)(xb + (size_t)(row0 + ai * HALF + m * 16) * DM + col0 + bj * HALF);
; #pragma unroll
;             for (int m = 0; m < 4; ++m) { const int row = row0 + ai * HALF + m * 16; const size_t ro = (size_t)row * DM + col0; float s = 0.f;
; #pragma unroll
;                 for (int bj = 0; bj < 2; ++bj) { float b8[8]; unpack8(bv[m][bj], b8);
;                     const f32x4 v0 = (f32x4){b8[0], b8[1], b8[2], b8[3]} + acc[ai][bj][m][0], v1 = (f32x4){b8[4], b8[5], b8[6], b8[7]} + acc[ai][bj][m][1];
;                     s += v0[0] * v0[0] + v0[1] * v0[1] + v0[2] * v0[2] + v0[3] * v0[3] + v1[0] * v1[0] + v1[1] * v1[1] + v1[2] * v1[2] + v1[3] * v1[3];
;                     if (LAST) { *(f32x4*)(out + ro + bj * HALF) = v0; *(f32x4*)(out + ro + bj * HALF + 4) = v1; }
;                     else { u32x4 w; w.x = pk2(v0[0], v0[1]); w.y = pk2(v0[2], v0[3]); w.z = pk2(v1[0], v1[1]); w.w = pk2(v1[2], v1[3]); *(u32x4*)(xb + ro + bj * HALF) = w; } }
;                 s += __shfl_xor(s, 16); s += __shfl_xor(s, 32);
;                 if (fq == 0) ss[(size_t)row * 16 + u.pn * 4 + wc] = s; }
	s_cbranch_scc0 .LBB0_1118
	v_lshl_or_b32 v170, s8, 8, v189
	v_lshl_add_u32 v172, s10, 8, v153
	v_ashrrev_i32_e32 v171, 31, v170
	v_lshlrev_b64 v[204:205], 1, v[170:171]
	v_ashrrev_i32_e32 v173, 31, v172
	v_lshl_add_u64 v[174:175], s[76:77], 0, v[204:205]
	v_lshlrev_b64 v[206:207], 11, v[172:173]
	v_lshl_add_u64 v[128:129], v[174:175], 0, v[206:207]
	global_load_dwordx4 v[196:199], v[128:129], off
	global_load_dwordx4 v[200:203], v[128:129], off offset:256
	v_or_b32_e32 v184, 16, v172
	v_or_b32_e32 v180, 32, v172
	v_or_b32_e32 v176, 48, v172
	v_ashrrev_i32_e32 v185, 31, v184
	v_ashrrev_i32_e32 v181, 31, v180
	v_ashrrev_i32_e32 v177, 31, v176
	v_lshlrev_b64 v[186:187], 11, v[184:185]
	v_lshlrev_b64 v[182:183], 11, v[180:181]
	v_lshlrev_b64 v[178:179], 11, v[176:177]
	v_lshl_add_u64 v[128:129], v[174:175], 0, v[186:187]
	v_lshl_add_u64 v[130:131], v[174:175], 0, v[182:183]
	v_lshl_add_u64 v[194:195], v[174:175], 0, v[178:179]
	global_load_dwordx4 v[148:151], v[128:129], off
	global_load_dwordx4 v[144:147], v[128:129], off offset:256
	global_load_dwordx4 v[140:143], v[130:131], off
	global_load_dwordx4 v[136:139], v[130:131], off offset:256
	global_load_dwordx4 v[132:135], v[194:195], off
	s_nop 0
	global_load_dwordx4 v[128:131], v[194:195], off offset:256
	v_add_u32_e32 v226, 0x80, v172
	v_ashrrev_i32_e32 v227, 31, v226
	v_lshlrev_b64 v[226:227], 11, v[226:227]
	v_lshl_add_u64 v[226:227], v[174:175], 0, v[226:227]
	global_load_dwordx4 v[216:219], v[226:227], off
	global_load_dwordx4 v[220:223], v[226:227], off offset:256
	v_add_u32_e32 v226, 0x90, v172
	v_ashrrev_i32_e32 v227, 31, v226
	v_lshlrev_b64 v[226:227], 11, v[226:227]
	v_lshl_add_u64 v[226:227], v[174:175], 0, v[226:227]
	global_load_dwordx4 v[228:231], v[226:227], off
	global_load_dwordx4 v[232:235], v[226:227], off offset:256
	v_add_u32_e32 v226, 0xa0, v172
	v_ashrrev_i32_e32 v227, 31, v226
	v_lshlrev_b64 v[226:227], 11, v[226:227]
	v_lshl_add_u64 v[226:227], v[174:175], 0, v[226:227]
	global_load_dwordx4 v[236:239], v[226:227], off
	global_load_dwordx4 v[240:243], v[226:227], off offset:256
	v_add_u32_e32 v226, 0xb0, v172
	v_ashrrev_i32_e32 v227, 31, v226
	v_lshlrev_b64 v[226:227], 11, v[226:227]
	v_lshl_add_u64 v[226:227], v[174:175], 0, v[226:227]
	global_load_dwordx4 v[244:247], v[226:227], off
	global_load_dwordx4 v[252:255], v[226:227], off offset:256
	v_and_b32_e32 v195, 64, v193
	v_xor_b32_e32 v194, 16, v193
	v_add_u32_e32 v195, 64, v195
	v_xor_b32_e32 v208, 32, v193
	v_cmp_lt_i32_e32 vcc, v194, v195
	s_waitcnt vmcnt(15)
	v_and_b32_e32 v209, 0xffff0000, v196
	v_cndmask_b32_e32 v194, v193, v194, vcc
	v_cmp_lt_i32_e32 vcc, v208, v195
	v_lshlrev_b32_e32 v195, 2, v194
	s_waitcnt vmcnt(14)
	v_lshlrev_b32_e32 v212, 16, v200
	v_cndmask_b32_e32 v208, v193, v208, vcc
	v_lshlrev_b32_e32 v194, 2, v208
	v_lshlrev_b32_e32 v208, 16, v196
	v_and_b32_e32 v213, 0xffff0000, v200
	v_lshlrev_b32_e32 v210, 16, v198
	v_and_b32_e32 v211, 0xffff0000, v198
	v_lshlrev_b32_e32 v198, 16, v199
	v_and_b32_e32 v199, 0xffff0000, v199
	v_lshlrev_b32_e32 v200, 16, v201
	v_and_b32_e32 v201, 0xffff0000, v201
	v_lshlrev_b32_e32 v214, 16, v202
	v_and_b32_e32 v215, 0xffff0000, v202
	v_pk_add_f32 v[124:125], v[124:125], v[208:209]
	v_pk_add_f32 v[116:117], v[116:117], v[212:213]
	v_lshlrev_b32_e32 v196, 16, v197
	v_and_b32_e32 v197, 0xffff0000, v197
	v_pk_add_f32 v[122:123], v[122:123], v[198:199]
	v_pk_add_f32 v[118:119], v[118:119], v[200:201]
	v_pk_add_f32 v[198:199], v[112:113], v[214:215]
	v_mul_f32_e32 v200, v125, v125
	v_cvt_pk_bf16_f32 v112, v124, v125
	v_mul_f32_e32 v125, v117, v117
	v_pk_add_f32 v[126:127], v[126:127], v[196:197]
	v_fmac_f32_e32 v200, v124, v124
	v_fmac_f32_e32 v125, v116, v116
	v_fmac_f32_e32 v200, v126, v126
	v_fmac_f32_e32 v125, v118, v118
	v_pk_add_f32 v[120:121], v[120:121], v[210:211]
	v_fmac_f32_e32 v200, v127, v127
	v_fmac_f32_e32 v125, v119, v119
	v_lshlrev_b32_e32 v202, 16, v203
	v_and_b32_e32 v203, 0xffff0000, v203
	v_fmac_f32_e32 v200, v120, v120
	v_fmac_f32_e32 v125, v198, v198
	v_pk_add_f32 v[196:197], v[114:115], v[202:203]
	v_fmac_f32_e32 v200, v121, v121
	v_fmac_f32_e32 v125, v199, v199
	v_fmac_f32_e32 v200, v122, v122
	v_fmac_f32_e32 v125, v196, v196
	v_fmac_f32_e32 v200, v123, v123
	v_fmac_f32_e32 v125, v197, v197
	v_cvt_pk_bf16_f32 v115, v122, v123
	v_add_f32_e32 v122, v200, v125
	ds_bpermute_b32 v123, v195, v122
	v_cvt_pk_bf16_f32 v114, v120, v121
	v_lshl_add_u64 v[120:121], s[76:77], 0, v[206:207]
	v_cvt_pk_bf16_f32 v113, v126, v127
	v_lshl_add_u64 v[120:121], v[120:121], 0, v[204:205]
	global_store_dwordx4 v[120:121], v[112:115], off
	s_waitcnt lgkmcnt(0)
	s_nop 0
	v_add_f32_e32 v112, v122, v123
	ds_bpermute_b32 v113, v194, v112
	v_cvt_pk_bf16_f32 v114, v116, v117
	v_cvt_pk_bf16_f32 v115, v118, v119
	v_cvt_pk_bf16_f32 v116, v198, v199
	v_cvt_pk_bf16_f32 v117, v196, v197
	global_store_dwordx4 v[120:121], v[114:117], off offset:256
	s_and_saveexec_b64 s[4:5], s[0:1]
	s_cbranch_execz .LBB0_1121
	s_waitcnt lgkmcnt(0)
	v_add_f32_e32 v114, v112, v113
	s_lshl_b32 s22, s8, 2
	v_lshlrev_b64 v[112:113], 6, v[172:173]
	s_ashr_i32 s23, s22, 31
	v_lshl_add_u64 v[112:113], s[12:13], 0, v[112:113]
	v_lshl_add_u64 v[112:113], s[22:23], 2, v[112:113]
	s_lshl_b32 s10, s35, 2
	v_lshl_add_u64 v[112:113], v[112:113], 0, s[10:11]
	global_store_dword v[112:113], v114, off

; #define PG8_STAGE(bufoff, gbase, voff) do { _Pragma("unroll") for (int _i = 0; _i < 2; ++_i) \
;         __builtin_amdgcn_global_load_lds((const unsigned*)((const char*)(gbase) + (voff)[_i]), (LAS unsigned*)(lds + (bufoff) + ldsw + _i * 8192), 16, 0, 0); } while (0)
; #define PG8_LDA(dst, b, h) do { _Pragma("unroll") for (int m = 0; m < 4; ++m) _Pragma("unroll") for (int k = 0; k < 2; ++k) dst[m][k] = *(const LAS bf16x8*)(lds + PG8_SA(b, h) + aoff + m * 2048 + k * 1024); } while (0)
; #define PG8_LDB(dst, b, h) do { _Pragma("unroll") for (int n = 0; n < 2; ++n) _Pragma("unroll") for (int k = 0; k < 2; ++k) dst[n][k] = *(const LAS bf16x8*)(lds + PG8_SB(b, h) + boff + n * 2048 + k * 1024); } while (0)
; #define PG8_WAIT_V(n) asm volatile("s_waitcnt vmcnt(" #n ")" ::: "memory")
; #define PG8_WAIT_L(n) asm volatile("s_waitcnt lgkmcnt(" #n ")" ::: "memory")
; #define PG8_BAR __builtin_amdgcn_s_barrier()
; #define PG8_SCHED __builtin_amdgcn_sched_barrier(0)
; template <class Epi>
; __device__ __forceinline__ void gemm_phase(LAS unsigned char* lds, const Gemm g, const StaticOrder& S, const Epi& E) {
;     ...
;     for (;;) {
;         const bool has_next = S.next(ui + 1, nxt);
;         const char* nA = has_next ? (const char*)g.A + (size_t)nxt.pm * tstepA : cA; const char* nB = has_next ? (const char*)g.Bt + (size_t)nxt.pn * tstepB : cB;
;         for (int t = 0; t < nt; t += 2) {
;             const bool last = (t == nt - 2);
;             const char* a1 = cA + (size_t)(t + 1) * kstep;
;             const char* a2 = last ? nA : cA + (size_t)(t + 2) * kstep; const char* b2 = last ? nB : cB + (size_t)(t + 2) * kstep;
;             const char* a3 = a2 + kstep; const char* b3 = b2 + kstep;
;             if (last) E.pre(cur, wr, fr, epre);
;             PG8_LDB(B0, 0, 0); PG8_SCHED; PG8_LDA(At, 0, 0); PG8_STAGE(PG8_SA(1, 1), a1 + hstepA, voffA);
;             PG8_WAIT_L(8); PG8_BAR; PG8_WAIT_L(0); PG8_MMA(0, 0, At, B0); PG8_BAR; PG8_SCHED;
;             PG8_LDB(B1, 0, 1); PG8_STAGE(PG8_SB(0, 0), b2, voffB);
;             PG8_BAR; PG8_WAIT_L(0); PG8_MMA(0, 1, At, B1); PG8_BAR;
;             PG8_LDA(At, 0, 1); PG8_STAGE(PG8_SA(0, 0), a2, voffA);
;             PG8_BAR; PG8_WAIT_L(0); PG8_MMA(1, 0, At, B0); PG8_BAR; PG8_SCHED;
;             PG8_STAGE(PG8_SB(0, 1), b2 + hstepB, voffB);
;             PG8_WAIT_V(6); PG8_BAR; PG8_MMA(1, 1, At, B1); PG8_BAR;
.LBB0_1203:
	s_ashr_i32 s13, s12, 31
	v_cmp_lt_i64_e32 vcc, s[14:15], v[142:143]
	s_lshl_b64 s[14:15], s[12:13], 19
	s_add_u32 s14, s76, s14
	s_addc_u32 s15, s77, s15
	s_and_b64 s[16:17], vcc, exec
	s_cselect_b32 s13, s15, s21
	s_cselect_b32 s41, s14, s20
	s_ashr_i32 s11, s10, 31
	s_lshl_b64 s[16:17], s[10:11], 19
	s_add_u32 s16, s26, s16
	s_addc_u32 s17, s27, s17
	s_and_b64 s[24:25], vcc, exec
	s_cselect_b32 s11, s17, s23
	s_cselect_b32 s42, s16, s22
	s_add_u32 s20, s20, 0x40080
	s_addc_u32 s21, s21, 0
	s_add_u32 s43, s22, 0x100
	s_addc_u32 s44, s23, 0
	s_mov_b32 s45, -2
	ds_read_b128 v[146:149], v176
	ds_read_b128 v[154:157], v176 offset:1024
	ds_read_b128 v[158:161], v176 offset:2048
	ds_read_b128 v[162:165], v176 offset:3072
	s_add_u32 s22, s20, 0xfffc0080
	s_addc_u32 s23, s21, -1
	s_cmp_eq_u32 s45, 12
	s_cselect_b32 s25, s13, s23
	s_cselect_b32 s24, s41, s22
	s_cselect_b32 s23, s11, s44
	s_cselect_b32 s22, s42, s43
	v_lshl_add_u64 v[150:151], s[20:21], 0, v[138:139]
	s_add_i32 m0, s19, 0xc000
	ds_read_b128 v[166:169], v177
	ds_read_b128 v[170:173], v177 offset:1024
	ds_read_b128 v[180:183], v177 offset:2048
	ds_read_b128 v[184:187], v177 offset:3072
	ds_read_b128 v[188:191], v177 offset:4096
	ds_read_b128 v[192:195], v177 offset:5120
	ds_read_b128 v[196:199], v177 offset:6144
	ds_read_b128 v[200:203], v177 offset:7168
	global_load_lds_dwordx4 v[150:151], off
	v_lshl_add_u64 v[150:151], s[20:21], 0, v[140:141]
	s_add_i32 m0, s19, 0xe000
	s_nop 0
	global_load_lds_dwordx4 v[150:151], off
	s_waitcnt lgkmcnt(8)
	s_barrier
	s_waitcnt lgkmcnt(0)
	v_mfma_f32_16x16x32_bf16 v[124:127], v[146:149], v[166:169], 0
	v_mfma_f32_16x16x32_bf16 v[120:123], v[158:161], v[166:169], 0
	v_mfma_f32_16x16x32_bf16 v[108:111], v[146:149], v[180:183], 0
	v_mfma_f32_16x16x32_bf16 v[104:107], v[158:161], v[180:183], 0
	v_mfma_f32_16x16x32_bf16 v[92:95], v[146:149], v[188:191], 0
	v_mfma_f32_16x16x32_bf16 v[88:91], v[158:161], v[188:191], 0
	v_mfma_f32_16x16x32_bf16 v[76:79], v[146:149], v[196:199], 0
	v_mfma_f32_16x16x32_bf16 v[72:75], v[158:161], v[196:199], 0
	v_mfma_f32_16x16x32_bf16 v[124:127], v[154:157], v[170:173], v[124:127]
	v_mfma_f32_16x16x32_bf16 v[120:123], v[162:165], v[170:173], v[120:123]
	v_mfma_f32_16x16x32_bf16 v[108:111], v[154:157], v[184:187], v[108:111]
	v_mfma_f32_16x16x32_bf16 v[104:107], v[162:165], v[184:187], v[104:107]
	v_mfma_f32_16x16x32_bf16 v[92:95], v[154:157], v[192:195], v[92:95]
	v_mfma_f32_16x16x32_bf16 v[88:91], v[162:165], v[192:195], v[88:91]
	v_mfma_f32_16x16x32_bf16 v[76:79], v[154:157], v[200:203], v[76:79]
	v_mfma_f32_16x16x32_bf16 v[72:75], v[162:165], v[200:203], v[72:75]
	s_barrier
	s_add_i32 s46, s37, s28
	v_lshl_add_u64 v[150:151], s[22:23], 0, v[130:131]
	s_mov_b32 m0, s46
	ds_read_b128 v[204:207], v178
	ds_read_b128 v[208:211], v178 offset:1024
	ds_read_b128 v[212:215], v178 offset:2048
	ds_read_b128 v[216:219], v178 offset:3072
	global_load_lds_dwordx4 v[150:151], off
	v_lshl_add_u64 v[220:221], s[22:23], 0, v[134:135]
	s_add_i32 m0, s46, 0x2000
	s_nop 0
	global_load_lds_dwordx4 v[220:221], off
	s_barrier
	s_waitcnt lgkmcnt(0)
	v_mfma_f32_16x16x32_bf16 v[116:119], v[204:207], v[166:169], 0
	v_mfma_f32_16x16x32_bf16 v[112:115], v[212:215], v[166:169], 0
	v_mfma_f32_16x16x32_bf16 v[100:103], v[204:207], v[180:183], 0
	v_mfma_f32_16x16x32_bf16 v[96:99], v[212:215], v[180:183], 0
	v_mfma_f32_16x16x32_bf16 v[84:87], v[204:207], v[188:191], 0
	v_mfma_f32_16x16x32_bf16 v[80:83], v[212:215], v[188:191], 0
	v_mfma_f32_16x16x32_bf16 v[68:71], v[204:207], v[196:199], 0
	v_mfma_f32_16x16x32_bf16 v[64:67], v[212:215], v[196:199], 0
	v_mfma_f32_16x16x32_bf16 v[116:119], v[208:211], v[170:173], v[116:119]
	v_mfma_f32_16x16x32_bf16 v[112:115], v[216:219], v[170:173], v[112:115]
	v_mfma_f32_16x16x32_bf16 v[100:103], v[208:211], v[184:187], v[100:103]
	v_mfma_f32_16x16x32_bf16 v[96:99], v[216:219], v[184:187], v[96:99]
	v_mfma_f32_16x16x32_bf16 v[84:87], v[208:211], v[192:195], v[84:87]
	v_mfma_f32_16x16x32_bf16 v[80:83], v[216:219], v[192:195], v[80:83]
	v_mfma_f32_16x16x32_bf16 v[68:71], v[208:211], v[200:203], v[68:71]
	v_mfma_f32_16x16x32_bf16 v[64:67], v[216:219], v[200:203], v[64:67]
	s_mov_b32 m0, s19
	v_lshl_add_u64 v[222:223], s[24:25], 0, v[128:129]
	s_barrier
	ds_read_b128 v[166:169], v177 offset:16384
	ds_read_b128 v[170:173], v177 offset:17408
	ds_read_b128 v[180:183], v177 offset:18432
	ds_read_b128 v[184:187], v177 offset:19456
	ds_read_b128 v[188:191], v177 offset:20480
	ds_read_b128 v[192:195], v177 offset:21504
	ds_read_b128 v[196:199], v177 offset:22528
	ds_read_b128 v[200:203], v177 offset:23552
	global_load_lds_dwordx4 v[222:223], off
	v_lshl_add_u64 v[224:225], s[24:25], 0, v[132:133]
	s_mov_b32 m0, s29
	s_nop 0
	global_load_lds_dwordx4 v[224:225], off
	s_barrier
	s_waitcnt lgkmcnt(0)
	v_mfma_f32_16x16x32_bf16 v[60:63], v[146:149], v[166:169], 0
	v_mfma_f32_16x16x32_bf16 v[56:59], v[158:161], v[166:169], 0
	v_mfma_f32_16x16x32_bf16 v[44:47], v[146:149], v[180:183], 0
	v_mfma_f32_16x16x32_bf16 v[40:43], v[158:161], v[180:183], 0
	v_mfma_f32_16x16x32_bf16 v[28:31], v[146:149], v[188:191], 0
	v_mfma_f32_16x16x32_bf16 v[24:27], v[158:161], v[188:191], 0
	v_mfma_f32_16x16x32_bf16 v[12:15], v[146:149], v[196:199], 0
	v_mfma_f32_16x16x32_bf16 v[8:11], v[158:161], v[196:199], 0
	v_mfma_f32_16x16x32_bf16 v[60:63], v[154:157], v[170:173], v[60:63]
	v_mfma_f32_16x16x32_bf16 v[56:59], v[162:165], v[170:173], v[56:59]
	v_mfma_f32_16x16x32_bf16 v[44:47], v[154:157], v[184:187], v[44:47]
	v_mfma_f32_16x16x32_bf16 v[40:43], v[162:165], v[184:187], v[40:43]
	v_mfma_f32_16x16x32_bf16 v[28:31], v[154:157], v[192:195], v[28:31]
	v_mfma_f32_16x16x32_bf16 v[24:27], v[162:165], v[192:195], v[24:27]
	v_mfma_f32_16x16x32_bf16 v[12:15], v[154:157], v[200:203], v[12:15]
	v_mfma_f32_16x16x32_bf16 v[8:11], v[162:165], v[200:203], v[8:11]
	s_barrier
; #define PG8_STAGE(bufoff, gbase, voff) do { _Pragma("unroll") for (int _i = 0; _i < 2; ++_i) \
;         __builtin_amdgcn_global_load_lds((const unsigned*)((const char*)(gbase) + (voff)[_i]), (LAS unsigned*)(lds + (bufoff) + ldsw + _i * 8192), 16, 0, 0); } while (0)
; #define PG8_LDA(dst, b, h) do { _Pragma("unroll") for (int m = 0; m < 4; ++m) _Pragma("unroll") for (int k = 0; k < 2; ++k) dst[m][k] = *(const LAS bf16x8*)(lds + PG8_SA(b, h) + aoff + m * 2048 + k * 1024); } while (0)
; #define PG8_LDB(dst, b, h) do { _Pragma("unroll") for (int n = 0; n < 2; ++n) _Pragma("unroll") for (int k = 0; k < 2; ++k) dst[n][k] = *(const LAS bf16x8*)(lds + PG8_SB(b, h) + boff + n * 2048 + k * 1024); } while (0)
; #define PG8_WAIT_V(n) asm volatile("s_waitcnt vmcnt(" #n ")" ::: "memory")
; #define PG8_WAIT_L(n) asm volatile("s_waitcnt lgkmcnt(" #n ")" ::: "memory")
; #define PG8_BAR __builtin_amdgcn_s_barrier()
; #define PG8_SCHED __builtin_amdgcn_sched_barrier(0)
; template <class Epi>
; __device__ __forceinline__ void gemm_phase(LAS unsigned char* lds, const Gemm g, const StaticOrder& S, const Epi& E) {
;     ...
;             PG8_LDB(B0, 0, 0); PG8_SCHED; PG8_LDA(At, 0, 0); PG8_STAGE(PG8_SA(1, 1), a1 + hstepA, voffA);
;             PG8_WAIT_L(8); PG8_BAR; PG8_WAIT_L(0); PG8_MMA(0, 0, At, B0); PG8_BAR; PG8_SCHED;
;             PG8_LDB(B1, 0, 1); PG8_STAGE(PG8_SB(0, 0), b2, voffB);
;             PG8_BAR; PG8_WAIT_L(0); PG8_MMA(0, 1, At, B1); PG8_BAR;
;             PG8_LDA(At, 0, 1); PG8_STAGE(PG8_SA(0, 0), a2, voffA);
;             PG8_BAR; PG8_WAIT_L(0); PG8_MMA(1, 0, At, B0); PG8_BAR; PG8_SCHED;
;             PG8_STAGE(PG8_SB(0, 1), b2 + hstepB, voffB);
;             PG8_WAIT_V(6); PG8_BAR; PG8_MMA(1, 1, At, B1); PG8_BAR;
;             PG8_LDB(B0, 1, 0); PG8_SCHED; PG8_LDA(At, 1, 0); PG8_STAGE(PG8_SA(0, 1), a2 + hstepA, voffA);
;             PG8_WAIT_L(8); PG8_BAR; PG8_WAIT_L(0); PG8_MMA(0, 0, At, B0); PG8_BAR; PG8_SCHED;
;             PG8_LDB(B1, 1, 1); PG8_STAGE(PG8_SB(1, 0), b3, voffB);
;             PG8_BAR; PG8_WAIT_L(0); PG8_MMA(0, 1, At, B1); PG8_BAR;
;             PG8_LDA(At, 1, 1); PG8_STAGE(PG8_SA(1, 0), a3, voffA);
;             PG8_BAR; PG8_WAIT_L(0); PG8_MMA(1, 0, At, B0); PG8_BAR; PG8_SCHED;
;             PG8_STAGE(PG8_SB(1, 1), b3 + hstepB, voffB);
;             PG8_WAIT_V(6); PG8_BAR; PG8_MMA(1, 1, At, B1); PG8_BAR;
	s_add_u32 s46, s22, 0x40000
	s_addc_u32 s47, s23, 0
	s_add_i32 s48, s38, s28
	v_lshl_add_u64 v[146:147], s[46:47], 0, v[130:131]
	s_mov_b32 m0, s48
	s_nop 0
	global_load_lds_dwordx4 v[146:147], off
	v_lshl_add_u64 v[146:147], s[46:47], 0, v[134:135]
	s_add_i32 m0, s48, 0x2000
	s_nop 0
	global_load_lds_dwordx4 v[146:147], off
	s_waitcnt vmcnt(6)
	s_barrier
	v_mfma_f32_16x16x32_bf16 v[52:55], v[204:207], v[166:169], 0
	v_mfma_f32_16x16x32_bf16 v[48:51], v[212:215], v[166:169], 0
	v_mfma_f32_16x16x32_bf16 v[36:39], v[204:207], v[180:183], 0
	v_mfma_f32_16x16x32_bf16 v[32:35], v[212:215], v[180:183], 0
	v_mfma_f32_16x16x32_bf16 v[20:23], v[204:207], v[188:191], 0
	v_mfma_f32_16x16x32_bf16 v[16:19], v[212:215], v[188:191], 0
	v_mfma_f32_16x16x32_bf16 v[4:7], v[204:207], v[196:199], 0
	v_mfma_f32_16x16x32_bf16 v[0:3], v[212:215], v[196:199], 0
	v_mfma_f32_16x16x32_bf16 v[52:55], v[208:211], v[170:173], v[52:55]
	v_mfma_f32_16x16x32_bf16 v[48:51], v[216:219], v[170:173], v[48:51]
	v_mfma_f32_16x16x32_bf16 v[36:39], v[208:211], v[184:187], v[36:39]
	v_mfma_f32_16x16x32_bf16 v[32:35], v[216:219], v[184:187], v[32:35]
	v_mfma_f32_16x16x32_bf16 v[20:23], v[208:211], v[192:195], v[20:23]
	v_mfma_f32_16x16x32_bf16 v[16:19], v[216:219], v[192:195], v[16:19]
	v_mfma_f32_16x16x32_bf16 v[4:7], v[208:211], v[200:203], v[4:7]
	v_mfma_f32_16x16x32_bf16 v[0:3], v[216:219], v[200:203], v[0:3]
	s_add_i32 s46, 0, 0x18000
	v_add_u32_e32 v162, s46, v174
	s_barrier
	ds_read_b128 v[146:149], v162
	ds_read_b128 v[154:157], v162 offset:1024
	ds_read_b128 v[158:161], v162 offset:2048
	ds_read_b128 v[162:165], v162 offset:3072
	s_add_u32 s24, s24, 0x40000
	s_addc_u32 s25, s25, 0
	s_mov_b32 m0, s30
	v_lshl_add_u64 v[204:205], s[24:25], 0, v[128:129]
	ds_read_b128 v[166:169], v177 offset:32768
	ds_read_b128 v[170:173], v177 offset:33792
	ds_read_b128 v[180:183], v177 offset:34816
	ds_read_b128 v[184:187], v177 offset:35840
	ds_read_b128 v[188:191], v177 offset:36864
	ds_read_b128 v[192:195], v177 offset:37888
	ds_read_b128 v[196:199], v177 offset:38912
	ds_read_b128 v[200:203], v177 offset:39936
	global_load_lds_dwordx4 v[204:205], off
	v_lshl_add_u64 v[204:205], s[24:25], 0, v[132:133]
	s_mov_b32 m0, s31
	s_nop 0
	global_load_lds_dwordx4 v[204:205], off
	s_waitcnt lgkmcnt(8)
	s_barrier
	s_waitcnt lgkmcnt(0)
	v_mfma_f32_16x16x32_bf16 v[124:127], v[146:149], v[166:169], v[124:127]
	v_mfma_f32_16x16x32_bf16 v[120:123], v[158:161], v[166:169], v[120:123]
	v_mfma_f32_16x16x32_bf16 v[108:111], v[146:149], v[180:183], v[108:111]
	v_mfma_f32_16x16x32_bf16 v[104:107], v[158:161], v[180:183], v[104:107]
	v_mfma_f32_16x16x32_bf16 v[92:95], v[146:149], v[188:191], v[92:95]
	v_mfma_f32_16x16x32_bf16 v[88:91], v[158:161], v[188:191], v[88:91]
	v_mfma_f32_16x16x32_bf16 v[76:79], v[146:149], v[196:199], v[76:79]
	v_mfma_f32_16x16x32_bf16 v[72:75], v[158:161], v[196:199], v[72:75]
	v_mfma_f32_16x16x32_bf16 v[124:127], v[154:157], v[170:173], v[124:127]
	v_mfma_f32_16x16x32_bf16 v[120:123], v[162:165], v[170:173], v[120:123]
	v_mfma_f32_16x16x32_bf16 v[108:111], v[154:157], v[184:187], v[108:111]
	v_mfma_f32_16x16x32_bf16 v[104:107], v[162:165], v[184:187], v[104:107]
	v_mfma_f32_16x16x32_bf16 v[92:95], v[154:157], v[192:195], v[92:95]
	v_mfma_f32_16x16x32_bf16 v[88:91], v[162:165], v[192:195], v[88:91]
	v_mfma_f32_16x16x32_bf16 v[76:79], v[154:157], v[200:203], v[76:79]
	v_mfma_f32_16x16x32_bf16 v[72:75], v[162:165], v[200:203], v[72:75]
	s_barrier
	s_add_i32 s24, 0, 0x1c000
	s_add_i32 s25, s46, s28
	v_add_u32_e32 v216, s24, v174
	v_lshl_add_u64 v[150:151], v[150:151], 0, s[4:5]
	s_mov_b32 m0, s25
	ds_read_b128 v[204:207], v216
	ds_read_b128 v[208:211], v216 offset:1024
	ds_read_b128 v[212:215], v216 offset:2048
	ds_read_b128 v[216:219], v216 offset:3072
	global_load_lds_dwordx4 v[150:151], off
	v_lshl_add_u64 v[150:151], v[220:221], 0, s[4:5]
	s_add_i32 m0, s25, 0x2000
	s_nop 0
	global_load_lds_dwordx4 v[150:151], off
	s_barrier
	s_waitcnt lgkmcnt(0)
	v_mfma_f32_16x16x32_bf16 v[116:119], v[204:207], v[166:169], v[116:119]
	v_mfma_f32_16x16x32_bf16 v[112:115], v[212:215], v[166:169], v[112:115]
	v_mfma_f32_16x16x32_bf16 v[100:103], v[204:207], v[180:183], v[100:103]
	v_mfma_f32_16x16x32_bf16 v[96:99], v[212:215], v[180:183], v[96:99]
	v_mfma_f32_16x16x32_bf16 v[84:87], v[204:207], v[188:191], v[84:87]
	v_mfma_f32_16x16x32_bf16 v[80:83], v[212:215], v[188:191], v[80:83]
	v_mfma_f32_16x16x32_bf16 v[68:71], v[204:207], v[196:199], v[68:71]
	v_mfma_f32_16x16x32_bf16 v[64:67], v[212:215], v[196:199], v[64:67]
	v_mfma_f32_16x16x32_bf16 v[116:119], v[208:211], v[170:173], v[116:119]
	v_mfma_f32_16x16x32_bf16 v[112:115], v[216:219], v[170:173], v[112:115]
	v_mfma_f32_16x16x32_bf16 v[100:103], v[208:211], v[184:187], v[100:103]
	v_mfma_f32_16x16x32_bf16 v[96:99], v[216:219], v[184:187], v[96:99]
	v_mfma_f32_16x16x32_bf16 v[84:87], v[208:211], v[192:195], v[84:87]
	v_mfma_f32_16x16x32_bf16 v[80:83], v[216:219], v[192:195], v[80:83]
	v_mfma_f32_16x16x32_bf16 v[68:71], v[208:211], v[200:203], v[68:71]
	v_mfma_f32_16x16x32_bf16 v[64:67], v[216:219], v[200:203], v[64:67]
	s_mov_b32 m0, s34
	v_lshl_add_u64 v[150:151], v[222:223], 0, s[4:5]
	s_barrier
	ds_read_b128 v[166:169], v177 offset:49152
	ds_read_b128 v[170:173], v177 offset:50176
	ds_read_b128 v[180:183], v177 offset:51200
	ds_read_b128 v[184:187], v177 offset:52224
	ds_read_b128 v[188:191], v177 offset:53248
	ds_read_b128 v[192:195], v177 offset:54272
	ds_read_b128 v[196:199], v177 offset:55296
	ds_read_b128 v[200:203], v177 offset:56320
	global_load_lds_dwordx4 v[150:151], off
	v_lshl_add_u64 v[150:151], v[224:225], 0, s[4:5]
	s_mov_b32 m0, s35
	s_nop 0
	global_load_lds_dwordx4 v[150:151], off
	s_barrier
; #define PG8_STAGE(bufoff, gbase, voff) do { _Pragma("unroll") for (int _i = 0; _i < 2; ++_i) \
;         __builtin_amdgcn_global_load_lds((const unsigned*)((const char*)(gbase) + (voff)[_i]), (LAS unsigned*)(lds + (bufoff) + ldsw + _i * 8192), 16, 0, 0); } while (0)
; #define PG8_LDA(dst, b, h) do { _Pragma("unroll") for (int m = 0; m < 4; ++m) _Pragma("unroll") for (int k = 0; k < 2; ++k) dst[m][k] = *(const LAS bf16x8*)(lds + PG8_SA(b, h) + aoff + m * 2048 + k * 1024); } while (0)
; #define PG8_WAIT_V(n) asm volatile("s_waitcnt vmcnt(" #n ")" ::: "memory")
; template <class Epi>
; __device__ __forceinline__ void gemm_phase(LAS unsigned char* lds, const Gemm g, const StaticOrder& S, const Epi& E) {
;     ...
;         for (int t = 0; t < nt; t += 2) {
;             const bool last = (t == nt - 2);
;             const char* a1 = cA + (size_t)(t + 1) * kstep;
;             const char* a2 = last ? nA : cA + (size_t)(t + 2) * kstep; const char* b2 = last ? nB : cB + (size_t)(t + 2) * kstep;
;             const char* a3 = a2 + kstep; const char* b3 = b2 + kstep;
;             if (last) E.pre(cur, wr, fr, epre);
;             PG8_LDB(B0, 0, 0); PG8_SCHED; PG8_LDA(At, 0, 0); PG8_STAGE(PG8_SA(1, 1), a1 + hstepA, voffA);
;             PG8_WAIT_L(8); PG8_BAR; PG8_WAIT_L(0); PG8_MMA(0, 0, At, B0); PG8_BAR; PG8_SCHED;
;             PG8_LDB(B1, 0, 1); PG8_STAGE(PG8_SB(0, 0), b2, voffB);
;             PG8_BAR; PG8_WAIT_L(0); PG8_MMA(0, 1, At, B1); PG8_BAR;
;             PG8_LDA(At, 0, 1); PG8_STAGE(PG8_SA(0, 0), a2, voffA);
;             PG8_BAR; PG8_WAIT_L(0); PG8_MMA(1, 0, At, B0); PG8_BAR; PG8_SCHED;
;             PG8_STAGE(PG8_SB(0, 1), b2 + hstepB, voffB);
;             PG8_WAIT_V(6); PG8_BAR; PG8_MMA(1, 1, At, B1); PG8_BAR;
;             PG8_LDB(B0, 1, 0); PG8_SCHED; PG8_LDA(At, 1, 0); PG8_STAGE(PG8_SA(0, 1), a2 + hstepA, voffA);
;             PG8_WAIT_L(8); PG8_BAR; PG8_WAIT_L(0); PG8_MMA(0, 0, At, B0); PG8_BAR; PG8_SCHED;
;             PG8_LDB(B1, 1, 1); PG8_STAGE(PG8_SB(1, 0), b3, voffB);
;             PG8_BAR; PG8_WAIT_L(0); PG8_MMA(0, 1, At, B1); PG8_BAR;
;             PG8_LDA(At, 1, 1); PG8_STAGE(PG8_SA(1, 0), a3, voffA);
;             PG8_BAR; PG8_WAIT_L(0); PG8_MMA(1, 0, At, B0); PG8_BAR; PG8_SCHED;
;             PG8_STAGE(PG8_SB(1, 1), b3 + hstepB, voffB);
;             PG8_WAIT_V(6); PG8_BAR; PG8_MMA(1, 1, At, B1); PG8_BAR;
	s_waitcnt lgkmcnt(0)
	v_mfma_f32_16x16x32_bf16 v[60:63], v[146:149], v[166:169], v[60:63]
	v_mfma_f32_16x16x32_bf16 v[56:59], v[158:161], v[166:169], v[56:59]
	v_mfma_f32_16x16x32_bf16 v[44:47], v[146:149], v[180:183], v[44:47]
	v_mfma_f32_16x16x32_bf16 v[40:43], v[158:161], v[180:183], v[40:43]
	v_mfma_f32_16x16x32_bf16 v[28:31], v[146:149], v[188:191], v[28:31]
	v_mfma_f32_16x16x32_bf16 v[24:27], v[158:161], v[188:191], v[24:27]
	v_mfma_f32_16x16x32_bf16 v[12:15], v[146:149], v[196:199], v[12:15]
	v_mfma_f32_16x16x32_bf16 v[8:11], v[158:161], v[196:199], v[8:11]
	v_mfma_f32_16x16x32_bf16 v[60:63], v[154:157], v[170:173], v[60:63]
	v_mfma_f32_16x16x32_bf16 v[56:59], v[162:165], v[170:173], v[56:59]
	v_mfma_f32_16x16x32_bf16 v[44:47], v[154:157], v[184:187], v[44:47]
	v_mfma_f32_16x16x32_bf16 v[40:43], v[162:165], v[184:187], v[40:43]
	v_mfma_f32_16x16x32_bf16 v[28:31], v[154:157], v[192:195], v[28:31]
	v_mfma_f32_16x16x32_bf16 v[24:27], v[162:165], v[192:195], v[24:27]
	v_mfma_f32_16x16x32_bf16 v[12:15], v[154:157], v[200:203], v[12:15]
	v_mfma_f32_16x16x32_bf16 v[8:11], v[162:165], v[200:203], v[8:11]
	s_barrier
	s_add_u32 s22, s22, 0x40080
	s_addc_u32 s23, s23, 0
	s_add_i32 s24, s24, s28
	v_lshl_add_u64 v[146:147], s[22:23], 0, v[130:131]
	s_mov_b32 m0, s24
	s_nop 0
	global_load_lds_dwordx4 v[146:147], off
	v_lshl_add_u64 v[146:147], s[22:23], 0, v[134:135]
	s_add_i32 m0, s24, 0x2000
	s_nop 0
	global_load_lds_dwordx4 v[146:147], off
	s_waitcnt vmcnt(6)
	s_barrier
	v_mfma_f32_16x16x32_bf16 v[52:55], v[204:207], v[166:169], v[52:55]
	v_mfma_f32_16x16x32_bf16 v[48:51], v[212:215], v[166:169], v[48:51]
	v_mfma_f32_16x16x32_bf16 v[36:39], v[204:207], v[180:183], v[36:39]
	v_mfma_f32_16x16x32_bf16 v[32:35], v[212:215], v[180:183], v[32:35]
	v_mfma_f32_16x16x32_bf16 v[20:23], v[204:207], v[188:191], v[20:23]
	v_mfma_f32_16x16x32_bf16 v[16:19], v[212:215], v[188:191], v[16:19]
	v_mfma_f32_16x16x32_bf16 v[4:7], v[204:207], v[196:199], v[4:7]
	v_mfma_f32_16x16x32_bf16 v[0:3], v[212:215], v[196:199], v[0:3]
	v_mfma_f32_16x16x32_bf16 v[52:55], v[208:211], v[170:173], v[52:55]
	v_mfma_f32_16x16x32_bf16 v[48:51], v[216:219], v[170:173], v[48:51]
	v_mfma_f32_16x16x32_bf16 v[36:39], v[208:211], v[184:187], v[36:39]
	v_mfma_f32_16x16x32_bf16 v[32:35], v[216:219], v[184:187], v[32:35]
	v_mfma_f32_16x16x32_bf16 v[20:23], v[208:211], v[192:195], v[20:23]
	v_mfma_f32_16x16x32_bf16 v[16:19], v[216:219], v[192:195], v[16:19]
	v_mfma_f32_16x16x32_bf16 v[4:7], v[208:211], v[200:203], v[4:7]
	v_mfma_f32_16x16x32_bf16 v[0:3], v[216:219], v[200:203], v[0:3]
	s_add_i32 s45, s45, 2
	s_add_u32 s20, s20, 0x100
	s_addc_u32 s21, s21, 0
	s_add_u32 s43, s43, 0x100
	s_addc_u32 s44, s44, 0
	s_cmp_gt_u32 s45, 13
	s_barrier
.LBB0_1204:
	ds_read_b128 v[146:149], v176
	ds_read_b128 v[154:157], v176 offset:1024
	ds_read_b128 v[158:161], v176 offset:2048
	ds_read_b128 v[162:165], v176 offset:3072
	s_add_u32 s22, s20, 0xfffc0080
	s_addc_u32 s23, s21, -1
	s_cmp_eq_u32 s45, 12
	s_cselect_b32 s25, s13, s23
	s_cselect_b32 s24, s41, s22
	s_cselect_b32 s23, s11, s44
	s_cselect_b32 s22, s42, s43
	v_lshl_add_u64 v[150:151], s[20:21], 0, v[138:139]
	s_add_i32 m0, s19, 0xc000
	ds_read_b128 v[166:169], v177
	ds_read_b128 v[170:173], v177 offset:1024
	ds_read_b128 v[180:183], v177 offset:2048
	ds_read_b128 v[184:187], v177 offset:3072
	ds_read_b128 v[188:191], v177 offset:4096
	ds_read_b128 v[192:195], v177 offset:5120
	ds_read_b128 v[196:199], v177 offset:6144
	ds_read_b128 v[200:203], v177 offset:7168
	global_load_lds_dwordx4 v[150:151], off
	v_lshl_add_u64 v[150:151], s[20:21], 0, v[140:141]
	s_add_i32 m0, s19, 0xe000
	s_nop 0
	global_load_lds_dwordx4 v[150:151], off
	s_waitcnt lgkmcnt(8)
	s_barrier
	s_waitcnt lgkmcnt(0)
	v_mfma_f32_16x16x32_bf16 v[124:127], v[146:149], v[166:169], v[124:127]
	v_mfma_f32_16x16x32_bf16 v[120:123], v[158:161], v[166:169], v[120:123]
	v_mfma_f32_16x16x32_bf16 v[108:111], v[146:149], v[180:183], v[108:111]
	v_mfma_f32_16x16x32_bf16 v[104:107], v[158:161], v[180:183], v[104:107]
	v_mfma_f32_16x16x32_bf16 v[92:95], v[146:149], v[188:191], v[92:95]
	v_mfma_f32_16x16x32_bf16 v[88:91], v[158:161], v[188:191], v[88:91]
	v_mfma_f32_16x16x32_bf16 v[76:79], v[146:149], v[196:199], v[76:79]
	v_mfma_f32_16x16x32_bf16 v[72:75], v[158:161], v[196:199], v[72:75]
	v_mfma_f32_16x16x32_bf16 v[124:127], v[154:157], v[170:173], v[124:127]
	v_mfma_f32_16x16x32_bf16 v[120:123], v[162:165], v[170:173], v[120:123]
	v_mfma_f32_16x16x32_bf16 v[108:111], v[154:157], v[184:187], v[108:111]
	v_mfma_f32_16x16x32_bf16 v[104:107], v[162:165], v[184:187], v[104:107]
	v_mfma_f32_16x16x32_bf16 v[92:95], v[154:157], v[192:195], v[92:95]
	v_mfma_f32_16x16x32_bf16 v[88:91], v[162:165], v[192:195], v[88:91]
	v_mfma_f32_16x16x32_bf16 v[76:79], v[154:157], v[200:203], v[76:79]
	v_mfma_f32_16x16x32_bf16 v[72:75], v[162:165], v[200:203], v[72:75]
	s_barrier
	s_add_i32 s46, s37, s28
	v_lshl_add_u64 v[150:151], s[22:23], 0, v[130:131]
	s_mov_b32 m0, s46
	ds_read_b128 v[204:207], v178
	ds_read_b128 v[208:211], v178 offset:1024
	ds_read_b128 v[212:215], v178 offset:2048
	ds_read_b128 v[216:219], v178 offset:3072
	global_load_lds_dwordx4 v[150:151], off
	v_lshl_add_u64 v[220:221], s[22:23], 0, v[134:135]
	s_add_i32 m0, s46, 0x2000
	s_nop 0
	global_load_lds_dwordx4 v[220:221], off
	s_barrier
; #define PG8_STAGE(bufoff, gbase, voff) do { _Pragma("unroll") for (int _i = 0; _i < 2; ++_i) \
;         __builtin_amdgcn_global_load_lds((const unsigned*)((const char*)(gbase) + (voff)[_i]), (LAS unsigned*)(lds + (bufoff) + ldsw + _i * 8192), 16, 0, 0); } while (0)
; #define PG8_LDA(dst, b, h) do { _Pragma("unroll") for (int m = 0; m < 4; ++m) _Pragma("unroll") for (int k = 0; k < 2; ++k) dst[m][k] = *(const LAS bf16x8*)(lds + PG8_SA(b, h) + aoff + m * 2048 + k * 1024); } while (0)
; #define PG8_LDB(dst, b, h) do { _Pragma("unroll") for (int n = 0; n < 2; ++n) _Pragma("unroll") for (int k = 0; k < 2; ++k) dst[n][k] = *(const LAS bf16x8*)(lds + PG8_SB(b, h) + boff + n * 2048 + k * 1024); } while (0)
; #define PG8_WAIT_V(n) asm volatile("s_waitcnt vmcnt(" #n ")" ::: "memory")
; #define PG8_WAIT_L(n) asm volatile("s_waitcnt lgkmcnt(" #n ")" ::: "memory")
; #define PG8_BAR __builtin_amdgcn_s_barrier()
; #define PG8_SCHED __builtin_amdgcn_sched_barrier(0)
; template <class Epi>
; __device__ __forceinline__ void gemm_phase(LAS unsigned char* lds, const Gemm g, const StaticOrder& S, const Epi& E) {
;     ...
;             PG8_LDB(B0, 0, 0); PG8_SCHED; PG8_LDA(At, 0, 0); PG8_STAGE(PG8_SA(1, 1), a1 + hstepA, voffA);
;             PG8_WAIT_L(8); PG8_BAR; PG8_WAIT_L(0); PG8_MMA(0, 0, At, B0); PG8_BAR; PG8_SCHED;
;             PG8_LDB(B1, 0, 1); PG8_STAGE(PG8_SB(0, 0), b2, voffB);
;             PG8_BAR; PG8_WAIT_L(0); PG8_MMA(0, 1, At, B1); PG8_BAR;
;             PG8_LDA(At, 0, 1); PG8_STAGE(PG8_SA(0, 0), a2, voffA);
;             PG8_BAR; PG8_WAIT_L(0); PG8_MMA(1, 0, At, B0); PG8_BAR; PG8_SCHED;
;             PG8_STAGE(PG8_SB(0, 1), b2 + hstepB, voffB);
;             PG8_WAIT_V(6); PG8_BAR; PG8_MMA(1, 1, At, B1); PG8_BAR;
;             PG8_LDB(B0, 1, 0); PG8_SCHED; PG8_LDA(At, 1, 0); PG8_STAGE(PG8_SA(0, 1), a2 + hstepA, voffA);
;             PG8_WAIT_L(8); PG8_BAR; PG8_WAIT_L(0); PG8_MMA(0, 0, At, B0); PG8_BAR; PG8_SCHED;
;             PG8_LDB(B1, 1, 1); PG8_STAGE(PG8_SB(1, 0), b3, voffB);
;             PG8_BAR; PG8_WAIT_L(0); PG8_MMA(0, 1, At, B1); PG8_BAR;
;             PG8_LDA(At, 1, 1); PG8_STAGE(PG8_SA(1, 0), a3, voffA);
;             PG8_BAR; PG8_WAIT_L(0); PG8_MMA(1, 0, At, B0); PG8_BAR; PG8_SCHED;
;             PG8_STAGE(PG8_SB(1, 1), b3 + hstepB, voffB);
;             PG8_WAIT_V(6); PG8_BAR; PG8_MMA(1, 1, At, B1); PG8_BAR;
	s_waitcnt lgkmcnt(0)
	v_mfma_f32_16x16x32_bf16 v[116:119], v[204:207], v[166:169], v[116:119]
	v_mfma_f32_16x16x32_bf16 v[112:115], v[212:215], v[166:169], v[112:115]
	v_mfma_f32_16x16x32_bf16 v[100:103], v[204:207], v[180:183], v[100:103]
	v_mfma_f32_16x16x32_bf16 v[96:99], v[212:215], v[180:183], v[96:99]
	v_mfma_f32_16x16x32_bf16 v[84:87], v[204:207], v[188:191], v[84:87]
	v_mfma_f32_16x16x32_bf16 v[80:83], v[212:215], v[188:191], v[80:83]
	v_mfma_f32_16x16x32_bf16 v[68:71], v[204:207], v[196:199], v[68:71]
	v_mfma_f32_16x16x32_bf16 v[64:67], v[212:215], v[196:199], v[64:67]
	v_mfma_f32_16x16x32_bf16 v[116:119], v[208:211], v[170:173], v[116:119]
	v_mfma_f32_16x16x32_bf16 v[112:115], v[216:219], v[170:173], v[112:115]
	v_mfma_f32_16x16x32_bf16 v[100:103], v[208:211], v[184:187], v[100:103]
	v_mfma_f32_16x16x32_bf16 v[96:99], v[216:219], v[184:187], v[96:99]
	v_mfma_f32_16x16x32_bf16 v[84:87], v[208:211], v[192:195], v[84:87]
	v_mfma_f32_16x16x32_bf16 v[80:83], v[216:219], v[192:195], v[80:83]
	v_mfma_f32_16x16x32_bf16 v[68:71], v[208:211], v[200:203], v[68:71]
	v_mfma_f32_16x16x32_bf16 v[64:67], v[216:219], v[200:203], v[64:67]
	s_mov_b32 m0, s19
	v_lshl_add_u64 v[222:223], s[24:25], 0, v[128:129]
	s_barrier
	ds_read_b128 v[166:169], v177 offset:16384
	ds_read_b128 v[170:173], v177 offset:17408
	ds_read_b128 v[180:183], v177 offset:18432
	ds_read_b128 v[184:187], v177 offset:19456
	ds_read_b128 v[188:191], v177 offset:20480
	ds_read_b128 v[192:195], v177 offset:21504
	ds_read_b128 v[196:199], v177 offset:22528
	ds_read_b128 v[200:203], v177 offset:23552
	global_load_lds_dwordx4 v[222:223], off
	v_lshl_add_u64 v[224:225], s[24:25], 0, v[132:133]
	s_mov_b32 m0, s29
	s_nop 0
	global_load_lds_dwordx4 v[224:225], off
	s_barrier
	s_waitcnt lgkmcnt(0)
	v_mfma_f32_16x16x32_bf16 v[60:63], v[146:149], v[166:169], v[60:63]
	v_mfma_f32_16x16x32_bf16 v[56:59], v[158:161], v[166:169], v[56:59]
	v_mfma_f32_16x16x32_bf16 v[44:47], v[146:149], v[180:183], v[44:47]
	v_mfma_f32_16x16x32_bf16 v[40:43], v[158:161], v[180:183], v[40:43]
	v_mfma_f32_16x16x32_bf16 v[28:31], v[146:149], v[188:191], v[28:31]
	v_mfma_f32_16x16x32_bf16 v[24:27], v[158:161], v[188:191], v[24:27]
	v_mfma_f32_16x16x32_bf16 v[12:15], v[146:149], v[196:199], v[12:15]
	v_mfma_f32_16x16x32_bf16 v[8:11], v[158:161], v[196:199], v[8:11]
	v_mfma_f32_16x16x32_bf16 v[60:63], v[154:157], v[170:173], v[60:63]
	v_mfma_f32_16x16x32_bf16 v[56:59], v[162:165], v[170:173], v[56:59]
	v_mfma_f32_16x16x32_bf16 v[44:47], v[154:157], v[184:187], v[44:47]
	v_mfma_f32_16x16x32_bf16 v[40:43], v[162:165], v[184:187], v[40:43]
	v_mfma_f32_16x16x32_bf16 v[28:31], v[154:157], v[192:195], v[28:31]
	v_mfma_f32_16x16x32_bf16 v[24:27], v[162:165], v[192:195], v[24:27]
	v_mfma_f32_16x16x32_bf16 v[12:15], v[154:157], v[200:203], v[12:15]
	v_mfma_f32_16x16x32_bf16 v[8:11], v[162:165], v[200:203], v[8:11]
	s_barrier
	s_add_u32 s46, s22, 0x40000
	s_addc_u32 s47, s23, 0
	s_add_i32 s48, s38, s28
	v_lshl_add_u64 v[146:147], s[46:47], 0, v[130:131]
	s_mov_b32 m0, s48
	s_nop 0
	global_load_lds_dwordx4 v[146:147], off
	v_lshl_add_u64 v[146:147], s[46:47], 0, v[134:135]
	s_add_i32 m0, s48, 0x2000
	s_nop 0
	global_load_lds_dwordx4 v[146:147], off
	s_waitcnt vmcnt(6)
	s_barrier
	v_mfma_f32_16x16x32_bf16 v[52:55], v[204:207], v[166:169], v[52:55]
	v_mfma_f32_16x16x32_bf16 v[48:51], v[212:215], v[166:169], v[48:51]
	v_mfma_f32_16x16x32_bf16 v[36:39], v[204:207], v[180:183], v[36:39]
	v_mfma_f32_16x16x32_bf16 v[32:35], v[212:215], v[180:183], v[32:35]
	v_mfma_f32_16x16x32_bf16 v[20:23], v[204:207], v[188:191], v[20:23]
	v_mfma_f32_16x16x32_bf16 v[16:19], v[212:215], v[188:191], v[16:19]
	v_mfma_f32_16x16x32_bf16 v[4:7], v[204:207], v[196:199], v[4:7]
	v_mfma_f32_16x16x32_bf16 v[0:3], v[212:215], v[196:199], v[0:3]
	v_mfma_f32_16x16x32_bf16 v[52:55], v[208:211], v[170:173], v[52:55]
	v_mfma_f32_16x16x32_bf16 v[48:51], v[216:219], v[170:173], v[48:51]
	v_mfma_f32_16x16x32_bf16 v[36:39], v[208:211], v[184:187], v[36:39]
	v_mfma_f32_16x16x32_bf16 v[32:35], v[216:219], v[184:187], v[32:35]
	v_mfma_f32_16x16x32_bf16 v[20:23], v[208:211], v[192:195], v[20:23]
	v_mfma_f32_16x16x32_bf16 v[16:19], v[216:219], v[192:195], v[16:19]
	v_mfma_f32_16x16x32_bf16 v[4:7], v[208:211], v[200:203], v[4:7]
	v_mfma_f32_16x16x32_bf16 v[0:3], v[216:219], v[200:203], v[0:3]
	s_add_i32 s46, 0, 0x18000
	v_add_u32_e32 v162, s46, v174
	s_barrier
	ds_read_b128 v[146:149], v162
	ds_read_b128 v[154:157], v162 offset:1024
	ds_read_b128 v[158:161], v162 offset:2048
	ds_read_b128 v[162:165], v162 offset:3072
	s_add_u32 s24, s24, 0x40000
	s_addc_u32 s25, s25, 0
	s_mov_b32 m0, s30
	v_lshl_add_u64 v[204:205], s[24:25], 0, v[128:129]
	ds_read_b128 v[166:169], v177 offset:32768
	ds_read_b128 v[170:173], v177 offset:33792
	ds_read_b128 v[180:183], v177 offset:34816
	ds_read_b128 v[184:187], v177 offset:35840
	ds_read_b128 v[188:191], v177 offset:36864
	ds_read_b128 v[192:195], v177 offset:37888
	ds_read_b128 v[196:199], v177 offset:38912
	ds_read_b128 v[200:203], v177 offset:39936
	global_load_lds_dwordx4 v[204:205], off
	v_lshl_add_u64 v[204:205], s[24:25], 0, v[132:133]
	s_mov_b32 m0, s31
	s_nop 0
	global_load_lds_dwordx4 v[204:205], off
	s_waitcnt lgkmcnt(8)
	s_barrier
; #define PG8_STAGE(bufoff, gbase, voff) do { _Pragma("unroll") for (int _i = 0; _i < 2; ++_i) \
;         __builtin_amdgcn_global_load_lds((const unsigned*)((const char*)(gbase) + (voff)[_i]), (LAS unsigned*)(lds + (bufoff) + ldsw + _i * 8192), 16, 0, 0); } while (0)
; #define PG8_LDA(dst, b, h) do { _Pragma("unroll") for (int m = 0; m < 4; ++m) _Pragma("unroll") for (int k = 0; k < 2; ++k) dst[m][k] = *(const LAS bf16x8*)(lds + PG8_SA(b, h) + aoff + m * 2048 + k * 1024); } while (0)
; #define PG8_LDB(dst, b, h) do { _Pragma("unroll") for (int n = 0; n < 2; ++n) _Pragma("unroll") for (int k = 0; k < 2; ++k) dst[n][k] = *(const LAS bf16x8*)(lds + PG8_SB(b, h) + boff + n * 2048 + k * 1024); } while (0)
; #define PG8_MMA(ai, bj, At, Bt) do { __builtin_amdgcn_s_setprio(1); _Pragma("unroll") for (int m = 0; m < 4; ++m) _Pragma("unroll") for (int n = 0; n < 2; ++n) _Pragma("unroll") for (int k = 0; k < 2; ++k) \
;         acc[ai][bj][m][n] = __builtin_amdgcn_mfma_f32_16x16x32_bf16(Bt[n][k], At[m][k], acc[ai][bj][m][n], 0, 0, 0); __builtin_amdgcn_s_setprio(0); } while (0)
; #define PG8_WAIT_V(n) asm volatile("s_waitcnt vmcnt(" #n ")" ::: "memory")
; #define PG8_WAIT_L(n) asm volatile("s_waitcnt lgkmcnt(" #n ")" ::: "memory")
; #define PG8_BAR __builtin_amdgcn_s_barrier()
; #define PG8_SCHED __builtin_amdgcn_sched_barrier(0)
; template <class Epi>
; __device__ __forceinline__ void gemm_phase(LAS unsigned char* lds, const Gemm g, const StaticOrder& S, const Epi& E) {
;     ...
;             PG8_WAIT_V(6); PG8_BAR; PG8_MMA(1, 1, At, B1); PG8_BAR;
;             PG8_LDB(B0, 1, 0); PG8_SCHED; PG8_LDA(At, 1, 0); PG8_STAGE(PG8_SA(0, 1), a2 + hstepA, voffA);
;             PG8_WAIT_L(8); PG8_BAR; PG8_WAIT_L(0); PG8_MMA(0, 0, At, B0); PG8_BAR; PG8_SCHED;
;             PG8_LDB(B1, 1, 1); PG8_STAGE(PG8_SB(1, 0), b3, voffB);
;             PG8_BAR; PG8_WAIT_L(0); PG8_MMA(0, 1, At, B1); PG8_BAR;
;             PG8_LDA(At, 1, 1); PG8_STAGE(PG8_SA(1, 0), a3, voffA);
;             PG8_BAR; PG8_WAIT_L(0); PG8_MMA(1, 0, At, B0); PG8_BAR; PG8_SCHED;
;             PG8_STAGE(PG8_SB(1, 1), b3 + hstepB, voffB);
;             PG8_WAIT_V(6); PG8_BAR; PG8_MMA(1, 1, At, B1); PG8_BAR;
	s_waitcnt lgkmcnt(0)
	v_mfma_f32_16x16x32_bf16 v[124:127], v[146:149], v[166:169], v[124:127]
	v_mfma_f32_16x16x32_bf16 v[120:123], v[158:161], v[166:169], v[120:123]
	v_mfma_f32_16x16x32_bf16 v[108:111], v[146:149], v[180:183], v[108:111]
	v_mfma_f32_16x16x32_bf16 v[104:107], v[158:161], v[180:183], v[104:107]
	v_mfma_f32_16x16x32_bf16 v[92:95], v[146:149], v[188:191], v[92:95]
	v_mfma_f32_16x16x32_bf16 v[88:91], v[158:161], v[188:191], v[88:91]
	v_mfma_f32_16x16x32_bf16 v[76:79], v[146:149], v[196:199], v[76:79]
	v_mfma_f32_16x16x32_bf16 v[72:75], v[158:161], v[196:199], v[72:75]
	v_mfma_f32_16x16x32_bf16 v[124:127], v[154:157], v[170:173], v[124:127]
	v_mfma_f32_16x16x32_bf16 v[120:123], v[162:165], v[170:173], v[120:123]
	v_mfma_f32_16x16x32_bf16 v[108:111], v[154:157], v[184:187], v[108:111]
	v_mfma_f32_16x16x32_bf16 v[104:107], v[162:165], v[184:187], v[104:107]
	v_mfma_f32_16x16x32_bf16 v[92:95], v[154:157], v[192:195], v[92:95]
	v_mfma_f32_16x16x32_bf16 v[88:91], v[162:165], v[192:195], v[88:91]
	v_mfma_f32_16x16x32_bf16 v[76:79], v[154:157], v[200:203], v[76:79]
	v_mfma_f32_16x16x32_bf16 v[72:75], v[162:165], v[200:203], v[72:75]
	s_barrier
	s_add_i32 s24, 0, 0x1c000
	s_add_i32 s25, s46, s28
	v_add_u32_e32 v216, s24, v174
	v_lshl_add_u64 v[150:151], v[150:151], 0, s[4:5]
	s_mov_b32 m0, s25
	ds_read_b128 v[204:207], v216
	ds_read_b128 v[208:211], v216 offset:1024
	ds_read_b128 v[212:215], v216 offset:2048
	ds_read_b128 v[216:219], v216 offset:3072
	global_load_lds_dwordx4 v[150:151], off
	v_lshl_add_u64 v[150:151], v[220:221], 0, s[4:5]
	s_add_i32 m0, s25, 0x2000
	s_nop 0
	global_load_lds_dwordx4 v[150:151], off
	s_barrier
	s_waitcnt lgkmcnt(0)
	v_mfma_f32_16x16x32_bf16 v[116:119], v[204:207], v[166:169], v[116:119]
	v_mfma_f32_16x16x32_bf16 v[112:115], v[212:215], v[166:169], v[112:115]
	v_mfma_f32_16x16x32_bf16 v[100:103], v[204:207], v[180:183], v[100:103]
	v_mfma_f32_16x16x32_bf16 v[96:99], v[212:215], v[180:183], v[96:99]
	v_mfma_f32_16x16x32_bf16 v[84:87], v[204:207], v[188:191], v[84:87]
	v_mfma_f32_16x16x32_bf16 v[80:83], v[212:215], v[188:191], v[80:83]
	v_mfma_f32_16x16x32_bf16 v[68:71], v[204:207], v[196:199], v[68:71]
	v_mfma_f32_16x16x32_bf16 v[64:67], v[212:215], v[196:199], v[64:67]
	v_mfma_f32_16x16x32_bf16 v[116:119], v[208:211], v[170:173], v[116:119]
	v_mfma_f32_16x16x32_bf16 v[112:115], v[216:219], v[170:173], v[112:115]
	v_mfma_f32_16x16x32_bf16 v[100:103], v[208:211], v[184:187], v[100:103]
	v_mfma_f32_16x16x32_bf16 v[96:99], v[216:219], v[184:187], v[96:99]
	v_mfma_f32_16x16x32_bf16 v[84:87], v[208:211], v[192:195], v[84:87]
	v_mfma_f32_16x16x32_bf16 v[80:83], v[216:219], v[192:195], v[80:83]
	v_mfma_f32_16x16x32_bf16 v[68:71], v[208:211], v[200:203], v[68:71]
	v_mfma_f32_16x16x32_bf16 v[64:67], v[216:219], v[200:203], v[64:67]
	s_mov_b32 m0, s34
	v_lshl_add_u64 v[150:151], v[222:223], 0, s[4:5]
	s_barrier
	ds_read_b128 v[166:169], v177 offset:49152
	ds_read_b128 v[170:173], v177 offset:50176
	ds_read_b128 v[180:183], v177 offset:51200
	ds_read_b128 v[184:187], v177 offset:52224
	ds_read_b128 v[188:191], v177 offset:53248
	ds_read_b128 v[192:195], v177 offset:54272
	ds_read_b128 v[196:199], v177 offset:55296
	ds_read_b128 v[200:203], v177 offset:56320
	global_load_lds_dwordx4 v[150:151], off
	v_lshl_add_u64 v[150:151], v[224:225], 0, s[4:5]
	s_mov_b32 m0, s35
	s_nop 0
	global_load_lds_dwordx4 v[150:151], off
	s_barrier
	s_waitcnt lgkmcnt(0)
	v_mfma_f32_16x16x32_bf16 v[60:63], v[146:149], v[166:169], v[60:63]
	v_mfma_f32_16x16x32_bf16 v[56:59], v[158:161], v[166:169], v[56:59]
	v_mfma_f32_16x16x32_bf16 v[44:47], v[146:149], v[180:183], v[44:47]
	v_mfma_f32_16x16x32_bf16 v[40:43], v[158:161], v[180:183], v[40:43]
	v_mfma_f32_16x16x32_bf16 v[28:31], v[146:149], v[188:191], v[28:31]
	v_mfma_f32_16x16x32_bf16 v[24:27], v[158:161], v[188:191], v[24:27]
	v_mfma_f32_16x16x32_bf16 v[12:15], v[146:149], v[196:199], v[12:15]
	v_mfma_f32_16x16x32_bf16 v[8:11], v[158:161], v[196:199], v[8:11]
	v_mfma_f32_16x16x32_bf16 v[60:63], v[154:157], v[170:173], v[60:63]
	v_mfma_f32_16x16x32_bf16 v[56:59], v[162:165], v[170:173], v[56:59]
	v_mfma_f32_16x16x32_bf16 v[44:47], v[154:157], v[184:187], v[44:47]
	v_mfma_f32_16x16x32_bf16 v[40:43], v[162:165], v[184:187], v[40:43]
	v_mfma_f32_16x16x32_bf16 v[28:31], v[154:157], v[192:195], v[28:31]
	v_mfma_f32_16x16x32_bf16 v[24:27], v[162:165], v[192:195], v[24:27]
	v_mfma_f32_16x16x32_bf16 v[12:15], v[154:157], v[200:203], v[12:15]
	v_mfma_f32_16x16x32_bf16 v[8:11], v[162:165], v[200:203], v[8:11]
	s_barrier
	s_add_u32 s22, s22, 0x40080
	s_addc_u32 s23, s23, 0
	s_add_i32 s24, s24, s28
	v_lshl_add_u64 v[146:147], s[22:23], 0, v[130:131]
	s_mov_b32 m0, s24
	s_nop 0
	global_load_lds_dwordx4 v[146:147], off
	v_lshl_add_u64 v[146:147], s[22:23], 0, v[134:135]
	s_add_i32 m0, s24, 0x2000
	s_nop 0
	global_load_lds_dwordx4 v[146:147], off
	s_waitcnt vmcnt(6)
	s_barrier
	v_mfma_f32_16x16x32_bf16 v[52:55], v[204:207], v[166:169], v[52:55]
	v_mfma_f32_16x16x32_bf16 v[48:51], v[212:215], v[166:169], v[48:51]
	v_mfma_f32_16x16x32_bf16 v[36:39], v[204:207], v[180:183], v[36:39]
	v_mfma_f32_16x16x32_bf16 v[32:35], v[212:215], v[180:183], v[32:35]
	v_mfma_f32_16x16x32_bf16 v[20:23], v[204:207], v[188:191], v[20:23]
	v_mfma_f32_16x16x32_bf16 v[16:19], v[212:215], v[188:191], v[16:19]
	v_mfma_f32_16x16x32_bf16 v[4:7], v[204:207], v[196:199], v[4:7]
	v_mfma_f32_16x16x32_bf16 v[0:3], v[212:215], v[196:199], v[0:3]
	v_mfma_f32_16x16x32_bf16 v[52:55], v[208:211], v[170:173], v[52:55]
	v_mfma_f32_16x16x32_bf16 v[48:51], v[216:219], v[170:173], v[48:51]
	v_mfma_f32_16x16x32_bf16 v[36:39], v[208:211], v[184:187], v[36:39]
	v_mfma_f32_16x16x32_bf16 v[32:35], v[216:219], v[184:187], v[32:35]
	v_mfma_f32_16x16x32_bf16 v[20:23], v[208:211], v[192:195], v[20:23]
	v_mfma_f32_16x16x32_bf16 v[16:19], v[216:219], v[192:195], v[16:19]
	v_mfma_f32_16x16x32_bf16 v[4:7], v[208:211], v[200:203], v[4:7]
	v_mfma_f32_16x16x32_bf16 v[0:3], v[216:219], v[200:203], v[0:3]
	s_add_i32 s45, s45, 2
	s_add_u32 s20, s20, 0x100
	s_addc_u32 s21, s21, 0
	s_add_u32 s43, s43, 0x100
	s_addc_u32 s44, s44, 0
	s_cmp_gt_u32 s45, 13
	s_barrier
; __device__ __forceinline__ unsigned pk2(float lo, float hi) { const f32x2 v = (f32x2){lo, hi}; const bf16x2_t b = __builtin_convertvector(v, bf16x2_t); return __builtin_bit_cast(unsigned, b); }
;     __device__ __forceinline__ void operator()(const f32x4 (&acc)[2][2][4][2], const Unit& u, int wr, int wc, int fr, int fq, const float (&)[8]) const {
;     ...
;             for (int m = 0; m < 4; ++m) { const int row = row0 + ai * HALF + m * 16;
;                 if (SLOTS == 1) ep[ai * 4 + m] = ss[row];
;                 else { const f32x4 pq = *(const f32x4*)(ss + (size_t)row * 16 + 4 * fq); ep[ai * 4 + m] = (pq[0] + pq[1]) + (pq[2] + pq[3]); } }
;         if (SLOTS != 1) {
; #pragma unroll
;             for (int q = 0; q < 8; ++q) { ep[q] += __shfl_xor(ep[q], 16); ep[q] += __shfl_xor(ep[q], 32); } }
;         if (DT && u.pn == 20) {
;             if (wc == 0) {
; #pragma unroll
;                 for (int ai = 0; ai < 2; ++ai)
; #pragma unroll
;                     for (int m = 0; m < 4; ++m) { const int row = row0 + ai * HALF + m * 16; const float rs = rsqrtf(ep[ai * 4 + m] * (1.0f / 1024.0f) + EPS);
;                         *(f32x4*)(dt + (size_t)row * 32 + 8 * fq) = acc[ai][0][m][0] * rs; *(f32x4*)(dt + (size_t)row * 32 + 8 * fq + 4) = acc[ai][0][m][1] * rs; }
;             }
;             return;
;         }
;         const int col0 = u.pn * BM + wc * 32 + 8 * fq;
; #pragma unroll
;         for (int ai = 0; ai < 2; ++ai)
; #pragma unroll
;             for (int m = 0; m < 4; ++m) { const int row = row0 + ai * HALF + m * 16; const float rs = rsqrtf(ep[ai * 4 + m] * (1.0f / 1024.0f) + EPS);
;                 u16* rowp = O + (size_t)row * ldc + col0;
; #pragma unroll
;                 for (int bj = 0; bj < 2; ++bj) { f32x4 v0 = acc[ai][bj][m][0] * rs, v1 = acc[ai][bj][m][1] * rs;
;                     if (ACT == 1) {
; #pragma unroll
;                         for (int j = 0; j < 4; ++j) { const float a0 = fmaxf(v0[j], 0.f), a1 = fmaxf(v1[j], 0.f); v0[j] = a0 * a0; v1[j] = a1 * a1; } }
;                     u32x4 w; w.x = pk2(v0[0], v0[1]); w.y = pk2(v0[2], v0[3]); w.z = pk2(v1[0], v1[1]); w.w = pk2(v1[2], v1[3]);
;                     *(u32x4*)(rowp + bj * HALF) = w; } }
	s_cbranch_scc0 .LBB0_1204
	s_bfe_u32 vcc_lo, s18, 0x20003
	s_lshl_b32 vcc_lo, vcc_lo, 10
	s_add_i32 vcc_lo, vcc_lo, 0x20010
	v_lshl_add_u32 v236, v153, 2, vcc_lo
	ds_read_b32 v228, v236
	ds_read_b32 v229, v236 offset:64
	ds_read_b32 v230, v236 offset:128
	ds_read_b32 v231, v236 offset:192
	ds_read_b32 v232, v236 offset:512
	ds_read_b32 v233, v236 offset:576
	ds_read_b32 v234, v236 offset:640
	ds_read_b32 v235, v236 offset:704
	s_waitcnt lgkmcnt(0)
	v_lshl_add_u32 v148, s18, 8, v153
	v_ashrrev_i32_e32 v149, 31, v148
	v_or_b32_e32 v172, 16, v148
	v_ashrrev_i32_e32 v173, 31, v172
	v_or_b32_e32 v168, 32, v148
	v_or_b32_e32 v164, 48, v148
	v_ashrrev_i32_e32 v169, 31, v168
	v_ashrrev_i32_e32 v165, 31, v164
	v_add_u32_e32 v162, 0x80, v148
	v_add_u32_e32 v156, 0x90, v148
	v_ashrrev_i32_e32 v163, 31, v162
	v_ashrrev_i32_e32 v157, 31, v156
	v_add_u32_e32 v150, 0xa0, v148
	v_ashrrev_i32_e32 v151, 31, v150
	v_add_u32_e32 v146, 0xb0, v148
	v_ashrrev_i32_e32 v147, 31, v146
	v_lshl_or_b32 v166, s40, 8, v175
	v_ashrrev_i32_e32 v167, 31, v166
	v_lshlrev_b64 v[170:171], 13, v[148:149]
	v_lshlrev_b64 v[148:149], 1, v[166:167]
	v_lshl_add_u64 v[166:167], s[96:97], 0, v[170:171]
	v_lshl_add_u64 v[210:211], v[166:167], 0, v[148:149]
	s_mov_b32 s40, s10
	s_mov_b32 s18, s12
	s_mov_b64 s[22:23], s[16:17]
	s_mov_b64 s[20:21], s[14:15]
	s_waitcnt vmcnt(8)
	s_waitcnt lgkmcnt(0)
	s_waitcnt lgkmcnt(0)
	v_mov_b32_e32 v182, v228
	v_pk_mul_f32 v[120:121], v[120:121], v[182:183] op_sel_hi:[1,0]
	v_pk_mul_f32 v[126:127], v[126:127], v[182:183] op_sel_hi:[1,0]
	v_pk_mul_f32 v[124:125], v[124:125], v[182:183] op_sel_hi:[1,0]
	v_pk_mul_f32 v[122:123], v[122:123], v[182:183] op_sel_hi:[1,0]
	v_max_f32_e32 v120, 0, v120
	v_max_f32_e32 v121, 0, v121
	v_max_f32_e32 v124, 0, v124
	v_max_f32_e32 v125, 0, v125
	v_pk_mul_f32 v[188:189], v[120:121], v[120:121]
	v_max_f32_e32 v120, 0, v126
	v_max_f32_e32 v122, 0, v122
	v_max_f32_e32 v121, 0, v127
	v_max_f32_e32 v123, 0, v123
	v_pk_mul_f32 v[124:125], v[124:125], v[124:125]
	v_pk_mul_f32 v[126:127], v[120:121], v[120:121]
	v_pk_mul_f32 v[192:193], v[122:123], v[122:123]
	v_pk_mul_f32 v[114:115], v[114:115], v[182:183] op_sel_hi:[1,0]
	v_cvt_pk_bf16_f32 v120, v124, v125
	v_cvt_pk_bf16_f32 v121, v126, v127
	v_cvt_pk_bf16_f32 v122, v188, v189
	v_cvt_pk_bf16_f32 v123, v192, v193
	v_pk_mul_f32 v[116:117], v[116:117], v[182:183] op_sel_hi:[1,0]
	v_pk_mul_f32 v[112:113], v[112:113], v[182:183] op_sel_hi:[1,0]
	v_max_f32_e32 v114, 0, v114
	v_max_f32_e32 v115, 0, v115
	global_store_dwordx4 v[210:211], v[120:123], off
	v_pk_mul_f32 v[118:119], v[118:119], v[182:183] op_sel_hi:[1,0]
	v_max_f32_e32 v116, 0, v116
	v_max_f32_e32 v112, 0, v112
	v_max_f32_e32 v117, 0, v117
	v_max_f32_e32 v113, 0, v113
	v_pk_mul_f32 v[122:123], v[114:115], v[114:115]
	v_pk_mul_f32 v[116:117], v[116:117], v[116:117]
	v_pk_mul_f32 v[120:121], v[112:113], v[112:113]
	v_max_f32_e32 v112, 0, v118
	v_max_f32_e32 v113, 0, v119
	v_pk_mul_f32 v[118:119], v[112:113], v[112:113]
	v_cvt_pk_bf16_f32 v112, v116, v117
	v_cvt_pk_bf16_f32 v113, v118, v119
	v_cvt_pk_bf16_f32 v114, v120, v121
	v_cvt_pk_bf16_f32 v115, v122, v123
	global_store_dwordx4 v[210:211], v[112:115], off offset:256
	s_nop 1
	v_mov_b32_e32 v112, v229
	v_pk_mul_f32 v[104:105], v[104:105], v[112:113] op_sel_hi:[1,0]
	v_pk_mul_f32 v[110:111], v[110:111], v[112:113] op_sel_hi:[1,0]
	v_pk_mul_f32 v[108:109], v[108:109], v[112:113] op_sel_hi:[1,0]
	v_pk_mul_f32 v[106:107], v[106:107], v[112:113] op_sel_hi:[1,0]
	v_max_f32_e32 v104, 0, v104
	v_max_f32_e32 v105, 0, v105
	v_lshlrev_b64 v[114:115], 13, v[172:173]
	v_max_f32_e32 v108, 0, v108
	v_max_f32_e32 v109, 0, v109
	v_pk_mul_f32 v[116:117], v[104:105], v[104:105]
	v_max_f32_e32 v104, 0, v110
	v_max_f32_e32 v106, 0, v106
	v_max_f32_e32 v105, 0, v111
	v_max_f32_e32 v107, 0, v107
	v_lshl_add_u64 v[114:115], s[96:97], 0, v[114:115]
	v_pk_mul_f32 v[108:109], v[108:109], v[108:109]
	v_pk_mul_f32 v[110:111], v[104:105], v[104:105]
	v_pk_mul_f32 v[118:119], v[106:107], v[106:107]
	v_pk_mul_f32 v[96:97], v[96:97], v[112:113] op_sel_hi:[1,0]
	v_lshl_add_u64 v[114:115], v[114:115], 0, v[148:149]
	v_cvt_pk_bf16_f32 v104, v108, v109
	v_cvt_pk_bf16_f32 v105, v110, v111
	v_cvt_pk_bf16_f32 v106, v116, v117
	v_cvt_pk_bf16_f32 v107, v118, v119
	v_pk_mul_f32 v[102:103], v[102:103], v[112:113] op_sel_hi:[1,0]
	v_max_f32_e32 v96, 0, v96
	v_max_f32_e32 v97, 0, v97
	global_store_dwordx4 v[114:115], v[104:107], off
	v_pk_mul_f32 v[100:101], v[100:101], v[112:113] op_sel_hi:[1,0]
	v_pk_mul_f32 v[98:99], v[98:99], v[112:113] op_sel_hi:[1,0]
	v_pk_mul_f32 v[104:105], v[96:97], v[96:97]
	v_max_f32_e32 v96, 0, v102
	v_max_f32_e32 v97, 0, v103
	v_max_f32_e32 v100, 0, v100
	v_max_f32_e32 v101, 0, v101
	v_pk_mul_f32 v[100:101], v[100:101], v[100:101]
	v_pk_mul_f32 v[108:109], v[96:97], v[96:97]
	v_cvt_pk_bf16_f32 v96, v100, v101
	s_waitcnt lgkmcnt(0)
	v_max_f32_e32 v98, 0, v98
	v_max_f32_e32 v99, 0, v99
	v_pk_mul_f32 v[110:111], v[98:99], v[98:99]
	v_cvt_pk_bf16_f32 v97, v108, v109
	v_cvt_pk_bf16_f32 v98, v104, v105
	v_cvt_pk_bf16_f32 v99, v110, v111
	global_store_dwordx4 v[114:115], v[96:99], off offset:256
	s_waitcnt lgkmcnt(0)
; __device__ __forceinline__ unsigned pk2(float lo, float hi) { const f32x2 v = (f32x2){lo, hi}; const bf16x2_t b = __builtin_convertvector(v, bf16x2_t); return __builtin_bit_cast(unsigned, b); }
;     __device__ __forceinline__ void operator()(const f32x4 (&acc)[2][2][4][2], const Unit& u, int wr, int wc, int fr, int fq, const float (&)[8]) const {
;     ...
;         for (int ai = 0; ai < 2; ++ai)
; #pragma unroll
;             for (int m = 0; m < 4; ++m) { const int row = row0 + ai * HALF + m * 16; const float rs = rsqrtf(ep[ai * 4 + m] * (1.0f / 1024.0f) + EPS);
;                 u16* rowp = O + (size_t)row * ldc + col0;
; #pragma unroll
;                 for (int bj = 0; bj < 2; ++bj) { f32x4 v0 = acc[ai][bj][m][0] * rs, v1 = acc[ai][bj][m][1] * rs;
;                     if (ACT == 1) {
; #pragma unroll
;                         for (int j = 0; j < 4; ++j) { const float a0 = fmaxf(v0[j], 0.f), a1 = fmaxf(v1[j], 0.f); v0[j] = a0 * a0; v1[j] = a1 * a1; } }
;                     u32x4 w; w.x = pk2(v0[0], v0[1]); w.y = pk2(v0[2], v0[3]); w.z = pk2(v1[0], v1[1]); w.w = pk2(v1[2], v1[3]);
;                     *(u32x4*)(rowp + bj * HALF) = w; } }
	s_nop 0
	s_nop 0
	s_nop 0
	s_nop 1
	v_lshlrev_b64 v[98:99], 13, v[168:169]
	v_lshl_add_u64 v[98:99], s[96:97], 0, v[98:99]
	v_lshl_add_u64 v[98:99], v[98:99], 0, v[148:149]
	v_mov_b32_e32 v100, v230
	v_pk_mul_f32 v[88:89], v[88:89], v[100:101] op_sel_hi:[1,0]
	v_pk_mul_f32 v[94:95], v[94:95], v[100:101] op_sel_hi:[1,0]
	v_pk_mul_f32 v[92:93], v[92:93], v[100:101] op_sel_hi:[1,0]
	v_pk_mul_f32 v[90:91], v[90:91], v[100:101] op_sel_hi:[1,0]
	v_max_f32_e32 v88, 0, v88
	v_max_f32_e32 v89, 0, v89
	v_max_f32_e32 v92, 0, v92
	v_max_f32_e32 v93, 0, v93
	v_pk_mul_f32 v[102:103], v[88:89], v[88:89]
	v_max_f32_e32 v88, 0, v94
	v_max_f32_e32 v90, 0, v90
	v_max_f32_e32 v89, 0, v95
	v_max_f32_e32 v91, 0, v91
	v_pk_mul_f32 v[92:93], v[92:93], v[92:93]
	v_pk_mul_f32 v[94:95], v[88:89], v[88:89]
	v_pk_mul_f32 v[104:105], v[90:91], v[90:91]
	v_pk_mul_f32 v[82:83], v[82:83], v[100:101] op_sel_hi:[1,0]
	v_cvt_pk_bf16_f32 v88, v92, v93
	v_cvt_pk_bf16_f32 v89, v94, v95
	v_cvt_pk_bf16_f32 v90, v102, v103
	v_cvt_pk_bf16_f32 v91, v104, v105
	v_pk_mul_f32 v[84:85], v[84:85], v[100:101] op_sel_hi:[1,0]
	v_pk_mul_f32 v[80:81], v[80:81], v[100:101] op_sel_hi:[1,0]
	v_max_f32_e32 v82, 0, v82
	v_max_f32_e32 v83, 0, v83
	global_store_dwordx4 v[98:99], v[88:91], off
	v_pk_mul_f32 v[86:87], v[86:87], v[100:101] op_sel_hi:[1,0]
	v_max_f32_e32 v84, 0, v84
	v_max_f32_e32 v80, 0, v80
	v_max_f32_e32 v85, 0, v85
	v_max_f32_e32 v81, 0, v81
	v_pk_mul_f32 v[90:91], v[82:83], v[82:83]
	v_pk_mul_f32 v[84:85], v[84:85], v[84:85]
	v_pk_mul_f32 v[88:89], v[80:81], v[80:81]
	v_max_f32_e32 v80, 0, v86
	v_max_f32_e32 v81, 0, v87
	v_pk_mul_f32 v[86:87], v[80:81], v[80:81]
	v_cvt_pk_bf16_f32 v80, v84, v85
	v_cvt_pk_bf16_f32 v81, v86, v87
	v_cvt_pk_bf16_f32 v82, v88, v89
	v_cvt_pk_bf16_f32 v83, v90, v91
	global_store_dwordx4 v[98:99], v[80:83], off offset:256
	s_nop 1
	v_mov_b32_e32 v80, v231
	v_pk_mul_f32 v[72:73], v[72:73], v[80:81] op_sel_hi:[1,0]
	v_pk_mul_f32 v[78:79], v[78:79], v[80:81] op_sel_hi:[1,0]
	v_pk_mul_f32 v[76:77], v[76:77], v[80:81] op_sel_hi:[1,0]
	v_pk_mul_f32 v[74:75], v[74:75], v[80:81] op_sel_hi:[1,0]
	v_max_f32_e32 v72, 0, v72
	v_max_f32_e32 v73, 0, v73
	v_lshlrev_b64 v[82:83], 13, v[164:165]
	v_max_f32_e32 v76, 0, v76
	v_max_f32_e32 v77, 0, v77
	v_pk_mul_f32 v[84:85], v[72:73], v[72:73]
	v_max_f32_e32 v72, 0, v78
	v_max_f32_e32 v74, 0, v74
	v_max_f32_e32 v73, 0, v79
	v_max_f32_e32 v75, 0, v75
	v_lshl_add_u64 v[82:83], s[96:97], 0, v[82:83]
	v_pk_mul_f32 v[76:77], v[76:77], v[76:77]
	v_pk_mul_f32 v[78:79], v[72:73], v[72:73]
	v_pk_mul_f32 v[86:87], v[74:75], v[74:75]
	v_pk_mul_f32 v[64:65], v[64:65], v[80:81] op_sel_hi:[1,0]
	v_lshl_add_u64 v[82:83], v[82:83], 0, v[148:149]
	v_cvt_pk_bf16_f32 v72, v76, v77
	v_cvt_pk_bf16_f32 v73, v78, v79
	v_cvt_pk_bf16_f32 v74, v84, v85
	v_cvt_pk_bf16_f32 v75, v86, v87
	v_pk_mul_f32 v[70:71], v[70:71], v[80:81] op_sel_hi:[1,0]
	v_max_f32_e32 v64, 0, v64
	v_max_f32_e32 v65, 0, v65
	global_store_dwordx4 v[82:83], v[72:75], off
	v_pk_mul_f32 v[68:69], v[68:69], v[80:81] op_sel_hi:[1,0]
	v_pk_mul_f32 v[66:67], v[66:67], v[80:81] op_sel_hi:[1,0]
	v_pk_mul_f32 v[72:73], v[64:65], v[64:65]
	v_max_f32_e32 v64, 0, v70
	v_max_f32_e32 v65, 0, v71
	v_max_f32_e32 v68, 0, v68
	v_max_f32_e32 v69, 0, v69
	v_pk_mul_f32 v[68:69], v[68:69], v[68:69]
	v_pk_mul_f32 v[76:77], v[64:65], v[64:65]
	v_cvt_pk_bf16_f32 v64, v68, v69
	s_waitcnt lgkmcnt(0)
	v_max_f32_e32 v66, 0, v66
	v_max_f32_e32 v67, 0, v67
	v_pk_mul_f32 v[78:79], v[66:67], v[66:67]
	v_cvt_pk_bf16_f32 v65, v76, v77
	v_cvt_pk_bf16_f32 v66, v72, v73
	v_cvt_pk_bf16_f32 v67, v78, v79
	global_store_dwordx4 v[82:83], v[64:67], off offset:256
	s_waitcnt lgkmcnt(0)
	s_nop 0
	s_nop 0
	s_nop 0
	s_nop 1
	v_lshlrev_b64 v[66:67], 13, v[162:163]
	v_lshl_add_u64 v[66:67], s[96:97], 0, v[66:67]
	v_lshl_add_u64 v[66:67], v[66:67], 0, v[148:149]
	v_mov_b32_e32 v68, v232
	v_pk_mul_f32 v[56:57], v[56:57], v[68:69] op_sel_hi:[1,0]
	v_pk_mul_f32 v[62:63], v[62:63], v[68:69] op_sel_hi:[1,0]
	v_pk_mul_f32 v[60:61], v[60:61], v[68:69] op_sel_hi:[1,0]
	v_pk_mul_f32 v[58:59], v[58:59], v[68:69] op_sel_hi:[1,0]
	v_max_f32_e32 v56, 0, v56
	v_max_f32_e32 v57, 0, v57
	v_max_f32_e32 v60, 0, v60
	v_max_f32_e32 v61, 0, v61
	v_pk_mul_f32 v[70:71], v[56:57], v[56:57]
	v_max_f32_e32 v56, 0, v62
	v_max_f32_e32 v58, 0, v58
	v_max_f32_e32 v57, 0, v63
	v_max_f32_e32 v59, 0, v59
	v_pk_mul_f32 v[60:61], v[60:61], v[60:61]
	v_pk_mul_f32 v[62:63], v[56:57], v[56:57]
	v_pk_mul_f32 v[72:73], v[58:59], v[58:59]
	v_pk_mul_f32 v[50:51], v[50:51], v[68:69] op_sel_hi:[1,0]
	v_cvt_pk_bf16_f32 v56, v60, v61
	v_cvt_pk_bf16_f32 v57, v62, v63
	v_cvt_pk_bf16_f32 v58, v70, v71
	v_cvt_pk_bf16_f32 v59, v72, v73
	v_pk_mul_f32 v[52:53], v[52:53], v[68:69] op_sel_hi:[1,0]
	v_pk_mul_f32 v[48:49], v[48:49], v[68:69] op_sel_hi:[1,0]
	v_max_f32_e32 v50, 0, v50
	v_max_f32_e32 v51, 0, v51
	global_store_dwordx4 v[66:67], v[56:59], off
	v_pk_mul_f32 v[54:55], v[54:55], v[68:69] op_sel_hi:[1,0]
	v_max_f32_e32 v52, 0, v52
	v_max_f32_e32 v48, 0, v48
	v_max_f32_e32 v53, 0, v53
	v_max_f32_e32 v49, 0, v49
	v_pk_mul_f32 v[58:59], v[50:51], v[50:51]
	v_pk_mul_f32 v[52:53], v[52:53], v[52:53]
	v_pk_mul_f32 v[56:57], v[48:49], v[48:49]
	v_max_f32_e32 v48, 0, v54
	v_max_f32_e32 v49, 0, v55
	v_pk_mul_f32 v[54:55], v[48:49], v[48:49]
	v_cvt_pk_bf16_f32 v48, v52, v53
	v_cvt_pk_bf16_f32 v49, v54, v55
	v_cvt_pk_bf16_f32 v50, v56, v57
	v_cvt_pk_bf16_f32 v51, v58, v59
	global_store_dwordx4 v[66:67], v[48:51], off offset:256
	s_nop 1
	v_mov_b32_e32 v48, v233
	v_pk_mul_f32 v[40:41], v[40:41], v[48:49] op_sel_hi:[1,0]
	v_pk_mul_f32 v[46:47], v[46:47], v[48:49] op_sel_hi:[1,0]
	v_pk_mul_f32 v[44:45], v[44:45], v[48:49] op_sel_hi:[1,0]
	v_pk_mul_f32 v[42:43], v[42:43], v[48:49] op_sel_hi:[1,0]
	v_max_f32_e32 v40, 0, v40
	v_max_f32_e32 v41, 0, v41
	v_lshlrev_b64 v[50:51], 13, v[156:157]
	v_max_f32_e32 v44, 0, v44
	v_max_f32_e32 v45, 0, v45
	v_pk_mul_f32 v[52:53], v[40:41], v[40:41]
	v_max_f32_e32 v40, 0, v46
	v_max_f32_e32 v42, 0, v42
	v_max_f32_e32 v41, 0, v47
	v_max_f32_e32 v43, 0, v43
	v_lshl_add_u64 v[50:51], s[96:97], 0, v[50:51]
	v_pk_mul_f32 v[44:45], v[44:45], v[44:45]
	v_pk_mul_f32 v[46:47], v[40:41], v[40:41]
	v_pk_mul_f32 v[54:55], v[42:43], v[42:43]
	v_pk_mul_f32 v[32:33], v[32:33], v[48:49] op_sel_hi:[1,0]
	v_lshl_add_u64 v[50:51], v[50:51], 0, v[148:149]
	v_cvt_pk_bf16_f32 v40, v44, v45
	v_cvt_pk_bf16_f32 v41, v46, v47
	v_cvt_pk_bf16_f32 v42, v52, v53
	v_cvt_pk_bf16_f32 v43, v54, v55
	v_pk_mul_f32 v[38:39], v[38:39], v[48:49] op_sel_hi:[1,0]
	v_max_f32_e32 v32, 0, v32
	v_max_f32_e32 v33, 0, v33
	global_store_dwordx4 v[50:51], v[40:43], off
	v_pk_mul_f32 v[36:37], v[36:37], v[48:49] op_sel_hi:[1,0]
	v_pk_mul_f32 v[34:35], v[34:35], v[48:49] op_sel_hi:[1,0]
	v_pk_mul_f32 v[40:41], v[32:33], v[32:33]
	v_max_f32_e32 v32, 0, v38
	v_max_f32_e32 v33, 0, v39
	v_max_f32_e32 v36, 0, v36
	v_max_f32_e32 v37, 0, v37
	v_pk_mul_f32 v[36:37], v[36:37], v[36:37]
	v_pk_mul_f32 v[44:45], v[32:33], v[32:33]
	v_cvt_pk_bf16_f32 v32, v36, v37
	s_waitcnt lgkmcnt(0)
; __device__ __forceinline__ unsigned pk2(float lo, float hi) { const f32x2 v = (f32x2){lo, hi}; const bf16x2_t b = __builtin_convertvector(v, bf16x2_t); return __builtin_bit_cast(unsigned, b); }
; #define PG8_WAIT_V(n) asm volatile("s_waitcnt vmcnt(" #n ")" ::: "memory")
; #define PG8_BAR __builtin_amdgcn_s_barrier()
;     __device__ __forceinline__ void operator()(const f32x4 (&acc)[2][2][4][2], const Unit& u, int wr, int wc, int fr, int fq, const float (&)[8]) const {
;     ...
;         for (int ai = 0; ai < 2; ++ai)
; #pragma unroll
;             for (int m = 0; m < 4; ++m) { const int row = row0 + ai * HALF + m * 16; const float rs = rsqrtf(ep[ai * 4 + m] * (1.0f / 1024.0f) + EPS);
;                 u16* rowp = O + (size_t)row * ldc + col0;
; #pragma unroll
;                 for (int bj = 0; bj < 2; ++bj) { f32x4 v0 = acc[ai][bj][m][0] * rs, v1 = acc[ai][bj][m][1] * rs;
;                     if (ACT == 1) {
; #pragma unroll
;                         for (int j = 0; j < 4; ++j) { const float a0 = fmaxf(v0[j], 0.f), a1 = fmaxf(v1[j], 0.f); v0[j] = a0 * a0; v1[j] = a1 * a1; } }
;                     u32x4 w; w.x = pk2(v0[0], v0[1]); w.y = pk2(v0[2], v0[3]); w.z = pk2(v1[0], v1[1]); w.w = pk2(v1[2], v1[3]);
;                     *(u32x4*)(rowp + bj * HALF) = w; } }
; template <class Epi>
; __device__ __forceinline__ void gemm_phase(LAS unsigned char* lds, const Gemm g, const StaticOrder& S, const Epi& E) {
;     ...
;         E(acc, cur, wr, wc, fr, fq, epre);
;         if (!has_next) break;
; #pragma unroll
;         for (int a = 0; a < 2; ++a)
; #pragma unroll
;             for (int b = 0; b < 2; ++b)
; #pragma unroll
;                 for (int m = 0; m < 4; ++m)
; #pragma unroll
;                     for (int n = 0; n < 2; ++n) acc[a][b][m][n] = (f32x4){0.f, 0.f, 0.f, 0.f};
;         cur = nxt; cA = nA; cB = nB; ++ui;
;     }
;     PG8_WAIT_V(0);
;     if (wr == 0) PG8_BAR;
;     PG8_BAR;
	v_max_f32_e32 v34, 0, v34
	v_max_f32_e32 v35, 0, v35
	v_pk_mul_f32 v[46:47], v[34:35], v[34:35]
	v_cvt_pk_bf16_f32 v33, v44, v45
	v_cvt_pk_bf16_f32 v34, v40, v41
	v_cvt_pk_bf16_f32 v35, v46, v47
	global_store_dwordx4 v[50:51], v[32:35], off offset:256
	s_waitcnt lgkmcnt(0)
	s_nop 0
	s_nop 0
	s_nop 0
	s_nop 1
	v_lshlrev_b64 v[34:35], 13, v[150:151]
	v_lshl_add_u64 v[34:35], s[96:97], 0, v[34:35]
	v_lshl_add_u64 v[34:35], v[34:35], 0, v[148:149]
	v_mov_b32_e32 v36, v234
	v_pk_mul_f32 v[24:25], v[24:25], v[36:37] op_sel_hi:[1,0]
	v_pk_mul_f32 v[30:31], v[30:31], v[36:37] op_sel_hi:[1,0]
	v_pk_mul_f32 v[28:29], v[28:29], v[36:37] op_sel_hi:[1,0]
	v_pk_mul_f32 v[26:27], v[26:27], v[36:37] op_sel_hi:[1,0]
	v_max_f32_e32 v24, 0, v24
	v_max_f32_e32 v25, 0, v25
	v_max_f32_e32 v28, 0, v28
	v_max_f32_e32 v29, 0, v29
	v_pk_mul_f32 v[38:39], v[24:25], v[24:25]
	v_max_f32_e32 v24, 0, v30
	v_max_f32_e32 v26, 0, v26
	v_max_f32_e32 v25, 0, v31
	v_max_f32_e32 v27, 0, v27
	v_pk_mul_f32 v[28:29], v[28:29], v[28:29]
	v_pk_mul_f32 v[30:31], v[24:25], v[24:25]
	v_pk_mul_f32 v[40:41], v[26:27], v[26:27]
	v_pk_mul_f32 v[18:19], v[18:19], v[36:37] op_sel_hi:[1,0]
	v_cvt_pk_bf16_f32 v24, v28, v29
	v_cvt_pk_bf16_f32 v25, v30, v31
	v_cvt_pk_bf16_f32 v26, v38, v39
	v_cvt_pk_bf16_f32 v27, v40, v41
	v_pk_mul_f32 v[20:21], v[20:21], v[36:37] op_sel_hi:[1,0]
	v_pk_mul_f32 v[16:17], v[16:17], v[36:37] op_sel_hi:[1,0]
	v_max_f32_e32 v18, 0, v18
	v_max_f32_e32 v19, 0, v19
	global_store_dwordx4 v[34:35], v[24:27], off
	v_pk_mul_f32 v[22:23], v[22:23], v[36:37] op_sel_hi:[1,0]
	v_max_f32_e32 v20, 0, v20
	v_max_f32_e32 v16, 0, v16
	v_max_f32_e32 v21, 0, v21
	v_max_f32_e32 v17, 0, v17
	v_pk_mul_f32 v[26:27], v[18:19], v[18:19]
	v_pk_mul_f32 v[20:21], v[20:21], v[20:21]
	v_pk_mul_f32 v[24:25], v[16:17], v[16:17]
	v_max_f32_e32 v16, 0, v22
	v_max_f32_e32 v17, 0, v23
	v_pk_mul_f32 v[22:23], v[16:17], v[16:17]
	v_cvt_pk_bf16_f32 v16, v20, v21
	v_cvt_pk_bf16_f32 v17, v22, v23
	v_cvt_pk_bf16_f32 v18, v24, v25
	v_cvt_pk_bf16_f32 v19, v26, v27
	global_store_dwordx4 v[34:35], v[16:19], off offset:256
	s_nop 1
	v_mov_b32_e32 v16, v235
	v_pk_mul_f32 v[8:9], v[8:9], v[16:17] op_sel_hi:[1,0]
	v_pk_mul_f32 v[14:15], v[14:15], v[16:17] op_sel_hi:[1,0]
	v_pk_mul_f32 v[12:13], v[12:13], v[16:17] op_sel_hi:[1,0]
	v_pk_mul_f32 v[10:11], v[10:11], v[16:17] op_sel_hi:[1,0]
	v_max_f32_e32 v8, 0, v8
	v_max_f32_e32 v9, 0, v9
	v_lshlrev_b64 v[18:19], 13, v[146:147]
	v_max_f32_e32 v12, 0, v12
	v_max_f32_e32 v13, 0, v13
	v_pk_mul_f32 v[20:21], v[8:9], v[8:9]
	v_max_f32_e32 v8, 0, v14
	v_max_f32_e32 v10, 0, v10
	v_max_f32_e32 v9, 0, v15
	v_max_f32_e32 v11, 0, v11
	v_lshl_add_u64 v[18:19], s[96:97], 0, v[18:19]
	v_pk_mul_f32 v[12:13], v[12:13], v[12:13]
	v_pk_mul_f32 v[14:15], v[8:9], v[8:9]
	v_pk_mul_f32 v[22:23], v[10:11], v[10:11]
	v_pk_mul_f32 v[0:1], v[0:1], v[16:17] op_sel_hi:[1,0]
	v_lshl_add_u64 v[18:19], v[18:19], 0, v[148:149]
	v_cvt_pk_bf16_f32 v8, v12, v13
	v_cvt_pk_bf16_f32 v9, v14, v15
	v_cvt_pk_bf16_f32 v10, v20, v21
	v_cvt_pk_bf16_f32 v11, v22, v23
	v_pk_mul_f32 v[6:7], v[6:7], v[16:17] op_sel_hi:[1,0]
	v_pk_mul_f32 v[4:5], v[4:5], v[16:17] op_sel_hi:[1,0]
	v_pk_mul_f32 v[2:3], v[2:3], v[16:17] op_sel_hi:[1,0]
	v_max_f32_e32 v0, 0, v0
	v_max_f32_e32 v1, 0, v1
	global_store_dwordx4 v[18:19], v[8:11], off
	v_max_f32_e32 v4, 0, v4
	v_max_f32_e32 v5, 0, v5
	v_pk_mul_f32 v[8:9], v[0:1], v[0:1]
	v_max_f32_e32 v0, 0, v6
	v_max_f32_e32 v2, 0, v2
	v_max_f32_e32 v1, 0, v7
	v_max_f32_e32 v3, 0, v3
	v_pk_mul_f32 v[4:5], v[4:5], v[4:5]
	v_pk_mul_f32 v[6:7], v[0:1], v[0:1]
	v_pk_mul_f32 v[10:11], v[2:3], v[2:3]
	v_cvt_pk_bf16_f32 v0, v4, v5
	v_cvt_pk_bf16_f32 v1, v6, v7
	v_cvt_pk_bf16_f32 v2, v8, v9
	v_cvt_pk_bf16_f32 v3, v10, v11
	s_and_b64 vcc, exec, s[0:1]
	global_store_dwordx4 v[18:19], v[0:3], off offset:256
	s_cbranch_vccz .LBB0_1197
	s_waitcnt vmcnt(0)
	s_cmpk_gt_u32 s7, 0xff
	s_cbranch_scc1 .LBB0_1208
	s_barrier

; #define PG8_STAGE(bufoff, gbase, voff) do { _Pragma("unroll") for (int _i = 0; _i < 2; ++_i) \
;         __builtin_amdgcn_global_load_lds((const unsigned*)((const char*)(gbase) + (voff)[_i]), (LAS unsigned*)(lds + (bufoff) + ldsw + _i * 8192), 16, 0, 0); } while (0)
; #define PG8_LDA(dst, b, h) do { _Pragma("unroll") for (int m = 0; m < 4; ++m) _Pragma("unroll") for (int k = 0; k < 2; ++k) dst[m][k] = *(const LAS bf16x8*)(lds + PG8_SA(b, h) + aoff + m * 2048 + k * 1024); } while (0)
; #define PG8_LDB(dst, b, h) do { _Pragma("unroll") for (int n = 0; n < 2; ++n) _Pragma("unroll") for (int k = 0; k < 2; ++k) dst[n][k] = *(const LAS bf16x8*)(lds + PG8_SB(b, h) + boff + n * 2048 + k * 1024); } while (0)
; #define PG8_WAIT_V(n) asm volatile("s_waitcnt vmcnt(" #n ")" ::: "memory")
; #define PG8_WAIT_L(n) asm volatile("s_waitcnt lgkmcnt(" #n ")" ::: "memory")
; #define PG8_BAR __builtin_amdgcn_s_barrier()
; #define PG8_SCHED __builtin_amdgcn_sched_barrier(0)
; template <class Epi>
; __device__ __forceinline__ void gemm_phase(LAS unsigned char* lds, const Gemm g, const StaticOrder& S, const Epi& E) {
;     ...
;     for (;;) {
;         const bool has_next = S.next(ui + 1, nxt);
;         const char* nA = has_next ? (const char*)g.A + (size_t)nxt.pm * tstepA : cA; const char* nB = has_next ? (const char*)g.Bt + (size_t)nxt.pn * tstepB : cB;
;         for (int t = 0; t < nt; t += 2) {
;             const bool last = (t == nt - 2);
;             const char* a1 = cA + (size_t)(t + 1) * kstep;
;             const char* a2 = last ? nA : cA + (size_t)(t + 2) * kstep; const char* b2 = last ? nB : cB + (size_t)(t + 2) * kstep;
;             const char* a3 = a2 + kstep; const char* b3 = b2 + kstep;
;             if (last) E.pre(cur, wr, fr, epre);
;             PG8_LDB(B0, 0, 0); PG8_SCHED; PG8_LDA(At, 0, 0); PG8_STAGE(PG8_SA(1, 1), a1 + hstepA, voffA);
;             PG8_WAIT_L(8); PG8_BAR; PG8_WAIT_L(0); PG8_MMA(0, 0, At, B0); PG8_BAR; PG8_SCHED;
;             PG8_LDB(B1, 0, 1); PG8_STAGE(PG8_SB(0, 0), b2, voffB);
;             PG8_BAR; PG8_WAIT_L(0); PG8_MMA(0, 1, At, B1); PG8_BAR;
;             PG8_LDA(At, 0, 1); PG8_STAGE(PG8_SA(0, 0), a2, voffA);
;             PG8_BAR; PG8_WAIT_L(0); PG8_MMA(1, 0, At, B0); PG8_BAR; PG8_SCHED;
;             PG8_STAGE(PG8_SB(0, 1), b2 + hstepB, voffB);
;             PG8_WAIT_V(6); PG8_BAR; PG8_MMA(1, 1, At, B1); PG8_BAR;
.LBB0_1277:
	s_ashr_i32 s17, s16, 31
	v_cmp_lt_i64_e32 vcc, s[18:19], v[166:167]
	s_lshl_b64 s[18:19], s[16:17], 21
	s_add_u32 s18, s96, s18
	s_addc_u32 s19, s97, s19
	s_and_b64 s[20:21], vcc, exec
	s_cselect_b32 s17, s19, s23
	s_cselect_b32 s44, s18, s22
	s_ashr_i32 s15, s14, 31
	s_lshl_b64 s[20:21], s[14:15], 21
	s_add_u32 s20, s29, s20
	s_addc_u32 s21, s30, s21
	s_and_b64 s[26:27], vcc, exec
	s_cselect_b32 s15, s21, s25
	s_cselect_b32 s45, s20, s24
	s_add_u32 s22, s22, 0x100080
	s_addc_u32 s23, s23, 0
	s_add_u32 s46, s24, 0x100
	s_addc_u32 s47, s25, 0
	s_mov_b32 s48, -2
	s_waitcnt lgkmcnt(0)
	ds_read_b128 v[128:131], v190
	ds_read_b128 v[132:135], v190 offset:1024
	ds_read_b128 v[136:139], v190 offset:2048
	ds_read_b128 v[140:143], v190 offset:3072
	s_add_u32 s24, s22, 0xfff00080
	s_addc_u32 s25, s23, -1
	s_cmp_eq_u32 s48, 60
	s_cselect_b32 s27, s17, s25
	s_cselect_b32 s26, s44, s24
	s_cselect_b32 s25, s15, s47
	s_cselect_b32 s24, s45, s46
	v_lshl_add_u64 v[186:187], s[22:23], 0, v[162:163]
	s_add_i32 m0, s7, 0xc000
	ds_read_b128 v[144:147], v191
	ds_read_b128 v[148:151], v191 offset:1024
	ds_read_b128 v[170:173], v191 offset:2048
	ds_read_b128 v[174:177], v191 offset:3072
	ds_read_b128 v[178:181], v191 offset:4096
	ds_read_b128 v[182:185], v191 offset:5120
	ds_read_b128 v[194:197], v191 offset:6144
	ds_read_b128 v[198:201], v191 offset:7168
	global_load_lds_dwordx4 v[186:187], off
	v_lshl_add_u64 v[186:187], s[22:23], 0, v[164:165]
	s_add_i32 m0, s7, 0xe000
	s_nop 0
	global_load_lds_dwordx4 v[186:187], off
	s_waitcnt lgkmcnt(8)
	s_barrier
	s_waitcnt lgkmcnt(0)
	v_mfma_f32_16x16x32_bf16 v[124:127], v[128:131], v[144:147], 0
	v_mfma_f32_16x16x32_bf16 v[120:123], v[136:139], v[144:147], 0
	v_mfma_f32_16x16x32_bf16 v[108:111], v[128:131], v[170:173], 0
	v_mfma_f32_16x16x32_bf16 v[104:107], v[136:139], v[170:173], 0
	v_mfma_f32_16x16x32_bf16 v[92:95], v[128:131], v[178:181], 0
	v_mfma_f32_16x16x32_bf16 v[88:91], v[136:139], v[178:181], 0
	v_mfma_f32_16x16x32_bf16 v[76:79], v[128:131], v[194:197], 0
	v_mfma_f32_16x16x32_bf16 v[72:75], v[136:139], v[194:197], 0
	v_mfma_f32_16x16x32_bf16 v[124:127], v[132:135], v[148:151], v[124:127]
	v_mfma_f32_16x16x32_bf16 v[120:123], v[140:143], v[148:151], v[120:123]
	v_mfma_f32_16x16x32_bf16 v[108:111], v[132:135], v[174:177], v[108:111]
	v_mfma_f32_16x16x32_bf16 v[104:107], v[140:143], v[174:177], v[104:107]
	v_mfma_f32_16x16x32_bf16 v[92:95], v[132:135], v[182:185], v[92:95]
	v_mfma_f32_16x16x32_bf16 v[88:91], v[140:143], v[182:185], v[88:91]
	v_mfma_f32_16x16x32_bf16 v[76:79], v[132:135], v[198:201], v[76:79]
	v_mfma_f32_16x16x32_bf16 v[72:75], v[140:143], v[198:201], v[72:75]
	s_barrier
	s_add_i32 s49, s42, s31
	v_lshl_add_u64 v[186:187], s[24:25], 0, v[156:157]
	s_mov_b32 m0, s49
	ds_read_b128 v[202:205], v192
	ds_read_b128 v[206:209], v192 offset:1024
	ds_read_b128 v[210:213], v192 offset:2048
	ds_read_b128 v[214:217], v192 offset:3072
	global_load_lds_dwordx4 v[186:187], off
	v_lshl_add_u64 v[218:219], s[24:25], 0, v[160:161]
	s_add_i32 m0, s49, 0x2000
	s_nop 0
	global_load_lds_dwordx4 v[218:219], off
	s_barrier
	s_waitcnt lgkmcnt(0)
	v_mfma_f32_16x16x32_bf16 v[116:119], v[202:205], v[144:147], 0
	v_mfma_f32_16x16x32_bf16 v[112:115], v[210:213], v[144:147], 0
	v_mfma_f32_16x16x32_bf16 v[100:103], v[202:205], v[170:173], 0
	v_mfma_f32_16x16x32_bf16 v[96:99], v[210:213], v[170:173], 0
	v_mfma_f32_16x16x32_bf16 v[84:87], v[202:205], v[178:181], 0
	v_mfma_f32_16x16x32_bf16 v[80:83], v[210:213], v[178:181], 0
	v_mfma_f32_16x16x32_bf16 v[68:71], v[202:205], v[194:197], 0
	v_mfma_f32_16x16x32_bf16 v[64:67], v[210:213], v[194:197], 0
	v_mfma_f32_16x16x32_bf16 v[116:119], v[206:209], v[148:151], v[116:119]
	v_mfma_f32_16x16x32_bf16 v[112:115], v[214:217], v[148:151], v[112:115]
	v_mfma_f32_16x16x32_bf16 v[100:103], v[206:209], v[174:177], v[100:103]
	v_mfma_f32_16x16x32_bf16 v[96:99], v[214:217], v[174:177], v[96:99]
	v_mfma_f32_16x16x32_bf16 v[84:87], v[206:209], v[182:185], v[84:87]
	v_mfma_f32_16x16x32_bf16 v[80:83], v[214:217], v[182:185], v[80:83]
	v_mfma_f32_16x16x32_bf16 v[68:71], v[206:209], v[198:201], v[68:71]
	v_mfma_f32_16x16x32_bf16 v[64:67], v[214:217], v[198:201], v[64:67]
	s_mov_b32 m0, s7
	v_lshl_add_u64 v[220:221], s[26:27], 0, v[154:155]
	s_barrier
	ds_read_b128 v[144:147], v191 offset:16384
	ds_read_b128 v[148:151], v191 offset:17408
	ds_read_b128 v[170:173], v191 offset:18432
	ds_read_b128 v[174:177], v191 offset:19456
	ds_read_b128 v[178:181], v191 offset:20480
	ds_read_b128 v[182:185], v191 offset:21504
	ds_read_b128 v[194:197], v191 offset:22528
	ds_read_b128 v[198:201], v191 offset:23552
	global_load_lds_dwordx4 v[220:221], off
	v_lshl_add_u64 v[222:223], s[26:27], 0, v[158:159]
	s_mov_b32 m0, s34
	s_nop 0
	global_load_lds_dwordx4 v[222:223], off
	s_barrier
	s_waitcnt lgkmcnt(0)
	v_mfma_f32_16x16x32_bf16 v[60:63], v[128:131], v[144:147], 0
	v_mfma_f32_16x16x32_bf16 v[56:59], v[136:139], v[144:147], 0
	v_mfma_f32_16x16x32_bf16 v[44:47], v[128:131], v[170:173], 0
	v_mfma_f32_16x16x32_bf16 v[40:43], v[136:139], v[170:173], 0
	v_mfma_f32_16x16x32_bf16 v[28:31], v[128:131], v[178:181], 0
	v_mfma_f32_16x16x32_bf16 v[24:27], v[136:139], v[178:181], 0
	v_mfma_f32_16x16x32_bf16 v[12:15], v[128:131], v[194:197], 0
	v_mfma_f32_16x16x32_bf16 v[8:11], v[136:139], v[194:197], 0
	v_mfma_f32_16x16x32_bf16 v[60:63], v[132:135], v[148:151], v[60:63]
	v_mfma_f32_16x16x32_bf16 v[56:59], v[140:143], v[148:151], v[56:59]
	v_mfma_f32_16x16x32_bf16 v[44:47], v[132:135], v[174:177], v[44:47]
	v_mfma_f32_16x16x32_bf16 v[40:43], v[140:143], v[174:177], v[40:43]
	v_mfma_f32_16x16x32_bf16 v[28:31], v[132:135], v[182:185], v[28:31]
	v_mfma_f32_16x16x32_bf16 v[24:27], v[140:143], v[182:185], v[24:27]
	v_mfma_f32_16x16x32_bf16 v[12:15], v[132:135], v[198:201], v[12:15]
	v_mfma_f32_16x16x32_bf16 v[8:11], v[140:143], v[198:201], v[8:11]
	s_barrier
; #define PG8_STAGE(bufoff, gbase, voff) do { _Pragma("unroll") for (int _i = 0; _i < 2; ++_i) \
;         __builtin_amdgcn_global_load_lds((const unsigned*)((const char*)(gbase) + (voff)[_i]), (LAS unsigned*)(lds + (bufoff) + ldsw + _i * 8192), 16, 0, 0); } while (0)
; #define PG8_LDA(dst, b, h) do { _Pragma("unroll") for (int m = 0; m < 4; ++m) _Pragma("unroll") for (int k = 0; k < 2; ++k) dst[m][k] = *(const LAS bf16x8*)(lds + PG8_SA(b, h) + aoff + m * 2048 + k * 1024); } while (0)
; #define PG8_LDB(dst, b, h) do { _Pragma("unroll") for (int n = 0; n < 2; ++n) _Pragma("unroll") for (int k = 0; k < 2; ++k) dst[n][k] = *(const LAS bf16x8*)(lds + PG8_SB(b, h) + boff + n * 2048 + k * 1024); } while (0)
; #define PG8_WAIT_V(n) asm volatile("s_waitcnt vmcnt(" #n ")" ::: "memory")
; #define PG8_WAIT_L(n) asm volatile("s_waitcnt lgkmcnt(" #n ")" ::: "memory")
; #define PG8_BAR __builtin_amdgcn_s_barrier()
; #define PG8_SCHED __builtin_amdgcn_sched_barrier(0)
; template <class Epi>
; __device__ __forceinline__ void gemm_phase(LAS unsigned char* lds, const Gemm g, const StaticOrder& S, const Epi& E) {
;     ...
;             PG8_LDB(B0, 0, 0); PG8_SCHED; PG8_LDA(At, 0, 0); PG8_STAGE(PG8_SA(1, 1), a1 + hstepA, voffA);
;             PG8_WAIT_L(8); PG8_BAR; PG8_WAIT_L(0); PG8_MMA(0, 0, At, B0); PG8_BAR; PG8_SCHED;
;             PG8_LDB(B1, 0, 1); PG8_STAGE(PG8_SB(0, 0), b2, voffB);
;             PG8_BAR; PG8_WAIT_L(0); PG8_MMA(0, 1, At, B1); PG8_BAR;
;             PG8_LDA(At, 0, 1); PG8_STAGE(PG8_SA(0, 0), a2, voffA);
;             PG8_BAR; PG8_WAIT_L(0); PG8_MMA(1, 0, At, B0); PG8_BAR; PG8_SCHED;
;             PG8_STAGE(PG8_SB(0, 1), b2 + hstepB, voffB);
;             PG8_WAIT_V(6); PG8_BAR; PG8_MMA(1, 1, At, B1); PG8_BAR;
;             PG8_LDB(B0, 1, 0); PG8_SCHED; PG8_LDA(At, 1, 0); PG8_STAGE(PG8_SA(0, 1), a2 + hstepA, voffA);
;             PG8_WAIT_L(8); PG8_BAR; PG8_WAIT_L(0); PG8_MMA(0, 0, At, B0); PG8_BAR; PG8_SCHED;
;             PG8_LDB(B1, 1, 1); PG8_STAGE(PG8_SB(1, 0), b3, voffB);
;             PG8_BAR; PG8_WAIT_L(0); PG8_MMA(0, 1, At, B1); PG8_BAR;
;             PG8_LDA(At, 1, 1); PG8_STAGE(PG8_SA(1, 0), a3, voffA);
;             PG8_BAR; PG8_WAIT_L(0); PG8_MMA(1, 0, At, B0); PG8_BAR; PG8_SCHED;
;             PG8_STAGE(PG8_SB(1, 1), b3 + hstepB, voffB);
;             PG8_WAIT_V(6); PG8_BAR; PG8_MMA(1, 1, At, B1); PG8_BAR;
	s_add_u32 s50, s24, 0x100000
	s_addc_u32 s51, s25, 0
	s_add_i32 s49, s43, s31
	v_lshl_add_u64 v[128:129], s[50:51], 0, v[156:157]
	s_mov_b32 m0, s49
	s_nop 0
	global_load_lds_dwordx4 v[128:129], off
	v_lshl_add_u64 v[128:129], s[50:51], 0, v[160:161]
	s_add_i32 m0, s49, 0x2000
	s_nop 0
	global_load_lds_dwordx4 v[128:129], off
	s_waitcnt vmcnt(6)
	s_barrier
	v_mfma_f32_16x16x32_bf16 v[52:55], v[202:205], v[144:147], 0
	v_mfma_f32_16x16x32_bf16 v[48:51], v[210:213], v[144:147], 0
	v_mfma_f32_16x16x32_bf16 v[36:39], v[202:205], v[170:173], 0
	v_mfma_f32_16x16x32_bf16 v[32:35], v[210:213], v[170:173], 0
	v_mfma_f32_16x16x32_bf16 v[20:23], v[202:205], v[178:181], 0
	v_mfma_f32_16x16x32_bf16 v[16:19], v[210:213], v[178:181], 0
	v_mfma_f32_16x16x32_bf16 v[4:7], v[202:205], v[194:197], 0
	v_mfma_f32_16x16x32_bf16 v[0:3], v[210:213], v[194:197], 0
	v_mfma_f32_16x16x32_bf16 v[52:55], v[206:209], v[148:151], v[52:55]
	v_mfma_f32_16x16x32_bf16 v[48:51], v[214:217], v[148:151], v[48:51]
	v_mfma_f32_16x16x32_bf16 v[36:39], v[206:209], v[174:177], v[36:39]
	v_mfma_f32_16x16x32_bf16 v[32:35], v[214:217], v[174:177], v[32:35]
	v_mfma_f32_16x16x32_bf16 v[20:23], v[206:209], v[182:185], v[20:23]
	v_mfma_f32_16x16x32_bf16 v[16:19], v[214:217], v[182:185], v[16:19]
	v_mfma_f32_16x16x32_bf16 v[4:7], v[206:209], v[198:201], v[4:7]
	v_mfma_f32_16x16x32_bf16 v[0:3], v[214:217], v[198:201], v[0:3]
	s_add_i32 s49, 0, 0x18000
	v_add_u32_e32 v140, s49, v188
	s_barrier
	ds_read_b128 v[128:131], v140
	ds_read_b128 v[132:135], v140 offset:1024
	ds_read_b128 v[136:139], v140 offset:2048
	ds_read_b128 v[140:143], v140 offset:3072
	s_add_u32 s26, s26, 0x100000
	s_addc_u32 s27, s27, 0
	s_mov_b32 m0, s35
	v_lshl_add_u64 v[202:203], s[26:27], 0, v[154:155]
	ds_read_b128 v[144:147], v191 offset:32768
	ds_read_b128 v[148:151], v191 offset:33792
	ds_read_b128 v[170:173], v191 offset:34816
	ds_read_b128 v[174:177], v191 offset:35840
	ds_read_b128 v[178:181], v191 offset:36864
	ds_read_b128 v[182:185], v191 offset:37888
	ds_read_b128 v[194:197], v191 offset:38912
	ds_read_b128 v[198:201], v191 offset:39936
	global_load_lds_dwordx4 v[202:203], off
	v_lshl_add_u64 v[202:203], s[26:27], 0, v[158:159]
	s_mov_b32 m0, s36
	s_nop 0
	global_load_lds_dwordx4 v[202:203], off
	s_waitcnt lgkmcnt(8)
	s_barrier
	s_waitcnt lgkmcnt(0)
	v_mfma_f32_16x16x32_bf16 v[124:127], v[128:131], v[144:147], v[124:127]
	v_mfma_f32_16x16x32_bf16 v[120:123], v[136:139], v[144:147], v[120:123]
	v_mfma_f32_16x16x32_bf16 v[108:111], v[128:131], v[170:173], v[108:111]
	v_mfma_f32_16x16x32_bf16 v[104:107], v[136:139], v[170:173], v[104:107]
	v_mfma_f32_16x16x32_bf16 v[92:95], v[128:131], v[178:181], v[92:95]
	v_mfma_f32_16x16x32_bf16 v[88:91], v[136:139], v[178:181], v[88:91]
	v_mfma_f32_16x16x32_bf16 v[76:79], v[128:131], v[194:197], v[76:79]
	v_mfma_f32_16x16x32_bf16 v[72:75], v[136:139], v[194:197], v[72:75]
	v_mfma_f32_16x16x32_bf16 v[124:127], v[132:135], v[148:151], v[124:127]
	v_mfma_f32_16x16x32_bf16 v[120:123], v[140:143], v[148:151], v[120:123]
	v_mfma_f32_16x16x32_bf16 v[108:111], v[132:135], v[174:177], v[108:111]
	v_mfma_f32_16x16x32_bf16 v[104:107], v[140:143], v[174:177], v[104:107]
	v_mfma_f32_16x16x32_bf16 v[92:95], v[132:135], v[182:185], v[92:95]
	v_mfma_f32_16x16x32_bf16 v[88:91], v[140:143], v[182:185], v[88:91]
	v_mfma_f32_16x16x32_bf16 v[76:79], v[132:135], v[198:201], v[76:79]
	v_mfma_f32_16x16x32_bf16 v[72:75], v[140:143], v[198:201], v[72:75]
	s_barrier
	s_add_i32 s26, 0, 0x1c000
	s_add_i32 s27, s49, s31
	v_add_u32_e32 v214, s26, v188
	v_lshl_add_u64 v[186:187], v[186:187], 0, s[12:13]
	s_mov_b32 m0, s27
	ds_read_b128 v[202:205], v214
	ds_read_b128 v[206:209], v214 offset:1024
	ds_read_b128 v[210:213], v214 offset:2048
	ds_read_b128 v[214:217], v214 offset:3072
	global_load_lds_dwordx4 v[186:187], off
	v_lshl_add_u64 v[186:187], v[218:219], 0, s[12:13]
	s_add_i32 m0, s27, 0x2000
	s_nop 0
	global_load_lds_dwordx4 v[186:187], off
	s_barrier
	s_waitcnt lgkmcnt(0)
	v_mfma_f32_16x16x32_bf16 v[116:119], v[202:205], v[144:147], v[116:119]
	v_mfma_f32_16x16x32_bf16 v[112:115], v[210:213], v[144:147], v[112:115]
	v_mfma_f32_16x16x32_bf16 v[100:103], v[202:205], v[170:173], v[100:103]
	v_mfma_f32_16x16x32_bf16 v[96:99], v[210:213], v[170:173], v[96:99]
	v_mfma_f32_16x16x32_bf16 v[84:87], v[202:205], v[178:181], v[84:87]
	v_mfma_f32_16x16x32_bf16 v[80:83], v[210:213], v[178:181], v[80:83]
	v_mfma_f32_16x16x32_bf16 v[68:71], v[202:205], v[194:197], v[68:71]
	v_mfma_f32_16x16x32_bf16 v[64:67], v[210:213], v[194:197], v[64:67]
	v_mfma_f32_16x16x32_bf16 v[116:119], v[206:209], v[148:151], v[116:119]
	v_mfma_f32_16x16x32_bf16 v[112:115], v[214:217], v[148:151], v[112:115]
	v_mfma_f32_16x16x32_bf16 v[100:103], v[206:209], v[174:177], v[100:103]
	v_mfma_f32_16x16x32_bf16 v[96:99], v[214:217], v[174:177], v[96:99]
	v_mfma_f32_16x16x32_bf16 v[84:87], v[206:209], v[182:185], v[84:87]
	v_mfma_f32_16x16x32_bf16 v[80:83], v[214:217], v[182:185], v[80:83]
	v_mfma_f32_16x16x32_bf16 v[68:71], v[206:209], v[198:201], v[68:71]
	v_mfma_f32_16x16x32_bf16 v[64:67], v[214:217], v[198:201], v[64:67]
	s_mov_b32 m0, s38
	v_lshl_add_u64 v[186:187], v[220:221], 0, s[12:13]
	s_barrier
	ds_read_b128 v[144:147], v191 offset:49152
	ds_read_b128 v[148:151], v191 offset:50176
	ds_read_b128 v[170:173], v191 offset:51200
	ds_read_b128 v[174:177], v191 offset:52224
	ds_read_b128 v[178:181], v191 offset:53248
	ds_read_b128 v[182:185], v191 offset:54272
	ds_read_b128 v[194:197], v191 offset:55296
	ds_read_b128 v[198:201], v191 offset:56320
	global_load_lds_dwordx4 v[186:187], off
	v_lshl_add_u64 v[186:187], v[222:223], 0, s[12:13]
	s_mov_b32 m0, s39
	s_nop 0
	global_load_lds_dwordx4 v[186:187], off
	s_barrier
; #define PG8_STAGE(bufoff, gbase, voff) do { _Pragma("unroll") for (int _i = 0; _i < 2; ++_i) \
;         __builtin_amdgcn_global_load_lds((const unsigned*)((const char*)(gbase) + (voff)[_i]), (LAS unsigned*)(lds + (bufoff) + ldsw + _i * 8192), 16, 0, 0); } while (0)
; #define PG8_LDA(dst, b, h) do { _Pragma("unroll") for (int m = 0; m < 4; ++m) _Pragma("unroll") for (int k = 0; k < 2; ++k) dst[m][k] = *(const LAS bf16x8*)(lds + PG8_SA(b, h) + aoff + m * 2048 + k * 1024); } while (0)
; #define PG8_WAIT_V(n) asm volatile("s_waitcnt vmcnt(" #n ")" ::: "memory")
; template <class Epi>
; __device__ __forceinline__ void gemm_phase(LAS unsigned char* lds, const Gemm g, const StaticOrder& S, const Epi& E) {
;     ...
;         for (int t = 0; t < nt; t += 2) {
;             const bool last = (t == nt - 2);
;             const char* a1 = cA + (size_t)(t + 1) * kstep;
;             const char* a2 = last ? nA : cA + (size_t)(t + 2) * kstep; const char* b2 = last ? nB : cB + (size_t)(t + 2) * kstep;
;             const char* a3 = a2 + kstep; const char* b3 = b2 + kstep;
;             if (last) E.pre(cur, wr, fr, epre);
;             PG8_LDB(B0, 0, 0); PG8_SCHED; PG8_LDA(At, 0, 0); PG8_STAGE(PG8_SA(1, 1), a1 + hstepA, voffA);
;             PG8_WAIT_L(8); PG8_BAR; PG8_WAIT_L(0); PG8_MMA(0, 0, At, B0); PG8_BAR; PG8_SCHED;
;             PG8_LDB(B1, 0, 1); PG8_STAGE(PG8_SB(0, 0), b2, voffB);
;             PG8_BAR; PG8_WAIT_L(0); PG8_MMA(0, 1, At, B1); PG8_BAR;
;             PG8_LDA(At, 0, 1); PG8_STAGE(PG8_SA(0, 0), a2, voffA);
;             PG8_BAR; PG8_WAIT_L(0); PG8_MMA(1, 0, At, B0); PG8_BAR; PG8_SCHED;
;             PG8_STAGE(PG8_SB(0, 1), b2 + hstepB, voffB);
;             PG8_WAIT_V(6); PG8_BAR; PG8_MMA(1, 1, At, B1); PG8_BAR;
;             PG8_LDB(B0, 1, 0); PG8_SCHED; PG8_LDA(At, 1, 0); PG8_STAGE(PG8_SA(0, 1), a2 + hstepA, voffA);
;             PG8_WAIT_L(8); PG8_BAR; PG8_WAIT_L(0); PG8_MMA(0, 0, At, B0); PG8_BAR; PG8_SCHED;
;             PG8_LDB(B1, 1, 1); PG8_STAGE(PG8_SB(1, 0), b3, voffB);
;             PG8_BAR; PG8_WAIT_L(0); PG8_MMA(0, 1, At, B1); PG8_BAR;
;             PG8_LDA(At, 1, 1); PG8_STAGE(PG8_SA(1, 0), a3, voffA);
;             PG8_BAR; PG8_WAIT_L(0); PG8_MMA(1, 0, At, B0); PG8_BAR; PG8_SCHED;
;             PG8_STAGE(PG8_SB(1, 1), b3 + hstepB, voffB);
;             PG8_WAIT_V(6); PG8_BAR; PG8_MMA(1, 1, At, B1); PG8_BAR;
	s_waitcnt lgkmcnt(0)
	v_mfma_f32_16x16x32_bf16 v[60:63], v[128:131], v[144:147], v[60:63]
	v_mfma_f32_16x16x32_bf16 v[56:59], v[136:139], v[144:147], v[56:59]
	v_mfma_f32_16x16x32_bf16 v[44:47], v[128:131], v[170:173], v[44:47]
	v_mfma_f32_16x16x32_bf16 v[40:43], v[136:139], v[170:173], v[40:43]
	v_mfma_f32_16x16x32_bf16 v[28:31], v[128:131], v[178:181], v[28:31]
	v_mfma_f32_16x16x32_bf16 v[24:27], v[136:139], v[178:181], v[24:27]
	v_mfma_f32_16x16x32_bf16 v[12:15], v[128:131], v[194:197], v[12:15]
	v_mfma_f32_16x16x32_bf16 v[8:11], v[136:139], v[194:197], v[8:11]
	v_mfma_f32_16x16x32_bf16 v[60:63], v[132:135], v[148:151], v[60:63]
	v_mfma_f32_16x16x32_bf16 v[56:59], v[140:143], v[148:151], v[56:59]
	v_mfma_f32_16x16x32_bf16 v[44:47], v[132:135], v[174:177], v[44:47]
	v_mfma_f32_16x16x32_bf16 v[40:43], v[140:143], v[174:177], v[40:43]
	v_mfma_f32_16x16x32_bf16 v[28:31], v[132:135], v[182:185], v[28:31]
	v_mfma_f32_16x16x32_bf16 v[24:27], v[140:143], v[182:185], v[24:27]
	v_mfma_f32_16x16x32_bf16 v[12:15], v[132:135], v[198:201], v[12:15]
	v_mfma_f32_16x16x32_bf16 v[8:11], v[140:143], v[198:201], v[8:11]
	s_barrier
	s_add_u32 s24, s24, 0x100080
	s_addc_u32 s25, s25, 0
	s_add_i32 s26, s26, s31
	v_lshl_add_u64 v[128:129], s[24:25], 0, v[156:157]
	s_mov_b32 m0, s26
	s_nop 0
	global_load_lds_dwordx4 v[128:129], off
	v_lshl_add_u64 v[128:129], s[24:25], 0, v[160:161]
	s_add_i32 m0, s26, 0x2000
	s_nop 0
	global_load_lds_dwordx4 v[128:129], off
	s_waitcnt vmcnt(6)
	s_barrier
	v_mfma_f32_16x16x32_bf16 v[52:55], v[202:205], v[144:147], v[52:55]
	v_mfma_f32_16x16x32_bf16 v[48:51], v[210:213], v[144:147], v[48:51]
	v_mfma_f32_16x16x32_bf16 v[36:39], v[202:205], v[170:173], v[36:39]
	v_mfma_f32_16x16x32_bf16 v[32:35], v[210:213], v[170:173], v[32:35]
	v_mfma_f32_16x16x32_bf16 v[20:23], v[202:205], v[178:181], v[20:23]
	v_mfma_f32_16x16x32_bf16 v[16:19], v[210:213], v[178:181], v[16:19]
	v_mfma_f32_16x16x32_bf16 v[4:7], v[202:205], v[194:197], v[4:7]
	v_mfma_f32_16x16x32_bf16 v[0:3], v[210:213], v[194:197], v[0:3]
	v_mfma_f32_16x16x32_bf16 v[52:55], v[206:209], v[148:151], v[52:55]
	v_mfma_f32_16x16x32_bf16 v[48:51], v[214:217], v[148:151], v[48:51]
	v_mfma_f32_16x16x32_bf16 v[36:39], v[206:209], v[174:177], v[36:39]
	v_mfma_f32_16x16x32_bf16 v[32:35], v[214:217], v[174:177], v[32:35]
	v_mfma_f32_16x16x32_bf16 v[20:23], v[206:209], v[182:185], v[20:23]
	v_mfma_f32_16x16x32_bf16 v[16:19], v[214:217], v[182:185], v[16:19]
	v_mfma_f32_16x16x32_bf16 v[4:7], v[206:209], v[198:201], v[4:7]
	v_mfma_f32_16x16x32_bf16 v[0:3], v[214:217], v[198:201], v[0:3]
	s_add_i32 s48, s48, 2
	s_add_u32 s22, s22, 0x100
	s_addc_u32 s23, s23, 0
	s_add_u32 s46, s46, 0x100
	s_addc_u32 s47, s47, 0
	s_cmp_gt_u32 s48, 61
	s_barrier
.LBB0_1278:
	ds_read_b128 v[128:131], v190
	ds_read_b128 v[132:135], v190 offset:1024
	ds_read_b128 v[136:139], v190 offset:2048
	ds_read_b128 v[140:143], v190 offset:3072
	s_add_u32 s24, s22, 0xfff00080
	s_addc_u32 s25, s23, -1
	s_cmp_eq_u32 s48, 60
	s_cselect_b32 s27, s17, s25
	s_cselect_b32 s26, s44, s24
	s_cselect_b32 s25, s15, s47
	s_cselect_b32 s24, s45, s46
	v_lshl_add_u64 v[186:187], s[22:23], 0, v[162:163]
	s_add_i32 m0, s7, 0xc000
	ds_read_b128 v[144:147], v191
	ds_read_b128 v[148:151], v191 offset:1024
	ds_read_b128 v[170:173], v191 offset:2048
	ds_read_b128 v[174:177], v191 offset:3072
	ds_read_b128 v[178:181], v191 offset:4096
	ds_read_b128 v[182:185], v191 offset:5120
	ds_read_b128 v[194:197], v191 offset:6144
	ds_read_b128 v[198:201], v191 offset:7168
	global_load_lds_dwordx4 v[186:187], off
	v_lshl_add_u64 v[186:187], s[22:23], 0, v[164:165]
	s_add_i32 m0, s7, 0xe000
	s_nop 0
	global_load_lds_dwordx4 v[186:187], off
	s_waitcnt lgkmcnt(8)
	s_barrier
	s_waitcnt lgkmcnt(0)
	v_mfma_f32_16x16x32_bf16 v[124:127], v[128:131], v[144:147], v[124:127]
	v_mfma_f32_16x16x32_bf16 v[120:123], v[136:139], v[144:147], v[120:123]
	v_mfma_f32_16x16x32_bf16 v[108:111], v[128:131], v[170:173], v[108:111]
	v_mfma_f32_16x16x32_bf16 v[104:107], v[136:139], v[170:173], v[104:107]
	v_mfma_f32_16x16x32_bf16 v[92:95], v[128:131], v[178:181], v[92:95]
	v_mfma_f32_16x16x32_bf16 v[88:91], v[136:139], v[178:181], v[88:91]
	v_mfma_f32_16x16x32_bf16 v[76:79], v[128:131], v[194:197], v[76:79]
	v_mfma_f32_16x16x32_bf16 v[72:75], v[136:139], v[194:197], v[72:75]
	v_mfma_f32_16x16x32_bf16 v[124:127], v[132:135], v[148:151], v[124:127]
	v_mfma_f32_16x16x32_bf16 v[120:123], v[140:143], v[148:151], v[120:123]
	v_mfma_f32_16x16x32_bf16 v[108:111], v[132:135], v[174:177], v[108:111]
	v_mfma_f32_16x16x32_bf16 v[104:107], v[140:143], v[174:177], v[104:107]
	v_mfma_f32_16x16x32_bf16 v[92:95], v[132:135], v[182:185], v[92:95]
	v_mfma_f32_16x16x32_bf16 v[88:91], v[140:143], v[182:185], v[88:91]
	v_mfma_f32_16x16x32_bf16 v[76:79], v[132:135], v[198:201], v[76:79]
	v_mfma_f32_16x16x32_bf16 v[72:75], v[140:143], v[198:201], v[72:75]
	s_barrier
	s_add_i32 s49, s42, s31
	v_lshl_add_u64 v[186:187], s[24:25], 0, v[156:157]
	s_mov_b32 m0, s49
	ds_read_b128 v[202:205], v192
	ds_read_b128 v[206:209], v192 offset:1024
	ds_read_b128 v[210:213], v192 offset:2048
	ds_read_b128 v[214:217], v192 offset:3072
	global_load_lds_dwordx4 v[186:187], off
	v_lshl_add_u64 v[218:219], s[24:25], 0, v[160:161]
	s_add_i32 m0, s49, 0x2000
	s_nop 0
	global_load_lds_dwordx4 v[218:219], off
	s_barrier
; #define PG8_STAGE(bufoff, gbase, voff) do { _Pragma("unroll") for (int _i = 0; _i < 2; ++_i) \
;         __builtin_amdgcn_global_load_lds((const unsigned*)((const char*)(gbase) + (voff)[_i]), (LAS unsigned*)(lds + (bufoff) + ldsw + _i * 8192), 16, 0, 0); } while (0)
; #define PG8_LDA(dst, b, h) do { _Pragma("unroll") for (int m = 0; m < 4; ++m) _Pragma("unroll") for (int k = 0; k < 2; ++k) dst[m][k] = *(const LAS bf16x8*)(lds + PG8_SA(b, h) + aoff + m * 2048 + k * 1024); } while (0)
; #define PG8_LDB(dst, b, h) do { _Pragma("unroll") for (int n = 0; n < 2; ++n) _Pragma("unroll") for (int k = 0; k < 2; ++k) dst[n][k] = *(const LAS bf16x8*)(lds + PG8_SB(b, h) + boff + n * 2048 + k * 1024); } while (0)
; #define PG8_WAIT_V(n) asm volatile("s_waitcnt vmcnt(" #n ")" ::: "memory")
; #define PG8_WAIT_L(n) asm volatile("s_waitcnt lgkmcnt(" #n ")" ::: "memory")
; #define PG8_BAR __builtin_amdgcn_s_barrier()
; #define PG8_SCHED __builtin_amdgcn_sched_barrier(0)
; template <class Epi>
; __device__ __forceinline__ void gemm_phase(LAS unsigned char* lds, const Gemm g, const StaticOrder& S, const Epi& E) {
;     ...
;             PG8_LDB(B0, 0, 0); PG8_SCHED; PG8_LDA(At, 0, 0); PG8_STAGE(PG8_SA(1, 1), a1 + hstepA, voffA);
;             PG8_WAIT_L(8); PG8_BAR; PG8_WAIT_L(0); PG8_MMA(0, 0, At, B0); PG8_BAR; PG8_SCHED;
;             PG8_LDB(B1, 0, 1); PG8_STAGE(PG8_SB(0, 0), b2, voffB);
;             PG8_BAR; PG8_WAIT_L(0); PG8_MMA(0, 1, At, B1); PG8_BAR;
;             PG8_LDA(At, 0, 1); PG8_STAGE(PG8_SA(0, 0), a2, voffA);
;             PG8_BAR; PG8_WAIT_L(0); PG8_MMA(1, 0, At, B0); PG8_BAR; PG8_SCHED;
;             PG8_STAGE(PG8_SB(0, 1), b2 + hstepB, voffB);
;             PG8_WAIT_V(6); PG8_BAR; PG8_MMA(1, 1, At, B1); PG8_BAR;
;             PG8_LDB(B0, 1, 0); PG8_SCHED; PG8_LDA(At, 1, 0); PG8_STAGE(PG8_SA(0, 1), a2 + hstepA, voffA);
;             PG8_WAIT_L(8); PG8_BAR; PG8_WAIT_L(0); PG8_MMA(0, 0, At, B0); PG8_BAR; PG8_SCHED;
;             PG8_LDB(B1, 1, 1); PG8_STAGE(PG8_SB(1, 0), b3, voffB);
;             PG8_BAR; PG8_WAIT_L(0); PG8_MMA(0, 1, At, B1); PG8_BAR;
;             PG8_LDA(At, 1, 1); PG8_STAGE(PG8_SA(1, 0), a3, voffA);
;             PG8_BAR; PG8_WAIT_L(0); PG8_MMA(1, 0, At, B0); PG8_BAR; PG8_SCHED;
;             PG8_STAGE(PG8_SB(1, 1), b3 + hstepB, voffB);
;             PG8_WAIT_V(6); PG8_BAR; PG8_MMA(1, 1, At, B1); PG8_BAR;
	s_waitcnt lgkmcnt(0)
	v_mfma_f32_16x16x32_bf16 v[116:119], v[202:205], v[144:147], v[116:119]
	v_mfma_f32_16x16x32_bf16 v[112:115], v[210:213], v[144:147], v[112:115]
	v_mfma_f32_16x16x32_bf16 v[100:103], v[202:205], v[170:173], v[100:103]
	v_mfma_f32_16x16x32_bf16 v[96:99], v[210:213], v[170:173], v[96:99]
	v_mfma_f32_16x16x32_bf16 v[84:87], v[202:205], v[178:181], v[84:87]
	v_mfma_f32_16x16x32_bf16 v[80:83], v[210:213], v[178:181], v[80:83]
	v_mfma_f32_16x16x32_bf16 v[68:71], v[202:205], v[194:197], v[68:71]
	v_mfma_f32_16x16x32_bf16 v[64:67], v[210:213], v[194:197], v[64:67]
	v_mfma_f32_16x16x32_bf16 v[116:119], v[206:209], v[148:151], v[116:119]
	v_mfma_f32_16x16x32_bf16 v[112:115], v[214:217], v[148:151], v[112:115]
	v_mfma_f32_16x16x32_bf16 v[100:103], v[206:209], v[174:177], v[100:103]
	v_mfma_f32_16x16x32_bf16 v[96:99], v[214:217], v[174:177], v[96:99]
	v_mfma_f32_16x16x32_bf16 v[84:87], v[206:209], v[182:185], v[84:87]
	v_mfma_f32_16x16x32_bf16 v[80:83], v[214:217], v[182:185], v[80:83]
	v_mfma_f32_16x16x32_bf16 v[68:71], v[206:209], v[198:201], v[68:71]
	v_mfma_f32_16x16x32_bf16 v[64:67], v[214:217], v[198:201], v[64:67]
	s_mov_b32 m0, s7
	v_lshl_add_u64 v[220:221], s[26:27], 0, v[154:155]
	s_barrier
	ds_read_b128 v[144:147], v191 offset:16384
	ds_read_b128 v[148:151], v191 offset:17408
	ds_read_b128 v[170:173], v191 offset:18432
	ds_read_b128 v[174:177], v191 offset:19456
	ds_read_b128 v[178:181], v191 offset:20480
	ds_read_b128 v[182:185], v191 offset:21504
	ds_read_b128 v[194:197], v191 offset:22528
	ds_read_b128 v[198:201], v191 offset:23552
	global_load_lds_dwordx4 v[220:221], off
	v_lshl_add_u64 v[222:223], s[26:27], 0, v[158:159]
	s_mov_b32 m0, s34
	s_nop 0
	global_load_lds_dwordx4 v[222:223], off
	s_barrier
	s_waitcnt lgkmcnt(0)
	v_mfma_f32_16x16x32_bf16 v[60:63], v[128:131], v[144:147], v[60:63]
	v_mfma_f32_16x16x32_bf16 v[56:59], v[136:139], v[144:147], v[56:59]
	v_mfma_f32_16x16x32_bf16 v[44:47], v[128:131], v[170:173], v[44:47]
	v_mfma_f32_16x16x32_bf16 v[40:43], v[136:139], v[170:173], v[40:43]
	v_mfma_f32_16x16x32_bf16 v[28:31], v[128:131], v[178:181], v[28:31]
	v_mfma_f32_16x16x32_bf16 v[24:27], v[136:139], v[178:181], v[24:27]
	v_mfma_f32_16x16x32_bf16 v[12:15], v[128:131], v[194:197], v[12:15]
	v_mfma_f32_16x16x32_bf16 v[8:11], v[136:139], v[194:197], v[8:11]
	v_mfma_f32_16x16x32_bf16 v[60:63], v[132:135], v[148:151], v[60:63]
	v_mfma_f32_16x16x32_bf16 v[56:59], v[140:143], v[148:151], v[56:59]
	v_mfma_f32_16x16x32_bf16 v[44:47], v[132:135], v[174:177], v[44:47]
	v_mfma_f32_16x16x32_bf16 v[40:43], v[140:143], v[174:177], v[40:43]
	v_mfma_f32_16x16x32_bf16 v[28:31], v[132:135], v[182:185], v[28:31]
	v_mfma_f32_16x16x32_bf16 v[24:27], v[140:143], v[182:185], v[24:27]
	v_mfma_f32_16x16x32_bf16 v[12:15], v[132:135], v[198:201], v[12:15]
	v_mfma_f32_16x16x32_bf16 v[8:11], v[140:143], v[198:201], v[8:11]
	s_barrier
	s_add_u32 s50, s24, 0x100000
	s_addc_u32 s51, s25, 0
	s_add_i32 s49, s43, s31
	v_lshl_add_u64 v[128:129], s[50:51], 0, v[156:157]
	s_mov_b32 m0, s49
	s_nop 0
	global_load_lds_dwordx4 v[128:129], off
	v_lshl_add_u64 v[128:129], s[50:51], 0, v[160:161]
	s_add_i32 m0, s49, 0x2000
	s_nop 0
	global_load_lds_dwordx4 v[128:129], off
	s_waitcnt vmcnt(6)
	s_barrier
	v_mfma_f32_16x16x32_bf16 v[52:55], v[202:205], v[144:147], v[52:55]
	v_mfma_f32_16x16x32_bf16 v[48:51], v[210:213], v[144:147], v[48:51]
	v_mfma_f32_16x16x32_bf16 v[36:39], v[202:205], v[170:173], v[36:39]
	v_mfma_f32_16x16x32_bf16 v[32:35], v[210:213], v[170:173], v[32:35]
	v_mfma_f32_16x16x32_bf16 v[20:23], v[202:205], v[178:181], v[20:23]
	v_mfma_f32_16x16x32_bf16 v[16:19], v[210:213], v[178:181], v[16:19]
	v_mfma_f32_16x16x32_bf16 v[4:7], v[202:205], v[194:197], v[4:7]
	v_mfma_f32_16x16x32_bf16 v[0:3], v[210:213], v[194:197], v[0:3]
	v_mfma_f32_16x16x32_bf16 v[52:55], v[206:209], v[148:151], v[52:55]
	v_mfma_f32_16x16x32_bf16 v[48:51], v[214:217], v[148:151], v[48:51]
	v_mfma_f32_16x16x32_bf16 v[36:39], v[206:209], v[174:177], v[36:39]
	v_mfma_f32_16x16x32_bf16 v[32:35], v[214:217], v[174:177], v[32:35]
	v_mfma_f32_16x16x32_bf16 v[20:23], v[206:209], v[182:185], v[20:23]
	v_mfma_f32_16x16x32_bf16 v[16:19], v[214:217], v[182:185], v[16:19]
	v_mfma_f32_16x16x32_bf16 v[4:7], v[206:209], v[198:201], v[4:7]
	v_mfma_f32_16x16x32_bf16 v[0:3], v[214:217], v[198:201], v[0:3]
	s_add_i32 s49, 0, 0x18000
	v_add_u32_e32 v140, s49, v188
	s_barrier
	ds_read_b128 v[128:131], v140
	ds_read_b128 v[132:135], v140 offset:1024
	ds_read_b128 v[136:139], v140 offset:2048
	ds_read_b128 v[140:143], v140 offset:3072
	s_add_u32 s26, s26, 0x100000
	s_addc_u32 s27, s27, 0
	s_mov_b32 m0, s35
	v_lshl_add_u64 v[202:203], s[26:27], 0, v[154:155]
	ds_read_b128 v[144:147], v191 offset:32768
	ds_read_b128 v[148:151], v191 offset:33792
	ds_read_b128 v[170:173], v191 offset:34816
	ds_read_b128 v[174:177], v191 offset:35840
	ds_read_b128 v[178:181], v191 offset:36864
	ds_read_b128 v[182:185], v191 offset:37888
	ds_read_b128 v[194:197], v191 offset:38912
	ds_read_b128 v[198:201], v191 offset:39936
	global_load_lds_dwordx4 v[202:203], off
	v_lshl_add_u64 v[202:203], s[26:27], 0, v[158:159]
	s_mov_b32 m0, s36
	s_nop 0
	global_load_lds_dwordx4 v[202:203], off
	s_waitcnt lgkmcnt(8)
	s_barrier
; #define PG8_STAGE(bufoff, gbase, voff) do { _Pragma("unroll") for (int _i = 0; _i < 2; ++_i) \
;         __builtin_amdgcn_global_load_lds((const unsigned*)((const char*)(gbase) + (voff)[_i]), (LAS unsigned*)(lds + (bufoff) + ldsw + _i * 8192), 16, 0, 0); } while (0)
; #define PG8_LDA(dst, b, h) do { _Pragma("unroll") for (int m = 0; m < 4; ++m) _Pragma("unroll") for (int k = 0; k < 2; ++k) dst[m][k] = *(const LAS bf16x8*)(lds + PG8_SA(b, h) + aoff + m * 2048 + k * 1024); } while (0)
; #define PG8_LDB(dst, b, h) do { _Pragma("unroll") for (int n = 0; n < 2; ++n) _Pragma("unroll") for (int k = 0; k < 2; ++k) dst[n][k] = *(const LAS bf16x8*)(lds + PG8_SB(b, h) + boff + n * 2048 + k * 1024); } while (0)
; #define PG8_MMA(ai, bj, At, Bt) do { __builtin_amdgcn_s_setprio(1); _Pragma("unroll") for (int m = 0; m < 4; ++m) _Pragma("unroll") for (int n = 0; n < 2; ++n) _Pragma("unroll") for (int k = 0; k < 2; ++k) \
;         acc[ai][bj][m][n] = __builtin_amdgcn_mfma_f32_16x16x32_bf16(Bt[n][k], At[m][k], acc[ai][bj][m][n], 0, 0, 0); __builtin_amdgcn_s_setprio(0); } while (0)
; #define PG8_WAIT_V(n) asm volatile("s_waitcnt vmcnt(" #n ")" ::: "memory")
; #define PG8_WAIT_L(n) asm volatile("s_waitcnt lgkmcnt(" #n ")" ::: "memory")
; #define PG8_BAR __builtin_amdgcn_s_barrier()
; #define PG8_SCHED __builtin_amdgcn_sched_barrier(0)
; template <class Epi>
; __device__ __forceinline__ void gemm_phase(LAS unsigned char* lds, const Gemm g, const StaticOrder& S, const Epi& E) {
;     ...
;             PG8_WAIT_V(6); PG8_BAR; PG8_MMA(1, 1, At, B1); PG8_BAR;
;             PG8_LDB(B0, 1, 0); PG8_SCHED; PG8_LDA(At, 1, 0); PG8_STAGE(PG8_SA(0, 1), a2 + hstepA, voffA);
;             PG8_WAIT_L(8); PG8_BAR; PG8_WAIT_L(0); PG8_MMA(0, 0, At, B0); PG8_BAR; PG8_SCHED;
;             PG8_LDB(B1, 1, 1); PG8_STAGE(PG8_SB(1, 0), b3, voffB);
;             PG8_BAR; PG8_WAIT_L(0); PG8_MMA(0, 1, At, B1); PG8_BAR;
;             PG8_LDA(At, 1, 1); PG8_STAGE(PG8_SA(1, 0), a3, voffA);
;             PG8_BAR; PG8_WAIT_L(0); PG8_MMA(1, 0, At, B0); PG8_BAR; PG8_SCHED;
;             PG8_STAGE(PG8_SB(1, 1), b3 + hstepB, voffB);
;             PG8_WAIT_V(6); PG8_BAR; PG8_MMA(1, 1, At, B1); PG8_BAR;
	s_waitcnt lgkmcnt(0)
	v_mfma_f32_16x16x32_bf16 v[124:127], v[128:131], v[144:147], v[124:127]
	v_mfma_f32_16x16x32_bf16 v[120:123], v[136:139], v[144:147], v[120:123]
	v_mfma_f32_16x16x32_bf16 v[108:111], v[128:131], v[170:173], v[108:111]
	v_mfma_f32_16x16x32_bf16 v[104:107], v[136:139], v[170:173], v[104:107]
	v_mfma_f32_16x16x32_bf16 v[92:95], v[128:131], v[178:181], v[92:95]
	v_mfma_f32_16x16x32_bf16 v[88:91], v[136:139], v[178:181], v[88:91]
	v_mfma_f32_16x16x32_bf16 v[76:79], v[128:131], v[194:197], v[76:79]
	v_mfma_f32_16x16x32_bf16 v[72:75], v[136:139], v[194:197], v[72:75]
	v_mfma_f32_16x16x32_bf16 v[124:127], v[132:135], v[148:151], v[124:127]
	v_mfma_f32_16x16x32_bf16 v[120:123], v[140:143], v[148:151], v[120:123]
	v_mfma_f32_16x16x32_bf16 v[108:111], v[132:135], v[174:177], v[108:111]
	v_mfma_f32_16x16x32_bf16 v[104:107], v[140:143], v[174:177], v[104:107]
	v_mfma_f32_16x16x32_bf16 v[92:95], v[132:135], v[182:185], v[92:95]
	v_mfma_f32_16x16x32_bf16 v[88:91], v[140:143], v[182:185], v[88:91]
	v_mfma_f32_16x16x32_bf16 v[76:79], v[132:135], v[198:201], v[76:79]
	v_mfma_f32_16x16x32_bf16 v[72:75], v[140:143], v[198:201], v[72:75]
	s_barrier
	s_add_i32 s26, 0, 0x1c000
	s_add_i32 s27, s49, s31
	v_add_u32_e32 v214, s26, v188
	v_lshl_add_u64 v[186:187], v[186:187], 0, s[12:13]
	s_mov_b32 m0, s27
	ds_read_b128 v[202:205], v214
	ds_read_b128 v[206:209], v214 offset:1024
	ds_read_b128 v[210:213], v214 offset:2048
	ds_read_b128 v[214:217], v214 offset:3072
	global_load_lds_dwordx4 v[186:187], off
	v_lshl_add_u64 v[186:187], v[218:219], 0, s[12:13]
	s_add_i32 m0, s27, 0x2000
	s_nop 0
	global_load_lds_dwordx4 v[186:187], off
	s_barrier
	s_waitcnt lgkmcnt(0)
	v_mfma_f32_16x16x32_bf16 v[116:119], v[202:205], v[144:147], v[116:119]
	v_mfma_f32_16x16x32_bf16 v[112:115], v[210:213], v[144:147], v[112:115]
	v_mfma_f32_16x16x32_bf16 v[100:103], v[202:205], v[170:173], v[100:103]
	v_mfma_f32_16x16x32_bf16 v[96:99], v[210:213], v[170:173], v[96:99]
	v_mfma_f32_16x16x32_bf16 v[84:87], v[202:205], v[178:181], v[84:87]
	v_mfma_f32_16x16x32_bf16 v[80:83], v[210:213], v[178:181], v[80:83]
	v_mfma_f32_16x16x32_bf16 v[68:71], v[202:205], v[194:197], v[68:71]
	v_mfma_f32_16x16x32_bf16 v[64:67], v[210:213], v[194:197], v[64:67]
	v_mfma_f32_16x16x32_bf16 v[116:119], v[206:209], v[148:151], v[116:119]
	v_mfma_f32_16x16x32_bf16 v[112:115], v[214:217], v[148:151], v[112:115]
	v_mfma_f32_16x16x32_bf16 v[100:103], v[206:209], v[174:177], v[100:103]
	v_mfma_f32_16x16x32_bf16 v[96:99], v[214:217], v[174:177], v[96:99]
	v_mfma_f32_16x16x32_bf16 v[84:87], v[206:209], v[182:185], v[84:87]
	v_mfma_f32_16x16x32_bf16 v[80:83], v[214:217], v[182:185], v[80:83]
	v_mfma_f32_16x16x32_bf16 v[68:71], v[206:209], v[198:201], v[68:71]
	v_mfma_f32_16x16x32_bf16 v[64:67], v[214:217], v[198:201], v[64:67]
	s_mov_b32 m0, s38
	v_lshl_add_u64 v[186:187], v[220:221], 0, s[12:13]
	s_barrier
	ds_read_b128 v[144:147], v191 offset:49152
	ds_read_b128 v[148:151], v191 offset:50176
	ds_read_b128 v[170:173], v191 offset:51200
	ds_read_b128 v[174:177], v191 offset:52224
	ds_read_b128 v[178:181], v191 offset:53248
	ds_read_b128 v[182:185], v191 offset:54272
	ds_read_b128 v[194:197], v191 offset:55296
	ds_read_b128 v[198:201], v191 offset:56320
	global_load_lds_dwordx4 v[186:187], off
	v_lshl_add_u64 v[186:187], v[222:223], 0, s[12:13]
	s_mov_b32 m0, s39
	s_nop 0
	global_load_lds_dwordx4 v[186:187], off
	s_barrier
	s_waitcnt lgkmcnt(0)
	v_mfma_f32_16x16x32_bf16 v[60:63], v[128:131], v[144:147], v[60:63]
	v_mfma_f32_16x16x32_bf16 v[56:59], v[136:139], v[144:147], v[56:59]
	v_mfma_f32_16x16x32_bf16 v[44:47], v[128:131], v[170:173], v[44:47]
	v_mfma_f32_16x16x32_bf16 v[40:43], v[136:139], v[170:173], v[40:43]
	v_mfma_f32_16x16x32_bf16 v[28:31], v[128:131], v[178:181], v[28:31]
	v_mfma_f32_16x16x32_bf16 v[24:27], v[136:139], v[178:181], v[24:27]
	v_mfma_f32_16x16x32_bf16 v[12:15], v[128:131], v[194:197], v[12:15]
	v_mfma_f32_16x16x32_bf16 v[8:11], v[136:139], v[194:197], v[8:11]
	v_mfma_f32_16x16x32_bf16 v[60:63], v[132:135], v[148:151], v[60:63]
	v_mfma_f32_16x16x32_bf16 v[56:59], v[140:143], v[148:151], v[56:59]
	v_mfma_f32_16x16x32_bf16 v[44:47], v[132:135], v[174:177], v[44:47]
	v_mfma_f32_16x16x32_bf16 v[40:43], v[140:143], v[174:177], v[40:43]
	v_mfma_f32_16x16x32_bf16 v[28:31], v[132:135], v[182:185], v[28:31]
	v_mfma_f32_16x16x32_bf16 v[24:27], v[140:143], v[182:185], v[24:27]
	v_mfma_f32_16x16x32_bf16 v[12:15], v[132:135], v[198:201], v[12:15]
	v_mfma_f32_16x16x32_bf16 v[8:11], v[140:143], v[198:201], v[8:11]
	s_barrier
	s_add_u32 s24, s24, 0x100080
	s_addc_u32 s25, s25, 0
	s_add_i32 s26, s26, s31
	v_lshl_add_u64 v[128:129], s[24:25], 0, v[156:157]
	s_mov_b32 m0, s26
	s_nop 0
	global_load_lds_dwordx4 v[128:129], off
	v_lshl_add_u64 v[128:129], s[24:25], 0, v[160:161]
	s_add_i32 m0, s26, 0x2000
	s_nop 0
	global_load_lds_dwordx4 v[128:129], off
	s_waitcnt vmcnt(6)
	s_barrier
	v_mfma_f32_16x16x32_bf16 v[52:55], v[202:205], v[144:147], v[52:55]
	v_mfma_f32_16x16x32_bf16 v[48:51], v[210:213], v[144:147], v[48:51]
	v_mfma_f32_16x16x32_bf16 v[36:39], v[202:205], v[170:173], v[36:39]
	v_mfma_f32_16x16x32_bf16 v[32:35], v[210:213], v[170:173], v[32:35]
	v_mfma_f32_16x16x32_bf16 v[20:23], v[202:205], v[178:181], v[20:23]
	v_mfma_f32_16x16x32_bf16 v[16:19], v[210:213], v[178:181], v[16:19]
	v_mfma_f32_16x16x32_bf16 v[4:7], v[202:205], v[194:197], v[4:7]
	v_mfma_f32_16x16x32_bf16 v[0:3], v[210:213], v[194:197], v[0:3]
	v_mfma_f32_16x16x32_bf16 v[52:55], v[206:209], v[148:151], v[52:55]
	v_mfma_f32_16x16x32_bf16 v[48:51], v[214:217], v[148:151], v[48:51]
	v_mfma_f32_16x16x32_bf16 v[36:39], v[206:209], v[174:177], v[36:39]
	v_mfma_f32_16x16x32_bf16 v[32:35], v[214:217], v[174:177], v[32:35]
	v_mfma_f32_16x16x32_bf16 v[20:23], v[206:209], v[182:185], v[20:23]
	v_mfma_f32_16x16x32_bf16 v[16:19], v[214:217], v[182:185], v[16:19]
	v_mfma_f32_16x16x32_bf16 v[4:7], v[206:209], v[198:201], v[4:7]
	v_mfma_f32_16x16x32_bf16 v[0:3], v[214:217], v[198:201], v[0:3]
	s_add_i32 s48, s48, 2
	s_add_u32 s22, s22, 0x100
	s_addc_u32 s23, s23, 0
	s_add_u32 s46, s46, 0x100
	s_addc_u32 s47, s47, 0
	s_cmp_gt_u32 s48, 61
	s_barrier
; __device__ __forceinline__ unsigned pk2(float lo, float hi) { const f32x2 v = (f32x2){lo, hi}; const bf16x2_t b = __builtin_convertvector(v, bf16x2_t); return __builtin_bit_cast(unsigned, b); }
; __device__ __forceinline__ void unpack8(const u32x4 v, float* f) { f[0] = bf_lo(v.x); f[1] = bf_hi(v.x); f[2] = bf_lo(v.y); f[3] = bf_hi(v.y); f[4] = bf_lo(v.z); f[5] = bf_hi(v.z); f[6] = bf_lo(v.w); f[7] = bf_hi(v.w); }
;     __device__ __forceinline__ void operator()(const f32x4 (&acc)[2][2][4][2], const Unit& u, int wr, int wc, int fr, int fq, const float (&)[8]) const {
;         const int row0 = u.pm * BM + wr * 64 + fr, col0 = u.pn * BM + wc * 32 + 8 * fq;
; #pragma unroll
;         for (int ai = 0; ai < 2; ++ai) {
;             u32x4 bv[4][2];
; #pragma unroll
;             for (int m = 0; m < 4; ++m)
; #pragma unroll
;                 for (int bj = 0; bj < 2; ++bj) bv[m][bj] = *(const u32x4*)(xb + (size_t)(row0 + ai * HALF + m * 16) * DM + col0 + bj * HALF);
; #pragma unroll
;             for (int m = 0; m < 4; ++m) { const int row = row0 + ai * HALF + m * 16; const size_t ro = (size_t)row * DM + col0; float s = 0.f;
; #pragma unroll
;                 for (int bj = 0; bj < 2; ++bj) { float b8[8]; unpack8(bv[m][bj], b8);
;                     const f32x4 v0 = (f32x4){b8[0], b8[1], b8[2], b8[3]} + acc[ai][bj][m][0], v1 = (f32x4){b8[4], b8[5], b8[6], b8[7]} + acc[ai][bj][m][1];
;                     s += v0[0] * v0[0] + v0[1] * v0[1] + v0[2] * v0[2] + v0[3] * v0[3] + v1[0] * v1[0] + v1[1] * v1[1] + v1[2] * v1[2] + v1[3] * v1[3];
;                     if (LAST) { *(f32x4*)(out + ro + bj * HALF) = v0; *(f32x4*)(out + ro + bj * HALF + 4) = v1; }
;                     else { u32x4 w; w.x = pk2(v0[0], v0[1]); w.y = pk2(v0[2], v0[3]); w.z = pk2(v1[0], v1[1]); w.w = pk2(v1[2], v1[3]); *(u32x4*)(xb + ro + bj * HALF) = w; } }
;                 s += __shfl_xor(s, 16); s += __shfl_xor(s, 32);
;                 if (fq == 0) ss[(size_t)row * 16 + u.pn * 4 + wc] = s; }
	s_cbranch_scc0 .LBB0_1278
	v_lshl_or_b32 v170, s6, 8, v189
	v_lshl_add_u32 v172, s8, 8, v153
	v_ashrrev_i32_e32 v171, 31, v170
	v_lshlrev_b64 v[204:205], 1, v[170:171]
	v_ashrrev_i32_e32 v173, 31, v172
	v_lshl_add_u64 v[174:175], s[76:77], 0, v[204:205]
	v_lshlrev_b64 v[206:207], 11, v[172:173]
	v_lshl_add_u64 v[128:129], v[174:175], 0, v[206:207]
	global_load_dwordx4 v[196:199], v[128:129], off
	global_load_dwordx4 v[200:203], v[128:129], off offset:256
	v_or_b32_e32 v184, 16, v172
	v_or_b32_e32 v180, 32, v172
	v_or_b32_e32 v176, 48, v172
	v_ashrrev_i32_e32 v185, 31, v184
	v_ashrrev_i32_e32 v181, 31, v180
	v_ashrrev_i32_e32 v177, 31, v176
	v_lshlrev_b64 v[186:187], 11, v[184:185]
	v_lshlrev_b64 v[182:183], 11, v[180:181]
	v_lshlrev_b64 v[178:179], 11, v[176:177]
	v_lshl_add_u64 v[128:129], v[174:175], 0, v[186:187]
	v_lshl_add_u64 v[130:131], v[174:175], 0, v[182:183]
	v_lshl_add_u64 v[194:195], v[174:175], 0, v[178:179]
	global_load_dwordx4 v[148:151], v[128:129], off
	global_load_dwordx4 v[144:147], v[128:129], off offset:256
	global_load_dwordx4 v[140:143], v[130:131], off
	global_load_dwordx4 v[136:139], v[130:131], off offset:256
	global_load_dwordx4 v[132:135], v[194:195], off
	s_nop 0
	global_load_dwordx4 v[128:131], v[194:195], off offset:256
	v_add_u32_e32 v226, 0x80, v172
	v_ashrrev_i32_e32 v227, 31, v226
	v_lshlrev_b64 v[226:227], 11, v[226:227]
	v_lshl_add_u64 v[226:227], v[174:175], 0, v[226:227]
	global_load_dwordx4 v[216:219], v[226:227], off
	global_load_dwordx4 v[220:223], v[226:227], off offset:256
	v_add_u32_e32 v226, 0x90, v172
	v_ashrrev_i32_e32 v227, 31, v226
	v_lshlrev_b64 v[226:227], 11, v[226:227]
	v_lshl_add_u64 v[226:227], v[174:175], 0, v[226:227]
	global_load_dwordx4 v[228:231], v[226:227], off
	global_load_dwordx4 v[232:235], v[226:227], off offset:256
	v_add_u32_e32 v226, 0xa0, v172
	v_ashrrev_i32_e32 v227, 31, v226
	v_lshlrev_b64 v[226:227], 11, v[226:227]
	v_lshl_add_u64 v[226:227], v[174:175], 0, v[226:227]
	global_load_dwordx4 v[236:239], v[226:227], off
	global_load_dwordx4 v[240:243], v[226:227], off offset:256
	v_add_u32_e32 v226, 0xb0, v172
	v_ashrrev_i32_e32 v227, 31, v226
	v_lshlrev_b64 v[226:227], 11, v[226:227]
	v_lshl_add_u64 v[226:227], v[174:175], 0, v[226:227]
	global_load_dwordx4 v[244:247], v[226:227], off
	global_load_dwordx4 v[252:255], v[226:227], off offset:256
	v_and_b32_e32 v195, 64, v193
	v_xor_b32_e32 v194, 16, v193
	v_add_u32_e32 v195, 64, v195
	v_xor_b32_e32 v208, 32, v193
	v_cmp_lt_i32_e32 vcc, v194, v195
	s_waitcnt vmcnt(15)
	v_and_b32_e32 v209, 0xffff0000, v196
	v_cndmask_b32_e32 v194, v193, v194, vcc
	v_cmp_lt_i32_e32 vcc, v208, v195
	v_lshlrev_b32_e32 v195, 2, v194
	s_waitcnt vmcnt(14)
	v_lshlrev_b32_e32 v212, 16, v200
	v_cndmask_b32_e32 v208, v193, v208, vcc
	v_lshlrev_b32_e32 v194, 2, v208
	v_lshlrev_b32_e32 v208, 16, v196
	v_and_b32_e32 v213, 0xffff0000, v200
	v_lshlrev_b32_e32 v210, 16, v198
	v_and_b32_e32 v211, 0xffff0000, v198
	v_lshlrev_b32_e32 v198, 16, v199
	v_and_b32_e32 v199, 0xffff0000, v199
	v_lshlrev_b32_e32 v200, 16, v201
	v_and_b32_e32 v201, 0xffff0000, v201
	v_lshlrev_b32_e32 v214, 16, v202
	v_and_b32_e32 v215, 0xffff0000, v202
	v_pk_add_f32 v[124:125], v[124:125], v[208:209]
	v_pk_add_f32 v[116:117], v[116:117], v[212:213]
	v_lshlrev_b32_e32 v196, 16, v197
	v_and_b32_e32 v197, 0xffff0000, v197
	v_pk_add_f32 v[122:123], v[122:123], v[198:199]
	v_pk_add_f32 v[118:119], v[118:119], v[200:201]
	v_pk_add_f32 v[198:199], v[112:113], v[214:215]
	v_mul_f32_e32 v200, v125, v125
	v_cvt_pk_bf16_f32 v112, v124, v125
	v_mul_f32_e32 v125, v117, v117
	v_pk_add_f32 v[126:127], v[126:127], v[196:197]
	v_fmac_f32_e32 v200, v124, v124
	v_fmac_f32_e32 v125, v116, v116
	v_fmac_f32_e32 v200, v126, v126
	v_fmac_f32_e32 v125, v118, v118
	v_pk_add_f32 v[120:121], v[120:121], v[210:211]
	v_fmac_f32_e32 v200, v127, v127
	v_fmac_f32_e32 v125, v119, v119
	v_lshlrev_b32_e32 v202, 16, v203
	v_and_b32_e32 v203, 0xffff0000, v203
	v_fmac_f32_e32 v200, v120, v120
	v_fmac_f32_e32 v125, v198, v198
	v_pk_add_f32 v[196:197], v[114:115], v[202:203]
	v_fmac_f32_e32 v200, v121, v121
	v_fmac_f32_e32 v125, v199, v199
	v_fmac_f32_e32 v200, v122, v122
	v_fmac_f32_e32 v125, v196, v196
	v_fmac_f32_e32 v200, v123, v123
	v_fmac_f32_e32 v125, v197, v197
	v_cvt_pk_bf16_f32 v115, v122, v123
	v_add_f32_e32 v122, v200, v125
	ds_bpermute_b32 v123, v195, v122
	v_cvt_pk_bf16_f32 v114, v120, v121
	v_lshl_add_u64 v[120:121], s[76:77], 0, v[206:207]
	v_cvt_pk_bf16_f32 v113, v126, v127
	v_lshl_add_u64 v[120:121], v[120:121], 0, v[204:205]
	global_store_dwordx4 v[120:121], v[112:115], off
	s_waitcnt lgkmcnt(0)
	s_nop 0
	v_add_f32_e32 v112, v122, v123
	ds_bpermute_b32 v113, v194, v112
	v_cvt_pk_bf16_f32 v114, v116, v117
	v_cvt_pk_bf16_f32 v115, v118, v119
	v_cvt_pk_bf16_f32 v116, v198, v199
	v_cvt_pk_bf16_f32 v117, v196, v197
	global_store_dwordx4 v[120:121], v[114:117], off offset:256
	s_and_saveexec_b64 s[22:23], s[0:1]
	s_cbranch_execz .LBB0_1281
	s_waitcnt lgkmcnt(0)
	v_add_f32_e32 v114, v112, v113
	s_lshl_b32 s24, s6, 2
	v_lshlrev_b64 v[112:113], 6, v[172:173]
	s_ashr_i32 s25, s24, 31
	v_lshl_add_u64 v[112:113], s[10:11], 0, v[112:113]
	v_lshl_add_u64 v[112:113], s[24:25], 2, v[112:113]
	s_lshl_b32 s8, s37, 2
	v_lshl_add_u64 v[112:113], v[112:113], 0, s[8:9]
	global_store_dword v[112:113], v114, off
